# gldsfirst
# baseline (speedup 1.0000x reference)
; #define STAGE(P, BASE, LD, br, kt) do { const char* _g = (const char*)((BASE) + (size_t)(br) * (LD) + (size_t)(kt) * 64); \
;     for (int _i = 0; _i < 2; ++_i) { int _b = tidx * 16 + _i * 8192; int _r, _c; stage_rc(_b, _r, _c); \
;       __builtin_amdgcn_global_load_lds((const unsigned*)(_g + (unsigned)((_r * (LD) + _c) * 2)), (unsigned*)((char*)(P) + _b), 16, 0, 0); } } while (0)
; #define LDA(dst, b, h) for (int m = 0; m < 4; ++m) for (int k = 0; k < 2; ++k) \
;     dst[m][k] = *reinterpret_cast<const bf16x8*>((char*)SA(b, h) + lds_byte(wr * 64 + m * 16 + fr, k * 32 + fq * 8))
; #define LDB(dst, b, h) for (int n = 0; n < 2; ++n) for (int k = 0; k < 2; ++k) \
;     dst[n][k] = *reinterpret_cast<const bf16x8*>((char*)SB(b, h) + lds_byte(wc * 32 + n * 16 + fr, k * 32 + fq * 8))
; #define MMA(ai, bj, At_, Bt_) do { __builtin_amdgcn_s_setprio(1); \
;     for (int k = 0; k < 2; ++k) for (int m = 0; m < 4; ++m) for (int n = 0; n < 2; ++n) \
;       acc[ai][bj][m][n] = __builtin_amdgcn_mfma_f32_16x16x32_bf16(At_[m][k], Bt_[n][k], acc[ai][bj][m][n], 0, 0, 0); \
;     __builtin_amdgcn_s_setprio(0); } while (0)
; #define WAIT_V(n) asm volatile("s_waitcnt vmcnt(" #n ")" ::: "memory")
; #define WAIT_L(n) asm volatile("s_waitcnt lgkmcnt(" #n ")" ::: "memory")
; #define BAR __builtin_amdgcn_s_barrier()
; #define SCHED __builtin_amdgcn_sched_barrier(0)
; template <int EPI, int lda, int ldb, int N, int K>
; __device__ __forceinline__ void gemm_phase(const u16* __restrict__ A, const u16* __restrict__ Bt, const GemmEpi ep, int wv) {
;     ...
;     for (int t = 0; t < nt - 2; t += 2) {
;       LDB(B0, 0, 0); SCHED; LDA(At, 0, 0); STAGE(SA(1, 1), Ab, lda, brow + HALF, t + 1);
;       WAIT_L(8); BAR; WAIT_L(0); MMA(0, 0, At, B0); BAR; SCHED;
;       LDB(B1, 0, 1); STAGE(SB(0, 0), Bt, ldb, bcol, t + 2);
;       BAR; WAIT_L(0); MMA(0, 1, At, B1); BAR;
;       LDA(At, 0, 1); STAGE(SA(0, 0), Ab, lda, brow, t + 2);
;       BAR; WAIT_L(0); MMA(1, 0, At, B0); BAR; SCHED;
;       STAGE(SB(0, 1), Bt, ldb, bcol + HALF, t + 2);
;       WAIT_V(6); BAR; MMA(1, 1, At, B1); BAR;
;       LDB(B0, 1, 0); SCHED; LDA(At, 1, 0); STAGE(SA(0, 1), Ab, lda, brow + HALF, t + 2);
;       WAIT_L(8); BAR; WAIT_L(0); MMA(0, 0, At, B0); BAR; SCHED;
.LBB0_53:
	ds_read_b128 v[172:175], v161
	ds_read_b128 v[176:179], v161 offset:1024
	ds_read_b128 v[180:183], v161 offset:2048
	ds_read_b128 v[184:187], v161 offset:3072
	v_add_u32_e32 v169, 0xc000, v148
	v_lshl_add_u64 v[236:237], v[136:137], 0, s[42:43]
	v_readfirstlane_b32 s45, v169
	v_add_u32_e32 v170, 0xe000, v148
	v_lshl_add_u64 v[162:163], v[236:237], 0, s[14:15]
	s_mov_b32 m0, s45
	v_lshl_add_u64 v[238:239], v[134:135], 0, s[42:43]
	v_readfirstlane_b32 s45, v170
	global_load_lds_dwordx4 v[162:163], off
	v_lshl_add_u64 v[162:163], v[238:239], 0, s[14:15]
	s_mov_b32 m0, s45
	s_nop 0
	global_load_lds_dwordx4 v[162:163], off
	ds_read_b128 v[164:167], v152
	ds_read_b128 v[188:191], v152 offset:1024
	ds_read_b128 v[192:195], v151
	ds_read_b128 v[196:199], v151 offset:1024
	ds_read_b128 v[200:203], v150
	ds_read_b128 v[204:207], v150 offset:1024
	ds_read_b128 v[208:211], v149
	ds_read_b128 v[212:215], v149 offset:1024
	s_waitcnt lgkmcnt(8)
	s_barrier
	s_waitcnt lgkmcnt(0)
	s_waitcnt lgkmcnt(0)
	v_mfma_f32_16x16x32_bf16 v[124:127], v[172:175], v[164:167], v[124:127]
	v_mfma_f32_16x16x32_bf16 v[120:123], v[180:183], v[164:167], v[120:123]
	v_mfma_f32_16x16x32_bf16 v[116:119], v[172:175], v[192:195], v[116:119]
	v_mfma_f32_16x16x32_bf16 v[112:115], v[180:183], v[192:195], v[112:115]
	v_mfma_f32_16x16x32_bf16 v[108:111], v[172:175], v[200:203], v[108:111]
	v_mfma_f32_16x16x32_bf16 v[104:107], v[180:183], v[200:203], v[104:107]
	v_mfma_f32_16x16x32_bf16 v[100:103], v[172:175], v[208:211], v[100:103]
	v_mfma_f32_16x16x32_bf16 v[96:99], v[180:183], v[208:211], v[96:99]
	v_mfma_f32_16x16x32_bf16 v[124:127], v[176:179], v[188:191], v[124:127]
	v_mfma_f32_16x16x32_bf16 v[120:123], v[184:187], v[188:191], v[120:123]
	v_mfma_f32_16x16x32_bf16 v[116:119], v[176:179], v[196:199], v[116:119]
	v_mfma_f32_16x16x32_bf16 v[112:115], v[184:187], v[196:199], v[112:115]
	v_mfma_f32_16x16x32_bf16 v[108:111], v[176:179], v[204:207], v[108:111]
	v_mfma_f32_16x16x32_bf16 v[104:107], v[184:187], v[204:207], v[104:107]
	v_mfma_f32_16x16x32_bf16 v[100:103], v[176:179], v[212:215], v[100:103]
	v_mfma_f32_16x16x32_bf16 v[96:99], v[184:187], v[212:215], v[96:99]
	s_barrier
	v_add_u32_e32 v162, s54, v153
	v_lshl_add_u64 v[240:241], v[140:141], 0, s[42:43]
	v_readfirstlane_b32 s45, v162
	v_add_u32_e32 v163, 0x2000, v162
	v_lshl_add_u64 v[232:233], v[240:241], 0, s[16:17]
	s_mov_b32 m0, s45
	v_lshl_add_u64 v[242:243], v[138:139], 0, s[42:43]
	v_readfirstlane_b32 s45, v163
	global_load_lds_dwordx4 v[232:233], off
	v_lshl_add_u64 v[232:233], v[242:243], 0, s[16:17]
	s_mov_b32 m0, s45
	s_nop 0
	global_load_lds_dwordx4 v[232:233], off
	ds_read_b128 v[216:219], v160
	ds_read_b128 v[220:223], v160 offset:1024
	ds_read_b128 v[224:227], v160 offset:2048
	ds_read_b128 v[228:231], v160 offset:3072
	s_barrier
	s_waitcnt lgkmcnt(0)
	s_waitcnt lgkmcnt(0)
	v_mfma_f32_16x16x32_bf16 v[92:95], v[216:219], v[164:167], v[92:95]
	v_mfma_f32_16x16x32_bf16 v[88:91], v[224:227], v[164:167], v[88:91]
	v_mfma_f32_16x16x32_bf16 v[84:87], v[216:219], v[192:195], v[84:87]
	v_mfma_f32_16x16x32_bf16 v[80:83], v[224:227], v[192:195], v[80:83]
	v_mfma_f32_16x16x32_bf16 v[76:79], v[216:219], v[200:203], v[76:79]
	v_mfma_f32_16x16x32_bf16 v[72:75], v[224:227], v[200:203], v[72:75]
	v_mfma_f32_16x16x32_bf16 v[68:71], v[216:219], v[208:211], v[68:71]
	v_mfma_f32_16x16x32_bf16 v[64:67], v[224:227], v[208:211], v[64:67]
	v_mfma_f32_16x16x32_bf16 v[92:95], v[220:223], v[188:191], v[92:95]
	v_mfma_f32_16x16x32_bf16 v[88:91], v[228:231], v[188:191], v[88:91]
	v_mfma_f32_16x16x32_bf16 v[84:87], v[220:223], v[196:199], v[84:87]
	v_mfma_f32_16x16x32_bf16 v[80:83], v[228:231], v[196:199], v[80:83]
	v_mfma_f32_16x16x32_bf16 v[76:79], v[220:223], v[204:207], v[76:79]
	v_mfma_f32_16x16x32_bf16 v[72:75], v[228:231], v[204:207], v[72:75]
	v_mfma_f32_16x16x32_bf16 v[68:71], v[220:223], v[212:215], v[68:71]
	v_mfma_f32_16x16x32_bf16 v[64:67], v[228:231], v[212:215], v[64:67]
	v_readfirstlane_b32 s45, v148
	v_lshl_add_u64 v[164:165], v[236:237], 0, s[18:19]
	s_mov_b32 m0, s45
	s_barrier
	global_load_lds_dwordx4 v[164:165], off
	v_add_u32_e32 v164, 0x2000, v148
	v_lshl_add_u64 v[166:167], v[238:239], 0, s[18:19]
	v_readfirstlane_b32 s45, v164
	s_mov_b32 m0, s45
	s_nop 0
	global_load_lds_dwordx4 v[166:167], off
	ds_read_b128 v[188:191], v152 offset:16384
	ds_read_b128 v[192:195], v152 offset:17408
	ds_read_b128 v[196:199], v151 offset:16384
	ds_read_b128 v[200:203], v151 offset:17408
	ds_read_b128 v[204:207], v150 offset:16384
	ds_read_b128 v[208:211], v150 offset:17408
	ds_read_b128 v[212:215], v149 offset:16384
	ds_read_b128 v[232:235], v149 offset:17408
	s_barrier
	s_waitcnt lgkmcnt(0)
	s_waitcnt lgkmcnt(0)
	v_mfma_f32_16x16x32_bf16 v[60:63], v[172:175], v[188:191], v[60:63]
	v_mfma_f32_16x16x32_bf16 v[56:59], v[180:183], v[188:191], v[56:59]
	v_mfma_f32_16x16x32_bf16 v[52:55], v[172:175], v[196:199], v[52:55]
	v_mfma_f32_16x16x32_bf16 v[48:51], v[180:183], v[196:199], v[48:51]
	v_mfma_f32_16x16x32_bf16 v[44:47], v[172:175], v[204:207], v[44:47]
	v_mfma_f32_16x16x32_bf16 v[40:43], v[180:183], v[204:207], v[40:43]
	v_mfma_f32_16x16x32_bf16 v[36:39], v[172:175], v[212:215], v[36:39]
	v_mfma_f32_16x16x32_bf16 v[32:35], v[180:183], v[212:215], v[32:35]
	v_mfma_f32_16x16x32_bf16 v[60:63], v[176:179], v[192:195], v[60:63]
	v_mfma_f32_16x16x32_bf16 v[56:59], v[184:187], v[192:195], v[56:59]
	v_mfma_f32_16x16x32_bf16 v[52:55], v[176:179], v[200:203], v[52:55]
	v_mfma_f32_16x16x32_bf16 v[48:51], v[184:187], v[200:203], v[48:51]
	v_mfma_f32_16x16x32_bf16 v[44:47], v[176:179], v[208:211], v[44:47]
	v_mfma_f32_16x16x32_bf16 v[40:43], v[184:187], v[208:211], v[40:43]
	v_mfma_f32_16x16x32_bf16 v[36:39], v[176:179], v[232:235], v[36:39]
	v_mfma_f32_16x16x32_bf16 v[32:35], v[184:187], v[232:235], v[32:35]
	s_barrier
; #define STAGE(P, BASE, LD, br, kt) do { const char* _g = (const char*)((BASE) + (size_t)(br) * (LD) + (size_t)(kt) * 64); \
;     for (int _i = 0; _i < 2; ++_i) { int _b = tidx * 16 + _i * 8192; int _r, _c; stage_rc(_b, _r, _c); \
;       __builtin_amdgcn_global_load_lds((const unsigned*)(_g + (unsigned)((_r * (LD) + _c) * 2)), (unsigned*)((char*)(P) + _b), 16, 0, 0); } } while (0)
; #define LDA(dst, b, h) for (int m = 0; m < 4; ++m) for (int k = 0; k < 2; ++k) \
;     dst[m][k] = *reinterpret_cast<const bf16x8*>((char*)SA(b, h) + lds_byte(wr * 64 + m * 16 + fr, k * 32 + fq * 8))
; #define LDB(dst, b, h) for (int n = 0; n < 2; ++n) for (int k = 0; k < 2; ++k) \
;     dst[n][k] = *reinterpret_cast<const bf16x8*>((char*)SB(b, h) + lds_byte(wc * 32 + n * 16 + fr, k * 32 + fq * 8))
; #define MMA(ai, bj, At_, Bt_) do { __builtin_amdgcn_s_setprio(1); \
;     for (int k = 0; k < 2; ++k) for (int m = 0; m < 4; ++m) for (int n = 0; n < 2; ++n) \
;       acc[ai][bj][m][n] = __builtin_amdgcn_mfma_f32_16x16x32_bf16(At_[m][k], Bt_[n][k], acc[ai][bj][m][n], 0, 0, 0); \
;     __builtin_amdgcn_s_setprio(0); } while (0)
; #define WAIT_V(n) asm volatile("s_waitcnt vmcnt(" #n ")" ::: "memory")
; #define WAIT_L(n) asm volatile("s_waitcnt lgkmcnt(" #n ")" ::: "memory")
; #define BAR __builtin_amdgcn_s_barrier()
; #define SCHED __builtin_amdgcn_sched_barrier(0)
; template <int EPI, int lda, int ldb, int N, int K>
; __device__ __forceinline__ void gemm_phase(const u16* __restrict__ A, const u16* __restrict__ Bt, const GemmEpi ep, int wv) {
;     ...
;       STAGE(SB(0, 1), Bt, ldb, bcol + HALF, t + 2);
;       WAIT_V(6); BAR; MMA(1, 1, At, B1); BAR;
;       LDB(B0, 1, 0); SCHED; LDA(At, 1, 0); STAGE(SA(0, 1), Ab, lda, brow + HALF, t + 2);
;       WAIT_L(8); BAR; WAIT_L(0); MMA(0, 0, At, B0); BAR; SCHED;
;       LDB(B1, 1, 1); STAGE(SB(1, 0), Bt, ldb, bcol, t + 3);
;       BAR; WAIT_L(0); MMA(0, 1, At, B1); BAR;
;       LDA(At, 1, 1); STAGE(SA(1, 0), Ab, lda, brow, t + 3);
;       BAR; WAIT_L(0); MMA(1, 0, At, B0); BAR; SCHED;
	v_add_u32_e32 v165, s55, v153
	v_lshl_add_u64 v[166:167], v[240:241], 0, s[20:21]
	v_readfirstlane_b32 s45, v165
	s_mov_b32 m0, s45
	v_lshl_add_u64 v[172:173], v[242:243], 0, s[20:21]
	global_load_lds_dwordx4 v[166:167], off
	v_add_u32_e32 v166, 0x2000, v165
	s_nop 0
	v_readfirstlane_b32 s45, v166
	s_mov_b32 m0, s45
	s_nop 0
	global_load_lds_dwordx4 v[172:173], off
	s_waitcnt vmcnt(6)
	s_barrier
	v_mfma_f32_16x16x32_bf16 v[28:31], v[216:219], v[188:191], v[28:31]
	v_mfma_f32_16x16x32_bf16 v[24:27], v[224:227], v[188:191], v[24:27]
	v_mfma_f32_16x16x32_bf16 v[20:23], v[216:219], v[196:199], v[20:23]
	v_mfma_f32_16x16x32_bf16 v[16:19], v[224:227], v[196:199], v[16:19]
	v_mfma_f32_16x16x32_bf16 v[12:15], v[216:219], v[204:207], v[12:15]
	v_mfma_f32_16x16x32_bf16 v[8:11], v[224:227], v[204:207], v[8:11]
	v_mfma_f32_16x16x32_bf16 v[4:7], v[216:219], v[212:215], v[4:7]
	v_mfma_f32_16x16x32_bf16 v[0:3], v[224:227], v[212:215], v[0:3]
	v_mfma_f32_16x16x32_bf16 v[28:31], v[220:223], v[192:195], v[28:31]
	v_mfma_f32_16x16x32_bf16 v[24:27], v[228:231], v[192:195], v[24:27]
	v_mfma_f32_16x16x32_bf16 v[20:23], v[220:223], v[200:203], v[20:23]
	v_mfma_f32_16x16x32_bf16 v[16:19], v[228:231], v[200:203], v[16:19]
	v_mfma_f32_16x16x32_bf16 v[12:15], v[220:223], v[208:211], v[12:15]
	v_mfma_f32_16x16x32_bf16 v[8:11], v[228:231], v[208:211], v[8:11]
	v_mfma_f32_16x16x32_bf16 v[4:7], v[220:223], v[232:235], v[4:7]
	v_mfma_f32_16x16x32_bf16 v[0:3], v[228:231], v[232:235], v[0:3]
	s_barrier
	ds_read_b128 v[172:175], v156
	ds_read_b128 v[176:179], v156 offset:1024
	ds_read_b128 v[180:183], v156 offset:2048
	ds_read_b128 v[184:187], v156 offset:3072
	v_add_u32_e32 v167, 0x4000, v148
	v_add_u32_e32 v168, 0x6000, v148
	v_readfirstlane_b32 s45, v167
	v_lshl_add_u64 v[220:221], v[236:237], 0, s[22:23]
	s_mov_b32 m0, s45
	v_readfirstlane_b32 s45, v168
	global_load_lds_dwordx4 v[220:221], off
	v_lshl_add_u64 v[220:221], v[238:239], 0, s[22:23]
	s_mov_b32 m0, s45
	s_nop 0
	global_load_lds_dwordx4 v[220:221], off
	ds_read_b128 v[188:191], v152 offset:32768
	ds_read_b128 v[192:195], v152 offset:33792
	ds_read_b128 v[196:199], v151 offset:32768
	ds_read_b128 v[200:203], v151 offset:33792
	ds_read_b128 v[204:207], v150 offset:32768
	ds_read_b128 v[208:211], v150 offset:33792
	ds_read_b128 v[212:215], v149 offset:32768
	ds_read_b128 v[216:219], v149 offset:33792
	s_waitcnt lgkmcnt(8)
	s_barrier
	s_waitcnt lgkmcnt(0)
	s_waitcnt lgkmcnt(0)
	v_mfma_f32_16x16x32_bf16 v[124:127], v[172:175], v[188:191], v[124:127]
	v_mfma_f32_16x16x32_bf16 v[120:123], v[180:183], v[188:191], v[120:123]
	v_mfma_f32_16x16x32_bf16 v[116:119], v[172:175], v[196:199], v[116:119]
	v_mfma_f32_16x16x32_bf16 v[112:115], v[180:183], v[196:199], v[112:115]
	v_mfma_f32_16x16x32_bf16 v[108:111], v[172:175], v[204:207], v[108:111]
	v_mfma_f32_16x16x32_bf16 v[104:107], v[180:183], v[204:207], v[104:107]
	v_mfma_f32_16x16x32_bf16 v[100:103], v[172:175], v[212:215], v[100:103]
	v_mfma_f32_16x16x32_bf16 v[96:99], v[180:183], v[212:215], v[96:99]
	v_mfma_f32_16x16x32_bf16 v[124:127], v[176:179], v[192:195], v[124:127]
	v_mfma_f32_16x16x32_bf16 v[120:123], v[184:187], v[192:195], v[120:123]
	v_mfma_f32_16x16x32_bf16 v[116:119], v[176:179], v[200:203], v[116:119]
	v_mfma_f32_16x16x32_bf16 v[112:115], v[184:187], v[200:203], v[112:115]
	v_mfma_f32_16x16x32_bf16 v[108:111], v[176:179], v[208:211], v[108:111]
	v_mfma_f32_16x16x32_bf16 v[104:107], v[184:187], v[208:211], v[104:107]
	v_mfma_f32_16x16x32_bf16 v[100:103], v[176:179], v[216:219], v[100:103]
	v_mfma_f32_16x16x32_bf16 v[96:99], v[184:187], v[216:219], v[96:99]
	s_barrier
	v_readfirstlane_b32 s45, v155
	v_add_u32_e32 v171, 0x2000, v155
	v_lshl_add_u64 v[244:245], v[240:241], 0, s[24:25]
	s_mov_b32 m0, s45
	v_readfirstlane_b32 s45, v171
	global_load_lds_dwordx4 v[244:245], off
	v_lshl_add_u64 v[244:245], v[242:243], 0, s[24:25]
	s_mov_b32 m0, s45
	s_nop 0
	global_load_lds_dwordx4 v[244:245], off
	ds_read_b128 v[220:223], v154
	ds_read_b128 v[224:227], v154 offset:1024
	ds_read_b128 v[228:231], v154 offset:2048
	ds_read_b128 v[232:235], v154 offset:3072
	s_barrier
	s_waitcnt lgkmcnt(0)
	s_waitcnt lgkmcnt(0)
	v_mfma_f32_16x16x32_bf16 v[92:95], v[220:223], v[188:191], v[92:95]
	v_mfma_f32_16x16x32_bf16 v[88:91], v[228:231], v[188:191], v[88:91]
	v_mfma_f32_16x16x32_bf16 v[84:87], v[220:223], v[196:199], v[84:87]
	v_mfma_f32_16x16x32_bf16 v[80:83], v[228:231], v[196:199], v[80:83]
	v_mfma_f32_16x16x32_bf16 v[76:79], v[220:223], v[204:207], v[76:79]
	v_mfma_f32_16x16x32_bf16 v[72:75], v[228:231], v[204:207], v[72:75]
	v_mfma_f32_16x16x32_bf16 v[68:71], v[220:223], v[212:215], v[68:71]
	v_mfma_f32_16x16x32_bf16 v[64:67], v[228:231], v[212:215], v[64:67]
	v_mfma_f32_16x16x32_bf16 v[92:95], v[224:227], v[192:195], v[92:95]
	v_mfma_f32_16x16x32_bf16 v[88:91], v[232:235], v[192:195], v[88:91]
	v_mfma_f32_16x16x32_bf16 v[84:87], v[224:227], v[200:203], v[84:87]
	v_mfma_f32_16x16x32_bf16 v[80:83], v[232:235], v[200:203], v[80:83]
	v_mfma_f32_16x16x32_bf16 v[76:79], v[224:227], v[208:211], v[76:79]
	v_mfma_f32_16x16x32_bf16 v[72:75], v[232:235], v[208:211], v[72:75]
	v_mfma_f32_16x16x32_bf16 v[68:71], v[224:227], v[216:219], v[68:71]
	v_mfma_f32_16x16x32_bf16 v[64:67], v[232:235], v[216:219], v[64:67]
	v_readfirstlane_b32 s45, v157
	v_lshl_add_u64 v[236:237], v[236:237], 0, s[26:27]
	s_mov_b32 m0, s45
	v_readfirstlane_b32 s45, v158
	s_barrier
; #define STAGE(P, BASE, LD, br, kt) do { const char* _g = (const char*)((BASE) + (size_t)(br) * (LD) + (size_t)(kt) * 64); \
;     for (int _i = 0; _i < 2; ++_i) { int _b = tidx * 16 + _i * 8192; int _r, _c; stage_rc(_b, _r, _c); \
;       __builtin_amdgcn_global_load_lds((const unsigned*)(_g + (unsigned)((_r * (LD) + _c) * 2)), (unsigned*)((char*)(P) + _b), 16, 0, 0); } } while (0)
; #define LDA(dst, b, h) for (int m = 0; m < 4; ++m) for (int k = 0; k < 2; ++k) \
;     dst[m][k] = *reinterpret_cast<const bf16x8*>((char*)SA(b, h) + lds_byte(wr * 64 + m * 16 + fr, k * 32 + fq * 8))
; #define LDB(dst, b, h) for (int n = 0; n < 2; ++n) for (int k = 0; k < 2; ++k) \
;     dst[n][k] = *reinterpret_cast<const bf16x8*>((char*)SB(b, h) + lds_byte(wc * 32 + n * 16 + fr, k * 32 + fq * 8))
; #define MMA(ai, bj, At_, Bt_) do { __builtin_amdgcn_s_setprio(1); \
;     for (int k = 0; k < 2; ++k) for (int m = 0; m < 4; ++m) for (int n = 0; n < 2; ++n) \
;       acc[ai][bj][m][n] = __builtin_amdgcn_mfma_f32_16x16x32_bf16(At_[m][k], Bt_[n][k], acc[ai][bj][m][n], 0, 0, 0); \
;     __builtin_amdgcn_s_setprio(0); } while (0)
; #define WAIT_V(n) asm volatile("s_waitcnt vmcnt(" #n ")" ::: "memory")
; #define WAIT_L(n) asm volatile("s_waitcnt lgkmcnt(" #n ")" ::: "memory")
; #define BAR __builtin_amdgcn_s_barrier()
; #define SCHED __builtin_amdgcn_sched_barrier(0)
; template <int EPI, int lda, int ldb, int N, int K>
; __device__ __forceinline__ void gemm_phase(const u16* __restrict__ A, const u16* __restrict__ Bt, const GemmEpi ep, int wv) {
;     ...
;       LDA(At, 1, 1); STAGE(SA(1, 0), Ab, lda, brow, t + 3);
;       BAR; WAIT_L(0); MMA(1, 0, At, B0); BAR; SCHED;
;       STAGE(SB(1, 1), Bt, ldb, bcol + HALF, t + 3);
;       WAIT_V(6); BAR; MMA(1, 1, At, B1); BAR;
;     }
;     { LDB(B0, 0, 0); LDA(At, 0, 0); STAGE(SA(1, 1), Ab, lda, brow + HALF, nt - 1);
;       BAR; WAIT_L(0); MMA(0, 0, At, B0); BAR;
;       LDB(B1, 0, 1); BAR; WAIT_L(0); MMA(0, 1, At, B1); BAR;
;       LDA(At, 0, 1); WAIT_V(4); BAR; WAIT_L(0); MMA(1, 0, At, B0); MMA(1, 1, At, B1); BAR; }
	global_load_lds_dwordx4 v[236:237], off
	v_lshl_add_u64 v[236:237], v[238:239], 0, s[26:27]
	s_mov_b32 m0, s45
	s_nop 0
	global_load_lds_dwordx4 v[236:237], off
	ds_read_b128 v[188:191], v152 offset:49152
	ds_read_b128 v[192:195], v152 offset:50176
	ds_read_b128 v[196:199], v151 offset:49152
	ds_read_b128 v[200:203], v151 offset:50176
	ds_read_b128 v[204:207], v150 offset:49152
	ds_read_b128 v[208:211], v150 offset:50176
	ds_read_b128 v[212:215], v149 offset:49152
	ds_read_b128 v[216:219], v149 offset:50176
	s_barrier
	s_waitcnt lgkmcnt(0)
	s_waitcnt lgkmcnt(0)
	v_mfma_f32_16x16x32_bf16 v[60:63], v[172:175], v[188:191], v[60:63]
	v_mfma_f32_16x16x32_bf16 v[56:59], v[180:183], v[188:191], v[56:59]
	v_mfma_f32_16x16x32_bf16 v[52:55], v[172:175], v[196:199], v[52:55]
	v_mfma_f32_16x16x32_bf16 v[48:51], v[180:183], v[196:199], v[48:51]
	v_mfma_f32_16x16x32_bf16 v[44:47], v[172:175], v[204:207], v[44:47]
	v_mfma_f32_16x16x32_bf16 v[40:43], v[180:183], v[204:207], v[40:43]
	v_mfma_f32_16x16x32_bf16 v[36:39], v[172:175], v[212:215], v[36:39]
	v_mfma_f32_16x16x32_bf16 v[32:35], v[180:183], v[212:215], v[32:35]
	v_mfma_f32_16x16x32_bf16 v[60:63], v[176:179], v[192:195], v[60:63]
	v_mfma_f32_16x16x32_bf16 v[56:59], v[184:187], v[192:195], v[56:59]
	v_mfma_f32_16x16x32_bf16 v[52:55], v[176:179], v[200:203], v[52:55]
	v_mfma_f32_16x16x32_bf16 v[48:51], v[184:187], v[200:203], v[48:51]
	v_mfma_f32_16x16x32_bf16 v[44:47], v[176:179], v[208:211], v[44:47]
	v_mfma_f32_16x16x32_bf16 v[40:43], v[184:187], v[208:211], v[40:43]
	v_mfma_f32_16x16x32_bf16 v[36:39], v[176:179], v[216:219], v[36:39]
	v_mfma_f32_16x16x32_bf16 v[32:35], v[184:187], v[216:219], v[32:35]
	s_barrier
	v_readfirstlane_b32 s45, v159
	v_add_u32_e32 v171, 0x2000, v159
	v_lshl_add_u64 v[172:173], v[240:241], 0, s[34:35]
	s_mov_b32 m0, s45
	v_readfirstlane_b32 s45, v171
	global_load_lds_dwordx4 v[172:173], off
	v_lshl_add_u64 v[172:173], v[242:243], 0, s[34:35]
	s_mov_b32 m0, s45
	s_nop 0
	global_load_lds_dwordx4 v[172:173], off
	s_waitcnt vmcnt(6)
	s_barrier
	v_mfma_f32_16x16x32_bf16 v[28:31], v[220:223], v[188:191], v[28:31]
	v_mfma_f32_16x16x32_bf16 v[24:27], v[228:231], v[188:191], v[24:27]
	v_mfma_f32_16x16x32_bf16 v[20:23], v[220:223], v[196:199], v[20:23]
	v_mfma_f32_16x16x32_bf16 v[16:19], v[228:231], v[196:199], v[16:19]
	v_mfma_f32_16x16x32_bf16 v[12:15], v[220:223], v[204:207], v[12:15]
	v_mfma_f32_16x16x32_bf16 v[8:11], v[228:231], v[204:207], v[8:11]
	v_mfma_f32_16x16x32_bf16 v[4:7], v[220:223], v[212:215], v[4:7]
	v_mfma_f32_16x16x32_bf16 v[0:3], v[228:231], v[212:215], v[0:3]
	v_mfma_f32_16x16x32_bf16 v[28:31], v[224:227], v[192:195], v[28:31]
	v_mfma_f32_16x16x32_bf16 v[24:27], v[232:235], v[192:195], v[24:27]
	v_mfma_f32_16x16x32_bf16 v[20:23], v[224:227], v[200:203], v[20:23]
	v_mfma_f32_16x16x32_bf16 v[16:19], v[232:235], v[200:203], v[16:19]
	v_mfma_f32_16x16x32_bf16 v[12:15], v[224:227], v[208:211], v[12:15]
	v_mfma_f32_16x16x32_bf16 v[8:11], v[232:235], v[208:211], v[8:11]
	v_mfma_f32_16x16x32_bf16 v[4:7], v[224:227], v[216:219], v[4:7]
	v_mfma_f32_16x16x32_bf16 v[0:3], v[232:235], v[216:219], v[0:3]
	s_add_i32 s44, s44, 2
	s_add_u32 s42, s42, 0x100
	s_addc_u32 s43, s43, 0
	s_cmp_gt_u32 s44, 27
	s_barrier
	s_cbranch_scc0 .LBB0_53
	s_add_i32 s42, s38, 0x80
	s_mul_hi_i32 s43, s42, 0x1080
	s_mulk_i32 s42, 0x1080
	s_add_u32 s42, s51, s42
	s_addc_u32 s43, s52, s43
	v_lshl_add_u64 v[158:159], s[42:43], 0, v[128:129]
	v_readfirstlane_b32 s44, v169
	v_lshl_add_u64 v[158:159], v[158:159], 0, s[36:37]
	s_mov_b32 m0, s44
	ds_read_b128 v[134:137], v161
	ds_read_b128 v[138:141], v161 offset:1024
	ds_read_b128 v[172:175], v161 offset:2048
	ds_read_b128 v[176:179], v161 offset:3072
	ds_read_b128 v[180:183], v152
	ds_read_b128 v[184:187], v152 offset:1024
	ds_read_b128 v[188:191], v151
	ds_read_b128 v[192:195], v151 offset:1024
	ds_read_b128 v[196:199], v150
	ds_read_b128 v[200:203], v150 offset:1024
	ds_read_b128 v[204:207], v149
	ds_read_b128 v[208:211], v149 offset:1024
	global_load_lds_dwordx4 v[158:159], off
	v_lshl_add_u64 v[158:159], s[42:43], 0, v[132:133]
	v_readfirstlane_b32 s42, v170
	v_lshl_add_u64 v[158:159], v[158:159], 0, s[36:37]
	s_mov_b32 m0, s42
	s_nop 0
	global_load_lds_dwordx4 v[158:159], off
	s_barrier
	s_waitcnt lgkmcnt(0)
	s_waitcnt lgkmcnt(0)
	v_mfma_f32_16x16x32_bf16 v[124:127], v[134:137], v[180:183], v[124:127]
	v_mfma_f32_16x16x32_bf16 v[120:123], v[172:175], v[180:183], v[120:123]
	v_mfma_f32_16x16x32_bf16 v[116:119], v[134:137], v[188:191], v[116:119]
	v_mfma_f32_16x16x32_bf16 v[112:115], v[172:175], v[188:191], v[112:115]
	v_mfma_f32_16x16x32_bf16 v[108:111], v[134:137], v[196:199], v[108:111]
	v_mfma_f32_16x16x32_bf16 v[104:107], v[172:175], v[196:199], v[104:107]
	v_mfma_f32_16x16x32_bf16 v[100:103], v[134:137], v[204:207], v[100:103]
	v_mfma_f32_16x16x32_bf16 v[96:99], v[172:175], v[204:207], v[96:99]
	v_mfma_f32_16x16x32_bf16 v[124:127], v[138:141], v[184:187], v[124:127]
	v_mfma_f32_16x16x32_bf16 v[120:123], v[176:179], v[184:187], v[120:123]
	v_mfma_f32_16x16x32_bf16 v[116:119], v[138:141], v[192:195], v[116:119]
	v_mfma_f32_16x16x32_bf16 v[112:115], v[176:179], v[192:195], v[112:115]
	v_mfma_f32_16x16x32_bf16 v[108:111], v[138:141], v[200:203], v[108:111]
	v_mfma_f32_16x16x32_bf16 v[104:107], v[176:179], v[200:203], v[104:107]
	v_mfma_f32_16x16x32_bf16 v[100:103], v[138:141], v[208:211], v[100:103]
	v_mfma_f32_16x16x32_bf16 v[96:99], v[176:179], v[208:211], v[96:99]
	s_barrier
	ds_read_b128 v[212:215], v160
	ds_read_b128 v[216:219], v160 offset:1024
	ds_read_b128 v[220:223], v160 offset:2048
	ds_read_b128 v[158:161], v160 offset:3072
	s_barrier
; #define LDA(dst, b, h) for (int m = 0; m < 4; ++m) for (int k = 0; k < 2; ++k) \
;     dst[m][k] = *reinterpret_cast<const bf16x8*>((char*)SA(b, h) + lds_byte(wr * 64 + m * 16 + fr, k * 32 + fq * 8))
; #define LDB(dst, b, h) for (int n = 0; n < 2; ++n) for (int k = 0; k < 2; ++k) \
;     dst[n][k] = *reinterpret_cast<const bf16x8*>((char*)SB(b, h) + lds_byte(wc * 32 + n * 16 + fr, k * 32 + fq * 8))
; #define MMA(ai, bj, At_, Bt_) do { __builtin_amdgcn_s_setprio(1); \
;     for (int k = 0; k < 2; ++k) for (int m = 0; m < 4; ++m) for (int n = 0; n < 2; ++n) \
;       acc[ai][bj][m][n] = __builtin_amdgcn_mfma_f32_16x16x32_bf16(At_[m][k], Bt_[n][k], acc[ai][bj][m][n], 0, 0, 0); \
;     __builtin_amdgcn_s_setprio(0); } while (0)
; #define WAIT_V(n) asm volatile("s_waitcnt vmcnt(" #n ")" ::: "memory")
; #define WAIT_L(n) asm volatile("s_waitcnt lgkmcnt(" #n ")" ::: "memory")
; #define BAR __builtin_amdgcn_s_barrier()
; template <int EPI, int lda, int ldb, int N, int K>
; __device__ __forceinline__ void gemm_phase(const u16* __restrict__ A, const u16* __restrict__ Bt, const GemmEpi ep, int wv) {
;     ...
;       BAR; WAIT_L(0); MMA(0, 0, At, B0); BAR;
;       LDB(B1, 0, 1); BAR; WAIT_L(0); MMA(0, 1, At, B1); BAR;
;       LDA(At, 0, 1); WAIT_V(4); BAR; WAIT_L(0); MMA(1, 0, At, B0); MMA(1, 1, At, B1); BAR; }
;     { LDB(B0, 1, 0); LDA(At, 1, 0); WAIT_V(2); BAR; WAIT_L(0); MMA(0, 0, At, B0); BAR;
	s_waitcnt lgkmcnt(0)
	s_waitcnt lgkmcnt(0)
	v_mfma_f32_16x16x32_bf16 v[92:95], v[212:215], v[180:183], v[92:95]
	v_mfma_f32_16x16x32_bf16 v[88:91], v[220:223], v[180:183], v[88:91]
	v_mfma_f32_16x16x32_bf16 v[76:79], v[212:215], v[196:199], v[76:79]
	v_mfma_f32_16x16x32_bf16 v[72:75], v[220:223], v[196:199], v[72:75]
	v_mfma_f32_16x16x32_bf16 v[84:87], v[212:215], v[188:191], v[84:87]
	v_mfma_f32_16x16x32_bf16 v[80:83], v[220:223], v[188:191], v[80:83]
	v_mfma_f32_16x16x32_bf16 v[68:71], v[212:215], v[204:207], v[68:71]
	v_mfma_f32_16x16x32_bf16 v[64:67], v[220:223], v[204:207], v[64:67]
	v_mfma_f32_16x16x32_bf16 v[92:95], v[216:219], v[184:187], v[92:95]
	v_mfma_f32_16x16x32_bf16 v[88:91], v[158:161], v[184:187], v[88:91]
	v_mfma_f32_16x16x32_bf16 v[76:79], v[216:219], v[200:203], v[76:79]
	v_mfma_f32_16x16x32_bf16 v[72:75], v[158:161], v[200:203], v[72:75]
	v_mfma_f32_16x16x32_bf16 v[180:183], v[216:219], v[192:195], v[84:87]
	v_mfma_f32_16x16x32_bf16 v[184:187], v[158:161], v[192:195], v[80:83]
	v_mfma_f32_16x16x32_bf16 v[188:191], v[216:219], v[208:211], v[68:71]
	v_mfma_f32_16x16x32_bf16 v[192:195], v[158:161], v[208:211], v[64:67]
	s_barrier
	s_nop 0
	ds_read_b128 v[64:67], v152 offset:16384
	ds_read_b128 v[68:71], v152 offset:17408
	ds_read_b128 v[80:83], v151 offset:16384
	ds_read_b128 v[84:87], v151 offset:17408
	ds_read_b128 v[196:199], v150 offset:16384
	ds_read_b128 v[200:203], v150 offset:17408
	ds_read_b128 v[204:207], v149 offset:16384
	ds_read_b128 v[208:211], v149 offset:17408
	s_waitcnt vmcnt(4)
	s_barrier
	s_waitcnt lgkmcnt(0)
	s_waitcnt lgkmcnt(0)
	v_mfma_f32_16x16x32_bf16 v[60:63], v[134:137], v[64:67], v[60:63]
	v_mfma_f32_16x16x32_bf16 v[56:59], v[172:175], v[64:67], v[56:59]
	v_mfma_f32_16x16x32_bf16 v[52:55], v[134:137], v[80:83], v[52:55]
	v_mfma_f32_16x16x32_bf16 v[48:51], v[172:175], v[80:83], v[48:51]
	v_mfma_f32_16x16x32_bf16 v[44:47], v[134:137], v[196:199], v[44:47]
	v_mfma_f32_16x16x32_bf16 v[40:43], v[172:175], v[196:199], v[40:43]
	v_mfma_f32_16x16x32_bf16 v[36:39], v[134:137], v[204:207], v[36:39]
	v_mfma_f32_16x16x32_bf16 v[32:35], v[172:175], v[204:207], v[32:35]
	v_mfma_f32_16x16x32_bf16 v[60:63], v[138:141], v[68:71], v[60:63]
	v_mfma_f32_16x16x32_bf16 v[56:59], v[176:179], v[68:71], v[56:59]
	v_mfma_f32_16x16x32_bf16 v[52:55], v[138:141], v[84:87], v[52:55]
	v_mfma_f32_16x16x32_bf16 v[48:51], v[176:179], v[84:87], v[48:51]
	v_mfma_f32_16x16x32_bf16 v[44:47], v[138:141], v[200:203], v[44:47]
	v_mfma_f32_16x16x32_bf16 v[40:43], v[176:179], v[200:203], v[40:43]
	v_mfma_f32_16x16x32_bf16 v[36:39], v[138:141], v[208:211], v[36:39]
	v_mfma_f32_16x16x32_bf16 v[32:35], v[176:179], v[208:211], v[32:35]
	v_mfma_f32_16x16x32_bf16 v[28:31], v[212:215], v[64:67], v[28:31]
	v_mfma_f32_16x16x32_bf16 v[24:27], v[220:223], v[64:67], v[24:27]
	v_mfma_f32_16x16x32_bf16 v[12:15], v[212:215], v[196:199], v[12:15]
	v_mfma_f32_16x16x32_bf16 v[8:11], v[220:223], v[196:199], v[8:11]
	v_mfma_f32_16x16x32_bf16 v[20:23], v[212:215], v[80:83], v[20:23]
	v_mfma_f32_16x16x32_bf16 v[16:19], v[220:223], v[80:83], v[16:19]
	v_mfma_f32_16x16x32_bf16 v[4:7], v[212:215], v[204:207], v[4:7]
	v_mfma_f32_16x16x32_bf16 v[0:3], v[220:223], v[204:207], v[0:3]
	v_mfma_f32_16x16x32_bf16 v[28:31], v[216:219], v[68:71], v[28:31]
	v_mfma_f32_16x16x32_bf16 v[24:27], v[158:161], v[68:71], v[24:27]
	v_mfma_f32_16x16x32_bf16 v[12:15], v[216:219], v[200:203], v[12:15]
	v_mfma_f32_16x16x32_bf16 v[8:11], v[158:161], v[200:203], v[8:11]
	v_mfma_f32_16x16x32_bf16 v[134:137], v[216:219], v[84:87], v[20:23]
	v_mfma_f32_16x16x32_bf16 v[138:141], v[158:161], v[84:87], v[16:19]
	v_mfma_f32_16x16x32_bf16 v[170:173], v[216:219], v[208:211], v[4:7]
	v_mfma_f32_16x16x32_bf16 v[158:161], v[158:161], v[208:211], v[0:3]
	s_barrier
	s_nop 0
	ds_read_b128 v[0:3], v156
	ds_read_b128 v[4:7], v156 offset:1024
	ds_read_b128 v[16:19], v156 offset:2048
	ds_read_b128 v[174:177], v156 offset:3072
	ds_read_b128 v[20:23], v152 offset:32768
	ds_read_b128 v[196:199], v152 offset:33792
	ds_read_b128 v[200:203], v151 offset:32768
	ds_read_b128 v[204:207], v151 offset:33792
	ds_read_b128 v[208:211], v150 offset:32768
	ds_read_b128 v[212:215], v150 offset:33792
	ds_read_b128 v[216:219], v149 offset:32768
	ds_read_b128 v[220:223], v149 offset:33792
	s_waitcnt vmcnt(2)
	s_barrier
; #define LDA(dst, b, h) for (int m = 0; m < 4; ++m) for (int k = 0; k < 2; ++k) \
;     dst[m][k] = *reinterpret_cast<const bf16x8*>((char*)SA(b, h) + lds_byte(wr * 64 + m * 16 + fr, k * 32 + fq * 8))
; #define LDB(dst, b, h) for (int n = 0; n < 2; ++n) for (int k = 0; k < 2; ++k) \
;     dst[n][k] = *reinterpret_cast<const bf16x8*>((char*)SB(b, h) + lds_byte(wc * 32 + n * 16 + fr, k * 32 + fq * 8))
; #define MMA(ai, bj, At_, Bt_) do { __builtin_amdgcn_s_setprio(1); \
;     for (int k = 0; k < 2; ++k) for (int m = 0; m < 4; ++m) for (int n = 0; n < 2; ++n) \
;       acc[ai][bj][m][n] = __builtin_amdgcn_mfma_f32_16x16x32_bf16(At_[m][k], Bt_[n][k], acc[ai][bj][m][n], 0, 0, 0); \
;     __builtin_amdgcn_s_setprio(0); } while (0)
; #define WAIT_V(n) asm volatile("s_waitcnt vmcnt(" #n ")" ::: "memory")
; #define WAIT_L(n) asm volatile("s_waitcnt lgkmcnt(" #n ")" ::: "memory")
; #define BAR __builtin_amdgcn_s_barrier()
; template <int EPI, int lda, int ldb, int N, int K>
; __device__ __forceinline__ void gemm_phase(const u16* __restrict__ A, const u16* __restrict__ Bt, const GemmEpi ep, int wv) {
;     ...
;     { LDB(B0, 1, 0); LDA(At, 1, 0); WAIT_V(2); BAR; WAIT_L(0); MMA(0, 0, At, B0); BAR;
;       LDB(B1, 1, 1); WAIT_V(0); BAR; WAIT_L(0); MMA(0, 1, At, B1); BAR;
;       LDA(At, 1, 1); BAR; WAIT_L(0); MMA(1, 0, At, B0); MMA(1, 1, At, B1); BAR; }
;     if (wr == 0) BAR;
	s_waitcnt lgkmcnt(0)
	s_waitcnt lgkmcnt(0)
	v_mfma_f32_16x16x32_bf16 v[64:67], v[0:3], v[20:23], v[124:127]
	v_mfma_f32_16x16x32_bf16 v[68:71], v[16:19], v[20:23], v[120:123]
	v_mfma_f32_16x16x32_bf16 v[80:83], v[0:3], v[200:203], v[116:119]
	v_mfma_f32_16x16x32_bf16 v[84:87], v[16:19], v[200:203], v[112:115]
	v_mfma_f32_16x16x32_bf16 v[108:111], v[0:3], v[208:211], v[108:111]
	v_mfma_f32_16x16x32_bf16 v[104:107], v[16:19], v[208:211], v[104:107]
	v_mfma_f32_16x16x32_bf16 v[120:123], v[0:3], v[216:219], v[100:103]
	v_mfma_f32_16x16x32_bf16 v[124:127], v[16:19], v[216:219], v[96:99]
	v_mfma_f32_16x16x32_bf16 v[116:119], v[4:7], v[196:199], v[64:67]
	v_mfma_f32_16x16x32_bf16 v[112:115], v[174:177], v[196:199], v[68:71]
	v_mfma_f32_16x16x32_bf16 v[100:103], v[4:7], v[204:207], v[80:83]
	v_mfma_f32_16x16x32_bf16 v[96:99], v[174:177], v[204:207], v[84:87]
	v_mfma_f32_16x16x32_bf16 v[84:87], v[4:7], v[212:215], v[108:111]
	v_mfma_f32_16x16x32_bf16 v[80:83], v[174:177], v[212:215], v[104:107]
	v_mfma_f32_16x16x32_bf16 v[68:71], v[4:7], v[220:223], v[120:123]
	v_mfma_f32_16x16x32_bf16 v[64:67], v[174:177], v[220:223], v[124:127]
	s_barrier
	ds_read_b128 v[224:227], v154
	ds_read_b128 v[228:231], v154 offset:1024
	ds_read_b128 v[232:235], v154 offset:2048
	ds_read_b128 v[154:157], v154 offset:3072
	s_waitcnt vmcnt(0)
	s_barrier
	s_waitcnt lgkmcnt(0)
	s_waitcnt lgkmcnt(0)
	v_mfma_f32_16x16x32_bf16 v[92:95], v[224:227], v[20:23], v[92:95]
	v_mfma_f32_16x16x32_bf16 v[20:23], v[232:235], v[20:23], v[88:91]
	v_mfma_f32_16x16x32_bf16 v[88:91], v[224:227], v[200:203], v[180:183]
	v_mfma_f32_16x16x32_bf16 v[104:107], v[232:235], v[200:203], v[184:187]
	v_mfma_f32_16x16x32_bf16 v[76:79], v[224:227], v[208:211], v[76:79]
	v_mfma_f32_16x16x32_bf16 v[72:75], v[232:235], v[208:211], v[72:75]
	v_mfma_f32_16x16x32_bf16 v[178:181], v[224:227], v[216:219], v[188:191]
	v_mfma_f32_16x16x32_bf16 v[182:185], v[232:235], v[216:219], v[192:195]
	v_mfma_f32_16x16x32_bf16 v[124:127], v[228:231], v[196:199], v[92:95]
	v_mfma_f32_16x16x32_bf16 v[120:123], v[154:157], v[196:199], v[20:23]
	v_mfma_f32_16x16x32_bf16 v[108:111], v[228:231], v[204:207], v[88:91]
	v_mfma_f32_16x16x32_bf16 v[104:107], v[154:157], v[204:207], v[104:107]
	v_mfma_f32_16x16x32_bf16 v[92:95], v[228:231], v[212:215], v[76:79]
	v_mfma_f32_16x16x32_bf16 v[88:91], v[154:157], v[212:215], v[72:75]
	v_mfma_f32_16x16x32_bf16 v[76:79], v[228:231], v[220:223], v[178:181]
	v_mfma_f32_16x16x32_bf16 v[72:75], v[154:157], v[220:223], v[182:185]
	s_barrier
	ds_read_b128 v[178:181], v152 offset:49152
	ds_read_b128 v[182:185], v152 offset:50176
	ds_read_b128 v[186:189], v151 offset:49152
	ds_read_b128 v[190:193], v151 offset:50176
	ds_read_b128 v[194:197], v150 offset:49152
	ds_read_b128 v[150:153], v150 offset:50176
	ds_read_b128 v[198:201], v149 offset:49152
	ds_read_b128 v[202:205], v149 offset:50176
	s_barrier
	s_waitcnt lgkmcnt(0)
	s_waitcnt lgkmcnt(0)
	v_mfma_f32_16x16x32_bf16 v[20:23], v[0:3], v[178:181], v[60:63]
	v_mfma_f32_16x16x32_bf16 v[56:59], v[16:19], v[178:181], v[56:59]
	v_mfma_f32_16x16x32_bf16 v[60:63], v[0:3], v[186:189], v[52:55]
	v_mfma_f32_16x16x32_bf16 v[206:209], v[16:19], v[186:189], v[48:51]
	v_mfma_f32_16x16x32_bf16 v[44:47], v[0:3], v[194:197], v[44:47]
	v_mfma_f32_16x16x32_bf16 v[40:43], v[16:19], v[194:197], v[40:43]
	v_mfma_f32_16x16x32_bf16 v[0:3], v[0:3], v[198:201], v[36:39]
	v_mfma_f32_16x16x32_bf16 v[210:213], v[16:19], v[198:201], v[32:35]
	v_mfma_f32_16x16x32_bf16 v[52:55], v[4:7], v[182:185], v[20:23]
	v_mfma_f32_16x16x32_bf16 v[48:51], v[174:177], v[182:185], v[56:59]
	v_mfma_f32_16x16x32_bf16 v[36:39], v[4:7], v[190:193], v[60:63]
	v_mfma_f32_16x16x32_bf16 v[32:35], v[174:177], v[190:193], v[206:209]
	v_mfma_f32_16x16x32_bf16 v[20:23], v[4:7], v[150:153], v[44:47]
	v_mfma_f32_16x16x32_bf16 v[16:19], v[174:177], v[150:153], v[40:43]
	v_mfma_f32_16x16x32_bf16 v[4:7], v[4:7], v[202:205], v[0:3]
	v_mfma_f32_16x16x32_bf16 v[0:3], v[174:177], v[202:205], v[210:213]
	v_mfma_f32_16x16x32_bf16 v[28:31], v[224:227], v[178:181], v[28:31]
	v_mfma_f32_16x16x32_bf16 v[24:27], v[232:235], v[178:181], v[24:27]
	v_mfma_f32_16x16x32_bf16 v[40:43], v[224:227], v[186:189], v[134:137]
	v_mfma_f32_16x16x32_bf16 v[134:137], v[232:235], v[186:189], v[138:141]
	v_mfma_f32_16x16x32_bf16 v[12:15], v[224:227], v[194:197], v[12:15]
	v_mfma_f32_16x16x32_bf16 v[8:11], v[232:235], v[194:197], v[8:11]
	v_mfma_f32_16x16x32_bf16 v[138:141], v[224:227], v[198:201], v[170:173]
	v_mfma_f32_16x16x32_bf16 v[158:161], v[232:235], v[198:201], v[158:161]
	v_mfma_f32_16x16x32_bf16 v[60:63], v[228:231], v[182:185], v[28:31]
	v_mfma_f32_16x16x32_bf16 v[56:59], v[154:157], v[182:185], v[24:27]
	v_mfma_f32_16x16x32_bf16 v[44:47], v[228:231], v[190:193], v[40:43]
	v_mfma_f32_16x16x32_bf16 v[40:43], v[154:157], v[190:193], v[134:137]
	v_mfma_f32_16x16x32_bf16 v[28:31], v[228:231], v[150:153], v[12:15]
	v_mfma_f32_16x16x32_bf16 v[24:27], v[154:157], v[150:153], v[8:11]
	v_mfma_f32_16x16x32_bf16 v[12:15], v[228:231], v[202:205], v[138:141]
	v_mfma_f32_16x16x32_bf16 v[8:11], v[154:157], v[202:205], v[158:161]
	v_cmp_gt_u32_e32 vcc, s56, v130
	s_barrier
	s_and_saveexec_b64 s[42:43], vcc
	s_cbranch_execz .LBB0_56
	s_barrier

; #define STAGE(P, BASE, LD, br, kt) do { const char* _g = (const char*)((BASE) + (size_t)(br) * (LD) + (size_t)(kt) * 64); \
;     for (int _i = 0; _i < 2; ++_i) { int _b = tidx * 16 + _i * 8192; int _r, _c; stage_rc(_b, _r, _c); \
;       __builtin_amdgcn_global_load_lds((const unsigned*)(_g + (unsigned)((_r * (LD) + _c) * 2)), (unsigned*)((char*)(P) + _b), 16, 0, 0); } } while (0)
; #define LDA(dst, b, h) for (int m = 0; m < 4; ++m) for (int k = 0; k < 2; ++k) \
;     dst[m][k] = *reinterpret_cast<const bf16x8*>((char*)SA(b, h) + lds_byte(wr * 64 + m * 16 + fr, k * 32 + fq * 8))
; #define LDB(dst, b, h) for (int n = 0; n < 2; ++n) for (int k = 0; k < 2; ++k) \
;     dst[n][k] = *reinterpret_cast<const bf16x8*>((char*)SB(b, h) + lds_byte(wc * 32 + n * 16 + fr, k * 32 + fq * 8))
; #define MMA(ai, bj, At_, Bt_) do { __builtin_amdgcn_s_setprio(1); \
;     for (int k = 0; k < 2; ++k) for (int m = 0; m < 4; ++m) for (int n = 0; n < 2; ++n) \
;       acc[ai][bj][m][n] = __builtin_amdgcn_mfma_f32_16x16x32_bf16(At_[m][k], Bt_[n][k], acc[ai][bj][m][n], 0, 0, 0); \
;     __builtin_amdgcn_s_setprio(0); } while (0)
; #define WAIT_V(n) asm volatile("s_waitcnt vmcnt(" #n ")" ::: "memory")
; #define WAIT_L(n) asm volatile("s_waitcnt lgkmcnt(" #n ")" ::: "memory")
; #define BAR __builtin_amdgcn_s_barrier()
; #define SCHED __builtin_amdgcn_sched_barrier(0)
; template <int EPI, int lda, int ldb, int N, int K>
; __device__ __forceinline__ void gemm_phase(const u16* __restrict__ A, const u16* __restrict__ Bt, const GemmEpi ep, int wv) {
;     ...
;     for (int t = 0; t < nt - 2; t += 2) {
;       LDB(B0, 0, 0); SCHED; LDA(At, 0, 0); STAGE(SA(1, 1), Ab, lda, brow + HALF, t + 1);
;       WAIT_L(8); BAR; WAIT_L(0); MMA(0, 0, At, B0); BAR; SCHED;
;       LDB(B1, 0, 1); STAGE(SB(0, 0), Bt, ldb, bcol, t + 2);
;       BAR; WAIT_L(0); MMA(0, 1, At, B1); BAR;
;       LDA(At, 0, 1); STAGE(SA(0, 0), Ab, lda, brow, t + 2);
;       BAR; WAIT_L(0); MMA(1, 0, At, B0); BAR; SCHED;
;       STAGE(SB(0, 1), Bt, ldb, bcol + HALF, t + 2);
;       WAIT_V(6); BAR; MMA(1, 1, At, B1); BAR;
;       LDB(B0, 1, 0); SCHED; LDA(At, 1, 0); STAGE(SA(0, 1), Ab, lda, brow + HALF, t + 2);
;       WAIT_L(8); BAR; WAIT_L(0); MMA(0, 0, At, B0); BAR; SCHED;
.LBB0_224:
	ds_read_b128 v[168:171], v164
	ds_read_b128 v[174:177], v164 offset:1024
	ds_read_b128 v[178:181], v164 offset:2048
	ds_read_b128 v[182:185], v164 offset:3072
	v_add_u32_e32 v172, 0xc000, v147
	v_lshl_add_u64 v[238:239], v[136:137], 0, s[44:45]
	v_readfirstlane_b32 s66, v172
	v_add_u32_e32 v173, 0xe000, v147
	v_lshl_add_u64 v[166:167], v[238:239], 0, s[18:19]
	s_mov_b32 m0, s66
	v_lshl_add_u64 v[240:241], v[134:135], 0, s[44:45]
	v_readfirstlane_b32 s66, v173
	global_load_lds_dwordx4 v[166:167], off
	v_lshl_add_u64 v[166:167], v[240:241], 0, s[18:19]
	s_mov_b32 m0, s66
	s_nop 0
	global_load_lds_dwordx4 v[166:167], off
	ds_read_b128 v[186:189], v155
	ds_read_b128 v[190:193], v155 offset:1024
	ds_read_b128 v[194:197], v154
	ds_read_b128 v[198:201], v154 offset:1024
	ds_read_b128 v[202:205], v153
	ds_read_b128 v[206:209], v153 offset:1024
	ds_read_b128 v[210:213], v152
	ds_read_b128 v[214:217], v152 offset:1024
	s_waitcnt lgkmcnt(8)
	s_barrier
	s_waitcnt lgkmcnt(0)
	s_waitcnt lgkmcnt(0)
	v_mfma_f32_16x16x32_bf16 v[124:127], v[168:171], v[186:189], v[124:127]
	v_mfma_f32_16x16x32_bf16 v[120:123], v[178:181], v[186:189], v[120:123]
	v_mfma_f32_16x16x32_bf16 v[116:119], v[168:171], v[194:197], v[116:119]
	v_mfma_f32_16x16x32_bf16 v[112:115], v[178:181], v[194:197], v[112:115]
	v_mfma_f32_16x16x32_bf16 v[108:111], v[168:171], v[202:205], v[108:111]
	v_mfma_f32_16x16x32_bf16 v[104:107], v[178:181], v[202:205], v[104:107]
	v_mfma_f32_16x16x32_bf16 v[100:103], v[168:171], v[210:213], v[100:103]
	v_mfma_f32_16x16x32_bf16 v[96:99], v[178:181], v[210:213], v[96:99]
	v_mfma_f32_16x16x32_bf16 v[124:127], v[174:177], v[190:193], v[124:127]
	v_mfma_f32_16x16x32_bf16 v[120:123], v[182:185], v[190:193], v[120:123]
	v_mfma_f32_16x16x32_bf16 v[116:119], v[174:177], v[198:201], v[116:119]
	v_mfma_f32_16x16x32_bf16 v[112:115], v[182:185], v[198:201], v[112:115]
	v_mfma_f32_16x16x32_bf16 v[108:111], v[174:177], v[206:209], v[108:111]
	v_mfma_f32_16x16x32_bf16 v[104:107], v[182:185], v[206:209], v[104:107]
	v_mfma_f32_16x16x32_bf16 v[100:103], v[174:177], v[214:217], v[100:103]
	v_mfma_f32_16x16x32_bf16 v[96:99], v[182:185], v[214:217], v[96:99]
	s_barrier
	v_add_u32_e32 v165, s55, v156
	v_lshl_add_u64 v[242:243], v[144:145], 0, s[44:45]
	v_readfirstlane_b32 s66, v165
	v_lshl_add_u64 v[166:167], v[242:243], 0, s[20:21]
	s_mov_b32 m0, s66
	global_load_lds_dwordx4 v[166:167], off
	v_add_u32_e32 v166, 0x2000, v165
	v_lshl_add_u64 v[244:245], v[142:143], 0, s[44:45]
	v_readfirstlane_b32 s66, v166
	v_lshl_add_u64 v[234:235], v[244:245], 0, s[20:21]
	s_mov_b32 m0, s66
	s_nop 0
	global_load_lds_dwordx4 v[234:235], off
	ds_read_b128 v[218:221], v163
	ds_read_b128 v[222:225], v163 offset:1024
	ds_read_b128 v[226:229], v163 offset:2048
	ds_read_b128 v[230:233], v163 offset:3072
	s_barrier
	s_waitcnt lgkmcnt(0)
	s_waitcnt lgkmcnt(0)
	v_mfma_f32_16x16x32_bf16 v[92:95], v[218:221], v[186:189], v[92:95]
	v_mfma_f32_16x16x32_bf16 v[88:91], v[226:229], v[186:189], v[88:91]
	v_mfma_f32_16x16x32_bf16 v[84:87], v[218:221], v[194:197], v[84:87]
	v_mfma_f32_16x16x32_bf16 v[80:83], v[226:229], v[194:197], v[80:83]
	v_mfma_f32_16x16x32_bf16 v[76:79], v[218:221], v[202:205], v[76:79]
	v_mfma_f32_16x16x32_bf16 v[72:75], v[226:229], v[202:205], v[72:75]
	v_mfma_f32_16x16x32_bf16 v[68:71], v[218:221], v[210:213], v[68:71]
	v_mfma_f32_16x16x32_bf16 v[64:67], v[226:229], v[210:213], v[64:67]
	v_mfma_f32_16x16x32_bf16 v[92:95], v[222:225], v[190:193], v[92:95]
	v_mfma_f32_16x16x32_bf16 v[88:91], v[230:233], v[190:193], v[88:91]
	v_mfma_f32_16x16x32_bf16 v[84:87], v[222:225], v[198:201], v[84:87]
	v_mfma_f32_16x16x32_bf16 v[80:83], v[230:233], v[198:201], v[80:83]
	v_mfma_f32_16x16x32_bf16 v[76:79], v[222:225], v[206:209], v[76:79]
	v_mfma_f32_16x16x32_bf16 v[72:75], v[230:233], v[206:209], v[72:75]
	v_mfma_f32_16x16x32_bf16 v[68:71], v[222:225], v[214:217], v[68:71]
	v_mfma_f32_16x16x32_bf16 v[64:67], v[230:233], v[214:217], v[64:67]
	v_readfirstlane_b32 s66, v147
	v_add_u32_e32 v167, 0x2000, v147
	v_lshl_add_u64 v[234:235], v[238:239], 0, s[22:23]
	s_mov_b32 m0, s66
	v_readfirstlane_b32 s66, v167
	s_barrier
	global_load_lds_dwordx4 v[234:235], off
	v_lshl_add_u64 v[234:235], v[240:241], 0, s[22:23]
	s_mov_b32 m0, s66
	s_nop 0
	global_load_lds_dwordx4 v[234:235], off
	ds_read_b128 v[186:189], v155 offset:16384
	ds_read_b128 v[190:193], v155 offset:17408
	ds_read_b128 v[194:197], v154 offset:16384
	ds_read_b128 v[198:201], v154 offset:17408
	ds_read_b128 v[202:205], v153 offset:16384
	ds_read_b128 v[206:209], v153 offset:17408
	ds_read_b128 v[210:213], v152 offset:16384
	ds_read_b128 v[214:217], v152 offset:17408
	s_barrier
	s_waitcnt lgkmcnt(0)
	s_waitcnt lgkmcnt(0)
	v_mfma_f32_16x16x32_bf16 v[60:63], v[168:171], v[186:189], v[60:63]
	v_mfma_f32_16x16x32_bf16 v[56:59], v[178:181], v[186:189], v[56:59]
	v_mfma_f32_16x16x32_bf16 v[52:55], v[168:171], v[194:197], v[52:55]
	v_mfma_f32_16x16x32_bf16 v[48:51], v[178:181], v[194:197], v[48:51]
	v_mfma_f32_16x16x32_bf16 v[44:47], v[168:171], v[202:205], v[44:47]
	v_mfma_f32_16x16x32_bf16 v[40:43], v[178:181], v[202:205], v[40:43]
	v_mfma_f32_16x16x32_bf16 v[36:39], v[168:171], v[210:213], v[36:39]
	v_mfma_f32_16x16x32_bf16 v[32:35], v[178:181], v[210:213], v[32:35]
	v_mfma_f32_16x16x32_bf16 v[60:63], v[174:177], v[190:193], v[60:63]
	v_mfma_f32_16x16x32_bf16 v[56:59], v[182:185], v[190:193], v[56:59]
	v_mfma_f32_16x16x32_bf16 v[52:55], v[174:177], v[198:201], v[52:55]
	v_mfma_f32_16x16x32_bf16 v[48:51], v[182:185], v[198:201], v[48:51]
	v_mfma_f32_16x16x32_bf16 v[44:47], v[174:177], v[206:209], v[44:47]
	v_mfma_f32_16x16x32_bf16 v[40:43], v[182:185], v[206:209], v[40:43]
	v_mfma_f32_16x16x32_bf16 v[36:39], v[174:177], v[214:217], v[36:39]
	v_mfma_f32_16x16x32_bf16 v[32:35], v[182:185], v[214:217], v[32:35]
	s_barrier
; #define STAGE(P, BASE, LD, br, kt) do { const char* _g = (const char*)((BASE) + (size_t)(br) * (LD) + (size_t)(kt) * 64); \
;     for (int _i = 0; _i < 2; ++_i) { int _b = tidx * 16 + _i * 8192; int _r, _c; stage_rc(_b, _r, _c); \
;       __builtin_amdgcn_global_load_lds((const unsigned*)(_g + (unsigned)((_r * (LD) + _c) * 2)), (unsigned*)((char*)(P) + _b), 16, 0, 0); } } while (0)
; #define LDA(dst, b, h) for (int m = 0; m < 4; ++m) for (int k = 0; k < 2; ++k) \
;     dst[m][k] = *reinterpret_cast<const bf16x8*>((char*)SA(b, h) + lds_byte(wr * 64 + m * 16 + fr, k * 32 + fq * 8))
; #define LDB(dst, b, h) for (int n = 0; n < 2; ++n) for (int k = 0; k < 2; ++k) \
;     dst[n][k] = *reinterpret_cast<const bf16x8*>((char*)SB(b, h) + lds_byte(wc * 32 + n * 16 + fr, k * 32 + fq * 8))
; #define MMA(ai, bj, At_, Bt_) do { __builtin_amdgcn_s_setprio(1); \
;     for (int k = 0; k < 2; ++k) for (int m = 0; m < 4; ++m) for (int n = 0; n < 2; ++n) \
;       acc[ai][bj][m][n] = __builtin_amdgcn_mfma_f32_16x16x32_bf16(At_[m][k], Bt_[n][k], acc[ai][bj][m][n], 0, 0, 0); \
;     __builtin_amdgcn_s_setprio(0); } while (0)
; #define WAIT_V(n) asm volatile("s_waitcnt vmcnt(" #n ")" ::: "memory")
; #define WAIT_L(n) asm volatile("s_waitcnt lgkmcnt(" #n ")" ::: "memory")
; #define BAR __builtin_amdgcn_s_barrier()
; #define SCHED __builtin_amdgcn_sched_barrier(0)
; template <int EPI, int lda, int ldb, int N, int K>
; __device__ __forceinline__ void gemm_phase(const u16* __restrict__ A, const u16* __restrict__ Bt, const GemmEpi ep, int wv) {
;     ...
;       STAGE(SB(0, 1), Bt, ldb, bcol + HALF, t + 2);
;       WAIT_V(6); BAR; MMA(1, 1, At, B1); BAR;
;       LDB(B0, 1, 0); SCHED; LDA(At, 1, 0); STAGE(SA(0, 1), Ab, lda, brow + HALF, t + 2);
;       WAIT_L(8); BAR; WAIT_L(0); MMA(0, 0, At, B0); BAR; SCHED;
;       LDB(B1, 1, 1); STAGE(SB(1, 0), Bt, ldb, bcol, t + 3);
;       BAR; WAIT_L(0); MMA(0, 1, At, B1); BAR;
;       LDA(At, 1, 1); STAGE(SA(1, 0), Ab, lda, brow, t + 3);
;       BAR; WAIT_L(0); MMA(1, 0, At, B0); BAR; SCHED;
	v_add_u32_e32 v168, s56, v156
	v_lshl_add_u64 v[246:247], v[140:141], 0, s[44:45]
	v_readfirstlane_b32 s66, v168
	v_add_u32_e32 v169, 0x2000, v168
	v_lshl_add_u64 v[170:171], v[246:247], 0, s[24:25]
	s_mov_b32 m0, s66
	v_lshl_add_u64 v[248:249], v[138:139], 0, s[44:45]
	v_readfirstlane_b32 s66, v169
	global_load_lds_dwordx4 v[170:171], off
	v_lshl_add_u64 v[170:171], v[248:249], 0, s[24:25]
	s_mov_b32 m0, s66
	s_nop 0
	global_load_lds_dwordx4 v[170:171], off
	s_waitcnt vmcnt(6)
	s_barrier
	v_mfma_f32_16x16x32_bf16 v[28:31], v[218:221], v[186:189], v[28:31]
	v_mfma_f32_16x16x32_bf16 v[24:27], v[226:229], v[186:189], v[24:27]
	v_mfma_f32_16x16x32_bf16 v[20:23], v[218:221], v[194:197], v[20:23]
	v_mfma_f32_16x16x32_bf16 v[16:19], v[226:229], v[194:197], v[16:19]
	v_mfma_f32_16x16x32_bf16 v[12:15], v[218:221], v[202:205], v[12:15]
	v_mfma_f32_16x16x32_bf16 v[8:11], v[226:229], v[202:205], v[8:11]
	v_mfma_f32_16x16x32_bf16 v[4:7], v[218:221], v[210:213], v[4:7]
	v_mfma_f32_16x16x32_bf16 v[0:3], v[226:229], v[210:213], v[0:3]
	v_mfma_f32_16x16x32_bf16 v[28:31], v[222:225], v[190:193], v[28:31]
	v_mfma_f32_16x16x32_bf16 v[24:27], v[230:233], v[190:193], v[24:27]
	v_mfma_f32_16x16x32_bf16 v[20:23], v[222:225], v[198:201], v[20:23]
	v_mfma_f32_16x16x32_bf16 v[16:19], v[230:233], v[198:201], v[16:19]
	v_mfma_f32_16x16x32_bf16 v[12:15], v[222:225], v[206:209], v[12:15]
	v_mfma_f32_16x16x32_bf16 v[8:11], v[230:233], v[206:209], v[8:11]
	v_mfma_f32_16x16x32_bf16 v[4:7], v[222:225], v[214:217], v[4:7]
	v_mfma_f32_16x16x32_bf16 v[0:3], v[230:233], v[214:217], v[0:3]
	s_barrier
	ds_read_b128 v[174:177], v159
	ds_read_b128 v[178:181], v159 offset:1024
	ds_read_b128 v[182:185], v159 offset:2048
	ds_read_b128 v[186:189], v159 offset:3072
	v_add_u32_e32 v170, 0x4000, v147
	v_add_u32_e32 v171, 0x6000, v147
	v_readfirstlane_b32 s66, v170
	v_lshl_add_u64 v[222:223], v[238:239], 0, s[26:27]
	s_mov_b32 m0, s66
	v_readfirstlane_b32 s66, v171
	global_load_lds_dwordx4 v[222:223], off
	v_lshl_add_u64 v[222:223], v[240:241], 0, s[26:27]
	s_mov_b32 m0, s66
	s_nop 0
	global_load_lds_dwordx4 v[222:223], off
	ds_read_b128 v[190:193], v155 offset:32768
	ds_read_b128 v[194:197], v155 offset:33792
	ds_read_b128 v[198:201], v154 offset:32768
	ds_read_b128 v[202:205], v154 offset:33792
	ds_read_b128 v[206:209], v153 offset:32768
	ds_read_b128 v[210:213], v153 offset:33792
	ds_read_b128 v[214:217], v152 offset:32768
	ds_read_b128 v[218:221], v152 offset:33792
	s_waitcnt lgkmcnt(8)
	s_barrier
	s_waitcnt lgkmcnt(0)
	s_waitcnt lgkmcnt(0)
	v_mfma_f32_16x16x32_bf16 v[124:127], v[174:177], v[190:193], v[124:127]
	v_mfma_f32_16x16x32_bf16 v[120:123], v[182:185], v[190:193], v[120:123]
	v_mfma_f32_16x16x32_bf16 v[116:119], v[174:177], v[198:201], v[116:119]
	v_mfma_f32_16x16x32_bf16 v[112:115], v[182:185], v[198:201], v[112:115]
	v_mfma_f32_16x16x32_bf16 v[108:111], v[174:177], v[206:209], v[108:111]
	v_mfma_f32_16x16x32_bf16 v[104:107], v[182:185], v[206:209], v[104:107]
	v_mfma_f32_16x16x32_bf16 v[100:103], v[174:177], v[214:217], v[100:103]
	v_mfma_f32_16x16x32_bf16 v[96:99], v[182:185], v[214:217], v[96:99]
	v_mfma_f32_16x16x32_bf16 v[124:127], v[178:181], v[194:197], v[124:127]
	v_mfma_f32_16x16x32_bf16 v[120:123], v[186:189], v[194:197], v[120:123]
	v_mfma_f32_16x16x32_bf16 v[116:119], v[178:181], v[202:205], v[116:119]
	v_mfma_f32_16x16x32_bf16 v[112:115], v[186:189], v[202:205], v[112:115]
	v_mfma_f32_16x16x32_bf16 v[108:111], v[178:181], v[210:213], v[108:111]
	v_mfma_f32_16x16x32_bf16 v[104:107], v[186:189], v[210:213], v[104:107]
	v_mfma_f32_16x16x32_bf16 v[100:103], v[178:181], v[218:221], v[100:103]
	v_mfma_f32_16x16x32_bf16 v[96:99], v[186:189], v[218:221], v[96:99]
	s_barrier
	v_readfirstlane_b32 s66, v158
	v_lshl_add_u64 v[242:243], v[242:243], 0, s[36:37]
	s_mov_b32 m0, s66
	global_load_lds_dwordx4 v[242:243], off
	v_lshl_add_u64 v[242:243], v[244:245], 0, s[36:37]
	v_add_u32_e32 v244, 0x2000, v158
	s_nop 0
	v_readfirstlane_b32 s66, v244
	s_mov_b32 m0, s66
	s_nop 0
	global_load_lds_dwordx4 v[242:243], off
	ds_read_b128 v[222:225], v157
	ds_read_b128 v[226:229], v157 offset:1024
	ds_read_b128 v[230:233], v157 offset:2048
	ds_read_b128 v[234:237], v157 offset:3072
	s_barrier
	s_waitcnt lgkmcnt(0)
	s_waitcnt lgkmcnt(0)
	v_mfma_f32_16x16x32_bf16 v[92:95], v[222:225], v[190:193], v[92:95]
	v_mfma_f32_16x16x32_bf16 v[88:91], v[230:233], v[190:193], v[88:91]
	v_mfma_f32_16x16x32_bf16 v[84:87], v[222:225], v[198:201], v[84:87]
	v_mfma_f32_16x16x32_bf16 v[80:83], v[230:233], v[198:201], v[80:83]
	v_mfma_f32_16x16x32_bf16 v[76:79], v[222:225], v[206:209], v[76:79]
	v_mfma_f32_16x16x32_bf16 v[72:75], v[230:233], v[206:209], v[72:75]
	v_mfma_f32_16x16x32_bf16 v[68:71], v[222:225], v[214:217], v[68:71]
	v_mfma_f32_16x16x32_bf16 v[64:67], v[230:233], v[214:217], v[64:67]
	v_mfma_f32_16x16x32_bf16 v[92:95], v[226:229], v[194:197], v[92:95]
	v_mfma_f32_16x16x32_bf16 v[88:91], v[234:237], v[194:197], v[88:91]
	v_mfma_f32_16x16x32_bf16 v[84:87], v[226:229], v[202:205], v[84:87]
	v_mfma_f32_16x16x32_bf16 v[80:83], v[234:237], v[202:205], v[80:83]
	v_mfma_f32_16x16x32_bf16 v[76:79], v[226:229], v[210:213], v[76:79]
	v_mfma_f32_16x16x32_bf16 v[72:75], v[234:237], v[210:213], v[72:75]
	v_mfma_f32_16x16x32_bf16 v[68:71], v[226:229], v[218:221], v[68:71]
	v_mfma_f32_16x16x32_bf16 v[64:67], v[234:237], v[218:221], v[64:67]
	v_readfirstlane_b32 s66, v160
	v_lshl_add_u64 v[238:239], v[238:239], 0, s[38:39]
	s_mov_b32 m0, s66
	v_readfirstlane_b32 s66, v161
	s_barrier
; #define STAGE(P, BASE, LD, br, kt) do { const char* _g = (const char*)((BASE) + (size_t)(br) * (LD) + (size_t)(kt) * 64); \
;     for (int _i = 0; _i < 2; ++_i) { int _b = tidx * 16 + _i * 8192; int _r, _c; stage_rc(_b, _r, _c); \
;       __builtin_amdgcn_global_load_lds((const unsigned*)(_g + (unsigned)((_r * (LD) + _c) * 2)), (unsigned*)((char*)(P) + _b), 16, 0, 0); } } while (0)
; #define LDA(dst, b, h) for (int m = 0; m < 4; ++m) for (int k = 0; k < 2; ++k) \
;     dst[m][k] = *reinterpret_cast<const bf16x8*>((char*)SA(b, h) + lds_byte(wr * 64 + m * 16 + fr, k * 32 + fq * 8))
; #define LDB(dst, b, h) for (int n = 0; n < 2; ++n) for (int k = 0; k < 2; ++k) \
;     dst[n][k] = *reinterpret_cast<const bf16x8*>((char*)SB(b, h) + lds_byte(wc * 32 + n * 16 + fr, k * 32 + fq * 8))
; #define MMA(ai, bj, At_, Bt_) do { __builtin_amdgcn_s_setprio(1); \
;     for (int k = 0; k < 2; ++k) for (int m = 0; m < 4; ++m) for (int n = 0; n < 2; ++n) \
;       acc[ai][bj][m][n] = __builtin_amdgcn_mfma_f32_16x16x32_bf16(At_[m][k], Bt_[n][k], acc[ai][bj][m][n], 0, 0, 0); \
;     __builtin_amdgcn_s_setprio(0); } while (0)
; #define WAIT_V(n) asm volatile("s_waitcnt vmcnt(" #n ")" ::: "memory")
; #define WAIT_L(n) asm volatile("s_waitcnt lgkmcnt(" #n ")" ::: "memory")
; #define BAR __builtin_amdgcn_s_barrier()
; #define SCHED __builtin_amdgcn_sched_barrier(0)
; template <int EPI, int lda, int ldb, int N, int K>
; __device__ __forceinline__ void gemm_phase(const u16* __restrict__ A, const u16* __restrict__ Bt, const GemmEpi ep, int wv) {
;     ...
;       LDA(At, 1, 1); STAGE(SA(1, 0), Ab, lda, brow, t + 3);
;       BAR; WAIT_L(0); MMA(1, 0, At, B0); BAR; SCHED;
;       STAGE(SB(1, 1), Bt, ldb, bcol + HALF, t + 3);
;       WAIT_V(6); BAR; MMA(1, 1, At, B1); BAR;
;     }
;     { LDB(B0, 0, 0); LDA(At, 0, 0); STAGE(SA(1, 1), Ab, lda, brow + HALF, nt - 1);
;       BAR; WAIT_L(0); MMA(0, 0, At, B0); BAR;
;       LDB(B1, 0, 1); BAR; WAIT_L(0); MMA(0, 1, At, B1); BAR;
;       LDA(At, 0, 1); WAIT_V(4); BAR; WAIT_L(0); MMA(1, 0, At, B0); MMA(1, 1, At, B1); BAR; }
	global_load_lds_dwordx4 v[238:239], off
	v_lshl_add_u64 v[238:239], v[240:241], 0, s[38:39]
	s_mov_b32 m0, s66
	s_nop 0
	global_load_lds_dwordx4 v[238:239], off
	ds_read_b128 v[190:193], v155 offset:49152
	ds_read_b128 v[194:197], v155 offset:50176
	ds_read_b128 v[198:201], v154 offset:49152
	ds_read_b128 v[202:205], v154 offset:50176
	ds_read_b128 v[206:209], v153 offset:49152
	ds_read_b128 v[210:213], v153 offset:50176
	ds_read_b128 v[214:217], v152 offset:49152
	ds_read_b128 v[218:221], v152 offset:50176
	s_barrier
	s_waitcnt lgkmcnt(0)
	s_waitcnt lgkmcnt(0)
	v_mfma_f32_16x16x32_bf16 v[60:63], v[174:177], v[190:193], v[60:63]
	v_mfma_f32_16x16x32_bf16 v[56:59], v[182:185], v[190:193], v[56:59]
	v_mfma_f32_16x16x32_bf16 v[52:55], v[174:177], v[198:201], v[52:55]
	v_mfma_f32_16x16x32_bf16 v[48:51], v[182:185], v[198:201], v[48:51]
	v_mfma_f32_16x16x32_bf16 v[44:47], v[174:177], v[206:209], v[44:47]
	v_mfma_f32_16x16x32_bf16 v[40:43], v[182:185], v[206:209], v[40:43]
	v_mfma_f32_16x16x32_bf16 v[36:39], v[174:177], v[214:217], v[36:39]
	v_mfma_f32_16x16x32_bf16 v[32:35], v[182:185], v[214:217], v[32:35]
	v_mfma_f32_16x16x32_bf16 v[60:63], v[178:181], v[194:197], v[60:63]
	v_mfma_f32_16x16x32_bf16 v[56:59], v[186:189], v[194:197], v[56:59]
	v_mfma_f32_16x16x32_bf16 v[52:55], v[178:181], v[202:205], v[52:55]
	v_mfma_f32_16x16x32_bf16 v[48:51], v[186:189], v[202:205], v[48:51]
	v_mfma_f32_16x16x32_bf16 v[44:47], v[178:181], v[210:213], v[44:47]
	v_mfma_f32_16x16x32_bf16 v[40:43], v[186:189], v[210:213], v[40:43]
	v_mfma_f32_16x16x32_bf16 v[36:39], v[178:181], v[218:221], v[36:39]
	v_mfma_f32_16x16x32_bf16 v[32:35], v[186:189], v[218:221], v[32:35]
	s_barrier
	v_readfirstlane_b32 s66, v162
	v_add_u32_e32 v176, 0x2000, v162
	v_lshl_add_u64 v[174:175], v[246:247], 0, s[42:43]
	s_mov_b32 m0, s66
	v_readfirstlane_b32 s66, v176
	global_load_lds_dwordx4 v[174:175], off
	v_lshl_add_u64 v[174:175], v[248:249], 0, s[42:43]
	s_mov_b32 m0, s66
	s_nop 0
	global_load_lds_dwordx4 v[174:175], off
	s_waitcnt vmcnt(6)
	s_barrier
	v_mfma_f32_16x16x32_bf16 v[28:31], v[222:225], v[190:193], v[28:31]
	v_mfma_f32_16x16x32_bf16 v[24:27], v[230:233], v[190:193], v[24:27]
	v_mfma_f32_16x16x32_bf16 v[20:23], v[222:225], v[198:201], v[20:23]
	v_mfma_f32_16x16x32_bf16 v[16:19], v[230:233], v[198:201], v[16:19]
	v_mfma_f32_16x16x32_bf16 v[12:15], v[222:225], v[206:209], v[12:15]
	v_mfma_f32_16x16x32_bf16 v[8:11], v[230:233], v[206:209], v[8:11]
	v_mfma_f32_16x16x32_bf16 v[4:7], v[222:225], v[214:217], v[4:7]
	v_mfma_f32_16x16x32_bf16 v[0:3], v[230:233], v[214:217], v[0:3]
	v_mfma_f32_16x16x32_bf16 v[28:31], v[226:229], v[194:197], v[28:31]
	v_mfma_f32_16x16x32_bf16 v[24:27], v[234:237], v[194:197], v[24:27]
	v_mfma_f32_16x16x32_bf16 v[20:23], v[226:229], v[202:205], v[20:23]
	v_mfma_f32_16x16x32_bf16 v[16:19], v[234:237], v[202:205], v[16:19]
	v_mfma_f32_16x16x32_bf16 v[12:15], v[226:229], v[210:213], v[12:15]
	v_mfma_f32_16x16x32_bf16 v[8:11], v[234:237], v[210:213], v[8:11]
	v_mfma_f32_16x16x32_bf16 v[4:7], v[226:229], v[218:221], v[4:7]
	v_mfma_f32_16x16x32_bf16 v[0:3], v[234:237], v[218:221], v[0:3]
	s_add_i32 s65, s65, 2
	s_add_u32 s44, s44, 0x100
	s_addc_u32 s45, s45, 0
	s_cmpk_gt_u32 s65, 0x51
	s_barrier
	s_cbranch_scc0 .LBB0_224
	s_add_i32 s44, s14, 0x80
	s_mul_hi_i32 s45, s44, 0x2b00
	s_mulk_i32 s44, 0x2b00
	s_add_u32 s44, s48, s44
	s_addc_u32 s45, s49, s45
	s_add_u32 s44, s44, 0x2a80
	s_addc_u32 s45, s45, 0
	v_readfirstlane_b32 s65, v172
	v_lshl_add_u64 v[160:161], s[44:45], 0, v[128:129]
	s_mov_b32 m0, s65
	ds_read_b128 v[134:137], v164
	ds_read_b128 v[138:141], v164 offset:1024
	ds_read_b128 v[142:145], v164 offset:2048
	ds_read_b128 v[174:177], v164 offset:3072
	ds_read_b128 v[178:181], v155
	ds_read_b128 v[182:185], v155 offset:1024
	ds_read_b128 v[186:189], v154
	ds_read_b128 v[190:193], v154 offset:1024
	ds_read_b128 v[194:197], v153
	ds_read_b128 v[198:201], v153 offset:1024
	ds_read_b128 v[202:205], v152
	ds_read_b128 v[206:209], v152 offset:1024
	global_load_lds_dwordx4 v[160:161], off
	v_lshl_add_u64 v[160:161], s[44:45], 0, v[132:133]
	v_readfirstlane_b32 s44, v173
	s_mov_b32 m0, s44
	s_nop 0
	global_load_lds_dwordx4 v[160:161], off
	s_barrier
	s_waitcnt lgkmcnt(0)
	s_waitcnt lgkmcnt(0)
	v_mfma_f32_16x16x32_bf16 v[124:127], v[134:137], v[178:181], v[124:127]
	v_mfma_f32_16x16x32_bf16 v[120:123], v[142:145], v[178:181], v[120:123]
	v_mfma_f32_16x16x32_bf16 v[116:119], v[134:137], v[186:189], v[116:119]
	v_mfma_f32_16x16x32_bf16 v[112:115], v[142:145], v[186:189], v[112:115]
	v_mfma_f32_16x16x32_bf16 v[108:111], v[134:137], v[194:197], v[108:111]
	v_mfma_f32_16x16x32_bf16 v[104:107], v[142:145], v[194:197], v[104:107]
	v_mfma_f32_16x16x32_bf16 v[100:103], v[134:137], v[202:205], v[100:103]
	v_mfma_f32_16x16x32_bf16 v[96:99], v[142:145], v[202:205], v[96:99]
	v_mfma_f32_16x16x32_bf16 v[124:127], v[138:141], v[182:185], v[124:127]
	v_mfma_f32_16x16x32_bf16 v[120:123], v[174:177], v[182:185], v[120:123]
	v_mfma_f32_16x16x32_bf16 v[116:119], v[138:141], v[190:193], v[116:119]
	v_mfma_f32_16x16x32_bf16 v[112:115], v[174:177], v[190:193], v[112:115]
	v_mfma_f32_16x16x32_bf16 v[108:111], v[138:141], v[198:201], v[108:111]
	v_mfma_f32_16x16x32_bf16 v[104:107], v[174:177], v[198:201], v[104:107]
	v_mfma_f32_16x16x32_bf16 v[100:103], v[138:141], v[206:209], v[100:103]
	v_mfma_f32_16x16x32_bf16 v[96:99], v[174:177], v[206:209], v[96:99]
	s_barrier
	ds_read_b128 v[210:213], v163
	ds_read_b128 v[214:217], v163 offset:1024
	ds_read_b128 v[218:221], v163 offset:2048
	ds_read_b128 v[160:163], v163 offset:3072
	s_barrier
; #define LDA(dst, b, h) for (int m = 0; m < 4; ++m) for (int k = 0; k < 2; ++k) \
;     dst[m][k] = *reinterpret_cast<const bf16x8*>((char*)SA(b, h) + lds_byte(wr * 64 + m * 16 + fr, k * 32 + fq * 8))
; #define LDB(dst, b, h) for (int n = 0; n < 2; ++n) for (int k = 0; k < 2; ++k) \
;     dst[n][k] = *reinterpret_cast<const bf16x8*>((char*)SB(b, h) + lds_byte(wc * 32 + n * 16 + fr, k * 32 + fq * 8))
; #define MMA(ai, bj, At_, Bt_) do { __builtin_amdgcn_s_setprio(1); \
;     for (int k = 0; k < 2; ++k) for (int m = 0; m < 4; ++m) for (int n = 0; n < 2; ++n) \
;       acc[ai][bj][m][n] = __builtin_amdgcn_mfma_f32_16x16x32_bf16(At_[m][k], Bt_[n][k], acc[ai][bj][m][n], 0, 0, 0); \
;     __builtin_amdgcn_s_setprio(0); } while (0)
; #define WAIT_V(n) asm volatile("s_waitcnt vmcnt(" #n ")" ::: "memory")
; #define WAIT_L(n) asm volatile("s_waitcnt lgkmcnt(" #n ")" ::: "memory")
; #define BAR __builtin_amdgcn_s_barrier()
; template <int EPI, int lda, int ldb, int N, int K>
; __device__ __forceinline__ void gemm_phase(const u16* __restrict__ A, const u16* __restrict__ Bt, const GemmEpi ep, int wv) {
;     ...
;       BAR; WAIT_L(0); MMA(0, 0, At, B0); BAR;
;       LDB(B1, 0, 1); BAR; WAIT_L(0); MMA(0, 1, At, B1); BAR;
;       LDA(At, 0, 1); WAIT_V(4); BAR; WAIT_L(0); MMA(1, 0, At, B0); MMA(1, 1, At, B1); BAR; }
;     { LDB(B0, 1, 0); LDA(At, 1, 0); WAIT_V(2); BAR; WAIT_L(0); MMA(0, 0, At, B0); BAR;
	s_waitcnt lgkmcnt(0)
	s_waitcnt lgkmcnt(0)
	v_mfma_f32_16x16x32_bf16 v[92:95], v[210:213], v[178:181], v[92:95]
	v_mfma_f32_16x16x32_bf16 v[88:91], v[218:221], v[178:181], v[88:91]
	v_mfma_f32_16x16x32_bf16 v[76:79], v[210:213], v[194:197], v[76:79]
	v_mfma_f32_16x16x32_bf16 v[72:75], v[218:221], v[194:197], v[72:75]
	v_mfma_f32_16x16x32_bf16 v[84:87], v[210:213], v[186:189], v[84:87]
	v_mfma_f32_16x16x32_bf16 v[80:83], v[218:221], v[186:189], v[80:83]
	v_mfma_f32_16x16x32_bf16 v[68:71], v[210:213], v[202:205], v[68:71]
	v_mfma_f32_16x16x32_bf16 v[64:67], v[218:221], v[202:205], v[64:67]
	v_mfma_f32_16x16x32_bf16 v[92:95], v[214:217], v[182:185], v[92:95]
	v_mfma_f32_16x16x32_bf16 v[88:91], v[160:163], v[182:185], v[88:91]
	v_mfma_f32_16x16x32_bf16 v[76:79], v[214:217], v[198:201], v[76:79]
	v_mfma_f32_16x16x32_bf16 v[72:75], v[160:163], v[198:201], v[72:75]
	v_mfma_f32_16x16x32_bf16 v[178:181], v[214:217], v[190:193], v[84:87]
	v_mfma_f32_16x16x32_bf16 v[182:185], v[160:163], v[190:193], v[80:83]
	v_mfma_f32_16x16x32_bf16 v[186:189], v[214:217], v[206:209], v[68:71]
	v_mfma_f32_16x16x32_bf16 v[190:193], v[160:163], v[206:209], v[64:67]
	s_barrier
	s_nop 0
	ds_read_b128 v[64:67], v155 offset:16384
	ds_read_b128 v[68:71], v155 offset:17408
	ds_read_b128 v[80:83], v154 offset:16384
	ds_read_b128 v[84:87], v154 offset:17408
	ds_read_b128 v[194:197], v153 offset:16384
	ds_read_b128 v[198:201], v153 offset:17408
	ds_read_b128 v[202:205], v152 offset:16384
	ds_read_b128 v[206:209], v152 offset:17408
	s_waitcnt vmcnt(4)
	s_barrier
	s_waitcnt lgkmcnt(0)
	s_waitcnt lgkmcnt(0)
	v_mfma_f32_16x16x32_bf16 v[60:63], v[134:137], v[64:67], v[60:63]
	v_mfma_f32_16x16x32_bf16 v[56:59], v[142:145], v[64:67], v[56:59]
	v_mfma_f32_16x16x32_bf16 v[52:55], v[134:137], v[80:83], v[52:55]
	v_mfma_f32_16x16x32_bf16 v[48:51], v[142:145], v[80:83], v[48:51]
	v_mfma_f32_16x16x32_bf16 v[44:47], v[134:137], v[194:197], v[44:47]
	v_mfma_f32_16x16x32_bf16 v[40:43], v[142:145], v[194:197], v[40:43]
	v_mfma_f32_16x16x32_bf16 v[36:39], v[134:137], v[202:205], v[36:39]
	v_mfma_f32_16x16x32_bf16 v[32:35], v[142:145], v[202:205], v[32:35]
	v_mfma_f32_16x16x32_bf16 v[60:63], v[138:141], v[68:71], v[60:63]
	v_mfma_f32_16x16x32_bf16 v[56:59], v[174:177], v[68:71], v[56:59]
	v_mfma_f32_16x16x32_bf16 v[52:55], v[138:141], v[84:87], v[52:55]
	v_mfma_f32_16x16x32_bf16 v[48:51], v[174:177], v[84:87], v[48:51]
	v_mfma_f32_16x16x32_bf16 v[44:47], v[138:141], v[198:201], v[44:47]
	v_mfma_f32_16x16x32_bf16 v[40:43], v[174:177], v[198:201], v[40:43]
	v_mfma_f32_16x16x32_bf16 v[36:39], v[138:141], v[206:209], v[36:39]
	v_mfma_f32_16x16x32_bf16 v[32:35], v[174:177], v[206:209], v[32:35]
	v_mfma_f32_16x16x32_bf16 v[28:31], v[210:213], v[64:67], v[28:31]
	v_mfma_f32_16x16x32_bf16 v[16:19], v[218:221], v[80:83], v[16:19]
	v_mfma_f32_16x16x32_bf16 v[12:15], v[210:213], v[194:197], v[12:15]
	v_mfma_f32_16x16x32_bf16 v[0:3], v[218:221], v[202:205], v[0:3]
	v_mfma_f32_16x16x32_bf16 v[24:27], v[218:221], v[64:67], v[24:27]
	v_mfma_f32_16x16x32_bf16 v[20:23], v[210:213], v[80:83], v[20:23]
	v_mfma_f32_16x16x32_bf16 v[8:11], v[218:221], v[194:197], v[8:11]
	v_mfma_f32_16x16x32_bf16 v[4:7], v[210:213], v[202:205], v[4:7]
	v_mfma_f32_16x16x32_bf16 v[28:31], v[214:217], v[68:71], v[28:31]
	v_mfma_f32_16x16x32_bf16 v[16:19], v[160:163], v[84:87], v[16:19]
	v_mfma_f32_16x16x32_bf16 v[12:15], v[214:217], v[198:201], v[12:15]
	v_mfma_f32_16x16x32_bf16 v[0:3], v[160:163], v[206:209], v[0:3]
	v_mfma_f32_16x16x32_bf16 v[134:137], v[160:163], v[68:71], v[24:27]
	v_mfma_f32_16x16x32_bf16 v[138:141], v[214:217], v[84:87], v[20:23]
	v_mfma_f32_16x16x32_bf16 v[142:145], v[160:163], v[198:201], v[8:11]
	v_mfma_f32_16x16x32_bf16 v[172:175], v[214:217], v[206:209], v[4:7]
	s_barrier
	s_nop 0
	ds_read_b128 v[4:7], v159
	ds_read_b128 v[8:11], v159 offset:1024
	ds_read_b128 v[20:23], v159 offset:2048
	ds_read_b128 v[158:161], v159 offset:3072
	ds_read_b128 v[24:27], v155 offset:32768
	ds_read_b128 v[194:197], v155 offset:33792
	ds_read_b128 v[198:201], v154 offset:32768
	ds_read_b128 v[202:205], v154 offset:33792
	ds_read_b128 v[206:209], v153 offset:32768
	ds_read_b128 v[210:213], v153 offset:33792
	ds_read_b128 v[214:217], v152 offset:32768
	ds_read_b128 v[218:221], v152 offset:33792
	s_waitcnt vmcnt(2)
	s_barrier
; #define LDA(dst, b, h) for (int m = 0; m < 4; ++m) for (int k = 0; k < 2; ++k) \
;     dst[m][k] = *reinterpret_cast<const bf16x8*>((char*)SA(b, h) + lds_byte(wr * 64 + m * 16 + fr, k * 32 + fq * 8))
; #define LDB(dst, b, h) for (int n = 0; n < 2; ++n) for (int k = 0; k < 2; ++k) \
;     dst[n][k] = *reinterpret_cast<const bf16x8*>((char*)SB(b, h) + lds_byte(wc * 32 + n * 16 + fr, k * 32 + fq * 8))
; #define MMA(ai, bj, At_, Bt_) do { __builtin_amdgcn_s_setprio(1); \
;     for (int k = 0; k < 2; ++k) for (int m = 0; m < 4; ++m) for (int n = 0; n < 2; ++n) \
;       acc[ai][bj][m][n] = __builtin_amdgcn_mfma_f32_16x16x32_bf16(At_[m][k], Bt_[n][k], acc[ai][bj][m][n], 0, 0, 0); \
;     __builtin_amdgcn_s_setprio(0); } while (0)
; #define WAIT_V(n) asm volatile("s_waitcnt vmcnt(" #n ")" ::: "memory")
; #define WAIT_L(n) asm volatile("s_waitcnt lgkmcnt(" #n ")" ::: "memory")
; #define BAR __builtin_amdgcn_s_barrier()
; template <int EPI, int lda, int ldb, int N, int K>
; __device__ __forceinline__ void gemm_phase(const u16* __restrict__ A, const u16* __restrict__ Bt, const GemmEpi ep, int wv) {
;     ...
;     { LDB(B0, 1, 0); LDA(At, 1, 0); WAIT_V(2); BAR; WAIT_L(0); MMA(0, 0, At, B0); BAR;
;       LDB(B1, 1, 1); WAIT_V(0); BAR; WAIT_L(0); MMA(0, 1, At, B1); BAR;
;       LDA(At, 1, 1); BAR; WAIT_L(0); MMA(1, 0, At, B0); MMA(1, 1, At, B1); BAR; }
;     if (wr == 0) BAR;
	s_waitcnt lgkmcnt(0)
	s_waitcnt lgkmcnt(0)
	v_mfma_f32_16x16x32_bf16 v[64:67], v[4:7], v[24:27], v[124:127]
	v_mfma_f32_16x16x32_bf16 v[68:71], v[20:23], v[24:27], v[120:123]
	v_mfma_f32_16x16x32_bf16 v[80:83], v[4:7], v[198:201], v[116:119]
	v_mfma_f32_16x16x32_bf16 v[84:87], v[20:23], v[198:201], v[112:115]
	v_mfma_f32_16x16x32_bf16 v[108:111], v[4:7], v[206:209], v[108:111]
	v_mfma_f32_16x16x32_bf16 v[104:107], v[20:23], v[206:209], v[104:107]
	v_mfma_f32_16x16x32_bf16 v[120:123], v[4:7], v[214:217], v[100:103]
	v_mfma_f32_16x16x32_bf16 v[124:127], v[20:23], v[214:217], v[96:99]
	v_mfma_f32_16x16x32_bf16 v[116:119], v[8:11], v[194:197], v[64:67]
	v_mfma_f32_16x16x32_bf16 v[112:115], v[158:161], v[194:197], v[68:71]
	v_mfma_f32_16x16x32_bf16 v[100:103], v[8:11], v[202:205], v[80:83]
	v_mfma_f32_16x16x32_bf16 v[96:99], v[158:161], v[202:205], v[84:87]
	v_mfma_f32_16x16x32_bf16 v[84:87], v[8:11], v[210:213], v[108:111]
	v_mfma_f32_16x16x32_bf16 v[80:83], v[158:161], v[210:213], v[104:107]
	v_mfma_f32_16x16x32_bf16 v[68:71], v[8:11], v[218:221], v[120:123]
	v_mfma_f32_16x16x32_bf16 v[64:67], v[158:161], v[218:221], v[124:127]
	s_barrier
	ds_read_b128 v[222:225], v157
	ds_read_b128 v[226:229], v157 offset:1024
	ds_read_b128 v[230:233], v157 offset:2048
	ds_read_b128 v[234:237], v157 offset:3072
	s_waitcnt vmcnt(0)
	s_barrier
	s_waitcnt lgkmcnt(0)
	s_waitcnt lgkmcnt(0)
	v_mfma_f32_16x16x32_bf16 v[92:95], v[222:225], v[24:27], v[92:95]
	v_mfma_f32_16x16x32_bf16 v[24:27], v[230:233], v[24:27], v[88:91]
	v_mfma_f32_16x16x32_bf16 v[88:91], v[222:225], v[198:201], v[178:181]
	v_mfma_f32_16x16x32_bf16 v[104:107], v[230:233], v[198:201], v[182:185]
	v_mfma_f32_16x16x32_bf16 v[76:79], v[222:225], v[206:209], v[76:79]
	v_mfma_f32_16x16x32_bf16 v[72:75], v[230:233], v[206:209], v[72:75]
	v_mfma_f32_16x16x32_bf16 v[176:179], v[222:225], v[214:217], v[186:189]
	v_mfma_f32_16x16x32_bf16 v[180:183], v[230:233], v[214:217], v[190:193]
	v_mfma_f32_16x16x32_bf16 v[124:127], v[226:229], v[194:197], v[92:95]
	v_mfma_f32_16x16x32_bf16 v[120:123], v[234:237], v[194:197], v[24:27]
	v_mfma_f32_16x16x32_bf16 v[108:111], v[226:229], v[202:205], v[88:91]
	v_mfma_f32_16x16x32_bf16 v[104:107], v[234:237], v[202:205], v[104:107]
	v_mfma_f32_16x16x32_bf16 v[92:95], v[226:229], v[210:213], v[76:79]
	v_mfma_f32_16x16x32_bf16 v[88:91], v[234:237], v[210:213], v[72:75]
	v_mfma_f32_16x16x32_bf16 v[76:79], v[226:229], v[218:221], v[176:179]
	v_mfma_f32_16x16x32_bf16 v[72:75], v[234:237], v[218:221], v[180:183]
	s_barrier
	ds_read_b128 v[176:179], v155 offset:49152
	ds_read_b128 v[180:183], v155 offset:50176
	ds_read_b128 v[184:187], v154 offset:49152
	ds_read_b128 v[154:157], v154 offset:50176
	ds_read_b128 v[188:191], v153 offset:49152
	ds_read_b128 v[192:195], v153 offset:50176
	ds_read_b128 v[196:199], v152 offset:49152
	ds_read_b128 v[200:203], v152 offset:50176
	s_barrier
	s_waitcnt lgkmcnt(0)
	s_waitcnt lgkmcnt(0)
	v_mfma_f32_16x16x32_bf16 v[24:27], v[4:7], v[176:179], v[60:63]
	v_mfma_f32_16x16x32_bf16 v[60:63], v[20:23], v[176:179], v[56:59]
	v_mfma_f32_16x16x32_bf16 v[204:207], v[4:7], v[184:187], v[52:55]
	v_mfma_f32_16x16x32_bf16 v[48:51], v[20:23], v[184:187], v[48:51]
	v_mfma_f32_16x16x32_bf16 v[44:47], v[4:7], v[188:191], v[44:47]
	v_mfma_f32_16x16x32_bf16 v[208:211], v[20:23], v[188:191], v[40:43]
	v_mfma_f32_16x16x32_bf16 v[4:7], v[4:7], v[196:199], v[36:39]
	v_mfma_f32_16x16x32_bf16 v[32:35], v[20:23], v[196:199], v[32:35]
	v_mfma_f32_16x16x32_bf16 v[56:59], v[8:11], v[180:183], v[24:27]
	v_mfma_f32_16x16x32_bf16 v[52:55], v[158:161], v[180:183], v[60:63]
	v_mfma_f32_16x16x32_bf16 v[40:43], v[8:11], v[154:157], v[204:207]
	v_mfma_f32_16x16x32_bf16 v[36:39], v[158:161], v[154:157], v[48:51]
	v_mfma_f32_16x16x32_bf16 v[24:27], v[8:11], v[192:195], v[44:47]
	v_mfma_f32_16x16x32_bf16 v[20:23], v[158:161], v[192:195], v[208:211]
	v_mfma_f32_16x16x32_bf16 v[8:11], v[8:11], v[200:203], v[4:7]
	v_mfma_f32_16x16x32_bf16 v[4:7], v[158:161], v[200:203], v[32:35]
	v_mfma_f32_16x16x32_bf16 v[28:31], v[222:225], v[176:179], v[28:31]
	v_mfma_f32_16x16x32_bf16 v[32:35], v[230:233], v[176:179], v[134:137]
	v_mfma_f32_16x16x32_bf16 v[44:47], v[222:225], v[184:187], v[138:141]
	v_mfma_f32_16x16x32_bf16 v[16:19], v[230:233], v[184:187], v[16:19]
	v_mfma_f32_16x16x32_bf16 v[12:15], v[222:225], v[188:191], v[12:15]
	v_mfma_f32_16x16x32_bf16 v[134:137], v[230:233], v[188:191], v[142:145]
	v_mfma_f32_16x16x32_bf16 v[138:141], v[222:225], v[196:199], v[172:175]
	v_mfma_f32_16x16x32_bf16 v[0:3], v[230:233], v[196:199], v[0:3]
	v_mfma_f32_16x16x32_bf16 v[60:63], v[226:229], v[180:183], v[28:31]
	v_mfma_f32_16x16x32_bf16 v[48:51], v[234:237], v[180:183], v[32:35]
	v_mfma_f32_16x16x32_bf16 v[44:47], v[226:229], v[154:157], v[44:47]
	v_mfma_f32_16x16x32_bf16 v[32:35], v[234:237], v[154:157], v[16:19]
	v_mfma_f32_16x16x32_bf16 v[28:31], v[226:229], v[192:195], v[12:15]
	v_mfma_f32_16x16x32_bf16 v[16:19], v[234:237], v[192:195], v[134:137]
	v_mfma_f32_16x16x32_bf16 v[12:15], v[226:229], v[200:203], v[138:141]
	v_mfma_f32_16x16x32_bf16 v[0:3], v[234:237], v[200:203], v[0:3]
	v_cmp_gt_u32_e32 vcc, s62, v130
	s_barrier
	s_and_saveexec_b64 s[44:45], vcc
	s_cbranch_execz .LBB0_227
	s_barrier

; #define STAGE(P, BASE, LD, br, kt) do { const char* _g = (const char*)((BASE) + (size_t)(br) * (LD) + (size_t)(kt) * 64); \
;     for (int _i = 0; _i < 2; ++_i) { int _b = tidx * 16 + _i * 8192; int _r, _c; stage_rc(_b, _r, _c); \
;       __builtin_amdgcn_global_load_lds((const unsigned*)(_g + (unsigned)((_r * (LD) + _c) * 2)), (unsigned*)((char*)(P) + _b), 16, 0, 0); } } while (0)
; #define LDA(dst, b, h) for (int m = 0; m < 4; ++m) for (int k = 0; k < 2; ++k) \
;     dst[m][k] = *reinterpret_cast<const bf16x8*>((char*)SA(b, h) + lds_byte(wr * 64 + m * 16 + fr, k * 32 + fq * 8))
; #define LDB(dst, b, h) for (int n = 0; n < 2; ++n) for (int k = 0; k < 2; ++k) \
;     dst[n][k] = *reinterpret_cast<const bf16x8*>((char*)SB(b, h) + lds_byte(wc * 32 + n * 16 + fr, k * 32 + fq * 8))
; #define MMA(ai, bj, At_, Bt_) do { __builtin_amdgcn_s_setprio(1); \
;     for (int k = 0; k < 2; ++k) for (int m = 0; m < 4; ++m) for (int n = 0; n < 2; ++n) \
;       acc[ai][bj][m][n] = __builtin_amdgcn_mfma_f32_16x16x32_bf16(At_[m][k], Bt_[n][k], acc[ai][bj][m][n], 0, 0, 0); \
;     __builtin_amdgcn_s_setprio(0); } while (0)
; #define WAIT_V(n) asm volatile("s_waitcnt vmcnt(" #n ")" ::: "memory")
; #define WAIT_L(n) asm volatile("s_waitcnt lgkmcnt(" #n ")" ::: "memory")
; #define BAR __builtin_amdgcn_s_barrier()
; #define SCHED __builtin_amdgcn_sched_barrier(0)
; template <int EPI, int lda, int ldb, int N, int K>
; __device__ __forceinline__ void gemm_phase(const u16* __restrict__ A, const u16* __restrict__ Bt, const GemmEpi ep, int wv) {
;     ...
;     for (int t = 0; t < nt - 2; t += 2) {
;       LDB(B0, 0, 0); SCHED; LDA(At, 0, 0); STAGE(SA(1, 1), Ab, lda, brow + HALF, t + 1);
;       WAIT_L(8); BAR; WAIT_L(0); MMA(0, 0, At, B0); BAR; SCHED;
;       LDB(B1, 0, 1); STAGE(SB(0, 0), Bt, ldb, bcol, t + 2);
;       BAR; WAIT_L(0); MMA(0, 1, At, B1); BAR;
;       LDA(At, 0, 1); STAGE(SA(0, 0), Ab, lda, brow, t + 2);
;       BAR; WAIT_L(0); MMA(1, 0, At, B0); BAR; SCHED;
;       STAGE(SB(0, 1), Bt, ldb, bcol + HALF, t + 2);
;       WAIT_V(6); BAR; MMA(1, 1, At, B1); BAR;
;       LDB(B0, 1, 0); SCHED; LDA(At, 1, 0); STAGE(SA(0, 1), Ab, lda, brow + HALF, t + 2);
;       WAIT_L(8); BAR; WAIT_L(0); MMA(0, 0, At, B0); BAR; SCHED;
.LBB0_340:
	ds_read_b128 v[166:169], v162
	ds_read_b128 v[172:175], v162 offset:1024
	ds_read_b128 v[176:179], v162 offset:2048
	ds_read_b128 v[180:183], v162 offset:3072
	v_add_u32_e32 v170, 0xc000, v149
	v_lshl_add_u64 v[236:237], v[138:139], 0, s[48:49]
	v_readfirstlane_b32 s51, v170
	v_add_u32_e32 v171, 0xe000, v149
	v_lshl_add_u64 v[164:165], v[236:237], 0, s[18:19]
	s_mov_b32 m0, s51
	v_lshl_add_u64 v[238:239], v[140:141], 0, s[48:49]
	v_readfirstlane_b32 s51, v171
	global_load_lds_dwordx4 v[164:165], off
	v_lshl_add_u64 v[164:165], v[238:239], 0, s[18:19]
	s_mov_b32 m0, s51
	s_nop 0
	global_load_lds_dwordx4 v[164:165], off
	ds_read_b128 v[184:187], v153
	ds_read_b128 v[188:191], v153 offset:1024
	ds_read_b128 v[192:195], v152
	ds_read_b128 v[196:199], v152 offset:1024
	ds_read_b128 v[200:203], v151
	ds_read_b128 v[204:207], v151 offset:1024
	ds_read_b128 v[208:211], v150
	ds_read_b128 v[212:215], v150 offset:1024
	s_waitcnt lgkmcnt(8)
	s_barrier
	s_waitcnt lgkmcnt(0)
	s_waitcnt lgkmcnt(0)
	v_mfma_f32_16x16x32_bf16 v[124:127], v[184:187], v[166:169], v[124:127]
	v_mfma_f32_16x16x32_bf16 v[120:123], v[184:187], v[176:179], v[120:123]
	v_mfma_f32_16x16x32_bf16 v[116:119], v[192:195], v[166:169], v[116:119]
	v_mfma_f32_16x16x32_bf16 v[112:115], v[192:195], v[176:179], v[112:115]
	v_mfma_f32_16x16x32_bf16 v[108:111], v[200:203], v[166:169], v[108:111]
	v_mfma_f32_16x16x32_bf16 v[104:107], v[200:203], v[176:179], v[104:107]
	v_mfma_f32_16x16x32_bf16 v[100:103], v[208:211], v[166:169], v[100:103]
	v_mfma_f32_16x16x32_bf16 v[96:99], v[208:211], v[176:179], v[96:99]
	v_mfma_f32_16x16x32_bf16 v[124:127], v[188:191], v[172:175], v[124:127]
	v_mfma_f32_16x16x32_bf16 v[120:123], v[188:191], v[180:183], v[120:123]
	v_mfma_f32_16x16x32_bf16 v[116:119], v[196:199], v[172:175], v[116:119]
	v_mfma_f32_16x16x32_bf16 v[112:115], v[196:199], v[180:183], v[112:115]
	v_mfma_f32_16x16x32_bf16 v[108:111], v[204:207], v[172:175], v[108:111]
	v_mfma_f32_16x16x32_bf16 v[104:107], v[204:207], v[180:183], v[104:107]
	v_mfma_f32_16x16x32_bf16 v[100:103], v[212:215], v[172:175], v[100:103]
	v_mfma_f32_16x16x32_bf16 v[96:99], v[212:215], v[180:183], v[96:99]
	s_barrier
	v_add_u32_e32 v163, s62, v155
	v_lshl_add_u64 v[240:241], v[134:135], 0, s[48:49]
	v_readfirstlane_b32 s51, v163
	v_lshl_add_u64 v[164:165], v[240:241], 0, s[20:21]
	s_mov_b32 m0, s51
	global_load_lds_dwordx4 v[164:165], off
	v_add_u32_e32 v164, 0x2000, v163
	v_lshl_add_u64 v[242:243], v[136:137], 0, s[48:49]
	v_readfirstlane_b32 s51, v164
	v_lshl_add_u64 v[232:233], v[242:243], 0, s[20:21]
	s_mov_b32 m0, s51
	s_nop 0
	global_load_lds_dwordx4 v[232:233], off
	ds_read_b128 v[216:219], v161
	ds_read_b128 v[220:223], v161 offset:1024
	ds_read_b128 v[224:227], v161 offset:2048
	ds_read_b128 v[228:231], v161 offset:3072
	s_barrier
	s_waitcnt lgkmcnt(0)
	s_waitcnt lgkmcnt(0)
	v_mfma_f32_16x16x32_bf16 v[92:95], v[184:187], v[216:219], v[92:95]
	v_mfma_f32_16x16x32_bf16 v[88:91], v[184:187], v[224:227], v[88:91]
	v_mfma_f32_16x16x32_bf16 v[84:87], v[192:195], v[216:219], v[84:87]
	v_mfma_f32_16x16x32_bf16 v[80:83], v[192:195], v[224:227], v[80:83]
	v_mfma_f32_16x16x32_bf16 v[76:79], v[200:203], v[216:219], v[76:79]
	v_mfma_f32_16x16x32_bf16 v[72:75], v[200:203], v[224:227], v[72:75]
	v_mfma_f32_16x16x32_bf16 v[68:71], v[208:211], v[216:219], v[68:71]
	v_mfma_f32_16x16x32_bf16 v[64:67], v[208:211], v[224:227], v[64:67]
	v_mfma_f32_16x16x32_bf16 v[92:95], v[188:191], v[220:223], v[92:95]
	v_mfma_f32_16x16x32_bf16 v[88:91], v[188:191], v[228:231], v[88:91]
	v_mfma_f32_16x16x32_bf16 v[84:87], v[196:199], v[220:223], v[84:87]
	v_mfma_f32_16x16x32_bf16 v[80:83], v[196:199], v[228:231], v[80:83]
	v_mfma_f32_16x16x32_bf16 v[76:79], v[204:207], v[220:223], v[76:79]
	v_mfma_f32_16x16x32_bf16 v[72:75], v[204:207], v[228:231], v[72:75]
	v_mfma_f32_16x16x32_bf16 v[68:71], v[212:215], v[220:223], v[68:71]
	v_mfma_f32_16x16x32_bf16 v[64:67], v[212:215], v[228:231], v[64:67]
	v_readfirstlane_b32 s51, v149
	v_add_u32_e32 v165, 0x2000, v149
	v_lshl_add_u64 v[232:233], v[236:237], 0, s[22:23]
	s_mov_b32 m0, s51
	v_readfirstlane_b32 s51, v165
	s_barrier
	global_load_lds_dwordx4 v[232:233], off
	v_lshl_add_u64 v[232:233], v[238:239], 0, s[22:23]
	s_mov_b32 m0, s51
	s_nop 0
	global_load_lds_dwordx4 v[232:233], off
	ds_read_b128 v[184:187], v153 offset:16384
	ds_read_b128 v[188:191], v153 offset:17408
	ds_read_b128 v[192:195], v152 offset:16384
	ds_read_b128 v[196:199], v152 offset:17408
	ds_read_b128 v[200:203], v151 offset:16384
	ds_read_b128 v[204:207], v151 offset:17408
	ds_read_b128 v[208:211], v150 offset:16384
	ds_read_b128 v[212:215], v150 offset:17408
	s_barrier
	s_waitcnt lgkmcnt(0)
	s_waitcnt lgkmcnt(0)
	v_mfma_f32_16x16x32_bf16 v[60:63], v[184:187], v[166:169], v[60:63]
	v_mfma_f32_16x16x32_bf16 v[56:59], v[184:187], v[176:179], v[56:59]
	v_mfma_f32_16x16x32_bf16 v[52:55], v[192:195], v[166:169], v[52:55]
	v_mfma_f32_16x16x32_bf16 v[48:51], v[192:195], v[176:179], v[48:51]
	v_mfma_f32_16x16x32_bf16 v[44:47], v[200:203], v[166:169], v[44:47]
	v_mfma_f32_16x16x32_bf16 v[40:43], v[200:203], v[176:179], v[40:43]
	v_mfma_f32_16x16x32_bf16 v[36:39], v[208:211], v[166:169], v[36:39]
	v_mfma_f32_16x16x32_bf16 v[32:35], v[208:211], v[176:179], v[32:35]
	v_mfma_f32_16x16x32_bf16 v[60:63], v[188:191], v[172:175], v[60:63]
	v_mfma_f32_16x16x32_bf16 v[56:59], v[188:191], v[180:183], v[56:59]
	v_mfma_f32_16x16x32_bf16 v[52:55], v[196:199], v[172:175], v[52:55]
	v_mfma_f32_16x16x32_bf16 v[48:51], v[196:199], v[180:183], v[48:51]
	v_mfma_f32_16x16x32_bf16 v[44:47], v[204:207], v[172:175], v[44:47]
	v_mfma_f32_16x16x32_bf16 v[40:43], v[204:207], v[180:183], v[40:43]
	v_mfma_f32_16x16x32_bf16 v[36:39], v[212:215], v[172:175], v[36:39]
	v_mfma_f32_16x16x32_bf16 v[32:35], v[212:215], v[180:183], v[32:35]
	s_barrier
; #define STAGE(P, BASE, LD, br, kt) do { const char* _g = (const char*)((BASE) + (size_t)(br) * (LD) + (size_t)(kt) * 64); \
;     for (int _i = 0; _i < 2; ++_i) { int _b = tidx * 16 + _i * 8192; int _r, _c; stage_rc(_b, _r, _c); \
;       __builtin_amdgcn_global_load_lds((const unsigned*)(_g + (unsigned)((_r * (LD) + _c) * 2)), (unsigned*)((char*)(P) + _b), 16, 0, 0); } } while (0)
; #define LDA(dst, b, h) for (int m = 0; m < 4; ++m) for (int k = 0; k < 2; ++k) \
;     dst[m][k] = *reinterpret_cast<const bf16x8*>((char*)SA(b, h) + lds_byte(wr * 64 + m * 16 + fr, k * 32 + fq * 8))
; #define LDB(dst, b, h) for (int n = 0; n < 2; ++n) for (int k = 0; k < 2; ++k) \
;     dst[n][k] = *reinterpret_cast<const bf16x8*>((char*)SB(b, h) + lds_byte(wc * 32 + n * 16 + fr, k * 32 + fq * 8))
; #define MMA(ai, bj, At_, Bt_) do { __builtin_amdgcn_s_setprio(1); \
;     for (int k = 0; k < 2; ++k) for (int m = 0; m < 4; ++m) for (int n = 0; n < 2; ++n) \
;       acc[ai][bj][m][n] = __builtin_amdgcn_mfma_f32_16x16x32_bf16(At_[m][k], Bt_[n][k], acc[ai][bj][m][n], 0, 0, 0); \
;     __builtin_amdgcn_s_setprio(0); } while (0)
; #define WAIT_V(n) asm volatile("s_waitcnt vmcnt(" #n ")" ::: "memory")
; #define WAIT_L(n) asm volatile("s_waitcnt lgkmcnt(" #n ")" ::: "memory")
; #define BAR __builtin_amdgcn_s_barrier()
; #define SCHED __builtin_amdgcn_sched_barrier(0)
; template <int EPI, int lda, int ldb, int N, int K>
; __device__ __forceinline__ void gemm_phase(const u16* __restrict__ A, const u16* __restrict__ Bt, const GemmEpi ep, int wv) {
;     ...
;       STAGE(SB(0, 1), Bt, ldb, bcol + HALF, t + 2);
;       WAIT_V(6); BAR; MMA(1, 1, At, B1); BAR;
;       LDB(B0, 1, 0); SCHED; LDA(At, 1, 0); STAGE(SA(0, 1), Ab, lda, brow + HALF, t + 2);
;       WAIT_L(8); BAR; WAIT_L(0); MMA(0, 0, At, B0); BAR; SCHED;
;       LDB(B1, 1, 1); STAGE(SB(1, 0), Bt, ldb, bcol, t + 3);
;       BAR; WAIT_L(0); MMA(0, 1, At, B1); BAR;
;       LDA(At, 1, 1); STAGE(SA(1, 0), Ab, lda, brow, t + 3);
;       BAR; WAIT_L(0); MMA(1, 0, At, B0); BAR; SCHED;
	v_add_u32_e32 v166, s63, v155
	v_add_u32_e32 v167, 0x2000, v166
	v_readfirstlane_b32 s51, v166
	v_lshl_add_u64 v[168:169], v[240:241], 0, s[24:25]
	s_mov_b32 m0, s51
	v_readfirstlane_b32 s51, v167
	global_load_lds_dwordx4 v[168:169], off
	v_lshl_add_u64 v[168:169], v[242:243], 0, s[24:25]
	s_mov_b32 m0, s51
	s_nop 0
	global_load_lds_dwordx4 v[168:169], off
	s_waitcnt vmcnt(6)
	s_barrier
	v_mfma_f32_16x16x32_bf16 v[28:31], v[184:187], v[216:219], v[28:31]
	v_mfma_f32_16x16x32_bf16 v[24:27], v[184:187], v[224:227], v[24:27]
	v_mfma_f32_16x16x32_bf16 v[20:23], v[192:195], v[216:219], v[20:23]
	v_mfma_f32_16x16x32_bf16 v[16:19], v[192:195], v[224:227], v[16:19]
	v_mfma_f32_16x16x32_bf16 v[12:15], v[200:203], v[216:219], v[12:15]
	v_mfma_f32_16x16x32_bf16 v[8:11], v[200:203], v[224:227], v[8:11]
	v_mfma_f32_16x16x32_bf16 v[4:7], v[208:211], v[216:219], v[4:7]
	v_mfma_f32_16x16x32_bf16 v[0:3], v[208:211], v[224:227], v[0:3]
	v_mfma_f32_16x16x32_bf16 v[28:31], v[188:191], v[220:223], v[28:31]
	v_mfma_f32_16x16x32_bf16 v[24:27], v[188:191], v[228:231], v[24:27]
	v_mfma_f32_16x16x32_bf16 v[20:23], v[196:199], v[220:223], v[20:23]
	v_mfma_f32_16x16x32_bf16 v[16:19], v[196:199], v[228:231], v[16:19]
	v_mfma_f32_16x16x32_bf16 v[12:15], v[204:207], v[220:223], v[12:15]
	v_mfma_f32_16x16x32_bf16 v[8:11], v[204:207], v[228:231], v[8:11]
	v_mfma_f32_16x16x32_bf16 v[4:7], v[212:215], v[220:223], v[4:7]
	v_mfma_f32_16x16x32_bf16 v[0:3], v[212:215], v[228:231], v[0:3]
	s_barrier
	ds_read_b128 v[172:175], v156
	ds_read_b128 v[176:179], v156 offset:1024
	ds_read_b128 v[180:183], v156 offset:2048
	ds_read_b128 v[184:187], v156 offset:3072
	v_add_u32_e32 v168, 0x4000, v149
	v_add_u32_e32 v169, 0x6000, v149
	v_readfirstlane_b32 s51, v168
	v_lshl_add_u64 v[220:221], v[236:237], 0, s[26:27]
	s_mov_b32 m0, s51
	v_readfirstlane_b32 s51, v169
	global_load_lds_dwordx4 v[220:221], off
	v_lshl_add_u64 v[220:221], v[238:239], 0, s[26:27]
	s_mov_b32 m0, s51
	s_nop 0
	global_load_lds_dwordx4 v[220:221], off
	ds_read_b128 v[188:191], v153 offset:32768
	ds_read_b128 v[192:195], v153 offset:33792
	ds_read_b128 v[196:199], v152 offset:32768
	ds_read_b128 v[200:203], v152 offset:33792
	ds_read_b128 v[204:207], v151 offset:32768
	ds_read_b128 v[208:211], v151 offset:33792
	ds_read_b128 v[212:215], v150 offset:32768
	ds_read_b128 v[216:219], v150 offset:33792
	s_waitcnt lgkmcnt(8)
	s_barrier
	s_waitcnt lgkmcnt(0)
	s_waitcnt lgkmcnt(0)
	v_mfma_f32_16x16x32_bf16 v[124:127], v[188:191], v[172:175], v[124:127]
	v_mfma_f32_16x16x32_bf16 v[120:123], v[188:191], v[180:183], v[120:123]
	v_mfma_f32_16x16x32_bf16 v[116:119], v[196:199], v[172:175], v[116:119]
	v_mfma_f32_16x16x32_bf16 v[112:115], v[196:199], v[180:183], v[112:115]
	v_mfma_f32_16x16x32_bf16 v[108:111], v[204:207], v[172:175], v[108:111]
	v_mfma_f32_16x16x32_bf16 v[104:107], v[204:207], v[180:183], v[104:107]
	v_mfma_f32_16x16x32_bf16 v[100:103], v[212:215], v[172:175], v[100:103]
	v_mfma_f32_16x16x32_bf16 v[96:99], v[212:215], v[180:183], v[96:99]
	v_mfma_f32_16x16x32_bf16 v[124:127], v[192:195], v[176:179], v[124:127]
	v_mfma_f32_16x16x32_bf16 v[120:123], v[192:195], v[184:187], v[120:123]
	v_mfma_f32_16x16x32_bf16 v[116:119], v[200:203], v[176:179], v[116:119]
	v_mfma_f32_16x16x32_bf16 v[112:115], v[200:203], v[184:187], v[112:115]
	v_mfma_f32_16x16x32_bf16 v[108:111], v[208:211], v[176:179], v[108:111]
	v_mfma_f32_16x16x32_bf16 v[104:107], v[208:211], v[184:187], v[104:107]
	v_mfma_f32_16x16x32_bf16 v[100:103], v[216:219], v[176:179], v[100:103]
	v_mfma_f32_16x16x32_bf16 v[96:99], v[216:219], v[184:187], v[96:99]
	s_barrier
	v_readfirstlane_b32 s51, v157
	v_add_u32_e32 v246, 0x2000, v157
	v_lshl_add_u64 v[244:245], v[240:241], 0, s[36:37]
	s_mov_b32 m0, s51
	v_readfirstlane_b32 s51, v246
	global_load_lds_dwordx4 v[244:245], off
	v_lshl_add_u64 v[244:245], v[242:243], 0, s[36:37]
	s_mov_b32 m0, s51
	s_nop 0
	global_load_lds_dwordx4 v[244:245], off
	ds_read_b128 v[220:223], v154
	ds_read_b128 v[224:227], v154 offset:1024
	ds_read_b128 v[228:231], v154 offset:2048
	ds_read_b128 v[232:235], v154 offset:3072
	s_barrier
	s_waitcnt lgkmcnt(0)
	s_waitcnt lgkmcnt(0)
	v_mfma_f32_16x16x32_bf16 v[92:95], v[188:191], v[220:223], v[92:95]
	v_mfma_f32_16x16x32_bf16 v[88:91], v[188:191], v[228:231], v[88:91]
	v_mfma_f32_16x16x32_bf16 v[84:87], v[196:199], v[220:223], v[84:87]
	v_mfma_f32_16x16x32_bf16 v[80:83], v[196:199], v[228:231], v[80:83]
	v_mfma_f32_16x16x32_bf16 v[76:79], v[204:207], v[220:223], v[76:79]
	v_mfma_f32_16x16x32_bf16 v[72:75], v[204:207], v[228:231], v[72:75]
	v_mfma_f32_16x16x32_bf16 v[68:71], v[212:215], v[220:223], v[68:71]
	v_mfma_f32_16x16x32_bf16 v[64:67], v[212:215], v[228:231], v[64:67]
	v_mfma_f32_16x16x32_bf16 v[92:95], v[192:195], v[224:227], v[92:95]
	v_mfma_f32_16x16x32_bf16 v[88:91], v[192:195], v[232:235], v[88:91]
	v_mfma_f32_16x16x32_bf16 v[84:87], v[200:203], v[224:227], v[84:87]
	v_mfma_f32_16x16x32_bf16 v[80:83], v[200:203], v[232:235], v[80:83]
	v_mfma_f32_16x16x32_bf16 v[76:79], v[208:211], v[224:227], v[76:79]
	v_mfma_f32_16x16x32_bf16 v[72:75], v[208:211], v[232:235], v[72:75]
	v_mfma_f32_16x16x32_bf16 v[68:71], v[216:219], v[224:227], v[68:71]
	v_mfma_f32_16x16x32_bf16 v[64:67], v[216:219], v[232:235], v[64:67]
	v_readfirstlane_b32 s51, v158
	v_lshl_add_u64 v[236:237], v[236:237], 0, s[38:39]
	s_mov_b32 m0, s51
	v_readfirstlane_b32 s51, v159
	s_barrier
; #define STAGE(P, BASE, LD, br, kt) do { const char* _g = (const char*)((BASE) + (size_t)(br) * (LD) + (size_t)(kt) * 64); \
;     for (int _i = 0; _i < 2; ++_i) { int _b = tidx * 16 + _i * 8192; int _r, _c; stage_rc(_b, _r, _c); \
;       __builtin_amdgcn_global_load_lds((const unsigned*)(_g + (unsigned)((_r * (LD) + _c) * 2)), (unsigned*)((char*)(P) + _b), 16, 0, 0); } } while (0)
; #define LDA(dst, b, h) for (int m = 0; m < 4; ++m) for (int k = 0; k < 2; ++k) \
;     dst[m][k] = *reinterpret_cast<const bf16x8*>((char*)SA(b, h) + lds_byte(wr * 64 + m * 16 + fr, k * 32 + fq * 8))
; #define LDB(dst, b, h) for (int n = 0; n < 2; ++n) for (int k = 0; k < 2; ++k) \
;     dst[n][k] = *reinterpret_cast<const bf16x8*>((char*)SB(b, h) + lds_byte(wc * 32 + n * 16 + fr, k * 32 + fq * 8))
; #define MMA(ai, bj, At_, Bt_) do { __builtin_amdgcn_s_setprio(1); \
;     for (int k = 0; k < 2; ++k) for (int m = 0; m < 4; ++m) for (int n = 0; n < 2; ++n) \
;       acc[ai][bj][m][n] = __builtin_amdgcn_mfma_f32_16x16x32_bf16(At_[m][k], Bt_[n][k], acc[ai][bj][m][n], 0, 0, 0); \
;     __builtin_amdgcn_s_setprio(0); } while (0)
; #define WAIT_V(n) asm volatile("s_waitcnt vmcnt(" #n ")" ::: "memory")
; #define WAIT_L(n) asm volatile("s_waitcnt lgkmcnt(" #n ")" ::: "memory")
; #define BAR __builtin_amdgcn_s_barrier()
; #define SCHED __builtin_amdgcn_sched_barrier(0)
; template <int EPI, int lda, int ldb, int N, int K>
; __device__ __forceinline__ void gemm_phase(const u16* __restrict__ A, const u16* __restrict__ Bt, const GemmEpi ep, int wv) {
;     ...
;       LDA(At, 1, 1); STAGE(SA(1, 0), Ab, lda, brow, t + 3);
;       BAR; WAIT_L(0); MMA(1, 0, At, B0); BAR; SCHED;
;       STAGE(SB(1, 1), Bt, ldb, bcol + HALF, t + 3);
;       WAIT_V(6); BAR; MMA(1, 1, At, B1); BAR;
;     }
;     { LDB(B0, 0, 0); LDA(At, 0, 0); STAGE(SA(1, 1), Ab, lda, brow + HALF, nt - 1);
;       BAR; WAIT_L(0); MMA(0, 0, At, B0); BAR;
;       LDB(B1, 0, 1); BAR; WAIT_L(0); MMA(0, 1, At, B1); BAR;
;       LDA(At, 0, 1); WAIT_V(4); BAR; WAIT_L(0); MMA(1, 0, At, B0); MMA(1, 1, At, B1); BAR; }
	global_load_lds_dwordx4 v[236:237], off
	v_lshl_add_u64 v[236:237], v[238:239], 0, s[38:39]
	s_mov_b32 m0, s51
	s_nop 0
	global_load_lds_dwordx4 v[236:237], off
	ds_read_b128 v[188:191], v153 offset:49152
	ds_read_b128 v[192:195], v153 offset:50176
	ds_read_b128 v[196:199], v152 offset:49152
	ds_read_b128 v[200:203], v152 offset:50176
	ds_read_b128 v[204:207], v151 offset:49152
	ds_read_b128 v[208:211], v151 offset:50176
	ds_read_b128 v[212:215], v150 offset:49152
	ds_read_b128 v[216:219], v150 offset:50176
	s_barrier
	s_waitcnt lgkmcnt(0)
	s_waitcnt lgkmcnt(0)
	v_mfma_f32_16x16x32_bf16 v[60:63], v[188:191], v[172:175], v[60:63]
	v_mfma_f32_16x16x32_bf16 v[56:59], v[188:191], v[180:183], v[56:59]
	v_mfma_f32_16x16x32_bf16 v[52:55], v[196:199], v[172:175], v[52:55]
	v_mfma_f32_16x16x32_bf16 v[48:51], v[196:199], v[180:183], v[48:51]
	v_mfma_f32_16x16x32_bf16 v[44:47], v[204:207], v[172:175], v[44:47]
	v_mfma_f32_16x16x32_bf16 v[40:43], v[204:207], v[180:183], v[40:43]
	v_mfma_f32_16x16x32_bf16 v[36:39], v[212:215], v[172:175], v[36:39]
	v_mfma_f32_16x16x32_bf16 v[32:35], v[212:215], v[180:183], v[32:35]
	v_mfma_f32_16x16x32_bf16 v[60:63], v[192:195], v[176:179], v[60:63]
	v_mfma_f32_16x16x32_bf16 v[56:59], v[192:195], v[184:187], v[56:59]
	v_mfma_f32_16x16x32_bf16 v[52:55], v[200:203], v[176:179], v[52:55]
	v_mfma_f32_16x16x32_bf16 v[48:51], v[200:203], v[184:187], v[48:51]
	v_mfma_f32_16x16x32_bf16 v[44:47], v[208:211], v[176:179], v[44:47]
	v_mfma_f32_16x16x32_bf16 v[40:43], v[208:211], v[184:187], v[40:43]
	v_mfma_f32_16x16x32_bf16 v[36:39], v[216:219], v[176:179], v[36:39]
	v_mfma_f32_16x16x32_bf16 v[32:35], v[216:219], v[184:187], v[32:35]
	s_barrier
	v_readfirstlane_b32 s51, v160
	v_add_u32_e32 v174, 0x2000, v160
	v_lshl_add_u64 v[172:173], v[240:241], 0, s[42:43]
	s_mov_b32 m0, s51
	v_readfirstlane_b32 s51, v174
	global_load_lds_dwordx4 v[172:173], off
	v_lshl_add_u64 v[172:173], v[242:243], 0, s[42:43]
	s_mov_b32 m0, s51
	s_nop 0
	global_load_lds_dwordx4 v[172:173], off
	s_waitcnt vmcnt(6)
	s_barrier
	v_mfma_f32_16x16x32_bf16 v[28:31], v[188:191], v[220:223], v[28:31]
	v_mfma_f32_16x16x32_bf16 v[24:27], v[188:191], v[228:231], v[24:27]
	v_mfma_f32_16x16x32_bf16 v[20:23], v[196:199], v[220:223], v[20:23]
	v_mfma_f32_16x16x32_bf16 v[16:19], v[196:199], v[228:231], v[16:19]
	v_mfma_f32_16x16x32_bf16 v[12:15], v[204:207], v[220:223], v[12:15]
	v_mfma_f32_16x16x32_bf16 v[8:11], v[204:207], v[228:231], v[8:11]
	v_mfma_f32_16x16x32_bf16 v[4:7], v[212:215], v[220:223], v[4:7]
	v_mfma_f32_16x16x32_bf16 v[0:3], v[212:215], v[228:231], v[0:3]
	v_mfma_f32_16x16x32_bf16 v[28:31], v[192:195], v[224:227], v[28:31]
	v_mfma_f32_16x16x32_bf16 v[24:27], v[192:195], v[232:235], v[24:27]
	v_mfma_f32_16x16x32_bf16 v[20:23], v[200:203], v[224:227], v[20:23]
	v_mfma_f32_16x16x32_bf16 v[16:19], v[200:203], v[232:235], v[16:19]
	v_mfma_f32_16x16x32_bf16 v[12:15], v[208:211], v[224:227], v[12:15]
	v_mfma_f32_16x16x32_bf16 v[8:11], v[208:211], v[232:235], v[8:11]
	v_mfma_f32_16x16x32_bf16 v[4:7], v[216:219], v[224:227], v[4:7]
	v_mfma_f32_16x16x32_bf16 v[0:3], v[216:219], v[232:235], v[0:3]
	s_add_i32 s50, s50, 2
	s_add_u32 s48, s48, 0x100
	s_addc_u32 s49, s49, 0
	s_cmp_gt_u32 s50, 27
	s_barrier
	s_cbranch_scc0 .LBB0_340
	s_add_i32 s48, s46, 0x80
	s_mul_hi_i32 s49, s48, 0x1080
	s_mulk_i32 s48, 0x1080
	s_add_u32 s48, s31, s48
	s_addc_u32 s49, s56, s49
	v_lshl_add_u64 v[158:159], s[48:49], 0, v[128:129]
	v_readfirstlane_b32 s50, v170
	v_lshl_add_u64 v[158:159], v[158:159], 0, s[44:45]
	s_mov_b32 m0, s50
	ds_read_b128 v[134:137], v162
	ds_read_b128 v[138:141], v162 offset:1024
	ds_read_b128 v[172:175], v162 offset:2048
	ds_read_b128 v[176:179], v162 offset:3072
	ds_read_b128 v[180:183], v153
	ds_read_b128 v[184:187], v153 offset:1024
	ds_read_b128 v[188:191], v152
	ds_read_b128 v[192:195], v152 offset:1024
	ds_read_b128 v[196:199], v151
	ds_read_b128 v[200:203], v151 offset:1024
	ds_read_b128 v[204:207], v150
	ds_read_b128 v[208:211], v150 offset:1024
	global_load_lds_dwordx4 v[158:159], off
	v_lshl_add_u64 v[158:159], s[48:49], 0, v[132:133]
	v_readfirstlane_b32 s48, v171
	v_lshl_add_u64 v[158:159], v[158:159], 0, s[44:45]
	s_mov_b32 m0, s48
	s_nop 0
	global_load_lds_dwordx4 v[158:159], off
	s_barrier
	s_waitcnt lgkmcnt(0)
	s_waitcnt lgkmcnt(0)
	v_mfma_f32_16x16x32_bf16 v[124:127], v[180:183], v[134:137], v[124:127]
	v_mfma_f32_16x16x32_bf16 v[120:123], v[180:183], v[172:175], v[120:123]
	v_mfma_f32_16x16x32_bf16 v[116:119], v[188:191], v[134:137], v[116:119]
	v_mfma_f32_16x16x32_bf16 v[112:115], v[188:191], v[172:175], v[112:115]
	v_mfma_f32_16x16x32_bf16 v[108:111], v[196:199], v[134:137], v[108:111]
	v_mfma_f32_16x16x32_bf16 v[104:107], v[196:199], v[172:175], v[104:107]
	v_mfma_f32_16x16x32_bf16 v[100:103], v[204:207], v[134:137], v[100:103]
	v_mfma_f32_16x16x32_bf16 v[96:99], v[204:207], v[172:175], v[96:99]
	v_mfma_f32_16x16x32_bf16 v[124:127], v[184:187], v[138:141], v[124:127]
	v_mfma_f32_16x16x32_bf16 v[120:123], v[184:187], v[176:179], v[120:123]
	v_mfma_f32_16x16x32_bf16 v[116:119], v[192:195], v[138:141], v[116:119]
	v_mfma_f32_16x16x32_bf16 v[112:115], v[192:195], v[176:179], v[112:115]
	v_mfma_f32_16x16x32_bf16 v[108:111], v[200:203], v[138:141], v[108:111]
	v_mfma_f32_16x16x32_bf16 v[104:107], v[200:203], v[176:179], v[104:107]
	v_mfma_f32_16x16x32_bf16 v[100:103], v[208:211], v[138:141], v[100:103]
	v_mfma_f32_16x16x32_bf16 v[96:99], v[208:211], v[176:179], v[96:99]
	s_barrier
	ds_read_b128 v[212:215], v161
	ds_read_b128 v[216:219], v161 offset:1024
	ds_read_b128 v[220:223], v161 offset:2048
	ds_read_b128 v[158:161], v161 offset:3072
	s_barrier
; #define LDA(dst, b, h) for (int m = 0; m < 4; ++m) for (int k = 0; k < 2; ++k) \
;     dst[m][k] = *reinterpret_cast<const bf16x8*>((char*)SA(b, h) + lds_byte(wr * 64 + m * 16 + fr, k * 32 + fq * 8))
; #define LDB(dst, b, h) for (int n = 0; n < 2; ++n) for (int k = 0; k < 2; ++k) \
;     dst[n][k] = *reinterpret_cast<const bf16x8*>((char*)SB(b, h) + lds_byte(wc * 32 + n * 16 + fr, k * 32 + fq * 8))
; #define MMA(ai, bj, At_, Bt_) do { __builtin_amdgcn_s_setprio(1); \
;     for (int k = 0; k < 2; ++k) for (int m = 0; m < 4; ++m) for (int n = 0; n < 2; ++n) \
;       acc[ai][bj][m][n] = __builtin_amdgcn_mfma_f32_16x16x32_bf16(At_[m][k], Bt_[n][k], acc[ai][bj][m][n], 0, 0, 0); \
;     __builtin_amdgcn_s_setprio(0); } while (0)
; #define WAIT_V(n) asm volatile("s_waitcnt vmcnt(" #n ")" ::: "memory")
; #define WAIT_L(n) asm volatile("s_waitcnt lgkmcnt(" #n ")" ::: "memory")
; #define BAR __builtin_amdgcn_s_barrier()
; template <int EPI, int lda, int ldb, int N, int K>
; __device__ __forceinline__ void gemm_phase(const u16* __restrict__ A, const u16* __restrict__ Bt, const GemmEpi ep, int wv) {
;     ...
;       BAR; WAIT_L(0); MMA(0, 0, At, B0); BAR;
;       LDB(B1, 0, 1); BAR; WAIT_L(0); MMA(0, 1, At, B1); BAR;
;       LDA(At, 0, 1); WAIT_V(4); BAR; WAIT_L(0); MMA(1, 0, At, B0); MMA(1, 1, At, B1); BAR; }
;     { LDB(B0, 1, 0); LDA(At, 1, 0); WAIT_V(2); BAR; WAIT_L(0); MMA(0, 0, At, B0); BAR;
	s_waitcnt lgkmcnt(0)
	s_waitcnt lgkmcnt(0)
	v_mfma_f32_16x16x32_bf16 v[92:95], v[180:183], v[212:215], v[92:95]
	v_mfma_f32_16x16x32_bf16 v[88:91], v[180:183], v[220:223], v[88:91]
	v_mfma_f32_16x16x32_bf16 v[76:79], v[196:199], v[212:215], v[76:79]
	v_mfma_f32_16x16x32_bf16 v[72:75], v[196:199], v[220:223], v[72:75]
	v_mfma_f32_16x16x32_bf16 v[68:71], v[204:207], v[212:215], v[68:71]
	v_mfma_f32_16x16x32_bf16 v[64:67], v[204:207], v[220:223], v[64:67]
	v_mfma_f32_16x16x32_bf16 v[84:87], v[188:191], v[212:215], v[84:87]
	v_mfma_f32_16x16x32_bf16 v[80:83], v[188:191], v[220:223], v[80:83]
	v_mfma_f32_16x16x32_bf16 v[92:95], v[184:187], v[216:219], v[92:95]
	v_mfma_f32_16x16x32_bf16 v[88:91], v[184:187], v[158:161], v[88:91]
	v_mfma_f32_16x16x32_bf16 v[76:79], v[200:203], v[216:219], v[76:79]
	v_mfma_f32_16x16x32_bf16 v[72:75], v[200:203], v[158:161], v[72:75]
	v_mfma_f32_16x16x32_bf16 v[68:71], v[208:211], v[216:219], v[68:71]
	v_mfma_f32_16x16x32_bf16 v[64:67], v[208:211], v[158:161], v[64:67]
	v_mfma_f32_16x16x32_bf16 v[180:183], v[192:195], v[216:219], v[84:87]
	v_mfma_f32_16x16x32_bf16 v[184:187], v[192:195], v[158:161], v[80:83]
	s_barrier
	s_nop 0
	ds_read_b128 v[80:83], v153 offset:16384
	ds_read_b128 v[84:87], v153 offset:17408
	ds_read_b128 v[188:191], v152 offset:16384
	ds_read_b128 v[192:195], v152 offset:17408
	ds_read_b128 v[196:199], v151 offset:16384
	ds_read_b128 v[200:203], v151 offset:17408
	ds_read_b128 v[204:207], v150 offset:16384
	ds_read_b128 v[208:211], v150 offset:17408
	s_waitcnt vmcnt(4)
	s_barrier
	s_waitcnt lgkmcnt(0)
	s_waitcnt lgkmcnt(0)
	v_mfma_f32_16x16x32_bf16 v[60:63], v[80:83], v[134:137], v[60:63]
	v_mfma_f32_16x16x32_bf16 v[44:47], v[196:199], v[134:137], v[44:47]
	v_mfma_f32_16x16x32_bf16 v[40:43], v[196:199], v[172:175], v[40:43]
	v_mfma_f32_16x16x32_bf16 v[36:39], v[204:207], v[134:137], v[36:39]
	v_mfma_f32_16x16x32_bf16 v[32:35], v[204:207], v[172:175], v[32:35]
	v_mfma_f32_16x16x32_bf16 v[56:59], v[80:83], v[172:175], v[56:59]
	v_mfma_f32_16x16x32_bf16 v[52:55], v[188:191], v[134:137], v[52:55]
	v_mfma_f32_16x16x32_bf16 v[48:51], v[188:191], v[172:175], v[48:51]
	v_mfma_f32_16x16x32_bf16 v[60:63], v[84:87], v[138:141], v[60:63]
	v_mfma_f32_16x16x32_bf16 v[44:47], v[200:203], v[138:141], v[44:47]
	v_mfma_f32_16x16x32_bf16 v[40:43], v[200:203], v[176:179], v[40:43]
	v_mfma_f32_16x16x32_bf16 v[36:39], v[208:211], v[138:141], v[36:39]
	v_mfma_f32_16x16x32_bf16 v[32:35], v[208:211], v[176:179], v[32:35]
	v_mfma_f32_16x16x32_bf16 v[134:137], v[84:87], v[176:179], v[56:59]
	v_mfma_f32_16x16x32_bf16 v[170:173], v[192:195], v[138:141], v[52:55]
	v_mfma_f32_16x16x32_bf16 v[224:227], v[192:195], v[176:179], v[48:51]
	v_mfma_f32_16x16x32_bf16 v[28:31], v[80:83], v[212:215], v[28:31]
	v_mfma_f32_16x16x32_bf16 v[20:23], v[188:191], v[212:215], v[20:23]
	v_mfma_f32_16x16x32_bf16 v[12:15], v[196:199], v[212:215], v[12:15]
	v_mfma_f32_16x16x32_bf16 v[4:7], v[204:207], v[212:215], v[4:7]
	v_mfma_f32_16x16x32_bf16 v[24:27], v[80:83], v[220:223], v[24:27]
	v_mfma_f32_16x16x32_bf16 v[16:19], v[188:191], v[220:223], v[16:19]
	v_mfma_f32_16x16x32_bf16 v[8:11], v[196:199], v[220:223], v[8:11]
	v_mfma_f32_16x16x32_bf16 v[0:3], v[204:207], v[220:223], v[0:3]
	v_mfma_f32_16x16x32_bf16 v[28:31], v[84:87], v[216:219], v[28:31]
	v_mfma_f32_16x16x32_bf16 v[20:23], v[192:195], v[216:219], v[20:23]
	v_mfma_f32_16x16x32_bf16 v[12:15], v[200:203], v[216:219], v[12:15]
	v_mfma_f32_16x16x32_bf16 v[4:7], v[208:211], v[216:219], v[4:7]
	v_mfma_f32_16x16x32_bf16 v[138:141], v[84:87], v[158:161], v[24:27]
	v_mfma_f32_16x16x32_bf16 v[174:177], v[192:195], v[158:161], v[16:19]
	v_mfma_f32_16x16x32_bf16 v[188:191], v[200:203], v[158:161], v[8:11]
	v_mfma_f32_16x16x32_bf16 v[158:161], v[208:211], v[158:161], v[0:3]
	s_barrier
	s_nop 0
	ds_read_b128 v[0:3], v156
	ds_read_b128 v[8:11], v156 offset:1024
	ds_read_b128 v[16:19], v156 offset:2048
	ds_read_b128 v[192:195], v156 offset:3072
	ds_read_b128 v[24:27], v153 offset:32768
	ds_read_b128 v[56:59], v153 offset:33792
	ds_read_b128 v[196:199], v152 offset:32768
	ds_read_b128 v[200:203], v152 offset:33792
	ds_read_b128 v[204:207], v151 offset:32768
	ds_read_b128 v[208:211], v151 offset:33792
	ds_read_b128 v[212:215], v150 offset:32768
	ds_read_b128 v[216:219], v150 offset:33792
	s_waitcnt vmcnt(2)
	s_barrier
; #define LDA(dst, b, h) for (int m = 0; m < 4; ++m) for (int k = 0; k < 2; ++k) \
;     dst[m][k] = *reinterpret_cast<const bf16x8*>((char*)SA(b, h) + lds_byte(wr * 64 + m * 16 + fr, k * 32 + fq * 8))
; #define LDB(dst, b, h) for (int n = 0; n < 2; ++n) for (int k = 0; k < 2; ++k) \
;     dst[n][k] = *reinterpret_cast<const bf16x8*>((char*)SB(b, h) + lds_byte(wc * 32 + n * 16 + fr, k * 32 + fq * 8))
; #define MMA(ai, bj, At_, Bt_) do { __builtin_amdgcn_s_setprio(1); \
;     for (int k = 0; k < 2; ++k) for (int m = 0; m < 4; ++m) for (int n = 0; n < 2; ++n) \
;       acc[ai][bj][m][n] = __builtin_amdgcn_mfma_f32_16x16x32_bf16(At_[m][k], Bt_[n][k], acc[ai][bj][m][n], 0, 0, 0); \
;     __builtin_amdgcn_s_setprio(0); } while (0)
; #define WAIT_V(n) asm volatile("s_waitcnt vmcnt(" #n ")" ::: "memory")
; #define WAIT_L(n) asm volatile("s_waitcnt lgkmcnt(" #n ")" ::: "memory")
; #define BAR __builtin_amdgcn_s_barrier()
; template <int EPI, int lda, int ldb, int N, int K>
; __device__ __forceinline__ void gemm_phase(const u16* __restrict__ A, const u16* __restrict__ Bt, const GemmEpi ep, int wv) {
;     ...
;     { LDB(B0, 1, 0); LDA(At, 1, 0); WAIT_V(2); BAR; WAIT_L(0); MMA(0, 0, At, B0); BAR;
;       LDB(B1, 1, 1); WAIT_V(0); BAR; WAIT_L(0); MMA(0, 1, At, B1); BAR;
;       LDA(At, 1, 1); BAR; WAIT_L(0); MMA(1, 0, At, B0); MMA(1, 1, At, B1); BAR; }
;     if (wr == 0) BAR;
	s_waitcnt lgkmcnt(0)
	s_waitcnt lgkmcnt(0)
	v_mfma_f32_16x16x32_bf16 v[48:51], v[24:27], v[0:3], v[124:127]
	v_mfma_f32_16x16x32_bf16 v[52:55], v[24:27], v[16:19], v[120:123]
	v_mfma_f32_16x16x32_bf16 v[80:83], v[196:199], v[0:3], v[116:119]
	v_mfma_f32_16x16x32_bf16 v[84:87], v[196:199], v[16:19], v[112:115]
	v_mfma_f32_16x16x32_bf16 v[108:111], v[204:207], v[0:3], v[108:111]
	v_mfma_f32_16x16x32_bf16 v[104:107], v[204:207], v[16:19], v[104:107]
	v_mfma_f32_16x16x32_bf16 v[112:115], v[212:215], v[0:3], v[100:103]
	v_mfma_f32_16x16x32_bf16 v[120:123], v[212:215], v[16:19], v[96:99]
	v_mfma_f32_16x16x32_bf16 v[124:127], v[56:59], v[8:11], v[48:51]
	v_mfma_f32_16x16x32_bf16 v[116:119], v[56:59], v[192:195], v[52:55]
	v_mfma_f32_16x16x32_bf16 v[100:103], v[200:203], v[8:11], v[80:83]
	v_mfma_f32_16x16x32_bf16 v[96:99], v[200:203], v[192:195], v[84:87]
	v_mfma_f32_16x16x32_bf16 v[84:87], v[208:211], v[8:11], v[108:111]
	v_mfma_f32_16x16x32_bf16 v[80:83], v[208:211], v[192:195], v[104:107]
	v_mfma_f32_16x16x32_bf16 v[52:55], v[216:219], v[8:11], v[112:115]
	v_mfma_f32_16x16x32_bf16 v[48:51], v[216:219], v[192:195], v[120:123]
	s_barrier
	ds_read_b128 v[220:223], v154
	ds_read_b128 v[228:231], v154 offset:1024
	ds_read_b128 v[232:235], v154 offset:2048
	ds_read_b128 v[154:157], v154 offset:3072
	s_waitcnt vmcnt(0)
	s_barrier
	s_waitcnt lgkmcnt(0)
	s_waitcnt lgkmcnt(0)
	v_mfma_f32_16x16x32_bf16 v[92:95], v[24:27], v[220:223], v[92:95]
	v_mfma_f32_16x16x32_bf16 v[24:27], v[24:27], v[232:235], v[88:91]
	v_mfma_f32_16x16x32_bf16 v[88:91], v[196:199], v[220:223], v[180:183]
	v_mfma_f32_16x16x32_bf16 v[104:107], v[196:199], v[232:235], v[184:187]
	v_mfma_f32_16x16x32_bf16 v[76:79], v[204:207], v[220:223], v[76:79]
	v_mfma_f32_16x16x32_bf16 v[72:75], v[204:207], v[232:235], v[72:75]
	v_mfma_f32_16x16x32_bf16 v[68:71], v[212:215], v[220:223], v[68:71]
	v_mfma_f32_16x16x32_bf16 v[64:67], v[212:215], v[232:235], v[64:67]
	v_mfma_f32_16x16x32_bf16 v[120:123], v[56:59], v[228:231], v[92:95]
	v_mfma_f32_16x16x32_bf16 v[112:115], v[56:59], v[154:157], v[24:27]
	v_mfma_f32_16x16x32_bf16 v[108:111], v[200:203], v[228:231], v[88:91]
	v_mfma_f32_16x16x32_bf16 v[104:107], v[200:203], v[154:157], v[104:107]
	v_mfma_f32_16x16x32_bf16 v[92:95], v[208:211], v[228:231], v[76:79]
	v_mfma_f32_16x16x32_bf16 v[88:91], v[208:211], v[154:157], v[72:75]
	v_mfma_f32_16x16x32_bf16 v[68:71], v[216:219], v[228:231], v[68:71]
	v_mfma_f32_16x16x32_bf16 v[56:59], v[216:219], v[154:157], v[64:67]
	s_barrier
	s_nop 0
	ds_read_b128 v[64:67], v153 offset:49152
	ds_read_b128 v[178:181], v153 offset:50176
	ds_read_b128 v[76:79], v152 offset:49152
	ds_read_b128 v[182:185], v152 offset:50176
	ds_read_b128 v[196:199], v151 offset:49152
	ds_read_b128 v[200:203], v151 offset:50176
	ds_read_b128 v[204:207], v150 offset:49152
	ds_read_b128 v[150:153], v150 offset:50176
	s_barrier
	s_waitcnt lgkmcnt(0)
	s_waitcnt lgkmcnt(0)
	v_mfma_f32_16x16x32_bf16 v[24:27], v[64:67], v[0:3], v[60:63]
	v_mfma_f32_16x16x32_bf16 v[60:63], v[64:67], v[16:19], v[134:137]
	v_mfma_f32_16x16x32_bf16 v[134:137], v[76:79], v[0:3], v[170:173]
	v_mfma_f32_16x16x32_bf16 v[170:173], v[76:79], v[16:19], v[224:227]
	v_mfma_f32_16x16x32_bf16 v[44:47], v[196:199], v[0:3], v[44:47]
	v_mfma_f32_16x16x32_bf16 v[208:211], v[196:199], v[16:19], v[40:43]
	v_mfma_f32_16x16x32_bf16 v[0:3], v[204:207], v[0:3], v[36:39]
	v_mfma_f32_16x16x32_bf16 v[36:39], v[204:207], v[16:19], v[32:35]
	v_mfma_f32_16x16x32_bf16 v[72:75], v[178:181], v[8:11], v[24:27]
	v_mfma_f32_16x16x32_bf16 v[60:63], v[178:181], v[192:195], v[60:63]
	v_mfma_f32_16x16x32_bf16 v[40:43], v[182:185], v[8:11], v[134:137]
	v_mfma_f32_16x16x32_bf16 v[32:35], v[182:185], v[192:195], v[170:173]
	v_mfma_f32_16x16x32_bf16 v[24:27], v[200:203], v[8:11], v[44:47]
	v_mfma_f32_16x16x32_bf16 v[16:19], v[200:203], v[192:195], v[208:211]
	v_mfma_f32_16x16x32_bf16 v[8:11], v[150:153], v[8:11], v[0:3]
	v_mfma_f32_16x16x32_bf16 v[0:3], v[150:153], v[192:195], v[36:39]
	v_mfma_f32_16x16x32_bf16 v[28:31], v[64:67], v[220:223], v[28:31]
	v_mfma_f32_16x16x32_bf16 v[36:39], v[64:67], v[232:235], v[138:141]
	v_mfma_f32_16x16x32_bf16 v[20:23], v[76:79], v[220:223], v[20:23]
	v_mfma_f32_16x16x32_bf16 v[134:137], v[76:79], v[232:235], v[174:177]
	v_mfma_f32_16x16x32_bf16 v[12:15], v[196:199], v[220:223], v[12:15]
	v_mfma_f32_16x16x32_bf16 v[138:141], v[196:199], v[232:235], v[188:191]
	v_mfma_f32_16x16x32_bf16 v[4:7], v[204:207], v[220:223], v[4:7]
	v_mfma_f32_16x16x32_bf16 v[158:161], v[204:207], v[232:235], v[158:161]
	v_mfma_f32_16x16x32_bf16 v[76:79], v[178:181], v[228:231], v[28:31]
	v_mfma_f32_16x16x32_bf16 v[64:67], v[178:181], v[154:157], v[36:39]
	v_mfma_f32_16x16x32_bf16 v[44:47], v[182:185], v[228:231], v[20:23]
	v_mfma_f32_16x16x32_bf16 v[36:39], v[182:185], v[154:157], v[134:137]
	v_mfma_f32_16x16x32_bf16 v[28:31], v[200:203], v[228:231], v[12:15]
	v_mfma_f32_16x16x32_bf16 v[20:23], v[200:203], v[154:157], v[138:141]
	v_mfma_f32_16x16x32_bf16 v[12:15], v[150:153], v[228:231], v[4:7]
	v_mfma_f32_16x16x32_bf16 v[4:7], v[150:153], v[154:157], v[158:161]
	v_cmp_gt_u32_e32 vcc, s64, v130
	s_barrier
	s_and_saveexec_b64 s[48:49], vcc
	s_cbranch_execz .LBB0_343
	s_barrier

; #define STAGE(P, BASE, LD, br, kt) do { const char* _g = (const char*)((BASE) + (size_t)(br) * (LD) + (size_t)(kt) * 64); \
;     for (int _i = 0; _i < 2; ++_i) { int _b = tidx * 16 + _i * 8192; int _r, _c; stage_rc(_b, _r, _c); \
;       __builtin_amdgcn_global_load_lds((const unsigned*)(_g + (unsigned)((_r * (LD) + _c) * 2)), (unsigned*)((char*)(P) + _b), 16, 0, 0); } } while (0)
; #define LDA(dst, b, h) for (int m = 0; m < 4; ++m) for (int k = 0; k < 2; ++k) \
;     dst[m][k] = *reinterpret_cast<const bf16x8*>((char*)SA(b, h) + lds_byte(wr * 64 + m * 16 + fr, k * 32 + fq * 8))
; #define LDB(dst, b, h) for (int n = 0; n < 2; ++n) for (int k = 0; k < 2; ++k) \
;     dst[n][k] = *reinterpret_cast<const bf16x8*>((char*)SB(b, h) + lds_byte(wc * 32 + n * 16 + fr, k * 32 + fq * 8))
; #define MMA(ai, bj, At_, Bt_) do { __builtin_amdgcn_s_setprio(1); \
;     for (int k = 0; k < 2; ++k) for (int m = 0; m < 4; ++m) for (int n = 0; n < 2; ++n) \
;       acc[ai][bj][m][n] = __builtin_amdgcn_mfma_f32_16x16x32_bf16(At_[m][k], Bt_[n][k], acc[ai][bj][m][n], 0, 0, 0); \
;     __builtin_amdgcn_s_setprio(0); } while (0)
; #define WAIT_V(n) asm volatile("s_waitcnt vmcnt(" #n ")" ::: "memory")
; #define WAIT_L(n) asm volatile("s_waitcnt lgkmcnt(" #n ")" ::: "memory")
; #define BAR __builtin_amdgcn_s_barrier()
; #define SCHED __builtin_amdgcn_sched_barrier(0)
; template <int EPI, int lda, int ldb, int N, int K>
; __device__ __forceinline__ void gemm_phase(const u16* __restrict__ A, const u16* __restrict__ Bt, const GemmEpi ep, int wv) {
;     ...
;     for (int t = 0; t < nt - 2; t += 2) {
;       LDB(B0, 0, 0); SCHED; LDA(At, 0, 0); STAGE(SA(1, 1), Ab, lda, brow + HALF, t + 1);
;       WAIT_L(8); BAR; WAIT_L(0); MMA(0, 0, At, B0); BAR; SCHED;
;       LDB(B1, 0, 1); STAGE(SB(0, 0), Bt, ldb, bcol, t + 2);
;       BAR; WAIT_L(0); MMA(0, 1, At, B1); BAR;
;       LDA(At, 0, 1); STAGE(SA(0, 0), Ab, lda, brow, t + 2);
;       BAR; WAIT_L(0); MMA(1, 0, At, B0); BAR; SCHED;
;       STAGE(SB(0, 1), Bt, ldb, bcol + HALF, t + 2);
;       WAIT_V(6); BAR; MMA(1, 1, At, B1); BAR;
;       LDB(B0, 1, 0); SCHED; LDA(At, 1, 0); STAGE(SA(0, 1), Ab, lda, brow + HALF, t + 2);
;       WAIT_L(8); BAR; WAIT_L(0); MMA(0, 0, At, B0); BAR; SCHED;
.LBB0_654:
	ds_read_b128 v[164:167], v160
	ds_read_b128 v[170:173], v160 offset:1024
	ds_read_b128 v[174:177], v160 offset:2048
	ds_read_b128 v[178:181], v160 offset:3072
	v_add_u32_e32 v168, 0xc000, v143
	v_lshl_add_u64 v[234:235], v[138:139], 0, s[52:53]
	v_readfirstlane_b32 s55, v168
	v_add_u32_e32 v169, 0xe000, v143
	v_lshl_add_u64 v[162:163], v[234:235], 0, s[20:21]
	s_mov_b32 m0, s55
	v_lshl_add_u64 v[236:237], v[140:141], 0, s[52:53]
	v_readfirstlane_b32 s55, v169
	global_load_lds_dwordx4 v[162:163], off
	v_lshl_add_u64 v[162:163], v[236:237], 0, s[20:21]
	s_mov_b32 m0, s55
	s_nop 0
	global_load_lds_dwordx4 v[162:163], off
	ds_read_b128 v[182:185], v151
	ds_read_b128 v[186:189], v151 offset:1024
	ds_read_b128 v[190:193], v150
	ds_read_b128 v[194:197], v150 offset:1024
	ds_read_b128 v[198:201], v149
	ds_read_b128 v[202:205], v149 offset:1024
	ds_read_b128 v[206:209], v148
	ds_read_b128 v[210:213], v148 offset:1024
	s_waitcnt lgkmcnt(8)
	s_barrier
	s_waitcnt lgkmcnt(0)
	s_waitcnt lgkmcnt(0)
	v_mfma_f32_16x16x32_bf16 v[124:127], v[164:167], v[182:185], v[124:127]
	v_mfma_f32_16x16x32_bf16 v[120:123], v[174:177], v[182:185], v[120:123]
	v_mfma_f32_16x16x32_bf16 v[116:119], v[164:167], v[190:193], v[116:119]
	v_mfma_f32_16x16x32_bf16 v[112:115], v[174:177], v[190:193], v[112:115]
	v_mfma_f32_16x16x32_bf16 v[108:111], v[164:167], v[198:201], v[108:111]
	v_mfma_f32_16x16x32_bf16 v[104:107], v[174:177], v[198:201], v[104:107]
	v_mfma_f32_16x16x32_bf16 v[100:103], v[164:167], v[206:209], v[100:103]
	v_mfma_f32_16x16x32_bf16 v[96:99], v[174:177], v[206:209], v[96:99]
	v_mfma_f32_16x16x32_bf16 v[124:127], v[170:173], v[186:189], v[124:127]
	v_mfma_f32_16x16x32_bf16 v[120:123], v[178:181], v[186:189], v[120:123]
	v_mfma_f32_16x16x32_bf16 v[116:119], v[170:173], v[194:197], v[116:119]
	v_mfma_f32_16x16x32_bf16 v[112:115], v[178:181], v[194:197], v[112:115]
	v_mfma_f32_16x16x32_bf16 v[108:111], v[170:173], v[202:205], v[108:111]
	v_mfma_f32_16x16x32_bf16 v[104:107], v[178:181], v[202:205], v[104:107]
	v_mfma_f32_16x16x32_bf16 v[100:103], v[170:173], v[210:213], v[100:103]
	v_mfma_f32_16x16x32_bf16 v[96:99], v[178:181], v[210:213], v[96:99]
	s_barrier
	v_add_u32_e32 v161, s65, v153
	v_lshl_add_u64 v[238:239], v[134:135], 0, s[52:53]
	v_readfirstlane_b32 s55, v161
	v_lshl_add_u64 v[162:163], v[238:239], 0, s[22:23]
	s_mov_b32 m0, s55
	global_load_lds_dwordx4 v[162:163], off
	v_add_u32_e32 v162, 0x2000, v161
	v_lshl_add_u64 v[240:241], v[136:137], 0, s[52:53]
	v_readfirstlane_b32 s55, v162
	v_lshl_add_u64 v[230:231], v[240:241], 0, s[22:23]
	s_mov_b32 m0, s55
	s_nop 0
	global_load_lds_dwordx4 v[230:231], off
	ds_read_b128 v[214:217], v159
	ds_read_b128 v[218:221], v159 offset:1024
	ds_read_b128 v[222:225], v159 offset:2048
	ds_read_b128 v[226:229], v159 offset:3072
	s_barrier
	s_waitcnt lgkmcnt(0)
	s_waitcnt lgkmcnt(0)
	v_mfma_f32_16x16x32_bf16 v[92:95], v[214:217], v[182:185], v[92:95]
	v_mfma_f32_16x16x32_bf16 v[88:91], v[222:225], v[182:185], v[88:91]
	v_mfma_f32_16x16x32_bf16 v[84:87], v[214:217], v[190:193], v[84:87]
	v_mfma_f32_16x16x32_bf16 v[80:83], v[222:225], v[190:193], v[80:83]
	v_mfma_f32_16x16x32_bf16 v[76:79], v[214:217], v[198:201], v[76:79]
	v_mfma_f32_16x16x32_bf16 v[72:75], v[222:225], v[198:201], v[72:75]
	v_mfma_f32_16x16x32_bf16 v[68:71], v[214:217], v[206:209], v[68:71]
	v_mfma_f32_16x16x32_bf16 v[64:67], v[222:225], v[206:209], v[64:67]
	v_mfma_f32_16x16x32_bf16 v[92:95], v[218:221], v[186:189], v[92:95]
	v_mfma_f32_16x16x32_bf16 v[88:91], v[226:229], v[186:189], v[88:91]
	v_mfma_f32_16x16x32_bf16 v[84:87], v[218:221], v[194:197], v[84:87]
	v_mfma_f32_16x16x32_bf16 v[80:83], v[226:229], v[194:197], v[80:83]
	v_mfma_f32_16x16x32_bf16 v[76:79], v[218:221], v[202:205], v[76:79]
	v_mfma_f32_16x16x32_bf16 v[72:75], v[226:229], v[202:205], v[72:75]
	v_mfma_f32_16x16x32_bf16 v[68:71], v[218:221], v[210:213], v[68:71]
	v_mfma_f32_16x16x32_bf16 v[64:67], v[226:229], v[210:213], v[64:67]
	v_readfirstlane_b32 s55, v143
	v_add_u32_e32 v163, 0x2000, v143
	v_lshl_add_u64 v[230:231], v[234:235], 0, s[24:25]
	s_mov_b32 m0, s55
	v_readfirstlane_b32 s55, v163
	s_barrier
	global_load_lds_dwordx4 v[230:231], off
	v_lshl_add_u64 v[230:231], v[236:237], 0, s[24:25]
	s_mov_b32 m0, s55
	s_nop 0
	global_load_lds_dwordx4 v[230:231], off
	ds_read_b128 v[182:185], v151 offset:16384
	ds_read_b128 v[186:189], v151 offset:17408
	ds_read_b128 v[190:193], v150 offset:16384
	ds_read_b128 v[194:197], v150 offset:17408
	ds_read_b128 v[198:201], v149 offset:16384
	ds_read_b128 v[202:205], v149 offset:17408
	ds_read_b128 v[206:209], v148 offset:16384
	ds_read_b128 v[210:213], v148 offset:17408
	s_barrier
	s_waitcnt lgkmcnt(0)
	s_waitcnt lgkmcnt(0)
	v_mfma_f32_16x16x32_bf16 v[60:63], v[164:167], v[182:185], v[60:63]
	v_mfma_f32_16x16x32_bf16 v[56:59], v[174:177], v[182:185], v[56:59]
	v_mfma_f32_16x16x32_bf16 v[52:55], v[164:167], v[190:193], v[52:55]
	v_mfma_f32_16x16x32_bf16 v[48:51], v[174:177], v[190:193], v[48:51]
	v_mfma_f32_16x16x32_bf16 v[44:47], v[164:167], v[198:201], v[44:47]
	v_mfma_f32_16x16x32_bf16 v[40:43], v[174:177], v[198:201], v[40:43]
	v_mfma_f32_16x16x32_bf16 v[36:39], v[164:167], v[206:209], v[36:39]
	v_mfma_f32_16x16x32_bf16 v[32:35], v[174:177], v[206:209], v[32:35]
	v_mfma_f32_16x16x32_bf16 v[60:63], v[170:173], v[186:189], v[60:63]
	v_mfma_f32_16x16x32_bf16 v[56:59], v[178:181], v[186:189], v[56:59]
	v_mfma_f32_16x16x32_bf16 v[52:55], v[170:173], v[194:197], v[52:55]
	v_mfma_f32_16x16x32_bf16 v[48:51], v[178:181], v[194:197], v[48:51]
	v_mfma_f32_16x16x32_bf16 v[44:47], v[170:173], v[202:205], v[44:47]
	v_mfma_f32_16x16x32_bf16 v[40:43], v[178:181], v[202:205], v[40:43]
	v_mfma_f32_16x16x32_bf16 v[36:39], v[170:173], v[210:213], v[36:39]
	v_mfma_f32_16x16x32_bf16 v[32:35], v[178:181], v[210:213], v[32:35]
	s_barrier
; #define STAGE(P, BASE, LD, br, kt) do { const char* _g = (const char*)((BASE) + (size_t)(br) * (LD) + (size_t)(kt) * 64); \
;     for (int _i = 0; _i < 2; ++_i) { int _b = tidx * 16 + _i * 8192; int _r, _c; stage_rc(_b, _r, _c); \
;       __builtin_amdgcn_global_load_lds((const unsigned*)(_g + (unsigned)((_r * (LD) + _c) * 2)), (unsigned*)((char*)(P) + _b), 16, 0, 0); } } while (0)
; #define LDA(dst, b, h) for (int m = 0; m < 4; ++m) for (int k = 0; k < 2; ++k) \
;     dst[m][k] = *reinterpret_cast<const bf16x8*>((char*)SA(b, h) + lds_byte(wr * 64 + m * 16 + fr, k * 32 + fq * 8))
; #define LDB(dst, b, h) for (int n = 0; n < 2; ++n) for (int k = 0; k < 2; ++k) \
;     dst[n][k] = *reinterpret_cast<const bf16x8*>((char*)SB(b, h) + lds_byte(wc * 32 + n * 16 + fr, k * 32 + fq * 8))
; #define MMA(ai, bj, At_, Bt_) do { __builtin_amdgcn_s_setprio(1); \
;     for (int k = 0; k < 2; ++k) for (int m = 0; m < 4; ++m) for (int n = 0; n < 2; ++n) \
;       acc[ai][bj][m][n] = __builtin_amdgcn_mfma_f32_16x16x32_bf16(At_[m][k], Bt_[n][k], acc[ai][bj][m][n], 0, 0, 0); \
;     __builtin_amdgcn_s_setprio(0); } while (0)
; #define WAIT_V(n) asm volatile("s_waitcnt vmcnt(" #n ")" ::: "memory")
; #define WAIT_L(n) asm volatile("s_waitcnt lgkmcnt(" #n ")" ::: "memory")
; #define BAR __builtin_amdgcn_s_barrier()
; #define SCHED __builtin_amdgcn_sched_barrier(0)
; template <int EPI, int lda, int ldb, int N, int K>
; __device__ __forceinline__ void gemm_phase(const u16* __restrict__ A, const u16* __restrict__ Bt, const GemmEpi ep, int wv) {
;     ...
;       STAGE(SB(0, 1), Bt, ldb, bcol + HALF, t + 2);
;       WAIT_V(6); BAR; MMA(1, 1, At, B1); BAR;
;       LDB(B0, 1, 0); SCHED; LDA(At, 1, 0); STAGE(SA(0, 1), Ab, lda, brow + HALF, t + 2);
;       WAIT_L(8); BAR; WAIT_L(0); MMA(0, 0, At, B0); BAR; SCHED;
;       LDB(B1, 1, 1); STAGE(SB(1, 0), Bt, ldb, bcol, t + 3);
;       BAR; WAIT_L(0); MMA(0, 1, At, B1); BAR;
;       LDA(At, 1, 1); STAGE(SA(1, 0), Ab, lda, brow, t + 3);
	v_add_u32_e32 v164, s66, v153
	v_add_u32_e32 v165, 0x2000, v164
	v_readfirstlane_b32 s55, v164
	v_lshl_add_u64 v[166:167], v[238:239], 0, s[26:27]
	s_mov_b32 m0, s55
	v_readfirstlane_b32 s55, v165
	global_load_lds_dwordx4 v[166:167], off
	v_lshl_add_u64 v[166:167], v[240:241], 0, s[26:27]
	s_mov_b32 m0, s55
	s_nop 0
	global_load_lds_dwordx4 v[166:167], off
	s_waitcnt vmcnt(6)
	s_barrier
	v_mfma_f32_16x16x32_bf16 v[28:31], v[214:217], v[182:185], v[28:31]
	v_mfma_f32_16x16x32_bf16 v[24:27], v[222:225], v[182:185], v[24:27]
	v_mfma_f32_16x16x32_bf16 v[20:23], v[214:217], v[190:193], v[20:23]
	v_mfma_f32_16x16x32_bf16 v[16:19], v[222:225], v[190:193], v[16:19]
	v_mfma_f32_16x16x32_bf16 v[12:15], v[214:217], v[198:201], v[12:15]
	v_mfma_f32_16x16x32_bf16 v[8:11], v[222:225], v[198:201], v[8:11]
	v_mfma_f32_16x16x32_bf16 v[4:7], v[214:217], v[206:209], v[4:7]
	v_mfma_f32_16x16x32_bf16 v[0:3], v[222:225], v[206:209], v[0:3]
	v_mfma_f32_16x16x32_bf16 v[28:31], v[218:221], v[186:189], v[28:31]
	v_mfma_f32_16x16x32_bf16 v[24:27], v[226:229], v[186:189], v[24:27]
	v_mfma_f32_16x16x32_bf16 v[20:23], v[218:221], v[194:197], v[20:23]
	v_mfma_f32_16x16x32_bf16 v[16:19], v[226:229], v[194:197], v[16:19]
	v_mfma_f32_16x16x32_bf16 v[12:15], v[218:221], v[202:205], v[12:15]
	v_mfma_f32_16x16x32_bf16 v[8:11], v[226:229], v[202:205], v[8:11]
	v_mfma_f32_16x16x32_bf16 v[4:7], v[218:221], v[210:213], v[4:7]
	v_mfma_f32_16x16x32_bf16 v[0:3], v[226:229], v[210:213], v[0:3]
	s_barrier
	ds_read_b128 v[170:173], v154
	ds_read_b128 v[174:177], v154 offset:1024
	ds_read_b128 v[178:181], v154 offset:2048
	ds_read_b128 v[182:185], v154 offset:3072
	v_add_u32_e32 v166, 0x4000, v143
	v_add_u32_e32 v167, 0x6000, v143
	v_readfirstlane_b32 s55, v166
	v_lshl_add_u64 v[218:219], v[234:235], 0, s[42:43]
	s_mov_b32 m0, s55
	v_readfirstlane_b32 s55, v167
	global_load_lds_dwordx4 v[218:219], off
	v_lshl_add_u64 v[218:219], v[236:237], 0, s[42:43]
	s_mov_b32 m0, s55
	s_nop 0
	global_load_lds_dwordx4 v[218:219], off
	ds_read_b128 v[186:189], v151 offset:32768
	ds_read_b128 v[190:193], v151 offset:33792
	ds_read_b128 v[194:197], v150 offset:32768
	ds_read_b128 v[198:201], v150 offset:33792
	ds_read_b128 v[202:205], v149 offset:32768
	ds_read_b128 v[206:209], v149 offset:33792
	ds_read_b128 v[210:213], v148 offset:32768
	ds_read_b128 v[214:217], v148 offset:33792
	s_waitcnt lgkmcnt(8)
	s_barrier
	s_waitcnt lgkmcnt(0)
	s_waitcnt lgkmcnt(0)
	v_mfma_f32_16x16x32_bf16 v[124:127], v[170:173], v[186:189], v[124:127]
	v_mfma_f32_16x16x32_bf16 v[120:123], v[178:181], v[186:189], v[120:123]
	v_mfma_f32_16x16x32_bf16 v[116:119], v[170:173], v[194:197], v[116:119]
	v_mfma_f32_16x16x32_bf16 v[112:115], v[178:181], v[194:197], v[112:115]
	v_mfma_f32_16x16x32_bf16 v[108:111], v[170:173], v[202:205], v[108:111]
	v_mfma_f32_16x16x32_bf16 v[104:107], v[178:181], v[202:205], v[104:107]
	v_mfma_f32_16x16x32_bf16 v[100:103], v[170:173], v[210:213], v[100:103]
	v_mfma_f32_16x16x32_bf16 v[96:99], v[178:181], v[210:213], v[96:99]
	v_mfma_f32_16x16x32_bf16 v[124:127], v[174:177], v[190:193], v[124:127]
	v_mfma_f32_16x16x32_bf16 v[120:123], v[182:185], v[190:193], v[120:123]
	v_mfma_f32_16x16x32_bf16 v[116:119], v[174:177], v[198:201], v[116:119]
	v_mfma_f32_16x16x32_bf16 v[112:115], v[182:185], v[198:201], v[112:115]
	v_mfma_f32_16x16x32_bf16 v[108:111], v[174:177], v[206:209], v[108:111]
	v_mfma_f32_16x16x32_bf16 v[104:107], v[182:185], v[206:209], v[104:107]
	v_mfma_f32_16x16x32_bf16 v[100:103], v[174:177], v[214:217], v[100:103]
	v_mfma_f32_16x16x32_bf16 v[96:99], v[182:185], v[214:217], v[96:99]
	s_barrier
	v_readfirstlane_b32 s55, v155
	v_add_u32_e32 v244, 0x2000, v155
	v_lshl_add_u64 v[242:243], v[238:239], 0, s[44:45]
	s_mov_b32 m0, s55
	v_readfirstlane_b32 s55, v244
	global_load_lds_dwordx4 v[242:243], off
	v_lshl_add_u64 v[242:243], v[240:241], 0, s[44:45]
	s_mov_b32 m0, s55
	s_nop 0
	global_load_lds_dwordx4 v[242:243], off
	ds_read_b128 v[218:221], v152
	ds_read_b128 v[222:225], v152 offset:1024
	ds_read_b128 v[226:229], v152 offset:2048
	ds_read_b128 v[230:233], v152 offset:3072
	s_barrier
	s_waitcnt lgkmcnt(0)
	s_waitcnt lgkmcnt(0)
	v_mfma_f32_16x16x32_bf16 v[92:95], v[218:221], v[186:189], v[92:95]
	v_mfma_f32_16x16x32_bf16 v[88:91], v[226:229], v[186:189], v[88:91]
	v_mfma_f32_16x16x32_bf16 v[84:87], v[218:221], v[194:197], v[84:87]
	v_mfma_f32_16x16x32_bf16 v[80:83], v[226:229], v[194:197], v[80:83]
	v_mfma_f32_16x16x32_bf16 v[76:79], v[218:221], v[202:205], v[76:79]
	v_mfma_f32_16x16x32_bf16 v[72:75], v[226:229], v[202:205], v[72:75]
	v_mfma_f32_16x16x32_bf16 v[68:71], v[218:221], v[210:213], v[68:71]
	v_mfma_f32_16x16x32_bf16 v[64:67], v[226:229], v[210:213], v[64:67]
	v_mfma_f32_16x16x32_bf16 v[92:95], v[222:225], v[190:193], v[92:95]
	v_mfma_f32_16x16x32_bf16 v[88:91], v[230:233], v[190:193], v[88:91]
	v_mfma_f32_16x16x32_bf16 v[84:87], v[222:225], v[198:201], v[84:87]
	v_mfma_f32_16x16x32_bf16 v[80:83], v[230:233], v[198:201], v[80:83]
	v_mfma_f32_16x16x32_bf16 v[76:79], v[222:225], v[206:209], v[76:79]
	v_mfma_f32_16x16x32_bf16 v[72:75], v[230:233], v[206:209], v[72:75]
	v_mfma_f32_16x16x32_bf16 v[68:71], v[222:225], v[214:217], v[68:71]
	v_mfma_f32_16x16x32_bf16 v[64:67], v[230:233], v[214:217], v[64:67]
	v_readfirstlane_b32 s55, v156
	v_lshl_add_u64 v[234:235], v[234:235], 0, s[46:47]
	s_mov_b32 m0, s55
	v_readfirstlane_b32 s55, v157
	s_barrier
; #define STAGE(P, BASE, LD, br, kt) do { const char* _g = (const char*)((BASE) + (size_t)(br) * (LD) + (size_t)(kt) * 64); \
;     for (int _i = 0; _i < 2; ++_i) { int _b = tidx * 16 + _i * 8192; int _r, _c; stage_rc(_b, _r, _c); \
;       __builtin_amdgcn_global_load_lds((const unsigned*)(_g + (unsigned)((_r * (LD) + _c) * 2)), (unsigned*)((char*)(P) + _b), 16, 0, 0); } } while (0)
; #define LDA(dst, b, h) for (int m = 0; m < 4; ++m) for (int k = 0; k < 2; ++k) \
;     dst[m][k] = *reinterpret_cast<const bf16x8*>((char*)SA(b, h) + lds_byte(wr * 64 + m * 16 + fr, k * 32 + fq * 8))
; #define LDB(dst, b, h) for (int n = 0; n < 2; ++n) for (int k = 0; k < 2; ++k) \
;     dst[n][k] = *reinterpret_cast<const bf16x8*>((char*)SB(b, h) + lds_byte(wc * 32 + n * 16 + fr, k * 32 + fq * 8))
; #define MMA(ai, bj, At_, Bt_) do { __builtin_amdgcn_s_setprio(1); \
;     for (int k = 0; k < 2; ++k) for (int m = 0; m < 4; ++m) for (int n = 0; n < 2; ++n) \
;       acc[ai][bj][m][n] = __builtin_amdgcn_mfma_f32_16x16x32_bf16(At_[m][k], Bt_[n][k], acc[ai][bj][m][n], 0, 0, 0); \
;     __builtin_amdgcn_s_setprio(0); } while (0)
; #define WAIT_V(n) asm volatile("s_waitcnt vmcnt(" #n ")" ::: "memory")
; #define WAIT_L(n) asm volatile("s_waitcnt lgkmcnt(" #n ")" ::: "memory")
; #define BAR __builtin_amdgcn_s_barrier()
; #define SCHED __builtin_amdgcn_sched_barrier(0)
; template <int EPI, int lda, int ldb, int N, int K>
; __device__ __forceinline__ void gemm_phase(const u16* __restrict__ A, const u16* __restrict__ Bt, const GemmEpi ep, int wv) {
;     ...
;       LDA(At, 1, 1); STAGE(SA(1, 0), Ab, lda, brow, t + 3);
;       BAR; WAIT_L(0); MMA(1, 0, At, B0); BAR; SCHED;
;       STAGE(SB(1, 1), Bt, ldb, bcol + HALF, t + 3);
;       WAIT_V(6); BAR; MMA(1, 1, At, B1); BAR;
;     }
;     { LDB(B0, 0, 0); LDA(At, 0, 0); STAGE(SA(1, 1), Ab, lda, brow + HALF, nt - 1);
;       BAR; WAIT_L(0); MMA(0, 0, At, B0); BAR;
;       LDB(B1, 0, 1); BAR; WAIT_L(0); MMA(0, 1, At, B1); BAR;
	global_load_lds_dwordx4 v[234:235], off
	v_lshl_add_u64 v[234:235], v[236:237], 0, s[46:47]
	s_mov_b32 m0, s55
	s_nop 0
	global_load_lds_dwordx4 v[234:235], off
	ds_read_b128 v[186:189], v151 offset:49152
	ds_read_b128 v[190:193], v151 offset:50176
	ds_read_b128 v[194:197], v150 offset:49152
	ds_read_b128 v[198:201], v150 offset:50176
	ds_read_b128 v[202:205], v149 offset:49152
	ds_read_b128 v[206:209], v149 offset:50176
	ds_read_b128 v[210:213], v148 offset:49152
	ds_read_b128 v[214:217], v148 offset:50176
	s_barrier
	s_waitcnt lgkmcnt(0)
	s_waitcnt lgkmcnt(0)
	v_mfma_f32_16x16x32_bf16 v[60:63], v[170:173], v[186:189], v[60:63]
	v_mfma_f32_16x16x32_bf16 v[56:59], v[178:181], v[186:189], v[56:59]
	v_mfma_f32_16x16x32_bf16 v[52:55], v[170:173], v[194:197], v[52:55]
	v_mfma_f32_16x16x32_bf16 v[48:51], v[178:181], v[194:197], v[48:51]
	v_mfma_f32_16x16x32_bf16 v[44:47], v[170:173], v[202:205], v[44:47]
	v_mfma_f32_16x16x32_bf16 v[40:43], v[178:181], v[202:205], v[40:43]
	v_mfma_f32_16x16x32_bf16 v[36:39], v[170:173], v[210:213], v[36:39]
	v_mfma_f32_16x16x32_bf16 v[32:35], v[178:181], v[210:213], v[32:35]
	v_mfma_f32_16x16x32_bf16 v[60:63], v[174:177], v[190:193], v[60:63]
	v_mfma_f32_16x16x32_bf16 v[56:59], v[182:185], v[190:193], v[56:59]
	v_mfma_f32_16x16x32_bf16 v[52:55], v[174:177], v[198:201], v[52:55]
	v_mfma_f32_16x16x32_bf16 v[48:51], v[182:185], v[198:201], v[48:51]
	v_mfma_f32_16x16x32_bf16 v[44:47], v[174:177], v[206:209], v[44:47]
	v_mfma_f32_16x16x32_bf16 v[40:43], v[182:185], v[206:209], v[40:43]
	v_mfma_f32_16x16x32_bf16 v[36:39], v[174:177], v[214:217], v[36:39]
	v_mfma_f32_16x16x32_bf16 v[32:35], v[182:185], v[214:217], v[32:35]
	s_barrier
	v_readfirstlane_b32 s55, v158
	v_add_u32_e32 v172, 0x2000, v158
	v_lshl_add_u64 v[170:171], v[238:239], 0, s[48:49]
	s_mov_b32 m0, s55
	v_readfirstlane_b32 s55, v172
	global_load_lds_dwordx4 v[170:171], off
	v_lshl_add_u64 v[170:171], v[240:241], 0, s[48:49]
	s_mov_b32 m0, s55
	s_nop 0
	global_load_lds_dwordx4 v[170:171], off
	s_waitcnt vmcnt(6)
	s_barrier
	v_mfma_f32_16x16x32_bf16 v[28:31], v[218:221], v[186:189], v[28:31]
	v_mfma_f32_16x16x32_bf16 v[24:27], v[226:229], v[186:189], v[24:27]
	v_mfma_f32_16x16x32_bf16 v[20:23], v[218:221], v[194:197], v[20:23]
	v_mfma_f32_16x16x32_bf16 v[16:19], v[226:229], v[194:197], v[16:19]
	v_mfma_f32_16x16x32_bf16 v[12:15], v[218:221], v[202:205], v[12:15]
	v_mfma_f32_16x16x32_bf16 v[8:11], v[226:229], v[202:205], v[8:11]
	v_mfma_f32_16x16x32_bf16 v[4:7], v[218:221], v[210:213], v[4:7]
	v_mfma_f32_16x16x32_bf16 v[0:3], v[226:229], v[210:213], v[0:3]
	v_mfma_f32_16x16x32_bf16 v[28:31], v[222:225], v[190:193], v[28:31]
	v_mfma_f32_16x16x32_bf16 v[24:27], v[230:233], v[190:193], v[24:27]
	v_mfma_f32_16x16x32_bf16 v[20:23], v[222:225], v[198:201], v[20:23]
	v_mfma_f32_16x16x32_bf16 v[16:19], v[230:233], v[198:201], v[16:19]
	v_mfma_f32_16x16x32_bf16 v[12:15], v[222:225], v[206:209], v[12:15]
	v_mfma_f32_16x16x32_bf16 v[8:11], v[230:233], v[206:209], v[8:11]
	v_mfma_f32_16x16x32_bf16 v[4:7], v[222:225], v[214:217], v[4:7]
	v_mfma_f32_16x16x32_bf16 v[0:3], v[230:233], v[214:217], v[0:3]
	s_add_i32 s54, s54, 2
	s_add_u32 s52, s52, 0x100
	s_addc_u32 s53, s53, 0
	s_cmp_gt_u32 s54, 27
	s_barrier
	s_cbranch_scc0 .LBB0_654
	s_lshl_b64 s[52:53], s[16:17], 12
	s_add_u32 s52, s14, s52
	s_addc_u32 s53, s15, s53
	s_add_u32 s52, s52, 0x80000
	s_addc_u32 s53, s53, 0
	v_lshl_add_u64 v[156:157], s[52:53], 0, v[128:129]
	v_readfirstlane_b32 s54, v168
	v_lshl_add_u64 v[156:157], v[156:157], 0, s[50:51]
	s_mov_b32 m0, s54
	ds_read_b128 v[134:137], v160
	ds_read_b128 v[138:141], v160 offset:1024
	ds_read_b128 v[170:173], v160 offset:2048
	ds_read_b128 v[174:177], v160 offset:3072
	ds_read_b128 v[178:181], v151
	ds_read_b128 v[182:185], v151 offset:1024
	ds_read_b128 v[186:189], v150
	ds_read_b128 v[190:193], v150 offset:1024
	ds_read_b128 v[194:197], v149
	ds_read_b128 v[198:201], v149 offset:1024
	ds_read_b128 v[202:205], v148
	ds_read_b128 v[206:209], v148 offset:1024
	global_load_lds_dwordx4 v[156:157], off
	v_lshl_add_u64 v[156:157], s[52:53], 0, v[132:133]
	v_readfirstlane_b32 s52, v169
	v_lshl_add_u64 v[156:157], v[156:157], 0, s[50:51]
	s_mov_b32 m0, s52
	s_nop 0
	global_load_lds_dwordx4 v[156:157], off
	s_barrier
	s_waitcnt lgkmcnt(0)
	s_waitcnt lgkmcnt(0)
	v_mfma_f32_16x16x32_bf16 v[124:127], v[134:137], v[178:181], v[124:127]
	v_mfma_f32_16x16x32_bf16 v[120:123], v[170:173], v[178:181], v[120:123]
	v_mfma_f32_16x16x32_bf16 v[116:119], v[134:137], v[186:189], v[116:119]
	v_mfma_f32_16x16x32_bf16 v[112:115], v[170:173], v[186:189], v[112:115]
	v_mfma_f32_16x16x32_bf16 v[108:111], v[134:137], v[194:197], v[108:111]
	v_mfma_f32_16x16x32_bf16 v[104:107], v[170:173], v[194:197], v[104:107]
	v_mfma_f32_16x16x32_bf16 v[100:103], v[134:137], v[202:205], v[100:103]
	v_mfma_f32_16x16x32_bf16 v[96:99], v[170:173], v[202:205], v[96:99]
	v_mfma_f32_16x16x32_bf16 v[124:127], v[138:141], v[182:185], v[124:127]
	v_mfma_f32_16x16x32_bf16 v[120:123], v[174:177], v[182:185], v[120:123]
	v_mfma_f32_16x16x32_bf16 v[116:119], v[138:141], v[190:193], v[116:119]
	v_mfma_f32_16x16x32_bf16 v[112:115], v[174:177], v[190:193], v[112:115]
	v_mfma_f32_16x16x32_bf16 v[108:111], v[138:141], v[198:201], v[108:111]
	v_mfma_f32_16x16x32_bf16 v[104:107], v[174:177], v[198:201], v[104:107]
	v_mfma_f32_16x16x32_bf16 v[100:103], v[138:141], v[206:209], v[100:103]
	v_mfma_f32_16x16x32_bf16 v[96:99], v[174:177], v[206:209], v[96:99]
	s_barrier
	ds_read_b128 v[210:213], v159
	ds_read_b128 v[214:217], v159 offset:1024
	ds_read_b128 v[218:221], v159 offset:2048
	ds_read_b128 v[156:159], v159 offset:3072
	s_barrier
; #define LDA(dst, b, h) for (int m = 0; m < 4; ++m) for (int k = 0; k < 2; ++k) \
;     dst[m][k] = *reinterpret_cast<const bf16x8*>((char*)SA(b, h) + lds_byte(wr * 64 + m * 16 + fr, k * 32 + fq * 8))
; #define LDB(dst, b, h) for (int n = 0; n < 2; ++n) for (int k = 0; k < 2; ++k) \
;     dst[n][k] = *reinterpret_cast<const bf16x8*>((char*)SB(b, h) + lds_byte(wc * 32 + n * 16 + fr, k * 32 + fq * 8))
; #define MMA(ai, bj, At_, Bt_) do { __builtin_amdgcn_s_setprio(1); \
;     for (int k = 0; k < 2; ++k) for (int m = 0; m < 4; ++m) for (int n = 0; n < 2; ++n) \
;       acc[ai][bj][m][n] = __builtin_amdgcn_mfma_f32_16x16x32_bf16(At_[m][k], Bt_[n][k], acc[ai][bj][m][n], 0, 0, 0); \
;     __builtin_amdgcn_s_setprio(0); } while (0)
; #define WAIT_V(n) asm volatile("s_waitcnt vmcnt(" #n ")" ::: "memory")
; #define WAIT_L(n) asm volatile("s_waitcnt lgkmcnt(" #n ")" ::: "memory")
; #define BAR __builtin_amdgcn_s_barrier()
; template <int EPI, int lda, int ldb, int N, int K>
; __device__ __forceinline__ void gemm_phase(const u16* __restrict__ A, const u16* __restrict__ Bt, const GemmEpi ep, int wv) {
;     ...
;       LDB(B1, 0, 1); BAR; WAIT_L(0); MMA(0, 1, At, B1); BAR;
;       LDA(At, 0, 1); WAIT_V(4); BAR; WAIT_L(0); MMA(1, 0, At, B0); MMA(1, 1, At, B1); BAR; }
;     { LDB(B0, 1, 0); LDA(At, 1, 0); WAIT_V(2); BAR; WAIT_L(0); MMA(0, 0, At, B0); BAR;
	s_waitcnt lgkmcnt(0)
	s_waitcnt lgkmcnt(0)
	v_mfma_f32_16x16x32_bf16 v[92:95], v[210:213], v[178:181], v[92:95]
	v_mfma_f32_16x16x32_bf16 v[88:91], v[218:221], v[178:181], v[88:91]
	v_mfma_f32_16x16x32_bf16 v[76:79], v[210:213], v[194:197], v[76:79]
	v_mfma_f32_16x16x32_bf16 v[72:75], v[218:221], v[194:197], v[72:75]
	v_mfma_f32_16x16x32_bf16 v[84:87], v[210:213], v[186:189], v[84:87]
	v_mfma_f32_16x16x32_bf16 v[80:83], v[218:221], v[186:189], v[80:83]
	v_mfma_f32_16x16x32_bf16 v[68:71], v[210:213], v[202:205], v[68:71]
	v_mfma_f32_16x16x32_bf16 v[64:67], v[218:221], v[202:205], v[64:67]
	v_mfma_f32_16x16x32_bf16 v[92:95], v[214:217], v[182:185], v[92:95]
	v_mfma_f32_16x16x32_bf16 v[88:91], v[156:159], v[182:185], v[88:91]
	v_mfma_f32_16x16x32_bf16 v[76:79], v[214:217], v[198:201], v[76:79]
	v_mfma_f32_16x16x32_bf16 v[72:75], v[156:159], v[198:201], v[72:75]
	v_mfma_f32_16x16x32_bf16 v[178:181], v[214:217], v[190:193], v[84:87]
	v_mfma_f32_16x16x32_bf16 v[182:185], v[156:159], v[190:193], v[80:83]
	v_mfma_f32_16x16x32_bf16 v[186:189], v[214:217], v[206:209], v[68:71]
	v_mfma_f32_16x16x32_bf16 v[190:193], v[156:159], v[206:209], v[64:67]
	s_barrier
	s_nop 0
	ds_read_b128 v[64:67], v151 offset:16384
	ds_read_b128 v[68:71], v151 offset:17408
	ds_read_b128 v[80:83], v150 offset:16384
	ds_read_b128 v[84:87], v150 offset:17408
	ds_read_b128 v[194:197], v149 offset:16384
	ds_read_b128 v[198:201], v149 offset:17408
	ds_read_b128 v[202:205], v148 offset:16384
	ds_read_b128 v[206:209], v148 offset:17408
	s_waitcnt vmcnt(4)
	s_barrier
	s_waitcnt lgkmcnt(0)
	s_waitcnt lgkmcnt(0)
	v_mfma_f32_16x16x32_bf16 v[60:63], v[134:137], v[64:67], v[60:63]
	v_mfma_f32_16x16x32_bf16 v[56:59], v[170:173], v[64:67], v[56:59]
	v_mfma_f32_16x16x32_bf16 v[52:55], v[134:137], v[80:83], v[52:55]
	v_mfma_f32_16x16x32_bf16 v[48:51], v[170:173], v[80:83], v[48:51]
	v_mfma_f32_16x16x32_bf16 v[44:47], v[134:137], v[194:197], v[44:47]
	v_mfma_f32_16x16x32_bf16 v[40:43], v[170:173], v[194:197], v[40:43]
	v_mfma_f32_16x16x32_bf16 v[36:39], v[134:137], v[202:205], v[36:39]
	v_mfma_f32_16x16x32_bf16 v[32:35], v[170:173], v[202:205], v[32:35]
	v_mfma_f32_16x16x32_bf16 v[60:63], v[138:141], v[68:71], v[60:63]
	v_mfma_f32_16x16x32_bf16 v[56:59], v[174:177], v[68:71], v[56:59]
	v_mfma_f32_16x16x32_bf16 v[52:55], v[138:141], v[84:87], v[52:55]
	v_mfma_f32_16x16x32_bf16 v[48:51], v[174:177], v[84:87], v[48:51]
	v_mfma_f32_16x16x32_bf16 v[44:47], v[138:141], v[198:201], v[44:47]
	v_mfma_f32_16x16x32_bf16 v[40:43], v[174:177], v[198:201], v[40:43]
	v_mfma_f32_16x16x32_bf16 v[36:39], v[138:141], v[206:209], v[36:39]
	v_mfma_f32_16x16x32_bf16 v[32:35], v[174:177], v[206:209], v[32:35]
	v_mfma_f32_16x16x32_bf16 v[28:31], v[210:213], v[64:67], v[28:31]
	v_mfma_f32_16x16x32_bf16 v[20:23], v[210:213], v[80:83], v[20:23]
	v_mfma_f32_16x16x32_bf16 v[12:15], v[210:213], v[194:197], v[12:15]
	v_mfma_f32_16x16x32_bf16 v[4:7], v[210:213], v[202:205], v[4:7]
	v_mfma_f32_16x16x32_bf16 v[24:27], v[218:221], v[64:67], v[24:27]
	v_mfma_f32_16x16x32_bf16 v[16:19], v[218:221], v[80:83], v[16:19]
	v_mfma_f32_16x16x32_bf16 v[8:11], v[218:221], v[194:197], v[8:11]
	v_mfma_f32_16x16x32_bf16 v[0:3], v[218:221], v[202:205], v[0:3]
	v_mfma_f32_16x16x32_bf16 v[28:31], v[214:217], v[68:71], v[28:31]
	v_mfma_f32_16x16x32_bf16 v[20:23], v[214:217], v[84:87], v[20:23]
	v_mfma_f32_16x16x32_bf16 v[12:15], v[214:217], v[198:201], v[12:15]
	v_mfma_f32_16x16x32_bf16 v[4:7], v[214:217], v[206:209], v[4:7]
	v_mfma_f32_16x16x32_bf16 v[134:137], v[156:159], v[68:71], v[24:27]
	v_mfma_f32_16x16x32_bf16 v[138:141], v[156:159], v[84:87], v[16:19]
	v_mfma_f32_16x16x32_bf16 v[168:171], v[156:159], v[198:201], v[8:11]
	v_mfma_f32_16x16x32_bf16 v[156:159], v[156:159], v[206:209], v[0:3]
	s_barrier
	s_nop 0
	ds_read_b128 v[0:3], v154
	ds_read_b128 v[8:11], v154 offset:1024
	ds_read_b128 v[16:19], v154 offset:2048
	ds_read_b128 v[172:175], v154 offset:3072
	ds_read_b128 v[24:27], v151 offset:32768
	ds_read_b128 v[194:197], v151 offset:33792
	ds_read_b128 v[198:201], v150 offset:32768
	ds_read_b128 v[202:205], v150 offset:33792
	ds_read_b128 v[206:209], v149 offset:32768
	ds_read_b128 v[210:213], v149 offset:33792
	ds_read_b128 v[214:217], v148 offset:32768
	ds_read_b128 v[218:221], v148 offset:33792
	s_waitcnt vmcnt(2)
	s_barrier
; #define LDA(dst, b, h) for (int m = 0; m < 4; ++m) for (int k = 0; k < 2; ++k) \
;     dst[m][k] = *reinterpret_cast<const bf16x8*>((char*)SA(b, h) + lds_byte(wr * 64 + m * 16 + fr, k * 32 + fq * 8))
; #define LDB(dst, b, h) for (int n = 0; n < 2; ++n) for (int k = 0; k < 2; ++k) \
;     dst[n][k] = *reinterpret_cast<const bf16x8*>((char*)SB(b, h) + lds_byte(wc * 32 + n * 16 + fr, k * 32 + fq * 8))
; #define MMA(ai, bj, At_, Bt_) do { __builtin_amdgcn_s_setprio(1); \
;     for (int k = 0; k < 2; ++k) for (int m = 0; m < 4; ++m) for (int n = 0; n < 2; ++n) \
;       acc[ai][bj][m][n] = __builtin_amdgcn_mfma_f32_16x16x32_bf16(At_[m][k], Bt_[n][k], acc[ai][bj][m][n], 0, 0, 0); \
;     __builtin_amdgcn_s_setprio(0); } while (0)
; #define WAIT_V(n) asm volatile("s_waitcnt vmcnt(" #n ")" ::: "memory")
; #define WAIT_L(n) asm volatile("s_waitcnt lgkmcnt(" #n ")" ::: "memory")
; #define BAR __builtin_amdgcn_s_barrier()
; template <int EPI, int lda, int ldb, int N, int K>
; __device__ __forceinline__ void gemm_phase(const u16* __restrict__ A, const u16* __restrict__ Bt, const GemmEpi ep, int wv) {
;     ...
;     { LDB(B0, 1, 0); LDA(At, 1, 0); WAIT_V(2); BAR; WAIT_L(0); MMA(0, 0, At, B0); BAR;
;       LDB(B1, 1, 1); WAIT_V(0); BAR; WAIT_L(0); MMA(0, 1, At, B1); BAR;
;       LDA(At, 1, 1); BAR; WAIT_L(0); MMA(1, 0, At, B0); MMA(1, 1, At, B1); BAR; }
;     if (wr == 0) BAR;
	s_waitcnt lgkmcnt(0)
	s_waitcnt lgkmcnt(0)
	v_mfma_f32_16x16x32_bf16 v[64:67], v[0:3], v[24:27], v[124:127]
	v_mfma_f32_16x16x32_bf16 v[68:71], v[16:19], v[24:27], v[120:123]
	v_mfma_f32_16x16x32_bf16 v[80:83], v[0:3], v[198:201], v[116:119]
	v_mfma_f32_16x16x32_bf16 v[84:87], v[16:19], v[198:201], v[112:115]
	v_mfma_f32_16x16x32_bf16 v[108:111], v[0:3], v[206:209], v[108:111]
	v_mfma_f32_16x16x32_bf16 v[104:107], v[16:19], v[206:209], v[104:107]
	v_mfma_f32_16x16x32_bf16 v[120:123], v[0:3], v[214:217], v[100:103]
	v_mfma_f32_16x16x32_bf16 v[124:127], v[16:19], v[214:217], v[96:99]
	v_mfma_f32_16x16x32_bf16 v[116:119], v[8:11], v[194:197], v[64:67]
	v_mfma_f32_16x16x32_bf16 v[112:115], v[172:175], v[194:197], v[68:71]
	v_mfma_f32_16x16x32_bf16 v[100:103], v[8:11], v[202:205], v[80:83]
	v_mfma_f32_16x16x32_bf16 v[96:99], v[172:175], v[202:205], v[84:87]
	v_mfma_f32_16x16x32_bf16 v[84:87], v[8:11], v[210:213], v[108:111]
	v_mfma_f32_16x16x32_bf16 v[80:83], v[172:175], v[210:213], v[104:107]
	v_mfma_f32_16x16x32_bf16 v[68:71], v[8:11], v[218:221], v[120:123]
	v_mfma_f32_16x16x32_bf16 v[64:67], v[172:175], v[218:221], v[124:127]
	s_barrier
	ds_read_b128 v[222:225], v152
	ds_read_b128 v[226:229], v152 offset:1024
	ds_read_b128 v[230:233], v152 offset:2048
	ds_read_b128 v[152:155], v152 offset:3072
	s_waitcnt vmcnt(0)
	s_barrier
	s_waitcnt lgkmcnt(0)
	s_waitcnt lgkmcnt(0)
	v_mfma_f32_16x16x32_bf16 v[92:95], v[222:225], v[24:27], v[92:95]
	v_mfma_f32_16x16x32_bf16 v[24:27], v[230:233], v[24:27], v[88:91]
	v_mfma_f32_16x16x32_bf16 v[88:91], v[222:225], v[198:201], v[178:181]
	v_mfma_f32_16x16x32_bf16 v[104:107], v[230:233], v[198:201], v[182:185]
	v_mfma_f32_16x16x32_bf16 v[76:79], v[222:225], v[206:209], v[76:79]
	v_mfma_f32_16x16x32_bf16 v[72:75], v[230:233], v[206:209], v[72:75]
	v_mfma_f32_16x16x32_bf16 v[176:179], v[222:225], v[214:217], v[186:189]
	v_mfma_f32_16x16x32_bf16 v[180:183], v[230:233], v[214:217], v[190:193]
	v_mfma_f32_16x16x32_bf16 v[124:127], v[226:229], v[194:197], v[92:95]
	v_mfma_f32_16x16x32_bf16 v[120:123], v[152:155], v[194:197], v[24:27]
	v_mfma_f32_16x16x32_bf16 v[108:111], v[226:229], v[202:205], v[88:91]
	v_mfma_f32_16x16x32_bf16 v[104:107], v[152:155], v[202:205], v[104:107]
	v_mfma_f32_16x16x32_bf16 v[92:95], v[226:229], v[210:213], v[76:79]
	v_mfma_f32_16x16x32_bf16 v[88:91], v[152:155], v[210:213], v[72:75]
	v_mfma_f32_16x16x32_bf16 v[76:79], v[226:229], v[218:221], v[176:179]
	v_mfma_f32_16x16x32_bf16 v[72:75], v[152:155], v[218:221], v[180:183]
	s_barrier
	ds_read_b128 v[176:179], v151 offset:49152
	ds_read_b128 v[180:183], v151 offset:50176
	ds_read_b128 v[184:187], v150 offset:49152
	ds_read_b128 v[188:191], v150 offset:50176
	ds_read_b128 v[192:195], v149 offset:49152
	ds_read_b128 v[196:199], v149 offset:50176
	ds_read_b128 v[200:203], v148 offset:49152
	ds_read_b128 v[148:151], v148 offset:50176
	s_barrier
	s_waitcnt lgkmcnt(0)
	s_waitcnt lgkmcnt(0)
	v_mfma_f32_16x16x32_bf16 v[24:27], v[0:3], v[176:179], v[60:63]
	v_mfma_f32_16x16x32_bf16 v[60:63], v[16:19], v[176:179], v[56:59]
	v_mfma_f32_16x16x32_bf16 v[52:55], v[0:3], v[184:187], v[52:55]
	v_mfma_f32_16x16x32_bf16 v[204:207], v[16:19], v[184:187], v[48:51]
	v_mfma_f32_16x16x32_bf16 v[44:47], v[0:3], v[192:195], v[44:47]
	v_mfma_f32_16x16x32_bf16 v[208:211], v[16:19], v[192:195], v[40:43]
	v_mfma_f32_16x16x32_bf16 v[0:3], v[0:3], v[200:203], v[36:39]
	v_mfma_f32_16x16x32_bf16 v[36:39], v[16:19], v[200:203], v[32:35]
	v_mfma_f32_16x16x32_bf16 v[56:59], v[8:11], v[180:183], v[24:27]
	v_mfma_f32_16x16x32_bf16 v[48:51], v[172:175], v[180:183], v[60:63]
	v_mfma_f32_16x16x32_bf16 v[40:43], v[8:11], v[188:191], v[52:55]
	v_mfma_f32_16x16x32_bf16 v[32:35], v[172:175], v[188:191], v[204:207]
	v_mfma_f32_16x16x32_bf16 v[24:27], v[8:11], v[196:199], v[44:47]
	v_mfma_f32_16x16x32_bf16 v[16:19], v[172:175], v[196:199], v[208:211]
	v_mfma_f32_16x16x32_bf16 v[8:11], v[8:11], v[148:151], v[0:3]
	v_mfma_f32_16x16x32_bf16 v[0:3], v[172:175], v[148:151], v[36:39]
	v_mfma_f32_16x16x32_bf16 v[28:31], v[222:225], v[176:179], v[28:31]
	v_mfma_f32_16x16x32_bf16 v[36:39], v[230:233], v[176:179], v[134:137]
	v_mfma_f32_16x16x32_bf16 v[20:23], v[222:225], v[184:187], v[20:23]
	v_mfma_f32_16x16x32_bf16 v[134:137], v[230:233], v[184:187], v[138:141]
	v_mfma_f32_16x16x32_bf16 v[12:15], v[222:225], v[192:195], v[12:15]
	v_mfma_f32_16x16x32_bf16 v[138:141], v[230:233], v[192:195], v[168:171]
	v_mfma_f32_16x16x32_bf16 v[4:7], v[222:225], v[200:203], v[4:7]
	v_mfma_f32_16x16x32_bf16 v[156:159], v[230:233], v[200:203], v[156:159]
	v_mfma_f32_16x16x32_bf16 v[60:63], v[226:229], v[180:183], v[28:31]
	v_mfma_f32_16x16x32_bf16 v[52:55], v[152:155], v[180:183], v[36:39]
	v_mfma_f32_16x16x32_bf16 v[44:47], v[226:229], v[188:191], v[20:23]
	v_mfma_f32_16x16x32_bf16 v[36:39], v[152:155], v[188:191], v[134:137]
	v_mfma_f32_16x16x32_bf16 v[28:31], v[226:229], v[196:199], v[12:15]
	v_mfma_f32_16x16x32_bf16 v[20:23], v[152:155], v[196:199], v[138:141]
	v_mfma_f32_16x16x32_bf16 v[12:15], v[226:229], v[148:151], v[4:7]
	v_mfma_f32_16x16x32_bf16 v[4:7], v[152:155], v[148:151], v[156:159]
	v_cmp_gt_u32_e32 vcc, s70, v130
	s_barrier
	s_and_saveexec_b64 s[52:53], vcc
	s_cbranch_execz .LBB0_657
	s_barrier

; #define STAGE(P, BASE, LD, br, kt) do { const char* _g = (const char*)((BASE) + (size_t)(br) * (LD) + (size_t)(kt) * 64); \
;     for (int _i = 0; _i < 2; ++_i) { int _b = tidx * 16 + _i * 8192; int _r, _c; stage_rc(_b, _r, _c); \
;       __builtin_amdgcn_global_load_lds((const unsigned*)(_g + (unsigned)((_r * (LD) + _c) * 2)), (unsigned*)((char*)(P) + _b), 16, 0, 0); } } while (0)
; #define LDA(dst, b, h) for (int m = 0; m < 4; ++m) for (int k = 0; k < 2; ++k) \
;     dst[m][k] = *reinterpret_cast<const bf16x8*>((char*)SA(b, h) + lds_byte(wr * 64 + m * 16 + fr, k * 32 + fq * 8))
; #define LDB(dst, b, h) for (int n = 0; n < 2; ++n) for (int k = 0; k < 2; ++k) \
;     dst[n][k] = *reinterpret_cast<const bf16x8*>((char*)SB(b, h) + lds_byte(wc * 32 + n * 16 + fr, k * 32 + fq * 8))
; #define MMA(ai, bj, At_, Bt_) do { __builtin_amdgcn_s_setprio(1); \
;     for (int k = 0; k < 2; ++k) for (int m = 0; m < 4; ++m) for (int n = 0; n < 2; ++n) \
;       acc[ai][bj][m][n] = __builtin_amdgcn_mfma_f32_16x16x32_bf16(At_[m][k], Bt_[n][k], acc[ai][bj][m][n], 0, 0, 0); \
;     __builtin_amdgcn_s_setprio(0); } while (0)
; #define WAIT_L(n) asm volatile("s_waitcnt lgkmcnt(" #n ")" ::: "memory")
; #define BAR __builtin_amdgcn_s_barrier()
; #define SCHED __builtin_amdgcn_sched_barrier(0)
; template <int EPI, int lda, int ldb, int N, int K>
; __device__ __forceinline__ void gemm_phase(const u16* __restrict__ A, const u16* __restrict__ Bt, const GemmEpi ep, int wv) {
;     ...
;       LDB(B0, 0, 0); SCHED; LDA(At, 0, 0); STAGE(SA(1, 1), Ab, lda, brow + HALF, t + 1);
;       WAIT_L(8); BAR; WAIT_L(0); MMA(0, 0, At, B0); BAR; SCHED;
;       LDB(B1, 0, 1); STAGE(SB(0, 0), Bt, ldb, bcol, t + 2);
;       BAR; WAIT_L(0); MMA(0, 1, At, B1); BAR;
;       LDA(At, 0, 1); STAGE(SA(0, 0), Ab, lda, brow, t + 2);
;       BAR; WAIT_L(0); MMA(1, 0, At, B0); BAR; SCHED;
;       STAGE(SB(0, 1), Bt, ldb, bcol + HALF, t + 2);
.LBB0_770:
	ds_read_b128 v[172:175], v161
	ds_read_b128 v[176:179], v161 offset:1024
	ds_read_b128 v[180:183], v161 offset:2048
	ds_read_b128 v[184:187], v161 offset:3072
	v_add_u32_e32 v169, 0xc000, v148
	v_lshl_add_u64 v[236:237], v[136:137], 0, s[50:51]
	v_readfirstlane_b32 s53, v169
	v_add_u32_e32 v170, 0xe000, v148
	v_lshl_add_u64 v[162:163], v[236:237], 0, s[18:19]
	s_mov_b32 m0, s53
	v_lshl_add_u64 v[238:239], v[134:135], 0, s[50:51]
	v_readfirstlane_b32 s53, v170
	global_load_lds_dwordx4 v[162:163], off
	v_lshl_add_u64 v[162:163], v[238:239], 0, s[18:19]
	s_mov_b32 m0, s53
	s_nop 0
	global_load_lds_dwordx4 v[162:163], off
	ds_read_b128 v[164:167], v152
	ds_read_b128 v[188:191], v152 offset:1024
	ds_read_b128 v[192:195], v151
	ds_read_b128 v[196:199], v151 offset:1024
	ds_read_b128 v[200:203], v150
	ds_read_b128 v[204:207], v150 offset:1024
	ds_read_b128 v[208:211], v149
	ds_read_b128 v[212:215], v149 offset:1024
	s_waitcnt lgkmcnt(8)
	s_barrier
	s_waitcnt lgkmcnt(0)
	s_waitcnt lgkmcnt(0)
	v_mfma_f32_16x16x32_bf16 v[124:127], v[172:175], v[164:167], v[124:127]
	v_mfma_f32_16x16x32_bf16 v[120:123], v[180:183], v[164:167], v[120:123]
	v_mfma_f32_16x16x32_bf16 v[116:119], v[172:175], v[192:195], v[116:119]
	v_mfma_f32_16x16x32_bf16 v[112:115], v[180:183], v[192:195], v[112:115]
	v_mfma_f32_16x16x32_bf16 v[108:111], v[172:175], v[200:203], v[108:111]
	v_mfma_f32_16x16x32_bf16 v[104:107], v[180:183], v[200:203], v[104:107]
	v_mfma_f32_16x16x32_bf16 v[100:103], v[172:175], v[208:211], v[100:103]
	v_mfma_f32_16x16x32_bf16 v[96:99], v[180:183], v[208:211], v[96:99]
	v_mfma_f32_16x16x32_bf16 v[124:127], v[176:179], v[188:191], v[124:127]
	v_mfma_f32_16x16x32_bf16 v[120:123], v[184:187], v[188:191], v[120:123]
	v_mfma_f32_16x16x32_bf16 v[116:119], v[176:179], v[196:199], v[116:119]
	v_mfma_f32_16x16x32_bf16 v[112:115], v[184:187], v[196:199], v[112:115]
	v_mfma_f32_16x16x32_bf16 v[108:111], v[176:179], v[204:207], v[108:111]
	v_mfma_f32_16x16x32_bf16 v[104:107], v[184:187], v[204:207], v[104:107]
	v_mfma_f32_16x16x32_bf16 v[100:103], v[176:179], v[212:215], v[100:103]
	v_mfma_f32_16x16x32_bf16 v[96:99], v[184:187], v[212:215], v[96:99]
	s_barrier
	v_add_u32_e32 v162, s64, v153
	v_lshl_add_u64 v[240:241], v[140:141], 0, s[50:51]
	v_readfirstlane_b32 s53, v162
	v_add_u32_e32 v163, 0x2000, v162
	v_lshl_add_u64 v[232:233], v[240:241], 0, s[20:21]
	s_mov_b32 m0, s53
	v_lshl_add_u64 v[242:243], v[138:139], 0, s[50:51]
	v_readfirstlane_b32 s53, v163
	global_load_lds_dwordx4 v[232:233], off
	v_lshl_add_u64 v[232:233], v[242:243], 0, s[20:21]
	s_mov_b32 m0, s53
	s_nop 0
	global_load_lds_dwordx4 v[232:233], off
	ds_read_b128 v[216:219], v160
	ds_read_b128 v[220:223], v160 offset:1024
	ds_read_b128 v[224:227], v160 offset:2048
	ds_read_b128 v[228:231], v160 offset:3072
	s_barrier
	s_waitcnt lgkmcnt(0)
	s_waitcnt lgkmcnt(0)
	v_mfma_f32_16x16x32_bf16 v[92:95], v[216:219], v[164:167], v[92:95]
	v_mfma_f32_16x16x32_bf16 v[88:91], v[224:227], v[164:167], v[88:91]
	v_mfma_f32_16x16x32_bf16 v[84:87], v[216:219], v[192:195], v[84:87]
	v_mfma_f32_16x16x32_bf16 v[80:83], v[224:227], v[192:195], v[80:83]
	v_mfma_f32_16x16x32_bf16 v[76:79], v[216:219], v[200:203], v[76:79]
	v_mfma_f32_16x16x32_bf16 v[72:75], v[224:227], v[200:203], v[72:75]
	v_mfma_f32_16x16x32_bf16 v[68:71], v[216:219], v[208:211], v[68:71]
	v_mfma_f32_16x16x32_bf16 v[64:67], v[224:227], v[208:211], v[64:67]
	v_mfma_f32_16x16x32_bf16 v[92:95], v[220:223], v[188:191], v[92:95]
	v_mfma_f32_16x16x32_bf16 v[88:91], v[228:231], v[188:191], v[88:91]
	v_mfma_f32_16x16x32_bf16 v[84:87], v[220:223], v[196:199], v[84:87]
	v_mfma_f32_16x16x32_bf16 v[80:83], v[228:231], v[196:199], v[80:83]
	v_mfma_f32_16x16x32_bf16 v[76:79], v[220:223], v[204:207], v[76:79]
	v_mfma_f32_16x16x32_bf16 v[72:75], v[228:231], v[204:207], v[72:75]
	v_mfma_f32_16x16x32_bf16 v[68:71], v[220:223], v[212:215], v[68:71]
	v_mfma_f32_16x16x32_bf16 v[64:67], v[228:231], v[212:215], v[64:67]
	v_readfirstlane_b32 s53, v148
	v_lshl_add_u64 v[164:165], v[236:237], 0, s[22:23]
	s_mov_b32 m0, s53
	s_barrier
	global_load_lds_dwordx4 v[164:165], off
	v_add_u32_e32 v164, 0x2000, v148
	v_lshl_add_u64 v[166:167], v[238:239], 0, s[22:23]
	v_readfirstlane_b32 s53, v164
	s_mov_b32 m0, s53
	s_nop 0
	global_load_lds_dwordx4 v[166:167], off
	ds_read_b128 v[188:191], v152 offset:16384
	ds_read_b128 v[192:195], v152 offset:17408
	ds_read_b128 v[196:199], v151 offset:16384
	ds_read_b128 v[200:203], v151 offset:17408
	ds_read_b128 v[204:207], v150 offset:16384
	ds_read_b128 v[208:211], v150 offset:17408
	ds_read_b128 v[212:215], v149 offset:16384
	ds_read_b128 v[232:235], v149 offset:17408
	s_barrier
	s_waitcnt lgkmcnt(0)
	s_waitcnt lgkmcnt(0)
	v_mfma_f32_16x16x32_bf16 v[60:63], v[172:175], v[188:191], v[60:63]
	v_mfma_f32_16x16x32_bf16 v[56:59], v[180:183], v[188:191], v[56:59]
	v_mfma_f32_16x16x32_bf16 v[52:55], v[172:175], v[196:199], v[52:55]
	v_mfma_f32_16x16x32_bf16 v[48:51], v[180:183], v[196:199], v[48:51]
	v_mfma_f32_16x16x32_bf16 v[44:47], v[172:175], v[204:207], v[44:47]
	v_mfma_f32_16x16x32_bf16 v[40:43], v[180:183], v[204:207], v[40:43]
	v_mfma_f32_16x16x32_bf16 v[36:39], v[172:175], v[212:215], v[36:39]
	v_mfma_f32_16x16x32_bf16 v[32:35], v[180:183], v[212:215], v[32:35]
	v_mfma_f32_16x16x32_bf16 v[60:63], v[176:179], v[192:195], v[60:63]
	v_mfma_f32_16x16x32_bf16 v[56:59], v[184:187], v[192:195], v[56:59]
	v_mfma_f32_16x16x32_bf16 v[52:55], v[176:179], v[200:203], v[52:55]
	v_mfma_f32_16x16x32_bf16 v[48:51], v[184:187], v[200:203], v[48:51]
	v_mfma_f32_16x16x32_bf16 v[44:47], v[176:179], v[208:211], v[44:47]
	v_mfma_f32_16x16x32_bf16 v[40:43], v[184:187], v[208:211], v[40:43]
	v_mfma_f32_16x16x32_bf16 v[36:39], v[176:179], v[232:235], v[36:39]
	v_mfma_f32_16x16x32_bf16 v[32:35], v[184:187], v[232:235], v[32:35]
	s_barrier
; #define STAGE(P, BASE, LD, br, kt) do { const char* _g = (const char*)((BASE) + (size_t)(br) * (LD) + (size_t)(kt) * 64); \
;     for (int _i = 0; _i < 2; ++_i) { int _b = tidx * 16 + _i * 8192; int _r, _c; stage_rc(_b, _r, _c); \
;       __builtin_amdgcn_global_load_lds((const unsigned*)(_g + (unsigned)((_r * (LD) + _c) * 2)), (unsigned*)((char*)(P) + _b), 16, 0, 0); } } while (0)
; #define LDA(dst, b, h) for (int m = 0; m < 4; ++m) for (int k = 0; k < 2; ++k) \
;     dst[m][k] = *reinterpret_cast<const bf16x8*>((char*)SA(b, h) + lds_byte(wr * 64 + m * 16 + fr, k * 32 + fq * 8))
; #define LDB(dst, b, h) for (int n = 0; n < 2; ++n) for (int k = 0; k < 2; ++k) \
;     dst[n][k] = *reinterpret_cast<const bf16x8*>((char*)SB(b, h) + lds_byte(wc * 32 + n * 16 + fr, k * 32 + fq * 8))
; #define MMA(ai, bj, At_, Bt_) do { __builtin_amdgcn_s_setprio(1); \
;     for (int k = 0; k < 2; ++k) for (int m = 0; m < 4; ++m) for (int n = 0; n < 2; ++n) \
;       acc[ai][bj][m][n] = __builtin_amdgcn_mfma_f32_16x16x32_bf16(At_[m][k], Bt_[n][k], acc[ai][bj][m][n], 0, 0, 0); \
;     __builtin_amdgcn_s_setprio(0); } while (0)
; #define WAIT_V(n) asm volatile("s_waitcnt vmcnt(" #n ")" ::: "memory")
; #define WAIT_L(n) asm volatile("s_waitcnt lgkmcnt(" #n ")" ::: "memory")
; #define BAR __builtin_amdgcn_s_barrier()
; #define SCHED __builtin_amdgcn_sched_barrier(0)
; template <int EPI, int lda, int ldb, int N, int K>
; __device__ __forceinline__ void gemm_phase(const u16* __restrict__ A, const u16* __restrict__ Bt, const GemmEpi ep, int wv) {
;     ...
;       STAGE(SB(0, 1), Bt, ldb, bcol + HALF, t + 2);
;       WAIT_V(6); BAR; MMA(1, 1, At, B1); BAR;
;       LDB(B0, 1, 0); SCHED; LDA(At, 1, 0); STAGE(SA(0, 1), Ab, lda, brow + HALF, t + 2);
;       WAIT_L(8); BAR; WAIT_L(0); MMA(0, 0, At, B0); BAR; SCHED;
;       LDB(B1, 1, 1); STAGE(SB(1, 0), Bt, ldb, bcol, t + 3);
;       BAR; WAIT_L(0); MMA(0, 1, At, B1); BAR;
;       LDA(At, 1, 1); STAGE(SA(1, 0), Ab, lda, brow, t + 3);
	v_add_u32_e32 v165, s65, v153
	v_lshl_add_u64 v[166:167], v[240:241], 0, s[24:25]
	v_readfirstlane_b32 s53, v165
	s_mov_b32 m0, s53
	v_lshl_add_u64 v[172:173], v[242:243], 0, s[24:25]
	global_load_lds_dwordx4 v[166:167], off
	v_add_u32_e32 v166, 0x2000, v165
	s_nop 0
	v_readfirstlane_b32 s53, v166
	s_mov_b32 m0, s53
	s_nop 0
	global_load_lds_dwordx4 v[172:173], off
	s_waitcnt vmcnt(6)
	s_barrier
	v_mfma_f32_16x16x32_bf16 v[28:31], v[216:219], v[188:191], v[28:31]
	v_mfma_f32_16x16x32_bf16 v[24:27], v[224:227], v[188:191], v[24:27]
	v_mfma_f32_16x16x32_bf16 v[20:23], v[216:219], v[196:199], v[20:23]
	v_mfma_f32_16x16x32_bf16 v[16:19], v[224:227], v[196:199], v[16:19]
	v_mfma_f32_16x16x32_bf16 v[12:15], v[216:219], v[204:207], v[12:15]
	v_mfma_f32_16x16x32_bf16 v[8:11], v[224:227], v[204:207], v[8:11]
	v_mfma_f32_16x16x32_bf16 v[4:7], v[216:219], v[212:215], v[4:7]
	v_mfma_f32_16x16x32_bf16 v[0:3], v[224:227], v[212:215], v[0:3]
	v_mfma_f32_16x16x32_bf16 v[28:31], v[220:223], v[192:195], v[28:31]
	v_mfma_f32_16x16x32_bf16 v[24:27], v[228:231], v[192:195], v[24:27]
	v_mfma_f32_16x16x32_bf16 v[20:23], v[220:223], v[200:203], v[20:23]
	v_mfma_f32_16x16x32_bf16 v[16:19], v[228:231], v[200:203], v[16:19]
	v_mfma_f32_16x16x32_bf16 v[12:15], v[220:223], v[208:211], v[12:15]
	v_mfma_f32_16x16x32_bf16 v[8:11], v[228:231], v[208:211], v[8:11]
	v_mfma_f32_16x16x32_bf16 v[4:7], v[220:223], v[232:235], v[4:7]
	v_mfma_f32_16x16x32_bf16 v[0:3], v[228:231], v[232:235], v[0:3]
	s_barrier
	ds_read_b128 v[172:175], v156
	ds_read_b128 v[176:179], v156 offset:1024
	ds_read_b128 v[180:183], v156 offset:2048
	ds_read_b128 v[184:187], v156 offset:3072
	v_add_u32_e32 v167, 0x4000, v148
	v_add_u32_e32 v168, 0x6000, v148
	v_readfirstlane_b32 s53, v167
	v_lshl_add_u64 v[220:221], v[236:237], 0, s[26:27]
	s_mov_b32 m0, s53
	v_readfirstlane_b32 s53, v168
	global_load_lds_dwordx4 v[220:221], off
	v_lshl_add_u64 v[220:221], v[238:239], 0, s[26:27]
	s_mov_b32 m0, s53
	s_nop 0
	global_load_lds_dwordx4 v[220:221], off
	ds_read_b128 v[188:191], v152 offset:32768
	ds_read_b128 v[192:195], v152 offset:33792
	ds_read_b128 v[196:199], v151 offset:32768
	ds_read_b128 v[200:203], v151 offset:33792
	ds_read_b128 v[204:207], v150 offset:32768
	ds_read_b128 v[208:211], v150 offset:33792
	ds_read_b128 v[212:215], v149 offset:32768
	ds_read_b128 v[216:219], v149 offset:33792
	s_waitcnt lgkmcnt(8)
	s_barrier
	s_waitcnt lgkmcnt(0)
	s_waitcnt lgkmcnt(0)
	v_mfma_f32_16x16x32_bf16 v[124:127], v[172:175], v[188:191], v[124:127]
	v_mfma_f32_16x16x32_bf16 v[120:123], v[180:183], v[188:191], v[120:123]
	v_mfma_f32_16x16x32_bf16 v[116:119], v[172:175], v[196:199], v[116:119]
	v_mfma_f32_16x16x32_bf16 v[112:115], v[180:183], v[196:199], v[112:115]
	v_mfma_f32_16x16x32_bf16 v[108:111], v[172:175], v[204:207], v[108:111]
	v_mfma_f32_16x16x32_bf16 v[104:107], v[180:183], v[204:207], v[104:107]
	v_mfma_f32_16x16x32_bf16 v[100:103], v[172:175], v[212:215], v[100:103]
	v_mfma_f32_16x16x32_bf16 v[96:99], v[180:183], v[212:215], v[96:99]
	v_mfma_f32_16x16x32_bf16 v[124:127], v[176:179], v[192:195], v[124:127]
	v_mfma_f32_16x16x32_bf16 v[120:123], v[184:187], v[192:195], v[120:123]
	v_mfma_f32_16x16x32_bf16 v[116:119], v[176:179], v[200:203], v[116:119]
	v_mfma_f32_16x16x32_bf16 v[112:115], v[184:187], v[200:203], v[112:115]
	v_mfma_f32_16x16x32_bf16 v[108:111], v[176:179], v[208:211], v[108:111]
	v_mfma_f32_16x16x32_bf16 v[104:107], v[184:187], v[208:211], v[104:107]
	v_mfma_f32_16x16x32_bf16 v[100:103], v[176:179], v[216:219], v[100:103]
	v_mfma_f32_16x16x32_bf16 v[96:99], v[184:187], v[216:219], v[96:99]
	s_barrier
	v_readfirstlane_b32 s53, v155
	v_add_u32_e32 v171, 0x2000, v155
	v_lshl_add_u64 v[244:245], v[240:241], 0, s[40:41]
	s_mov_b32 m0, s53
	v_readfirstlane_b32 s53, v171
	global_load_lds_dwordx4 v[244:245], off
	v_lshl_add_u64 v[244:245], v[242:243], 0, s[40:41]
	s_mov_b32 m0, s53
	s_nop 0
	global_load_lds_dwordx4 v[244:245], off
	ds_read_b128 v[220:223], v154
	ds_read_b128 v[224:227], v154 offset:1024
	ds_read_b128 v[228:231], v154 offset:2048
	ds_read_b128 v[232:235], v154 offset:3072
	s_barrier
	s_waitcnt lgkmcnt(0)
	s_waitcnt lgkmcnt(0)
	v_mfma_f32_16x16x32_bf16 v[92:95], v[220:223], v[188:191], v[92:95]
	v_mfma_f32_16x16x32_bf16 v[88:91], v[228:231], v[188:191], v[88:91]
	v_mfma_f32_16x16x32_bf16 v[84:87], v[220:223], v[196:199], v[84:87]
	v_mfma_f32_16x16x32_bf16 v[80:83], v[228:231], v[196:199], v[80:83]
	v_mfma_f32_16x16x32_bf16 v[76:79], v[220:223], v[204:207], v[76:79]
	v_mfma_f32_16x16x32_bf16 v[72:75], v[228:231], v[204:207], v[72:75]
	v_mfma_f32_16x16x32_bf16 v[68:71], v[220:223], v[212:215], v[68:71]
	v_mfma_f32_16x16x32_bf16 v[64:67], v[228:231], v[212:215], v[64:67]
	v_mfma_f32_16x16x32_bf16 v[92:95], v[224:227], v[192:195], v[92:95]
	v_mfma_f32_16x16x32_bf16 v[88:91], v[232:235], v[192:195], v[88:91]
	v_mfma_f32_16x16x32_bf16 v[84:87], v[224:227], v[200:203], v[84:87]
	v_mfma_f32_16x16x32_bf16 v[80:83], v[232:235], v[200:203], v[80:83]
	v_mfma_f32_16x16x32_bf16 v[76:79], v[224:227], v[208:211], v[76:79]
	v_mfma_f32_16x16x32_bf16 v[72:75], v[232:235], v[208:211], v[72:75]
	v_mfma_f32_16x16x32_bf16 v[68:71], v[224:227], v[216:219], v[68:71]
	v_mfma_f32_16x16x32_bf16 v[64:67], v[232:235], v[216:219], v[64:67]
	v_readfirstlane_b32 s53, v157
	v_lshl_add_u64 v[236:237], v[236:237], 0, s[42:43]
	s_mov_b32 m0, s53
	v_readfirstlane_b32 s53, v158
	s_barrier
; #define STAGE(P, BASE, LD, br, kt) do { const char* _g = (const char*)((BASE) + (size_t)(br) * (LD) + (size_t)(kt) * 64); \
;     for (int _i = 0; _i < 2; ++_i) { int _b = tidx * 16 + _i * 8192; int _r, _c; stage_rc(_b, _r, _c); \
;       __builtin_amdgcn_global_load_lds((const unsigned*)(_g + (unsigned)((_r * (LD) + _c) * 2)), (unsigned*)((char*)(P) + _b), 16, 0, 0); } } while (0)
; #define LDA(dst, b, h) for (int m = 0; m < 4; ++m) for (int k = 0; k < 2; ++k) \
;     dst[m][k] = *reinterpret_cast<const bf16x8*>((char*)SA(b, h) + lds_byte(wr * 64 + m * 16 + fr, k * 32 + fq * 8))
; #define LDB(dst, b, h) for (int n = 0; n < 2; ++n) for (int k = 0; k < 2; ++k) \
;     dst[n][k] = *reinterpret_cast<const bf16x8*>((char*)SB(b, h) + lds_byte(wc * 32 + n * 16 + fr, k * 32 + fq * 8))
; #define MMA(ai, bj, At_, Bt_) do { __builtin_amdgcn_s_setprio(1); \
;     for (int k = 0; k < 2; ++k) for (int m = 0; m < 4; ++m) for (int n = 0; n < 2; ++n) \
;       acc[ai][bj][m][n] = __builtin_amdgcn_mfma_f32_16x16x32_bf16(At_[m][k], Bt_[n][k], acc[ai][bj][m][n], 0, 0, 0); \
;     __builtin_amdgcn_s_setprio(0); } while (0)
; #define WAIT_V(n) asm volatile("s_waitcnt vmcnt(" #n ")" ::: "memory")
; #define WAIT_L(n) asm volatile("s_waitcnt lgkmcnt(" #n ")" ::: "memory")
; #define BAR __builtin_amdgcn_s_barrier()
; #define SCHED __builtin_amdgcn_sched_barrier(0)
; template <int EPI, int lda, int ldb, int N, int K>
; __device__ __forceinline__ void gemm_phase(const u16* __restrict__ A, const u16* __restrict__ Bt, const GemmEpi ep, int wv) {
;     ...
;       LDA(At, 1, 1); STAGE(SA(1, 0), Ab, lda, brow, t + 3);
;       BAR; WAIT_L(0); MMA(1, 0, At, B0); BAR; SCHED;
;       STAGE(SB(1, 1), Bt, ldb, bcol + HALF, t + 3);
;       WAIT_V(6); BAR; MMA(1, 1, At, B1); BAR;
;     }
;     { LDB(B0, 0, 0); LDA(At, 0, 0); STAGE(SA(1, 1), Ab, lda, brow + HALF, nt - 1);
;       BAR; WAIT_L(0); MMA(0, 0, At, B0); BAR;
;       LDB(B1, 0, 1); BAR; WAIT_L(0); MMA(0, 1, At, B1); BAR;
	global_load_lds_dwordx4 v[236:237], off
	v_lshl_add_u64 v[236:237], v[238:239], 0, s[42:43]
	s_mov_b32 m0, s53
	s_nop 0
	global_load_lds_dwordx4 v[236:237], off
	ds_read_b128 v[188:191], v152 offset:49152
	ds_read_b128 v[192:195], v152 offset:50176
	ds_read_b128 v[196:199], v151 offset:49152
	ds_read_b128 v[200:203], v151 offset:50176
	ds_read_b128 v[204:207], v150 offset:49152
	ds_read_b128 v[208:211], v150 offset:50176
	ds_read_b128 v[212:215], v149 offset:49152
	ds_read_b128 v[216:219], v149 offset:50176
	s_barrier
	s_waitcnt lgkmcnt(0)
	s_waitcnt lgkmcnt(0)
	v_mfma_f32_16x16x32_bf16 v[60:63], v[172:175], v[188:191], v[60:63]
	v_mfma_f32_16x16x32_bf16 v[56:59], v[180:183], v[188:191], v[56:59]
	v_mfma_f32_16x16x32_bf16 v[52:55], v[172:175], v[196:199], v[52:55]
	v_mfma_f32_16x16x32_bf16 v[48:51], v[180:183], v[196:199], v[48:51]
	v_mfma_f32_16x16x32_bf16 v[44:47], v[172:175], v[204:207], v[44:47]
	v_mfma_f32_16x16x32_bf16 v[40:43], v[180:183], v[204:207], v[40:43]
	v_mfma_f32_16x16x32_bf16 v[36:39], v[172:175], v[212:215], v[36:39]
	v_mfma_f32_16x16x32_bf16 v[32:35], v[180:183], v[212:215], v[32:35]
	v_mfma_f32_16x16x32_bf16 v[60:63], v[176:179], v[192:195], v[60:63]
	v_mfma_f32_16x16x32_bf16 v[56:59], v[184:187], v[192:195], v[56:59]
	v_mfma_f32_16x16x32_bf16 v[52:55], v[176:179], v[200:203], v[52:55]
	v_mfma_f32_16x16x32_bf16 v[48:51], v[184:187], v[200:203], v[48:51]
	v_mfma_f32_16x16x32_bf16 v[44:47], v[176:179], v[208:211], v[44:47]
	v_mfma_f32_16x16x32_bf16 v[40:43], v[184:187], v[208:211], v[40:43]
	v_mfma_f32_16x16x32_bf16 v[36:39], v[176:179], v[216:219], v[36:39]
	v_mfma_f32_16x16x32_bf16 v[32:35], v[184:187], v[216:219], v[32:35]
	s_barrier
	v_readfirstlane_b32 s53, v159
	v_add_u32_e32 v171, 0x2000, v159
	v_lshl_add_u64 v[172:173], v[240:241], 0, s[44:45]
	s_mov_b32 m0, s53
	v_readfirstlane_b32 s53, v171
	global_load_lds_dwordx4 v[172:173], off
	v_lshl_add_u64 v[172:173], v[242:243], 0, s[44:45]
	s_mov_b32 m0, s53
	s_nop 0
	global_load_lds_dwordx4 v[172:173], off
	s_waitcnt vmcnt(6)
	s_barrier
	v_mfma_f32_16x16x32_bf16 v[28:31], v[220:223], v[188:191], v[28:31]
	v_mfma_f32_16x16x32_bf16 v[24:27], v[228:231], v[188:191], v[24:27]
	v_mfma_f32_16x16x32_bf16 v[20:23], v[220:223], v[196:199], v[20:23]
	v_mfma_f32_16x16x32_bf16 v[16:19], v[228:231], v[196:199], v[16:19]
	v_mfma_f32_16x16x32_bf16 v[12:15], v[220:223], v[204:207], v[12:15]
	v_mfma_f32_16x16x32_bf16 v[8:11], v[228:231], v[204:207], v[8:11]
	v_mfma_f32_16x16x32_bf16 v[4:7], v[220:223], v[212:215], v[4:7]
	v_mfma_f32_16x16x32_bf16 v[0:3], v[228:231], v[212:215], v[0:3]
	v_mfma_f32_16x16x32_bf16 v[28:31], v[224:227], v[192:195], v[28:31]
	v_mfma_f32_16x16x32_bf16 v[24:27], v[232:235], v[192:195], v[24:27]
	v_mfma_f32_16x16x32_bf16 v[20:23], v[224:227], v[200:203], v[20:23]
	v_mfma_f32_16x16x32_bf16 v[16:19], v[232:235], v[200:203], v[16:19]
	v_mfma_f32_16x16x32_bf16 v[12:15], v[224:227], v[208:211], v[12:15]
	v_mfma_f32_16x16x32_bf16 v[8:11], v[232:235], v[208:211], v[8:11]
	v_mfma_f32_16x16x32_bf16 v[4:7], v[224:227], v[216:219], v[4:7]
	v_mfma_f32_16x16x32_bf16 v[0:3], v[232:235], v[216:219], v[0:3]
	s_add_i32 s52, s52, 2
	s_add_u32 s50, s50, 0x100
	s_addc_u32 s51, s51, 0
	s_cmp_gt_u32 s52, 27
	s_barrier
	s_cbranch_scc0 .LBB0_770
	s_add_i32 s50, s48, 0x80
	s_mul_hi_i32 s51, s50, 0x1080
	s_mulk_i32 s50, 0x1080
	s_add_u32 s50, s61, s50
	s_addc_u32 s51, s62, s51
	v_lshl_add_u64 v[158:159], s[50:51], 0, v[128:129]
	v_readfirstlane_b32 s52, v169
	v_lshl_add_u64 v[158:159], v[158:159], 0, s[46:47]
	s_mov_b32 m0, s52
	ds_read_b128 v[134:137], v161
	ds_read_b128 v[138:141], v161 offset:1024
	ds_read_b128 v[172:175], v161 offset:2048
	ds_read_b128 v[176:179], v161 offset:3072
	ds_read_b128 v[180:183], v152
	ds_read_b128 v[184:187], v152 offset:1024
	ds_read_b128 v[188:191], v151
	ds_read_b128 v[192:195], v151 offset:1024
	ds_read_b128 v[196:199], v150
	ds_read_b128 v[200:203], v150 offset:1024
	ds_read_b128 v[204:207], v149
	ds_read_b128 v[208:211], v149 offset:1024
	global_load_lds_dwordx4 v[158:159], off
	v_lshl_add_u64 v[158:159], s[50:51], 0, v[132:133]
	v_readfirstlane_b32 s50, v170
	v_lshl_add_u64 v[158:159], v[158:159], 0, s[46:47]
	s_mov_b32 m0, s50
	s_nop 0
	global_load_lds_dwordx4 v[158:159], off
	s_barrier
	s_waitcnt lgkmcnt(0)
	s_waitcnt lgkmcnt(0)
	v_mfma_f32_16x16x32_bf16 v[124:127], v[134:137], v[180:183], v[124:127]
	v_mfma_f32_16x16x32_bf16 v[120:123], v[172:175], v[180:183], v[120:123]
	v_mfma_f32_16x16x32_bf16 v[116:119], v[134:137], v[188:191], v[116:119]
	v_mfma_f32_16x16x32_bf16 v[112:115], v[172:175], v[188:191], v[112:115]
	v_mfma_f32_16x16x32_bf16 v[108:111], v[134:137], v[196:199], v[108:111]
	v_mfma_f32_16x16x32_bf16 v[104:107], v[172:175], v[196:199], v[104:107]
	v_mfma_f32_16x16x32_bf16 v[100:103], v[134:137], v[204:207], v[100:103]
	v_mfma_f32_16x16x32_bf16 v[96:99], v[172:175], v[204:207], v[96:99]
	v_mfma_f32_16x16x32_bf16 v[124:127], v[138:141], v[184:187], v[124:127]
	v_mfma_f32_16x16x32_bf16 v[120:123], v[176:179], v[184:187], v[120:123]
	v_mfma_f32_16x16x32_bf16 v[116:119], v[138:141], v[192:195], v[116:119]
	v_mfma_f32_16x16x32_bf16 v[112:115], v[176:179], v[192:195], v[112:115]
	v_mfma_f32_16x16x32_bf16 v[108:111], v[138:141], v[200:203], v[108:111]
	v_mfma_f32_16x16x32_bf16 v[104:107], v[176:179], v[200:203], v[104:107]
	v_mfma_f32_16x16x32_bf16 v[100:103], v[138:141], v[208:211], v[100:103]
	v_mfma_f32_16x16x32_bf16 v[96:99], v[176:179], v[208:211], v[96:99]
	s_barrier
	ds_read_b128 v[212:215], v160
	ds_read_b128 v[216:219], v160 offset:1024
	ds_read_b128 v[220:223], v160 offset:2048
	ds_read_b128 v[158:161], v160 offset:3072
	s_barrier
; #define LDA(dst, b, h) for (int m = 0; m < 4; ++m) for (int k = 0; k < 2; ++k) \
;     dst[m][k] = *reinterpret_cast<const bf16x8*>((char*)SA(b, h) + lds_byte(wr * 64 + m * 16 + fr, k * 32 + fq * 8))
; #define LDB(dst, b, h) for (int n = 0; n < 2; ++n) for (int k = 0; k < 2; ++k) \
;     dst[n][k] = *reinterpret_cast<const bf16x8*>((char*)SB(b, h) + lds_byte(wc * 32 + n * 16 + fr, k * 32 + fq * 8))
; #define MMA(ai, bj, At_, Bt_) do { __builtin_amdgcn_s_setprio(1); \
;     for (int k = 0; k < 2; ++k) for (int m = 0; m < 4; ++m) for (int n = 0; n < 2; ++n) \
;       acc[ai][bj][m][n] = __builtin_amdgcn_mfma_f32_16x16x32_bf16(At_[m][k], Bt_[n][k], acc[ai][bj][m][n], 0, 0, 0); \
;     __builtin_amdgcn_s_setprio(0); } while (0)
; #define WAIT_V(n) asm volatile("s_waitcnt vmcnt(" #n ")" ::: "memory")
; #define WAIT_L(n) asm volatile("s_waitcnt lgkmcnt(" #n ")" ::: "memory")
; #define BAR __builtin_amdgcn_s_barrier()
; template <int EPI, int lda, int ldb, int N, int K>
; __device__ __forceinline__ void gemm_phase(const u16* __restrict__ A, const u16* __restrict__ Bt, const GemmEpi ep, int wv) {
;     ...
;       LDB(B1, 0, 1); BAR; WAIT_L(0); MMA(0, 1, At, B1); BAR;
;       LDA(At, 0, 1); WAIT_V(4); BAR; WAIT_L(0); MMA(1, 0, At, B0); MMA(1, 1, At, B1); BAR; }
;     { LDB(B0, 1, 0); LDA(At, 1, 0); WAIT_V(2); BAR; WAIT_L(0); MMA(0, 0, At, B0); BAR;
	s_waitcnt lgkmcnt(0)
	s_waitcnt lgkmcnt(0)
	v_mfma_f32_16x16x32_bf16 v[92:95], v[212:215], v[180:183], v[92:95]
	v_mfma_f32_16x16x32_bf16 v[88:91], v[220:223], v[180:183], v[88:91]
	v_mfma_f32_16x16x32_bf16 v[76:79], v[212:215], v[196:199], v[76:79]
	v_mfma_f32_16x16x32_bf16 v[72:75], v[220:223], v[196:199], v[72:75]
	v_mfma_f32_16x16x32_bf16 v[84:87], v[212:215], v[188:191], v[84:87]
	v_mfma_f32_16x16x32_bf16 v[80:83], v[220:223], v[188:191], v[80:83]
	v_mfma_f32_16x16x32_bf16 v[68:71], v[212:215], v[204:207], v[68:71]
	v_mfma_f32_16x16x32_bf16 v[64:67], v[220:223], v[204:207], v[64:67]
	v_mfma_f32_16x16x32_bf16 v[92:95], v[216:219], v[184:187], v[92:95]
	v_mfma_f32_16x16x32_bf16 v[88:91], v[158:161], v[184:187], v[88:91]
	v_mfma_f32_16x16x32_bf16 v[76:79], v[216:219], v[200:203], v[76:79]
	v_mfma_f32_16x16x32_bf16 v[72:75], v[158:161], v[200:203], v[72:75]
	v_mfma_f32_16x16x32_bf16 v[180:183], v[216:219], v[192:195], v[84:87]
	v_mfma_f32_16x16x32_bf16 v[184:187], v[158:161], v[192:195], v[80:83]
	v_mfma_f32_16x16x32_bf16 v[188:191], v[216:219], v[208:211], v[68:71]
	v_mfma_f32_16x16x32_bf16 v[192:195], v[158:161], v[208:211], v[64:67]
	s_barrier
	s_nop 0
	ds_read_b128 v[64:67], v152 offset:16384
	ds_read_b128 v[68:71], v152 offset:17408
	ds_read_b128 v[80:83], v151 offset:16384
	ds_read_b128 v[84:87], v151 offset:17408
	ds_read_b128 v[196:199], v150 offset:16384
	ds_read_b128 v[200:203], v150 offset:17408
	ds_read_b128 v[204:207], v149 offset:16384
	ds_read_b128 v[208:211], v149 offset:17408
	s_waitcnt vmcnt(4)
	s_barrier
	s_waitcnt lgkmcnt(0)
	s_waitcnt lgkmcnt(0)
	v_mfma_f32_16x16x32_bf16 v[60:63], v[134:137], v[64:67], v[60:63]
	v_mfma_f32_16x16x32_bf16 v[56:59], v[172:175], v[64:67], v[56:59]
	v_mfma_f32_16x16x32_bf16 v[52:55], v[134:137], v[80:83], v[52:55]
	v_mfma_f32_16x16x32_bf16 v[48:51], v[172:175], v[80:83], v[48:51]
	v_mfma_f32_16x16x32_bf16 v[44:47], v[134:137], v[196:199], v[44:47]
	v_mfma_f32_16x16x32_bf16 v[40:43], v[172:175], v[196:199], v[40:43]
	v_mfma_f32_16x16x32_bf16 v[36:39], v[134:137], v[204:207], v[36:39]
	v_mfma_f32_16x16x32_bf16 v[32:35], v[172:175], v[204:207], v[32:35]
	v_mfma_f32_16x16x32_bf16 v[60:63], v[138:141], v[68:71], v[60:63]
	v_mfma_f32_16x16x32_bf16 v[56:59], v[176:179], v[68:71], v[56:59]
	v_mfma_f32_16x16x32_bf16 v[52:55], v[138:141], v[84:87], v[52:55]
	v_mfma_f32_16x16x32_bf16 v[48:51], v[176:179], v[84:87], v[48:51]
	v_mfma_f32_16x16x32_bf16 v[44:47], v[138:141], v[200:203], v[44:47]
	v_mfma_f32_16x16x32_bf16 v[40:43], v[176:179], v[200:203], v[40:43]
	v_mfma_f32_16x16x32_bf16 v[36:39], v[138:141], v[208:211], v[36:39]
	v_mfma_f32_16x16x32_bf16 v[32:35], v[176:179], v[208:211], v[32:35]
	v_mfma_f32_16x16x32_bf16 v[28:31], v[212:215], v[64:67], v[28:31]
	v_mfma_f32_16x16x32_bf16 v[24:27], v[220:223], v[64:67], v[24:27]
	v_mfma_f32_16x16x32_bf16 v[12:15], v[212:215], v[196:199], v[12:15]
	v_mfma_f32_16x16x32_bf16 v[8:11], v[220:223], v[196:199], v[8:11]
	v_mfma_f32_16x16x32_bf16 v[20:23], v[212:215], v[80:83], v[20:23]
	v_mfma_f32_16x16x32_bf16 v[16:19], v[220:223], v[80:83], v[16:19]
	v_mfma_f32_16x16x32_bf16 v[4:7], v[212:215], v[204:207], v[4:7]
	v_mfma_f32_16x16x32_bf16 v[0:3], v[220:223], v[204:207], v[0:3]
	v_mfma_f32_16x16x32_bf16 v[28:31], v[216:219], v[68:71], v[28:31]
	v_mfma_f32_16x16x32_bf16 v[24:27], v[158:161], v[68:71], v[24:27]
	v_mfma_f32_16x16x32_bf16 v[12:15], v[216:219], v[200:203], v[12:15]
	v_mfma_f32_16x16x32_bf16 v[8:11], v[158:161], v[200:203], v[8:11]
	v_mfma_f32_16x16x32_bf16 v[134:137], v[216:219], v[84:87], v[20:23]
	v_mfma_f32_16x16x32_bf16 v[138:141], v[158:161], v[84:87], v[16:19]
	v_mfma_f32_16x16x32_bf16 v[170:173], v[216:219], v[208:211], v[4:7]
	v_mfma_f32_16x16x32_bf16 v[158:161], v[158:161], v[208:211], v[0:3]
	s_barrier
	s_nop 0
	ds_read_b128 v[0:3], v156
	ds_read_b128 v[4:7], v156 offset:1024
	ds_read_b128 v[16:19], v156 offset:2048
	ds_read_b128 v[174:177], v156 offset:3072
	ds_read_b128 v[20:23], v152 offset:32768
	ds_read_b128 v[196:199], v152 offset:33792
	ds_read_b128 v[200:203], v151 offset:32768
	ds_read_b128 v[204:207], v151 offset:33792
	ds_read_b128 v[208:211], v150 offset:32768
	ds_read_b128 v[212:215], v150 offset:33792
	ds_read_b128 v[216:219], v149 offset:32768
	ds_read_b128 v[220:223], v149 offset:33792
	s_waitcnt vmcnt(2)
	s_barrier
; #define LDA(dst, b, h) for (int m = 0; m < 4; ++m) for (int k = 0; k < 2; ++k) \
;     dst[m][k] = *reinterpret_cast<const bf16x8*>((char*)SA(b, h) + lds_byte(wr * 64 + m * 16 + fr, k * 32 + fq * 8))
; #define LDB(dst, b, h) for (int n = 0; n < 2; ++n) for (int k = 0; k < 2; ++k) \
;     dst[n][k] = *reinterpret_cast<const bf16x8*>((char*)SB(b, h) + lds_byte(wc * 32 + n * 16 + fr, k * 32 + fq * 8))
; #define MMA(ai, bj, At_, Bt_) do { __builtin_amdgcn_s_setprio(1); \
;     for (int k = 0; k < 2; ++k) for (int m = 0; m < 4; ++m) for (int n = 0; n < 2; ++n) \
;       acc[ai][bj][m][n] = __builtin_amdgcn_mfma_f32_16x16x32_bf16(At_[m][k], Bt_[n][k], acc[ai][bj][m][n], 0, 0, 0); \
;     __builtin_amdgcn_s_setprio(0); } while (0)
; #define WAIT_V(n) asm volatile("s_waitcnt vmcnt(" #n ")" ::: "memory")
; #define WAIT_L(n) asm volatile("s_waitcnt lgkmcnt(" #n ")" ::: "memory")
; #define BAR __builtin_amdgcn_s_barrier()
; template <int EPI, int lda, int ldb, int N, int K>
; __device__ __forceinline__ void gemm_phase(const u16* __restrict__ A, const u16* __restrict__ Bt, const GemmEpi ep, int wv) {
;     ...
;     { LDB(B0, 1, 0); LDA(At, 1, 0); WAIT_V(2); BAR; WAIT_L(0); MMA(0, 0, At, B0); BAR;
;       LDB(B1, 1, 1); WAIT_V(0); BAR; WAIT_L(0); MMA(0, 1, At, B1); BAR;
;       LDA(At, 1, 1); BAR; WAIT_L(0); MMA(1, 0, At, B0); MMA(1, 1, At, B1); BAR; }
;     if (wr == 0) BAR;
	s_waitcnt lgkmcnt(0)
	s_waitcnt lgkmcnt(0)
	v_mfma_f32_16x16x32_bf16 v[64:67], v[0:3], v[20:23], v[124:127]
	v_mfma_f32_16x16x32_bf16 v[68:71], v[16:19], v[20:23], v[120:123]
	v_mfma_f32_16x16x32_bf16 v[80:83], v[0:3], v[200:203], v[116:119]
	v_mfma_f32_16x16x32_bf16 v[84:87], v[16:19], v[200:203], v[112:115]
	v_mfma_f32_16x16x32_bf16 v[108:111], v[0:3], v[208:211], v[108:111]
	v_mfma_f32_16x16x32_bf16 v[104:107], v[16:19], v[208:211], v[104:107]
	v_mfma_f32_16x16x32_bf16 v[120:123], v[0:3], v[216:219], v[100:103]
	v_mfma_f32_16x16x32_bf16 v[124:127], v[16:19], v[216:219], v[96:99]
	v_mfma_f32_16x16x32_bf16 v[116:119], v[4:7], v[196:199], v[64:67]
	v_mfma_f32_16x16x32_bf16 v[112:115], v[174:177], v[196:199], v[68:71]
	v_mfma_f32_16x16x32_bf16 v[100:103], v[4:7], v[204:207], v[80:83]
	v_mfma_f32_16x16x32_bf16 v[96:99], v[174:177], v[204:207], v[84:87]
	v_mfma_f32_16x16x32_bf16 v[84:87], v[4:7], v[212:215], v[108:111]
	v_mfma_f32_16x16x32_bf16 v[80:83], v[174:177], v[212:215], v[104:107]
	v_mfma_f32_16x16x32_bf16 v[68:71], v[4:7], v[220:223], v[120:123]
	v_mfma_f32_16x16x32_bf16 v[64:67], v[174:177], v[220:223], v[124:127]
	s_barrier
	ds_read_b128 v[224:227], v154
	ds_read_b128 v[228:231], v154 offset:1024
	ds_read_b128 v[232:235], v154 offset:2048
	ds_read_b128 v[154:157], v154 offset:3072
	s_waitcnt vmcnt(0)
	s_barrier
	s_waitcnt lgkmcnt(0)
	s_waitcnt lgkmcnt(0)
	v_mfma_f32_16x16x32_bf16 v[92:95], v[224:227], v[20:23], v[92:95]
	v_mfma_f32_16x16x32_bf16 v[20:23], v[232:235], v[20:23], v[88:91]
	v_mfma_f32_16x16x32_bf16 v[88:91], v[224:227], v[200:203], v[180:183]
	v_mfma_f32_16x16x32_bf16 v[104:107], v[232:235], v[200:203], v[184:187]
	v_mfma_f32_16x16x32_bf16 v[76:79], v[224:227], v[208:211], v[76:79]
	v_mfma_f32_16x16x32_bf16 v[72:75], v[232:235], v[208:211], v[72:75]
	v_mfma_f32_16x16x32_bf16 v[178:181], v[224:227], v[216:219], v[188:191]
	v_mfma_f32_16x16x32_bf16 v[182:185], v[232:235], v[216:219], v[192:195]
	v_mfma_f32_16x16x32_bf16 v[124:127], v[228:231], v[196:199], v[92:95]
	v_mfma_f32_16x16x32_bf16 v[120:123], v[154:157], v[196:199], v[20:23]
	v_mfma_f32_16x16x32_bf16 v[108:111], v[228:231], v[204:207], v[88:91]
	v_mfma_f32_16x16x32_bf16 v[104:107], v[154:157], v[204:207], v[104:107]
	v_mfma_f32_16x16x32_bf16 v[92:95], v[228:231], v[212:215], v[76:79]
	v_mfma_f32_16x16x32_bf16 v[88:91], v[154:157], v[212:215], v[72:75]
	v_mfma_f32_16x16x32_bf16 v[76:79], v[228:231], v[220:223], v[178:181]
	v_mfma_f32_16x16x32_bf16 v[72:75], v[154:157], v[220:223], v[182:185]
	s_barrier
	ds_read_b128 v[178:181], v152 offset:49152
	ds_read_b128 v[182:185], v152 offset:50176
	ds_read_b128 v[186:189], v151 offset:49152
	ds_read_b128 v[190:193], v151 offset:50176
	ds_read_b128 v[194:197], v150 offset:49152
	ds_read_b128 v[150:153], v150 offset:50176
	ds_read_b128 v[198:201], v149 offset:49152
	ds_read_b128 v[202:205], v149 offset:50176
	s_barrier
	s_waitcnt lgkmcnt(0)
	s_waitcnt lgkmcnt(0)
	v_mfma_f32_16x16x32_bf16 v[20:23], v[0:3], v[178:181], v[60:63]
	v_mfma_f32_16x16x32_bf16 v[56:59], v[16:19], v[178:181], v[56:59]
	v_mfma_f32_16x16x32_bf16 v[60:63], v[0:3], v[186:189], v[52:55]
	v_mfma_f32_16x16x32_bf16 v[206:209], v[16:19], v[186:189], v[48:51]
	v_mfma_f32_16x16x32_bf16 v[44:47], v[0:3], v[194:197], v[44:47]
	v_mfma_f32_16x16x32_bf16 v[40:43], v[16:19], v[194:197], v[40:43]
	v_mfma_f32_16x16x32_bf16 v[0:3], v[0:3], v[198:201], v[36:39]
	v_mfma_f32_16x16x32_bf16 v[210:213], v[16:19], v[198:201], v[32:35]
	v_mfma_f32_16x16x32_bf16 v[52:55], v[4:7], v[182:185], v[20:23]
	v_mfma_f32_16x16x32_bf16 v[48:51], v[174:177], v[182:185], v[56:59]
	v_mfma_f32_16x16x32_bf16 v[36:39], v[4:7], v[190:193], v[60:63]
	v_mfma_f32_16x16x32_bf16 v[32:35], v[174:177], v[190:193], v[206:209]
	v_mfma_f32_16x16x32_bf16 v[20:23], v[4:7], v[150:153], v[44:47]
	v_mfma_f32_16x16x32_bf16 v[16:19], v[174:177], v[150:153], v[40:43]
	v_mfma_f32_16x16x32_bf16 v[4:7], v[4:7], v[202:205], v[0:3]
	v_mfma_f32_16x16x32_bf16 v[0:3], v[174:177], v[202:205], v[210:213]
	v_mfma_f32_16x16x32_bf16 v[28:31], v[224:227], v[178:181], v[28:31]
	v_mfma_f32_16x16x32_bf16 v[24:27], v[232:235], v[178:181], v[24:27]
	v_mfma_f32_16x16x32_bf16 v[40:43], v[224:227], v[186:189], v[134:137]
	v_mfma_f32_16x16x32_bf16 v[134:137], v[232:235], v[186:189], v[138:141]
	v_mfma_f32_16x16x32_bf16 v[12:15], v[224:227], v[194:197], v[12:15]
	v_mfma_f32_16x16x32_bf16 v[8:11], v[232:235], v[194:197], v[8:11]
	v_mfma_f32_16x16x32_bf16 v[138:141], v[224:227], v[198:201], v[170:173]
	v_mfma_f32_16x16x32_bf16 v[158:161], v[232:235], v[198:201], v[158:161]
	v_mfma_f32_16x16x32_bf16 v[60:63], v[228:231], v[182:185], v[28:31]
	v_mfma_f32_16x16x32_bf16 v[56:59], v[154:157], v[182:185], v[24:27]
	v_mfma_f32_16x16x32_bf16 v[44:47], v[228:231], v[190:193], v[40:43]
	v_mfma_f32_16x16x32_bf16 v[40:43], v[154:157], v[190:193], v[134:137]
	v_mfma_f32_16x16x32_bf16 v[28:31], v[228:231], v[150:153], v[12:15]
	v_mfma_f32_16x16x32_bf16 v[24:27], v[154:157], v[150:153], v[8:11]
	v_mfma_f32_16x16x32_bf16 v[12:15], v[228:231], v[202:205], v[138:141]
	v_mfma_f32_16x16x32_bf16 v[8:11], v[154:157], v[202:205], v[158:161]
	v_cmp_gt_u32_e32 vcc, s66, v130
	s_barrier
	s_and_saveexec_b64 s[50:51], vcc
	s_cbranch_execz .LBB0_773
	s_barrier

; #define STAGE(P, BASE, LD, br, kt) do { const char* _g = (const char*)((BASE) + (size_t)(br) * (LD) + (size_t)(kt) * 64); \
;     for (int _i = 0; _i < 2; ++_i) { int _b = tidx * 16 + _i * 8192; int _r, _c; stage_rc(_b, _r, _c); \
;       __builtin_amdgcn_global_load_lds((const unsigned*)(_g + (unsigned)((_r * (LD) + _c) * 2)), (unsigned*)((char*)(P) + _b), 16, 0, 0); } } while (0)
; #define LDA(dst, b, h) for (int m = 0; m < 4; ++m) for (int k = 0; k < 2; ++k) \
;     dst[m][k] = *reinterpret_cast<const bf16x8*>((char*)SA(b, h) + lds_byte(wr * 64 + m * 16 + fr, k * 32 + fq * 8))
; #define LDB(dst, b, h) for (int n = 0; n < 2; ++n) for (int k = 0; k < 2; ++k) \
;     dst[n][k] = *reinterpret_cast<const bf16x8*>((char*)SB(b, h) + lds_byte(wc * 32 + n * 16 + fr, k * 32 + fq * 8))
; #define MMA(ai, bj, At_, Bt_) do { __builtin_amdgcn_s_setprio(1); \
;     for (int k = 0; k < 2; ++k) for (int m = 0; m < 4; ++m) for (int n = 0; n < 2; ++n) \
;       acc[ai][bj][m][n] = __builtin_amdgcn_mfma_f32_16x16x32_bf16(At_[m][k], Bt_[n][k], acc[ai][bj][m][n], 0, 0, 0); \
;     __builtin_amdgcn_s_setprio(0); } while (0)
; #define WAIT_L(n) asm volatile("s_waitcnt lgkmcnt(" #n ")" ::: "memory")
; #define BAR __builtin_amdgcn_s_barrier()
; #define SCHED __builtin_amdgcn_sched_barrier(0)
; template <int EPI, int lda, int ldb, int N, int K>
; __device__ __forceinline__ void gemm_phase(const u16* __restrict__ A, const u16* __restrict__ Bt, const GemmEpi ep, int wv) {
;     ...
;       LDB(B0, 0, 0); SCHED; LDA(At, 0, 0); STAGE(SA(1, 1), Ab, lda, brow + HALF, t + 1);
;       WAIT_L(8); BAR; WAIT_L(0); MMA(0, 0, At, B0); BAR; SCHED;
;       LDB(B1, 0, 1); STAGE(SB(0, 0), Bt, ldb, bcol, t + 2);
;       BAR; WAIT_L(0); MMA(0, 1, At, B1); BAR;
;       LDA(At, 0, 1); STAGE(SA(0, 0), Ab, lda, brow, t + 2);
;       BAR; WAIT_L(0); MMA(1, 0, At, B0); BAR; SCHED;
;       STAGE(SB(0, 1), Bt, ldb, bcol + HALF, t + 2);
.LBB0_838:
	ds_read_b128 v[168:171], v164
	ds_read_b128 v[174:177], v164 offset:1024
	ds_read_b128 v[178:181], v164 offset:2048
	ds_read_b128 v[182:185], v164 offset:3072
	v_add_u32_e32 v172, 0xc000, v147
	v_lshl_add_u64 v[238:239], v[136:137], 0, s[50:51]
	v_readfirstlane_b32 s73, v172
	v_add_u32_e32 v173, 0xe000, v147
	v_lshl_add_u64 v[166:167], v[238:239], 0, s[22:23]
	s_mov_b32 m0, s73
	v_lshl_add_u64 v[240:241], v[134:135], 0, s[50:51]
	v_readfirstlane_b32 s73, v173
	global_load_lds_dwordx4 v[166:167], off
	v_lshl_add_u64 v[166:167], v[240:241], 0, s[22:23]
	s_mov_b32 m0, s73
	s_nop 0
	global_load_lds_dwordx4 v[166:167], off
	ds_read_b128 v[186:189], v155
	ds_read_b128 v[190:193], v155 offset:1024
	ds_read_b128 v[194:197], v154
	ds_read_b128 v[198:201], v154 offset:1024
	ds_read_b128 v[202:205], v153
	ds_read_b128 v[206:209], v153 offset:1024
	ds_read_b128 v[210:213], v152
	ds_read_b128 v[214:217], v152 offset:1024
	s_waitcnt lgkmcnt(8)
	s_barrier
	s_waitcnt lgkmcnt(0)
	s_waitcnt lgkmcnt(0)
	v_mfma_f32_16x16x32_bf16 v[124:127], v[168:171], v[186:189], v[124:127]
	v_mfma_f32_16x16x32_bf16 v[120:123], v[178:181], v[186:189], v[120:123]
	v_mfma_f32_16x16x32_bf16 v[116:119], v[168:171], v[194:197], v[116:119]
	v_mfma_f32_16x16x32_bf16 v[112:115], v[178:181], v[194:197], v[112:115]
	v_mfma_f32_16x16x32_bf16 v[108:111], v[168:171], v[202:205], v[108:111]
	v_mfma_f32_16x16x32_bf16 v[104:107], v[178:181], v[202:205], v[104:107]
	v_mfma_f32_16x16x32_bf16 v[100:103], v[168:171], v[210:213], v[100:103]
	v_mfma_f32_16x16x32_bf16 v[96:99], v[178:181], v[210:213], v[96:99]
	v_mfma_f32_16x16x32_bf16 v[124:127], v[174:177], v[190:193], v[124:127]
	v_mfma_f32_16x16x32_bf16 v[120:123], v[182:185], v[190:193], v[120:123]
	v_mfma_f32_16x16x32_bf16 v[116:119], v[174:177], v[198:201], v[116:119]
	v_mfma_f32_16x16x32_bf16 v[112:115], v[182:185], v[198:201], v[112:115]
	v_mfma_f32_16x16x32_bf16 v[108:111], v[174:177], v[206:209], v[108:111]
	v_mfma_f32_16x16x32_bf16 v[104:107], v[182:185], v[206:209], v[104:107]
	v_mfma_f32_16x16x32_bf16 v[100:103], v[174:177], v[214:217], v[100:103]
	v_mfma_f32_16x16x32_bf16 v[96:99], v[182:185], v[214:217], v[96:99]
	s_barrier
	v_add_u32_e32 v165, s63, v156
	v_lshl_add_u64 v[242:243], v[144:145], 0, s[50:51]
	v_readfirstlane_b32 s73, v165
	v_lshl_add_u64 v[166:167], v[242:243], 0, s[24:25]
	s_mov_b32 m0, s73
	global_load_lds_dwordx4 v[166:167], off
	v_add_u32_e32 v166, 0x2000, v165
	v_lshl_add_u64 v[244:245], v[142:143], 0, s[50:51]
	v_readfirstlane_b32 s73, v166
	v_lshl_add_u64 v[234:235], v[244:245], 0, s[24:25]
	s_mov_b32 m0, s73
	s_nop 0
	global_load_lds_dwordx4 v[234:235], off
	ds_read_b128 v[218:221], v163
	ds_read_b128 v[222:225], v163 offset:1024
	ds_read_b128 v[226:229], v163 offset:2048
	ds_read_b128 v[230:233], v163 offset:3072
	s_barrier
	s_waitcnt lgkmcnt(0)
	s_waitcnt lgkmcnt(0)
	v_mfma_f32_16x16x32_bf16 v[92:95], v[218:221], v[186:189], v[92:95]
	v_mfma_f32_16x16x32_bf16 v[88:91], v[226:229], v[186:189], v[88:91]
	v_mfma_f32_16x16x32_bf16 v[84:87], v[218:221], v[194:197], v[84:87]
	v_mfma_f32_16x16x32_bf16 v[80:83], v[226:229], v[194:197], v[80:83]
	v_mfma_f32_16x16x32_bf16 v[76:79], v[218:221], v[202:205], v[76:79]
	v_mfma_f32_16x16x32_bf16 v[72:75], v[226:229], v[202:205], v[72:75]
	v_mfma_f32_16x16x32_bf16 v[68:71], v[218:221], v[210:213], v[68:71]
	v_mfma_f32_16x16x32_bf16 v[64:67], v[226:229], v[210:213], v[64:67]
	v_mfma_f32_16x16x32_bf16 v[92:95], v[222:225], v[190:193], v[92:95]
	v_mfma_f32_16x16x32_bf16 v[88:91], v[230:233], v[190:193], v[88:91]
	v_mfma_f32_16x16x32_bf16 v[84:87], v[222:225], v[198:201], v[84:87]
	v_mfma_f32_16x16x32_bf16 v[80:83], v[230:233], v[198:201], v[80:83]
	v_mfma_f32_16x16x32_bf16 v[76:79], v[222:225], v[206:209], v[76:79]
	v_mfma_f32_16x16x32_bf16 v[72:75], v[230:233], v[206:209], v[72:75]
	v_mfma_f32_16x16x32_bf16 v[68:71], v[222:225], v[214:217], v[68:71]
	v_mfma_f32_16x16x32_bf16 v[64:67], v[230:233], v[214:217], v[64:67]
	v_readfirstlane_b32 s73, v147
	v_add_u32_e32 v167, 0x2000, v147
	v_lshl_add_u64 v[234:235], v[238:239], 0, s[26:27]
	s_mov_b32 m0, s73
	v_readfirstlane_b32 s73, v167
	s_barrier
	global_load_lds_dwordx4 v[234:235], off
	v_lshl_add_u64 v[234:235], v[240:241], 0, s[26:27]
	s_mov_b32 m0, s73
	s_nop 0
	global_load_lds_dwordx4 v[234:235], off
	ds_read_b128 v[186:189], v155 offset:16384
	ds_read_b128 v[190:193], v155 offset:17408
	ds_read_b128 v[194:197], v154 offset:16384
	ds_read_b128 v[198:201], v154 offset:17408
	ds_read_b128 v[202:205], v153 offset:16384
	ds_read_b128 v[206:209], v153 offset:17408
	ds_read_b128 v[210:213], v152 offset:16384
	ds_read_b128 v[214:217], v152 offset:17408
	s_barrier
	s_waitcnt lgkmcnt(0)
	s_waitcnt lgkmcnt(0)
	v_mfma_f32_16x16x32_bf16 v[60:63], v[168:171], v[186:189], v[60:63]
	v_mfma_f32_16x16x32_bf16 v[56:59], v[178:181], v[186:189], v[56:59]
	v_mfma_f32_16x16x32_bf16 v[52:55], v[168:171], v[194:197], v[52:55]
	v_mfma_f32_16x16x32_bf16 v[48:51], v[178:181], v[194:197], v[48:51]
	v_mfma_f32_16x16x32_bf16 v[44:47], v[168:171], v[202:205], v[44:47]
	v_mfma_f32_16x16x32_bf16 v[40:43], v[178:181], v[202:205], v[40:43]
	v_mfma_f32_16x16x32_bf16 v[36:39], v[168:171], v[210:213], v[36:39]
	v_mfma_f32_16x16x32_bf16 v[32:35], v[178:181], v[210:213], v[32:35]
	v_mfma_f32_16x16x32_bf16 v[60:63], v[174:177], v[190:193], v[60:63]
	v_mfma_f32_16x16x32_bf16 v[56:59], v[182:185], v[190:193], v[56:59]
	v_mfma_f32_16x16x32_bf16 v[52:55], v[174:177], v[198:201], v[52:55]
	v_mfma_f32_16x16x32_bf16 v[48:51], v[182:185], v[198:201], v[48:51]
	v_mfma_f32_16x16x32_bf16 v[44:47], v[174:177], v[206:209], v[44:47]
	v_mfma_f32_16x16x32_bf16 v[40:43], v[182:185], v[206:209], v[40:43]
	v_mfma_f32_16x16x32_bf16 v[36:39], v[174:177], v[214:217], v[36:39]
	v_mfma_f32_16x16x32_bf16 v[32:35], v[182:185], v[214:217], v[32:35]
	s_barrier
; #define STAGE(P, BASE, LD, br, kt) do { const char* _g = (const char*)((BASE) + (size_t)(br) * (LD) + (size_t)(kt) * 64); \
;     for (int _i = 0; _i < 2; ++_i) { int _b = tidx * 16 + _i * 8192; int _r, _c; stage_rc(_b, _r, _c); \
;       __builtin_amdgcn_global_load_lds((const unsigned*)(_g + (unsigned)((_r * (LD) + _c) * 2)), (unsigned*)((char*)(P) + _b), 16, 0, 0); } } while (0)
; #define LDA(dst, b, h) for (int m = 0; m < 4; ++m) for (int k = 0; k < 2; ++k) \
;     dst[m][k] = *reinterpret_cast<const bf16x8*>((char*)SA(b, h) + lds_byte(wr * 64 + m * 16 + fr, k * 32 + fq * 8))
; #define LDB(dst, b, h) for (int n = 0; n < 2; ++n) for (int k = 0; k < 2; ++k) \
;     dst[n][k] = *reinterpret_cast<const bf16x8*>((char*)SB(b, h) + lds_byte(wc * 32 + n * 16 + fr, k * 32 + fq * 8))
; #define MMA(ai, bj, At_, Bt_) do { __builtin_amdgcn_s_setprio(1); \
;     for (int k = 0; k < 2; ++k) for (int m = 0; m < 4; ++m) for (int n = 0; n < 2; ++n) \
;       acc[ai][bj][m][n] = __builtin_amdgcn_mfma_f32_16x16x32_bf16(At_[m][k], Bt_[n][k], acc[ai][bj][m][n], 0, 0, 0); \
;     __builtin_amdgcn_s_setprio(0); } while (0)
; #define WAIT_V(n) asm volatile("s_waitcnt vmcnt(" #n ")" ::: "memory")
; #define WAIT_L(n) asm volatile("s_waitcnt lgkmcnt(" #n ")" ::: "memory")
; #define BAR __builtin_amdgcn_s_barrier()
; #define SCHED __builtin_amdgcn_sched_barrier(0)
; template <int EPI, int lda, int ldb, int N, int K>
; __device__ __forceinline__ void gemm_phase(const u16* __restrict__ A, const u16* __restrict__ Bt, const GemmEpi ep, int wv) {
;     ...
;       STAGE(SB(0, 1), Bt, ldb, bcol + HALF, t + 2);
;       WAIT_V(6); BAR; MMA(1, 1, At, B1); BAR;
;       LDB(B0, 1, 0); SCHED; LDA(At, 1, 0); STAGE(SA(0, 1), Ab, lda, brow + HALF, t + 2);
;       WAIT_L(8); BAR; WAIT_L(0); MMA(0, 0, At, B0); BAR; SCHED;
;       LDB(B1, 1, 1); STAGE(SB(1, 0), Bt, ldb, bcol, t + 3);
;       BAR; WAIT_L(0); MMA(0, 1, At, B1); BAR;
;       LDA(At, 1, 1); STAGE(SA(1, 0), Ab, lda, brow, t + 3);
	v_add_u32_e32 v168, s64, v156
	v_lshl_add_u64 v[246:247], v[140:141], 0, s[50:51]
	v_readfirstlane_b32 s73, v168
	v_add_u32_e32 v169, 0x2000, v168
	v_lshl_add_u64 v[170:171], v[246:247], 0, s[40:41]
	s_mov_b32 m0, s73
	v_lshl_add_u64 v[248:249], v[138:139], 0, s[50:51]
	v_readfirstlane_b32 s73, v169
	global_load_lds_dwordx4 v[170:171], off
	v_lshl_add_u64 v[170:171], v[248:249], 0, s[40:41]
	s_mov_b32 m0, s73
	s_nop 0
	global_load_lds_dwordx4 v[170:171], off
	s_waitcnt vmcnt(6)
	s_barrier
	v_mfma_f32_16x16x32_bf16 v[28:31], v[218:221], v[186:189], v[28:31]
	v_mfma_f32_16x16x32_bf16 v[24:27], v[226:229], v[186:189], v[24:27]
	v_mfma_f32_16x16x32_bf16 v[20:23], v[218:221], v[194:197], v[20:23]
	v_mfma_f32_16x16x32_bf16 v[16:19], v[226:229], v[194:197], v[16:19]
	v_mfma_f32_16x16x32_bf16 v[12:15], v[218:221], v[202:205], v[12:15]
	v_mfma_f32_16x16x32_bf16 v[8:11], v[226:229], v[202:205], v[8:11]
	v_mfma_f32_16x16x32_bf16 v[4:7], v[218:221], v[210:213], v[4:7]
	v_mfma_f32_16x16x32_bf16 v[0:3], v[226:229], v[210:213], v[0:3]
	v_mfma_f32_16x16x32_bf16 v[28:31], v[222:225], v[190:193], v[28:31]
	v_mfma_f32_16x16x32_bf16 v[24:27], v[230:233], v[190:193], v[24:27]
	v_mfma_f32_16x16x32_bf16 v[20:23], v[222:225], v[198:201], v[20:23]
	v_mfma_f32_16x16x32_bf16 v[16:19], v[230:233], v[198:201], v[16:19]
	v_mfma_f32_16x16x32_bf16 v[12:15], v[222:225], v[206:209], v[12:15]
	v_mfma_f32_16x16x32_bf16 v[8:11], v[230:233], v[206:209], v[8:11]
	v_mfma_f32_16x16x32_bf16 v[4:7], v[222:225], v[214:217], v[4:7]
	v_mfma_f32_16x16x32_bf16 v[0:3], v[230:233], v[214:217], v[0:3]
	s_barrier
	ds_read_b128 v[174:177], v159
	ds_read_b128 v[178:181], v159 offset:1024
	ds_read_b128 v[182:185], v159 offset:2048
	ds_read_b128 v[186:189], v159 offset:3072
	v_add_u32_e32 v170, 0x4000, v147
	v_add_u32_e32 v171, 0x6000, v147
	v_readfirstlane_b32 s73, v170
	v_lshl_add_u64 v[222:223], v[238:239], 0, s[42:43]
	s_mov_b32 m0, s73
	v_readfirstlane_b32 s73, v171
	global_load_lds_dwordx4 v[222:223], off
	v_lshl_add_u64 v[222:223], v[240:241], 0, s[42:43]
	s_mov_b32 m0, s73
	s_nop 0
	global_load_lds_dwordx4 v[222:223], off
	ds_read_b128 v[190:193], v155 offset:32768
	ds_read_b128 v[194:197], v155 offset:33792
	ds_read_b128 v[198:201], v154 offset:32768
	ds_read_b128 v[202:205], v154 offset:33792
	ds_read_b128 v[206:209], v153 offset:32768
	ds_read_b128 v[210:213], v153 offset:33792
	ds_read_b128 v[214:217], v152 offset:32768
	ds_read_b128 v[218:221], v152 offset:33792
	s_waitcnt lgkmcnt(8)
	s_barrier
	s_waitcnt lgkmcnt(0)
	s_waitcnt lgkmcnt(0)
	v_mfma_f32_16x16x32_bf16 v[124:127], v[174:177], v[190:193], v[124:127]
	v_mfma_f32_16x16x32_bf16 v[120:123], v[182:185], v[190:193], v[120:123]
	v_mfma_f32_16x16x32_bf16 v[116:119], v[174:177], v[198:201], v[116:119]
	v_mfma_f32_16x16x32_bf16 v[112:115], v[182:185], v[198:201], v[112:115]
	v_mfma_f32_16x16x32_bf16 v[108:111], v[174:177], v[206:209], v[108:111]
	v_mfma_f32_16x16x32_bf16 v[104:107], v[182:185], v[206:209], v[104:107]
	v_mfma_f32_16x16x32_bf16 v[100:103], v[174:177], v[214:217], v[100:103]
	v_mfma_f32_16x16x32_bf16 v[96:99], v[182:185], v[214:217], v[96:99]
	v_mfma_f32_16x16x32_bf16 v[124:127], v[178:181], v[194:197], v[124:127]
	v_mfma_f32_16x16x32_bf16 v[120:123], v[186:189], v[194:197], v[120:123]
	v_mfma_f32_16x16x32_bf16 v[116:119], v[178:181], v[202:205], v[116:119]
	v_mfma_f32_16x16x32_bf16 v[112:115], v[186:189], v[202:205], v[112:115]
	v_mfma_f32_16x16x32_bf16 v[108:111], v[178:181], v[210:213], v[108:111]
	v_mfma_f32_16x16x32_bf16 v[104:107], v[186:189], v[210:213], v[104:107]
	v_mfma_f32_16x16x32_bf16 v[100:103], v[178:181], v[218:221], v[100:103]
	v_mfma_f32_16x16x32_bf16 v[96:99], v[186:189], v[218:221], v[96:99]
	s_barrier
	v_readfirstlane_b32 s73, v158
	v_lshl_add_u64 v[242:243], v[242:243], 0, s[44:45]
	s_mov_b32 m0, s73
	global_load_lds_dwordx4 v[242:243], off
	v_lshl_add_u64 v[242:243], v[244:245], 0, s[44:45]
	v_add_u32_e32 v244, 0x2000, v158
	s_nop 0
	v_readfirstlane_b32 s73, v244
	s_mov_b32 m0, s73
	s_nop 0
	global_load_lds_dwordx4 v[242:243], off
	ds_read_b128 v[222:225], v157
	ds_read_b128 v[226:229], v157 offset:1024
	ds_read_b128 v[230:233], v157 offset:2048
	ds_read_b128 v[234:237], v157 offset:3072
	s_barrier
	s_waitcnt lgkmcnt(0)
	s_waitcnt lgkmcnt(0)
	v_mfma_f32_16x16x32_bf16 v[92:95], v[222:225], v[190:193], v[92:95]
	v_mfma_f32_16x16x32_bf16 v[88:91], v[230:233], v[190:193], v[88:91]
	v_mfma_f32_16x16x32_bf16 v[84:87], v[222:225], v[198:201], v[84:87]
	v_mfma_f32_16x16x32_bf16 v[80:83], v[230:233], v[198:201], v[80:83]
	v_mfma_f32_16x16x32_bf16 v[76:79], v[222:225], v[206:209], v[76:79]
	v_mfma_f32_16x16x32_bf16 v[72:75], v[230:233], v[206:209], v[72:75]
	v_mfma_f32_16x16x32_bf16 v[68:71], v[222:225], v[214:217], v[68:71]
	v_mfma_f32_16x16x32_bf16 v[64:67], v[230:233], v[214:217], v[64:67]
	v_mfma_f32_16x16x32_bf16 v[92:95], v[226:229], v[194:197], v[92:95]
	v_mfma_f32_16x16x32_bf16 v[88:91], v[234:237], v[194:197], v[88:91]
	v_mfma_f32_16x16x32_bf16 v[84:87], v[226:229], v[202:205], v[84:87]
	v_mfma_f32_16x16x32_bf16 v[80:83], v[234:237], v[202:205], v[80:83]
	v_mfma_f32_16x16x32_bf16 v[76:79], v[226:229], v[210:213], v[76:79]
	v_mfma_f32_16x16x32_bf16 v[72:75], v[234:237], v[210:213], v[72:75]
	v_mfma_f32_16x16x32_bf16 v[68:71], v[226:229], v[218:221], v[68:71]
	v_mfma_f32_16x16x32_bf16 v[64:67], v[234:237], v[218:221], v[64:67]
	v_readfirstlane_b32 s73, v160
	v_lshl_add_u64 v[238:239], v[238:239], 0, s[46:47]
	s_mov_b32 m0, s73
	v_readfirstlane_b32 s73, v161
	s_barrier
; #define STAGE(P, BASE, LD, br, kt) do { const char* _g = (const char*)((BASE) + (size_t)(br) * (LD) + (size_t)(kt) * 64); \
;     for (int _i = 0; _i < 2; ++_i) { int _b = tidx * 16 + _i * 8192; int _r, _c; stage_rc(_b, _r, _c); \
;       __builtin_amdgcn_global_load_lds((const unsigned*)(_g + (unsigned)((_r * (LD) + _c) * 2)), (unsigned*)((char*)(P) + _b), 16, 0, 0); } } while (0)
; #define LDA(dst, b, h) for (int m = 0; m < 4; ++m) for (int k = 0; k < 2; ++k) \
;     dst[m][k] = *reinterpret_cast<const bf16x8*>((char*)SA(b, h) + lds_byte(wr * 64 + m * 16 + fr, k * 32 + fq * 8))
; #define LDB(dst, b, h) for (int n = 0; n < 2; ++n) for (int k = 0; k < 2; ++k) \
;     dst[n][k] = *reinterpret_cast<const bf16x8*>((char*)SB(b, h) + lds_byte(wc * 32 + n * 16 + fr, k * 32 + fq * 8))
; #define MMA(ai, bj, At_, Bt_) do { __builtin_amdgcn_s_setprio(1); \
;     for (int k = 0; k < 2; ++k) for (int m = 0; m < 4; ++m) for (int n = 0; n < 2; ++n) \
;       acc[ai][bj][m][n] = __builtin_amdgcn_mfma_f32_16x16x32_bf16(At_[m][k], Bt_[n][k], acc[ai][bj][m][n], 0, 0, 0); \
;     __builtin_amdgcn_s_setprio(0); } while (0)
; #define WAIT_V(n) asm volatile("s_waitcnt vmcnt(" #n ")" ::: "memory")
; #define WAIT_L(n) asm volatile("s_waitcnt lgkmcnt(" #n ")" ::: "memory")
; #define BAR __builtin_amdgcn_s_barrier()
; #define SCHED __builtin_amdgcn_sched_barrier(0)
; template <int EPI, int lda, int ldb, int N, int K>
; __device__ __forceinline__ void gemm_phase(const u16* __restrict__ A, const u16* __restrict__ Bt, const GemmEpi ep, int wv) {
;     ...
;       LDA(At, 1, 1); STAGE(SA(1, 0), Ab, lda, brow, t + 3);
;       BAR; WAIT_L(0); MMA(1, 0, At, B0); BAR; SCHED;
;       STAGE(SB(1, 1), Bt, ldb, bcol + HALF, t + 3);
;       WAIT_V(6); BAR; MMA(1, 1, At, B1); BAR;
;     }
;     { LDB(B0, 0, 0); LDA(At, 0, 0); STAGE(SA(1, 1), Ab, lda, brow + HALF, nt - 1);
;       BAR; WAIT_L(0); MMA(0, 0, At, B0); BAR;
;       LDB(B1, 0, 1); BAR; WAIT_L(0); MMA(0, 1, At, B1); BAR;
	global_load_lds_dwordx4 v[238:239], off
	v_lshl_add_u64 v[238:239], v[240:241], 0, s[46:47]
	s_mov_b32 m0, s73
	s_nop 0
	global_load_lds_dwordx4 v[238:239], off
	ds_read_b128 v[190:193], v155 offset:49152
	ds_read_b128 v[194:197], v155 offset:50176
	ds_read_b128 v[198:201], v154 offset:49152
	ds_read_b128 v[202:205], v154 offset:50176
	ds_read_b128 v[206:209], v153 offset:49152
	ds_read_b128 v[210:213], v153 offset:50176
	ds_read_b128 v[214:217], v152 offset:49152
	ds_read_b128 v[218:221], v152 offset:50176
	s_barrier
	s_waitcnt lgkmcnt(0)
	s_waitcnt lgkmcnt(0)
	v_mfma_f32_16x16x32_bf16 v[60:63], v[174:177], v[190:193], v[60:63]
	v_mfma_f32_16x16x32_bf16 v[56:59], v[182:185], v[190:193], v[56:59]
	v_mfma_f32_16x16x32_bf16 v[52:55], v[174:177], v[198:201], v[52:55]
	v_mfma_f32_16x16x32_bf16 v[48:51], v[182:185], v[198:201], v[48:51]
	v_mfma_f32_16x16x32_bf16 v[44:47], v[174:177], v[206:209], v[44:47]
	v_mfma_f32_16x16x32_bf16 v[40:43], v[182:185], v[206:209], v[40:43]
	v_mfma_f32_16x16x32_bf16 v[36:39], v[174:177], v[214:217], v[36:39]
	v_mfma_f32_16x16x32_bf16 v[32:35], v[182:185], v[214:217], v[32:35]
	v_mfma_f32_16x16x32_bf16 v[60:63], v[178:181], v[194:197], v[60:63]
	v_mfma_f32_16x16x32_bf16 v[56:59], v[186:189], v[194:197], v[56:59]
	v_mfma_f32_16x16x32_bf16 v[52:55], v[178:181], v[202:205], v[52:55]
	v_mfma_f32_16x16x32_bf16 v[48:51], v[186:189], v[202:205], v[48:51]
	v_mfma_f32_16x16x32_bf16 v[44:47], v[178:181], v[210:213], v[44:47]
	v_mfma_f32_16x16x32_bf16 v[40:43], v[186:189], v[210:213], v[40:43]
	v_mfma_f32_16x16x32_bf16 v[36:39], v[178:181], v[218:221], v[36:39]
	v_mfma_f32_16x16x32_bf16 v[32:35], v[186:189], v[218:221], v[32:35]
	s_barrier
	v_readfirstlane_b32 s73, v162
	v_add_u32_e32 v176, 0x2000, v162
	v_lshl_add_u64 v[174:175], v[246:247], 0, s[48:49]
	s_mov_b32 m0, s73
	v_readfirstlane_b32 s73, v176
	global_load_lds_dwordx4 v[174:175], off
	v_lshl_add_u64 v[174:175], v[248:249], 0, s[48:49]
	s_mov_b32 m0, s73
	s_nop 0
	global_load_lds_dwordx4 v[174:175], off
	s_waitcnt vmcnt(6)
	s_barrier
	v_mfma_f32_16x16x32_bf16 v[28:31], v[222:225], v[190:193], v[28:31]
	v_mfma_f32_16x16x32_bf16 v[24:27], v[230:233], v[190:193], v[24:27]
	v_mfma_f32_16x16x32_bf16 v[20:23], v[222:225], v[198:201], v[20:23]
	v_mfma_f32_16x16x32_bf16 v[16:19], v[230:233], v[198:201], v[16:19]
	v_mfma_f32_16x16x32_bf16 v[12:15], v[222:225], v[206:209], v[12:15]
	v_mfma_f32_16x16x32_bf16 v[8:11], v[230:233], v[206:209], v[8:11]
	v_mfma_f32_16x16x32_bf16 v[4:7], v[222:225], v[214:217], v[4:7]
	v_mfma_f32_16x16x32_bf16 v[0:3], v[230:233], v[214:217], v[0:3]
	v_mfma_f32_16x16x32_bf16 v[28:31], v[226:229], v[194:197], v[28:31]
	v_mfma_f32_16x16x32_bf16 v[24:27], v[234:237], v[194:197], v[24:27]
	v_mfma_f32_16x16x32_bf16 v[20:23], v[226:229], v[202:205], v[20:23]
	v_mfma_f32_16x16x32_bf16 v[16:19], v[234:237], v[202:205], v[16:19]
	v_mfma_f32_16x16x32_bf16 v[12:15], v[226:229], v[210:213], v[12:15]
	v_mfma_f32_16x16x32_bf16 v[8:11], v[234:237], v[210:213], v[8:11]
	v_mfma_f32_16x16x32_bf16 v[4:7], v[226:229], v[218:221], v[4:7]
	v_mfma_f32_16x16x32_bf16 v[0:3], v[234:237], v[218:221], v[0:3]
	s_add_i32 s72, s72, 2
	s_add_u32 s50, s50, 0x100
	s_addc_u32 s51, s51, 0
	s_cmpk_gt_u32 s72, 0x51
	s_barrier
	s_cbranch_scc0 .LBB0_838
	s_add_i32 s50, s18, 0x80
	s_mul_hi_i32 s51, s50, 0x2b00
	s_mulk_i32 s50, 0x2b00
	s_add_u32 s50, s56, s50
	s_addc_u32 s51, s57, s51
	s_add_u32 s50, s50, 0x2a80
	s_addc_u32 s51, s51, 0
	v_readfirstlane_b32 s72, v172
	v_lshl_add_u64 v[160:161], s[50:51], 0, v[128:129]
	s_mov_b32 m0, s72
	ds_read_b128 v[134:137], v164
	ds_read_b128 v[138:141], v164 offset:1024
	ds_read_b128 v[142:145], v164 offset:2048
	ds_read_b128 v[174:177], v164 offset:3072
	ds_read_b128 v[178:181], v155
	ds_read_b128 v[182:185], v155 offset:1024
	ds_read_b128 v[186:189], v154
	ds_read_b128 v[190:193], v154 offset:1024
	ds_read_b128 v[194:197], v153
	ds_read_b128 v[198:201], v153 offset:1024
	ds_read_b128 v[202:205], v152
	ds_read_b128 v[206:209], v152 offset:1024
	global_load_lds_dwordx4 v[160:161], off
	v_lshl_add_u64 v[160:161], s[50:51], 0, v[132:133]
	v_readfirstlane_b32 s50, v173
	s_mov_b32 m0, s50
	s_nop 0
	global_load_lds_dwordx4 v[160:161], off
	s_barrier
	s_waitcnt lgkmcnt(0)
	s_waitcnt lgkmcnt(0)
	v_mfma_f32_16x16x32_bf16 v[124:127], v[134:137], v[178:181], v[124:127]
	v_mfma_f32_16x16x32_bf16 v[120:123], v[142:145], v[178:181], v[120:123]
	v_mfma_f32_16x16x32_bf16 v[116:119], v[134:137], v[186:189], v[116:119]
	v_mfma_f32_16x16x32_bf16 v[112:115], v[142:145], v[186:189], v[112:115]
	v_mfma_f32_16x16x32_bf16 v[108:111], v[134:137], v[194:197], v[108:111]
	v_mfma_f32_16x16x32_bf16 v[104:107], v[142:145], v[194:197], v[104:107]
	v_mfma_f32_16x16x32_bf16 v[100:103], v[134:137], v[202:205], v[100:103]
	v_mfma_f32_16x16x32_bf16 v[96:99], v[142:145], v[202:205], v[96:99]
	v_mfma_f32_16x16x32_bf16 v[124:127], v[138:141], v[182:185], v[124:127]
	v_mfma_f32_16x16x32_bf16 v[120:123], v[174:177], v[182:185], v[120:123]
	v_mfma_f32_16x16x32_bf16 v[116:119], v[138:141], v[190:193], v[116:119]
	v_mfma_f32_16x16x32_bf16 v[112:115], v[174:177], v[190:193], v[112:115]
	v_mfma_f32_16x16x32_bf16 v[108:111], v[138:141], v[198:201], v[108:111]
	v_mfma_f32_16x16x32_bf16 v[104:107], v[174:177], v[198:201], v[104:107]
	v_mfma_f32_16x16x32_bf16 v[100:103], v[138:141], v[206:209], v[100:103]
	v_mfma_f32_16x16x32_bf16 v[96:99], v[174:177], v[206:209], v[96:99]
	s_barrier
	ds_read_b128 v[210:213], v163
	ds_read_b128 v[214:217], v163 offset:1024
	ds_read_b128 v[218:221], v163 offset:2048
	ds_read_b128 v[160:163], v163 offset:3072
	s_barrier
; #define LDA(dst, b, h) for (int m = 0; m < 4; ++m) for (int k = 0; k < 2; ++k) \
;     dst[m][k] = *reinterpret_cast<const bf16x8*>((char*)SA(b, h) + lds_byte(wr * 64 + m * 16 + fr, k * 32 + fq * 8))
; #define LDB(dst, b, h) for (int n = 0; n < 2; ++n) for (int k = 0; k < 2; ++k) \
;     dst[n][k] = *reinterpret_cast<const bf16x8*>((char*)SB(b, h) + lds_byte(wc * 32 + n * 16 + fr, k * 32 + fq * 8))
; #define MMA(ai, bj, At_, Bt_) do { __builtin_amdgcn_s_setprio(1); \
;     for (int k = 0; k < 2; ++k) for (int m = 0; m < 4; ++m) for (int n = 0; n < 2; ++n) \
;       acc[ai][bj][m][n] = __builtin_amdgcn_mfma_f32_16x16x32_bf16(At_[m][k], Bt_[n][k], acc[ai][bj][m][n], 0, 0, 0); \
;     __builtin_amdgcn_s_setprio(0); } while (0)
; #define WAIT_V(n) asm volatile("s_waitcnt vmcnt(" #n ")" ::: "memory")
; #define WAIT_L(n) asm volatile("s_waitcnt lgkmcnt(" #n ")" ::: "memory")
; #define BAR __builtin_amdgcn_s_barrier()
; template <int EPI, int lda, int ldb, int N, int K>
; __device__ __forceinline__ void gemm_phase(const u16* __restrict__ A, const u16* __restrict__ Bt, const GemmEpi ep, int wv) {
;     ...
;       LDB(B1, 0, 1); BAR; WAIT_L(0); MMA(0, 1, At, B1); BAR;
;       LDA(At, 0, 1); WAIT_V(4); BAR; WAIT_L(0); MMA(1, 0, At, B0); MMA(1, 1, At, B1); BAR; }
;     { LDB(B0, 1, 0); LDA(At, 1, 0); WAIT_V(2); BAR; WAIT_L(0); MMA(0, 0, At, B0); BAR;
	s_waitcnt lgkmcnt(0)
	s_waitcnt lgkmcnt(0)
	v_mfma_f32_16x16x32_bf16 v[92:95], v[210:213], v[178:181], v[92:95]
	v_mfma_f32_16x16x32_bf16 v[88:91], v[218:221], v[178:181], v[88:91]
	v_mfma_f32_16x16x32_bf16 v[76:79], v[210:213], v[194:197], v[76:79]
	v_mfma_f32_16x16x32_bf16 v[72:75], v[218:221], v[194:197], v[72:75]
	v_mfma_f32_16x16x32_bf16 v[84:87], v[210:213], v[186:189], v[84:87]
	v_mfma_f32_16x16x32_bf16 v[80:83], v[218:221], v[186:189], v[80:83]
	v_mfma_f32_16x16x32_bf16 v[68:71], v[210:213], v[202:205], v[68:71]
	v_mfma_f32_16x16x32_bf16 v[64:67], v[218:221], v[202:205], v[64:67]
	v_mfma_f32_16x16x32_bf16 v[92:95], v[214:217], v[182:185], v[92:95]
	v_mfma_f32_16x16x32_bf16 v[88:91], v[160:163], v[182:185], v[88:91]
	v_mfma_f32_16x16x32_bf16 v[76:79], v[214:217], v[198:201], v[76:79]
	v_mfma_f32_16x16x32_bf16 v[72:75], v[160:163], v[198:201], v[72:75]
	v_mfma_f32_16x16x32_bf16 v[178:181], v[214:217], v[190:193], v[84:87]
	v_mfma_f32_16x16x32_bf16 v[182:185], v[160:163], v[190:193], v[80:83]
	v_mfma_f32_16x16x32_bf16 v[186:189], v[214:217], v[206:209], v[68:71]
	v_mfma_f32_16x16x32_bf16 v[190:193], v[160:163], v[206:209], v[64:67]
	s_barrier
	s_nop 0
	ds_read_b128 v[64:67], v155 offset:16384
	ds_read_b128 v[68:71], v155 offset:17408
	ds_read_b128 v[80:83], v154 offset:16384
	ds_read_b128 v[84:87], v154 offset:17408
	ds_read_b128 v[194:197], v153 offset:16384
	ds_read_b128 v[198:201], v153 offset:17408
	ds_read_b128 v[202:205], v152 offset:16384
	ds_read_b128 v[206:209], v152 offset:17408
	s_waitcnt vmcnt(4)
	s_barrier
	s_waitcnt lgkmcnt(0)
	s_waitcnt lgkmcnt(0)
	v_mfma_f32_16x16x32_bf16 v[60:63], v[134:137], v[64:67], v[60:63]
	v_mfma_f32_16x16x32_bf16 v[56:59], v[142:145], v[64:67], v[56:59]
	v_mfma_f32_16x16x32_bf16 v[52:55], v[134:137], v[80:83], v[52:55]
	v_mfma_f32_16x16x32_bf16 v[48:51], v[142:145], v[80:83], v[48:51]
	v_mfma_f32_16x16x32_bf16 v[44:47], v[134:137], v[194:197], v[44:47]
	v_mfma_f32_16x16x32_bf16 v[40:43], v[142:145], v[194:197], v[40:43]
	v_mfma_f32_16x16x32_bf16 v[36:39], v[134:137], v[202:205], v[36:39]
	v_mfma_f32_16x16x32_bf16 v[32:35], v[142:145], v[202:205], v[32:35]
	v_mfma_f32_16x16x32_bf16 v[60:63], v[138:141], v[68:71], v[60:63]
	v_mfma_f32_16x16x32_bf16 v[56:59], v[174:177], v[68:71], v[56:59]
	v_mfma_f32_16x16x32_bf16 v[52:55], v[138:141], v[84:87], v[52:55]
	v_mfma_f32_16x16x32_bf16 v[48:51], v[174:177], v[84:87], v[48:51]
	v_mfma_f32_16x16x32_bf16 v[44:47], v[138:141], v[198:201], v[44:47]
	v_mfma_f32_16x16x32_bf16 v[40:43], v[174:177], v[198:201], v[40:43]
	v_mfma_f32_16x16x32_bf16 v[36:39], v[138:141], v[206:209], v[36:39]
	v_mfma_f32_16x16x32_bf16 v[32:35], v[174:177], v[206:209], v[32:35]
	v_mfma_f32_16x16x32_bf16 v[28:31], v[210:213], v[64:67], v[28:31]
	v_mfma_f32_16x16x32_bf16 v[16:19], v[218:221], v[80:83], v[16:19]
	v_mfma_f32_16x16x32_bf16 v[12:15], v[210:213], v[194:197], v[12:15]
	v_mfma_f32_16x16x32_bf16 v[0:3], v[218:221], v[202:205], v[0:3]
	v_mfma_f32_16x16x32_bf16 v[24:27], v[218:221], v[64:67], v[24:27]
	v_mfma_f32_16x16x32_bf16 v[20:23], v[210:213], v[80:83], v[20:23]
	v_mfma_f32_16x16x32_bf16 v[8:11], v[218:221], v[194:197], v[8:11]
	v_mfma_f32_16x16x32_bf16 v[4:7], v[210:213], v[202:205], v[4:7]
	v_mfma_f32_16x16x32_bf16 v[28:31], v[214:217], v[68:71], v[28:31]
	v_mfma_f32_16x16x32_bf16 v[16:19], v[160:163], v[84:87], v[16:19]
	v_mfma_f32_16x16x32_bf16 v[12:15], v[214:217], v[198:201], v[12:15]
	v_mfma_f32_16x16x32_bf16 v[0:3], v[160:163], v[206:209], v[0:3]
	v_mfma_f32_16x16x32_bf16 v[134:137], v[160:163], v[68:71], v[24:27]
	v_mfma_f32_16x16x32_bf16 v[138:141], v[214:217], v[84:87], v[20:23]
	v_mfma_f32_16x16x32_bf16 v[142:145], v[160:163], v[198:201], v[8:11]
	v_mfma_f32_16x16x32_bf16 v[172:175], v[214:217], v[206:209], v[4:7]
	s_barrier
	s_nop 0
	ds_read_b128 v[4:7], v159
	ds_read_b128 v[8:11], v159 offset:1024
	ds_read_b128 v[20:23], v159 offset:2048
	ds_read_b128 v[158:161], v159 offset:3072
	ds_read_b128 v[24:27], v155 offset:32768
	ds_read_b128 v[194:197], v155 offset:33792
	ds_read_b128 v[198:201], v154 offset:32768
	ds_read_b128 v[202:205], v154 offset:33792
	ds_read_b128 v[206:209], v153 offset:32768
	ds_read_b128 v[210:213], v153 offset:33792
	ds_read_b128 v[214:217], v152 offset:32768
	ds_read_b128 v[218:221], v152 offset:33792
	s_waitcnt vmcnt(2)
	s_barrier
; #define LDA(dst, b, h) for (int m = 0; m < 4; ++m) for (int k = 0; k < 2; ++k) \
;     dst[m][k] = *reinterpret_cast<const bf16x8*>((char*)SA(b, h) + lds_byte(wr * 64 + m * 16 + fr, k * 32 + fq * 8))
; #define LDB(dst, b, h) for (int n = 0; n < 2; ++n) for (int k = 0; k < 2; ++k) \
;     dst[n][k] = *reinterpret_cast<const bf16x8*>((char*)SB(b, h) + lds_byte(wc * 32 + n * 16 + fr, k * 32 + fq * 8))
; #define MMA(ai, bj, At_, Bt_) do { __builtin_amdgcn_s_setprio(1); \
;     for (int k = 0; k < 2; ++k) for (int m = 0; m < 4; ++m) for (int n = 0; n < 2; ++n) \
;       acc[ai][bj][m][n] = __builtin_amdgcn_mfma_f32_16x16x32_bf16(At_[m][k], Bt_[n][k], acc[ai][bj][m][n], 0, 0, 0); \
;     __builtin_amdgcn_s_setprio(0); } while (0)
; #define WAIT_V(n) asm volatile("s_waitcnt vmcnt(" #n ")" ::: "memory")
; #define WAIT_L(n) asm volatile("s_waitcnt lgkmcnt(" #n ")" ::: "memory")
; #define BAR __builtin_amdgcn_s_barrier()
; template <int EPI, int lda, int ldb, int N, int K>
; __device__ __forceinline__ void gemm_phase(const u16* __restrict__ A, const u16* __restrict__ Bt, const GemmEpi ep, int wv) {
;     ...
;     { LDB(B0, 1, 0); LDA(At, 1, 0); WAIT_V(2); BAR; WAIT_L(0); MMA(0, 0, At, B0); BAR;
;       LDB(B1, 1, 1); WAIT_V(0); BAR; WAIT_L(0); MMA(0, 1, At, B1); BAR;
;       LDA(At, 1, 1); BAR; WAIT_L(0); MMA(1, 0, At, B0); MMA(1, 1, At, B1); BAR; }
;     if (wr == 0) BAR;
	s_waitcnt lgkmcnt(0)
	s_waitcnt lgkmcnt(0)
	v_mfma_f32_16x16x32_bf16 v[64:67], v[4:7], v[24:27], v[124:127]
	v_mfma_f32_16x16x32_bf16 v[68:71], v[20:23], v[24:27], v[120:123]
	v_mfma_f32_16x16x32_bf16 v[80:83], v[4:7], v[198:201], v[116:119]
	v_mfma_f32_16x16x32_bf16 v[84:87], v[20:23], v[198:201], v[112:115]
	v_mfma_f32_16x16x32_bf16 v[108:111], v[4:7], v[206:209], v[108:111]
	v_mfma_f32_16x16x32_bf16 v[104:107], v[20:23], v[206:209], v[104:107]
	v_mfma_f32_16x16x32_bf16 v[120:123], v[4:7], v[214:217], v[100:103]
	v_mfma_f32_16x16x32_bf16 v[124:127], v[20:23], v[214:217], v[96:99]
	v_mfma_f32_16x16x32_bf16 v[116:119], v[8:11], v[194:197], v[64:67]
	v_mfma_f32_16x16x32_bf16 v[112:115], v[158:161], v[194:197], v[68:71]
	v_mfma_f32_16x16x32_bf16 v[100:103], v[8:11], v[202:205], v[80:83]
	v_mfma_f32_16x16x32_bf16 v[96:99], v[158:161], v[202:205], v[84:87]
	v_mfma_f32_16x16x32_bf16 v[84:87], v[8:11], v[210:213], v[108:111]
	v_mfma_f32_16x16x32_bf16 v[80:83], v[158:161], v[210:213], v[104:107]
	v_mfma_f32_16x16x32_bf16 v[68:71], v[8:11], v[218:221], v[120:123]
	v_mfma_f32_16x16x32_bf16 v[64:67], v[158:161], v[218:221], v[124:127]
	s_barrier
	ds_read_b128 v[222:225], v157
	ds_read_b128 v[226:229], v157 offset:1024
	ds_read_b128 v[230:233], v157 offset:2048
	ds_read_b128 v[234:237], v157 offset:3072
	s_waitcnt vmcnt(0)
	s_barrier
	s_waitcnt lgkmcnt(0)
	s_waitcnt lgkmcnt(0)
	v_mfma_f32_16x16x32_bf16 v[92:95], v[222:225], v[24:27], v[92:95]
	v_mfma_f32_16x16x32_bf16 v[24:27], v[230:233], v[24:27], v[88:91]
	v_mfma_f32_16x16x32_bf16 v[88:91], v[222:225], v[198:201], v[178:181]
	v_mfma_f32_16x16x32_bf16 v[104:107], v[230:233], v[198:201], v[182:185]
	v_mfma_f32_16x16x32_bf16 v[76:79], v[222:225], v[206:209], v[76:79]
	v_mfma_f32_16x16x32_bf16 v[72:75], v[230:233], v[206:209], v[72:75]
	v_mfma_f32_16x16x32_bf16 v[176:179], v[222:225], v[214:217], v[186:189]
	v_mfma_f32_16x16x32_bf16 v[180:183], v[230:233], v[214:217], v[190:193]
	v_mfma_f32_16x16x32_bf16 v[124:127], v[226:229], v[194:197], v[92:95]
	v_mfma_f32_16x16x32_bf16 v[120:123], v[234:237], v[194:197], v[24:27]
	v_mfma_f32_16x16x32_bf16 v[108:111], v[226:229], v[202:205], v[88:91]
	v_mfma_f32_16x16x32_bf16 v[104:107], v[234:237], v[202:205], v[104:107]
	v_mfma_f32_16x16x32_bf16 v[92:95], v[226:229], v[210:213], v[76:79]
	v_mfma_f32_16x16x32_bf16 v[88:91], v[234:237], v[210:213], v[72:75]
	v_mfma_f32_16x16x32_bf16 v[76:79], v[226:229], v[218:221], v[176:179]
	v_mfma_f32_16x16x32_bf16 v[72:75], v[234:237], v[218:221], v[180:183]
	s_barrier
	ds_read_b128 v[176:179], v155 offset:49152
	ds_read_b128 v[180:183], v155 offset:50176
	ds_read_b128 v[184:187], v154 offset:49152
	ds_read_b128 v[154:157], v154 offset:50176
	ds_read_b128 v[188:191], v153 offset:49152
	ds_read_b128 v[192:195], v153 offset:50176
	ds_read_b128 v[196:199], v152 offset:49152
	ds_read_b128 v[200:203], v152 offset:50176
	s_barrier
	s_waitcnt lgkmcnt(0)
	s_waitcnt lgkmcnt(0)
	v_mfma_f32_16x16x32_bf16 v[24:27], v[4:7], v[176:179], v[60:63]
	v_mfma_f32_16x16x32_bf16 v[60:63], v[20:23], v[176:179], v[56:59]
	v_mfma_f32_16x16x32_bf16 v[204:207], v[4:7], v[184:187], v[52:55]
	v_mfma_f32_16x16x32_bf16 v[48:51], v[20:23], v[184:187], v[48:51]
	v_mfma_f32_16x16x32_bf16 v[44:47], v[4:7], v[188:191], v[44:47]
	v_mfma_f32_16x16x32_bf16 v[208:211], v[20:23], v[188:191], v[40:43]
	v_mfma_f32_16x16x32_bf16 v[4:7], v[4:7], v[196:199], v[36:39]
	v_mfma_f32_16x16x32_bf16 v[32:35], v[20:23], v[196:199], v[32:35]
	v_mfma_f32_16x16x32_bf16 v[56:59], v[8:11], v[180:183], v[24:27]
	v_mfma_f32_16x16x32_bf16 v[52:55], v[158:161], v[180:183], v[60:63]
	v_mfma_f32_16x16x32_bf16 v[40:43], v[8:11], v[154:157], v[204:207]
	v_mfma_f32_16x16x32_bf16 v[36:39], v[158:161], v[154:157], v[48:51]
	v_mfma_f32_16x16x32_bf16 v[24:27], v[8:11], v[192:195], v[44:47]
	v_mfma_f32_16x16x32_bf16 v[20:23], v[158:161], v[192:195], v[208:211]
	v_mfma_f32_16x16x32_bf16 v[8:11], v[8:11], v[200:203], v[4:7]
	v_mfma_f32_16x16x32_bf16 v[4:7], v[158:161], v[200:203], v[32:35]
	v_mfma_f32_16x16x32_bf16 v[28:31], v[222:225], v[176:179], v[28:31]
	v_mfma_f32_16x16x32_bf16 v[32:35], v[230:233], v[176:179], v[134:137]
	v_mfma_f32_16x16x32_bf16 v[44:47], v[222:225], v[184:187], v[138:141]
	v_mfma_f32_16x16x32_bf16 v[16:19], v[230:233], v[184:187], v[16:19]
	v_mfma_f32_16x16x32_bf16 v[12:15], v[222:225], v[188:191], v[12:15]
	v_mfma_f32_16x16x32_bf16 v[134:137], v[230:233], v[188:191], v[142:145]
	v_mfma_f32_16x16x32_bf16 v[138:141], v[222:225], v[196:199], v[172:175]
	v_mfma_f32_16x16x32_bf16 v[0:3], v[230:233], v[196:199], v[0:3]
	v_mfma_f32_16x16x32_bf16 v[60:63], v[226:229], v[180:183], v[28:31]
	v_mfma_f32_16x16x32_bf16 v[48:51], v[234:237], v[180:183], v[32:35]
	v_mfma_f32_16x16x32_bf16 v[44:47], v[226:229], v[154:157], v[44:47]
	v_mfma_f32_16x16x32_bf16 v[32:35], v[234:237], v[154:157], v[16:19]
	v_mfma_f32_16x16x32_bf16 v[28:31], v[226:229], v[192:195], v[12:15]
	v_mfma_f32_16x16x32_bf16 v[16:19], v[234:237], v[192:195], v[134:137]
	v_mfma_f32_16x16x32_bf16 v[12:15], v[226:229], v[200:203], v[138:141]
	v_mfma_f32_16x16x32_bf16 v[0:3], v[234:237], v[200:203], v[0:3]
	v_cmp_gt_u32_e32 vcc, s69, v130
	s_barrier
	s_and_saveexec_b64 s[50:51], vcc
	s_cbranch_execz .LBB0_841
	s_barrier

; #define STAGE(P, BASE, LD, br, kt) do { const char* _g = (const char*)((BASE) + (size_t)(br) * (LD) + (size_t)(kt) * 64); \
;     for (int _i = 0; _i < 2; ++_i) { int _b = tidx * 16 + _i * 8192; int _r, _c; stage_rc(_b, _r, _c); \
;       __builtin_amdgcn_global_load_lds((const unsigned*)(_g + (unsigned)((_r * (LD) + _c) * 2)), (unsigned*)((char*)(P) + _b), 16, 0, 0); } } while (0)
; #define LDA(dst, b, h) for (int m = 0; m < 4; ++m) for (int k = 0; k < 2; ++k) \
;     dst[m][k] = *reinterpret_cast<const bf16x8*>((char*)SA(b, h) + lds_byte(wr * 64 + m * 16 + fr, k * 32 + fq * 8))
; #define LDB(dst, b, h) for (int n = 0; n < 2; ++n) for (int k = 0; k < 2; ++k) \
;     dst[n][k] = *reinterpret_cast<const bf16x8*>((char*)SB(b, h) + lds_byte(wc * 32 + n * 16 + fr, k * 32 + fq * 8))
; #define MMA(ai, bj, At_, Bt_) do { __builtin_amdgcn_s_setprio(1); \
;     for (int k = 0; k < 2; ++k) for (int m = 0; m < 4; ++m) for (int n = 0; n < 2; ++n) \
;       acc[ai][bj][m][n] = __builtin_amdgcn_mfma_f32_16x16x32_bf16(At_[m][k], Bt_[n][k], acc[ai][bj][m][n], 0, 0, 0); \
;     __builtin_amdgcn_s_setprio(0); } while (0)
; #define WAIT_L(n) asm volatile("s_waitcnt lgkmcnt(" #n ")" ::: "memory")
; #define BAR __builtin_amdgcn_s_barrier()
; #define SCHED __builtin_amdgcn_sched_barrier(0)
; template <int EPI, int lda, int ldb, int N, int K>
; __device__ __forceinline__ void gemm_phase(const u16* __restrict__ A, const u16* __restrict__ Bt, const GemmEpi ep, int wv) {
;     ...
;       LDB(B0, 0, 0); SCHED; LDA(At, 0, 0); STAGE(SA(1, 1), Ab, lda, brow + HALF, t + 1);
;       WAIT_L(8); BAR; WAIT_L(0); MMA(0, 0, At, B0); BAR; SCHED;
;       LDB(B1, 0, 1); STAGE(SB(0, 0), Bt, ldb, bcol, t + 2);
;       BAR; WAIT_L(0); MMA(0, 1, At, B1); BAR;
;       LDA(At, 0, 1); STAGE(SA(0, 0), Ab, lda, brow, t + 2);
;       BAR; WAIT_L(0); MMA(1, 0, At, B0); BAR; SCHED;
;       STAGE(SB(0, 1), Bt, ldb, bcol + HALF, t + 2);
.LBB0_1147:
	ds_read_b128 v[172:175], v161
	ds_read_b128 v[176:179], v161 offset:1024
	ds_read_b128 v[180:183], v161 offset:2048
	ds_read_b128 v[184:187], v161 offset:3072
	v_add_u32_e32 v169, 0xc000, v148
	v_lshl_add_u64 v[236:237], v[138:139], 0, s[60:61]
	v_readfirstlane_b32 s63, v169
	v_add_u32_e32 v170, 0xe000, v148
	v_lshl_add_u64 v[162:163], v[236:237], 0, s[22:23]
	s_mov_b32 m0, s63
	v_lshl_add_u64 v[238:239], v[140:141], 0, s[60:61]
	v_readfirstlane_b32 s63, v170
	global_load_lds_dwordx4 v[162:163], off
	v_lshl_add_u64 v[162:163], v[238:239], 0, s[22:23]
	s_mov_b32 m0, s63
	s_nop 0
	global_load_lds_dwordx4 v[162:163], off
	ds_read_b128 v[164:167], v152
	ds_read_b128 v[188:191], v152 offset:1024
	ds_read_b128 v[192:195], v151
	ds_read_b128 v[196:199], v151 offset:1024
	ds_read_b128 v[200:203], v150
	ds_read_b128 v[204:207], v150 offset:1024
	ds_read_b128 v[208:211], v149
	ds_read_b128 v[212:215], v149 offset:1024
	s_waitcnt lgkmcnt(8)
	s_barrier
	s_waitcnt lgkmcnt(0)
	s_waitcnt lgkmcnt(0)
	v_mfma_f32_16x16x32_bf16 v[124:127], v[164:167], v[172:175], v[124:127]
	v_mfma_f32_16x16x32_bf16 v[120:123], v[164:167], v[180:183], v[120:123]
	v_mfma_f32_16x16x32_bf16 v[116:119], v[192:195], v[172:175], v[116:119]
	v_mfma_f32_16x16x32_bf16 v[112:115], v[192:195], v[180:183], v[112:115]
	v_mfma_f32_16x16x32_bf16 v[108:111], v[200:203], v[172:175], v[108:111]
	v_mfma_f32_16x16x32_bf16 v[104:107], v[200:203], v[180:183], v[104:107]
	v_mfma_f32_16x16x32_bf16 v[100:103], v[208:211], v[172:175], v[100:103]
	v_mfma_f32_16x16x32_bf16 v[96:99], v[208:211], v[180:183], v[96:99]
	v_mfma_f32_16x16x32_bf16 v[124:127], v[188:191], v[176:179], v[124:127]
	v_mfma_f32_16x16x32_bf16 v[120:123], v[188:191], v[184:187], v[120:123]
	v_mfma_f32_16x16x32_bf16 v[116:119], v[196:199], v[176:179], v[116:119]
	v_mfma_f32_16x16x32_bf16 v[112:115], v[196:199], v[184:187], v[112:115]
	v_mfma_f32_16x16x32_bf16 v[108:111], v[204:207], v[176:179], v[108:111]
	v_mfma_f32_16x16x32_bf16 v[104:107], v[204:207], v[184:187], v[104:107]
	v_mfma_f32_16x16x32_bf16 v[100:103], v[212:215], v[176:179], v[100:103]
	v_mfma_f32_16x16x32_bf16 v[96:99], v[212:215], v[184:187], v[96:99]
	s_barrier
	v_add_u32_e32 v162, s75, v154
	v_lshl_add_u64 v[240:241], v[134:135], 0, s[60:61]
	v_readfirstlane_b32 s63, v162
	v_add_u32_e32 v163, 0x2000, v162
	v_lshl_add_u64 v[232:233], v[240:241], 0, s[24:25]
	s_mov_b32 m0, s63
	v_lshl_add_u64 v[242:243], v[136:137], 0, s[60:61]
	v_readfirstlane_b32 s63, v163
	global_load_lds_dwordx4 v[232:233], off
	v_lshl_add_u64 v[232:233], v[242:243], 0, s[24:25]
	s_mov_b32 m0, s63
	s_nop 0
	global_load_lds_dwordx4 v[232:233], off
	ds_read_b128 v[216:219], v160
	ds_read_b128 v[220:223], v160 offset:1024
	ds_read_b128 v[224:227], v160 offset:2048
	ds_read_b128 v[228:231], v160 offset:3072
	s_barrier
	s_waitcnt lgkmcnt(0)
	s_waitcnt lgkmcnt(0)
	v_mfma_f32_16x16x32_bf16 v[92:95], v[164:167], v[216:219], v[92:95]
	v_mfma_f32_16x16x32_bf16 v[88:91], v[164:167], v[224:227], v[88:91]
	v_mfma_f32_16x16x32_bf16 v[84:87], v[192:195], v[216:219], v[84:87]
	v_mfma_f32_16x16x32_bf16 v[80:83], v[192:195], v[224:227], v[80:83]
	v_mfma_f32_16x16x32_bf16 v[76:79], v[200:203], v[216:219], v[76:79]
	v_mfma_f32_16x16x32_bf16 v[72:75], v[200:203], v[224:227], v[72:75]
	v_mfma_f32_16x16x32_bf16 v[68:71], v[208:211], v[216:219], v[68:71]
	v_mfma_f32_16x16x32_bf16 v[64:67], v[208:211], v[224:227], v[64:67]
	v_mfma_f32_16x16x32_bf16 v[92:95], v[188:191], v[220:223], v[92:95]
	v_mfma_f32_16x16x32_bf16 v[88:91], v[188:191], v[228:231], v[88:91]
	v_mfma_f32_16x16x32_bf16 v[84:87], v[196:199], v[220:223], v[84:87]
	v_mfma_f32_16x16x32_bf16 v[80:83], v[196:199], v[228:231], v[80:83]
	v_mfma_f32_16x16x32_bf16 v[76:79], v[204:207], v[220:223], v[76:79]
	v_mfma_f32_16x16x32_bf16 v[72:75], v[204:207], v[228:231], v[72:75]
	v_mfma_f32_16x16x32_bf16 v[68:71], v[212:215], v[220:223], v[68:71]
	v_mfma_f32_16x16x32_bf16 v[64:67], v[212:215], v[228:231], v[64:67]
	v_readfirstlane_b32 s63, v148
	v_lshl_add_u64 v[164:165], v[236:237], 0, s[26:27]
	s_mov_b32 m0, s63
	s_barrier
	global_load_lds_dwordx4 v[164:165], off
	v_add_u32_e32 v164, 0x2000, v148
	v_lshl_add_u64 v[166:167], v[238:239], 0, s[26:27]
	v_readfirstlane_b32 s63, v164
	s_mov_b32 m0, s63
	s_nop 0
	global_load_lds_dwordx4 v[166:167], off
	ds_read_b128 v[188:191], v152 offset:16384
	ds_read_b128 v[192:195], v152 offset:17408
	ds_read_b128 v[196:199], v151 offset:16384
	ds_read_b128 v[200:203], v151 offset:17408
	ds_read_b128 v[204:207], v150 offset:16384
	ds_read_b128 v[208:211], v150 offset:17408
	ds_read_b128 v[212:215], v149 offset:16384
	ds_read_b128 v[232:235], v149 offset:17408
	s_barrier
	s_waitcnt lgkmcnt(0)
	s_waitcnt lgkmcnt(0)
	v_mfma_f32_16x16x32_bf16 v[60:63], v[188:191], v[172:175], v[60:63]
	v_mfma_f32_16x16x32_bf16 v[56:59], v[188:191], v[180:183], v[56:59]
	v_mfma_f32_16x16x32_bf16 v[52:55], v[196:199], v[172:175], v[52:55]
	v_mfma_f32_16x16x32_bf16 v[48:51], v[196:199], v[180:183], v[48:51]
	v_mfma_f32_16x16x32_bf16 v[44:47], v[204:207], v[172:175], v[44:47]
	v_mfma_f32_16x16x32_bf16 v[40:43], v[204:207], v[180:183], v[40:43]
	v_mfma_f32_16x16x32_bf16 v[36:39], v[212:215], v[172:175], v[36:39]
	v_mfma_f32_16x16x32_bf16 v[32:35], v[212:215], v[180:183], v[32:35]
	v_mfma_f32_16x16x32_bf16 v[60:63], v[192:195], v[176:179], v[60:63]
	v_mfma_f32_16x16x32_bf16 v[56:59], v[192:195], v[184:187], v[56:59]
	v_mfma_f32_16x16x32_bf16 v[52:55], v[200:203], v[176:179], v[52:55]
	v_mfma_f32_16x16x32_bf16 v[48:51], v[200:203], v[184:187], v[48:51]
	v_mfma_f32_16x16x32_bf16 v[44:47], v[208:211], v[176:179], v[44:47]
	v_mfma_f32_16x16x32_bf16 v[40:43], v[208:211], v[184:187], v[40:43]
	v_mfma_f32_16x16x32_bf16 v[36:39], v[232:235], v[176:179], v[36:39]
	v_mfma_f32_16x16x32_bf16 v[32:35], v[232:235], v[184:187], v[32:35]
	s_barrier
; #define STAGE(P, BASE, LD, br, kt) do { const char* _g = (const char*)((BASE) + (size_t)(br) * (LD) + (size_t)(kt) * 64); \
;     for (int _i = 0; _i < 2; ++_i) { int _b = tidx * 16 + _i * 8192; int _r, _c; stage_rc(_b, _r, _c); \
;       __builtin_amdgcn_global_load_lds((const unsigned*)(_g + (unsigned)((_r * (LD) + _c) * 2)), (unsigned*)((char*)(P) + _b), 16, 0, 0); } } while (0)
; #define LDA(dst, b, h) for (int m = 0; m < 4; ++m) for (int k = 0; k < 2; ++k) \
;     dst[m][k] = *reinterpret_cast<const bf16x8*>((char*)SA(b, h) + lds_byte(wr * 64 + m * 16 + fr, k * 32 + fq * 8))
; #define LDB(dst, b, h) for (int n = 0; n < 2; ++n) for (int k = 0; k < 2; ++k) \
;     dst[n][k] = *reinterpret_cast<const bf16x8*>((char*)SB(b, h) + lds_byte(wc * 32 + n * 16 + fr, k * 32 + fq * 8))
; #define MMA(ai, bj, At_, Bt_) do { __builtin_amdgcn_s_setprio(1); \
;     for (int k = 0; k < 2; ++k) for (int m = 0; m < 4; ++m) for (int n = 0; n < 2; ++n) \
;       acc[ai][bj][m][n] = __builtin_amdgcn_mfma_f32_16x16x32_bf16(At_[m][k], Bt_[n][k], acc[ai][bj][m][n], 0, 0, 0); \
;     __builtin_amdgcn_s_setprio(0); } while (0)
; #define WAIT_V(n) asm volatile("s_waitcnt vmcnt(" #n ")" ::: "memory")
; #define WAIT_L(n) asm volatile("s_waitcnt lgkmcnt(" #n ")" ::: "memory")
; #define BAR __builtin_amdgcn_s_barrier()
; #define SCHED __builtin_amdgcn_sched_barrier(0)
; template <int EPI, int lda, int ldb, int N, int K>
; __device__ __forceinline__ void gemm_phase(const u16* __restrict__ A, const u16* __restrict__ Bt, const GemmEpi ep, int wv) {
;     ...
;       STAGE(SB(0, 1), Bt, ldb, bcol + HALF, t + 2);
;       WAIT_V(6); BAR; MMA(1, 1, At, B1); BAR;
;       LDB(B0, 1, 0); SCHED; LDA(At, 1, 0); STAGE(SA(0, 1), Ab, lda, brow + HALF, t + 2);
;       WAIT_L(8); BAR; WAIT_L(0); MMA(0, 0, At, B0); BAR; SCHED;
;       LDB(B1, 1, 1); STAGE(SB(1, 0), Bt, ldb, bcol, t + 3);
;       BAR; WAIT_L(0); MMA(0, 1, At, B1); BAR;
;       LDA(At, 1, 1); STAGE(SA(1, 0), Ab, lda, brow, t + 3);
	v_add_u32_e32 v165, s76, v154
	v_lshl_add_u64 v[166:167], v[240:241], 0, s[40:41]
	v_readfirstlane_b32 s63, v165
	s_mov_b32 m0, s63
	v_lshl_add_u64 v[172:173], v[242:243], 0, s[40:41]
	global_load_lds_dwordx4 v[166:167], off
	v_add_u32_e32 v166, 0x2000, v165
	s_nop 0
	v_readfirstlane_b32 s63, v166
	s_mov_b32 m0, s63
	s_nop 0
	global_load_lds_dwordx4 v[172:173], off
	s_waitcnt vmcnt(6)
	s_barrier
	v_mfma_f32_16x16x32_bf16 v[28:31], v[188:191], v[216:219], v[28:31]
	v_mfma_f32_16x16x32_bf16 v[24:27], v[188:191], v[224:227], v[24:27]
	v_mfma_f32_16x16x32_bf16 v[20:23], v[196:199], v[216:219], v[20:23]
	v_mfma_f32_16x16x32_bf16 v[16:19], v[196:199], v[224:227], v[16:19]
	v_mfma_f32_16x16x32_bf16 v[12:15], v[204:207], v[216:219], v[12:15]
	v_mfma_f32_16x16x32_bf16 v[8:11], v[204:207], v[224:227], v[8:11]
	v_mfma_f32_16x16x32_bf16 v[4:7], v[212:215], v[216:219], v[4:7]
	v_mfma_f32_16x16x32_bf16 v[0:3], v[212:215], v[224:227], v[0:3]
	v_mfma_f32_16x16x32_bf16 v[28:31], v[192:195], v[220:223], v[28:31]
	v_mfma_f32_16x16x32_bf16 v[24:27], v[192:195], v[228:231], v[24:27]
	v_mfma_f32_16x16x32_bf16 v[20:23], v[200:203], v[220:223], v[20:23]
	v_mfma_f32_16x16x32_bf16 v[16:19], v[200:203], v[228:231], v[16:19]
	v_mfma_f32_16x16x32_bf16 v[12:15], v[208:211], v[220:223], v[12:15]
	v_mfma_f32_16x16x32_bf16 v[8:11], v[208:211], v[228:231], v[8:11]
	v_mfma_f32_16x16x32_bf16 v[4:7], v[232:235], v[220:223], v[4:7]
	v_mfma_f32_16x16x32_bf16 v[0:3], v[232:235], v[228:231], v[0:3]
	s_barrier
	ds_read_b128 v[172:175], v155
	ds_read_b128 v[176:179], v155 offset:1024
	ds_read_b128 v[180:183], v155 offset:2048
	ds_read_b128 v[184:187], v155 offset:3072
	v_add_u32_e32 v167, 0x4000, v148
	v_add_u32_e32 v168, 0x6000, v148
	v_readfirstlane_b32 s63, v167
	v_lshl_add_u64 v[220:221], v[236:237], 0, s[42:43]
	s_mov_b32 m0, s63
	v_readfirstlane_b32 s63, v168
	global_load_lds_dwordx4 v[220:221], off
	v_lshl_add_u64 v[220:221], v[238:239], 0, s[42:43]
	s_mov_b32 m0, s63
	s_nop 0
	global_load_lds_dwordx4 v[220:221], off
	ds_read_b128 v[188:191], v152 offset:32768
	ds_read_b128 v[192:195], v152 offset:33792
	ds_read_b128 v[196:199], v151 offset:32768
	ds_read_b128 v[200:203], v151 offset:33792
	ds_read_b128 v[204:207], v150 offset:32768
	ds_read_b128 v[208:211], v150 offset:33792
	ds_read_b128 v[212:215], v149 offset:32768
	ds_read_b128 v[216:219], v149 offset:33792
	s_waitcnt lgkmcnt(8)
	s_barrier
	s_waitcnt lgkmcnt(0)
	s_waitcnt lgkmcnt(0)
	v_mfma_f32_16x16x32_bf16 v[124:127], v[188:191], v[172:175], v[124:127]
	v_mfma_f32_16x16x32_bf16 v[120:123], v[188:191], v[180:183], v[120:123]
	v_mfma_f32_16x16x32_bf16 v[116:119], v[196:199], v[172:175], v[116:119]
	v_mfma_f32_16x16x32_bf16 v[112:115], v[196:199], v[180:183], v[112:115]
	v_mfma_f32_16x16x32_bf16 v[108:111], v[204:207], v[172:175], v[108:111]
	v_mfma_f32_16x16x32_bf16 v[104:107], v[204:207], v[180:183], v[104:107]
	v_mfma_f32_16x16x32_bf16 v[100:103], v[212:215], v[172:175], v[100:103]
	v_mfma_f32_16x16x32_bf16 v[96:99], v[212:215], v[180:183], v[96:99]
	v_mfma_f32_16x16x32_bf16 v[124:127], v[192:195], v[176:179], v[124:127]
	v_mfma_f32_16x16x32_bf16 v[120:123], v[192:195], v[184:187], v[120:123]
	v_mfma_f32_16x16x32_bf16 v[116:119], v[200:203], v[176:179], v[116:119]
	v_mfma_f32_16x16x32_bf16 v[112:115], v[200:203], v[184:187], v[112:115]
	v_mfma_f32_16x16x32_bf16 v[108:111], v[208:211], v[176:179], v[108:111]
	v_mfma_f32_16x16x32_bf16 v[104:107], v[208:211], v[184:187], v[104:107]
	v_mfma_f32_16x16x32_bf16 v[100:103], v[216:219], v[176:179], v[100:103]
	v_mfma_f32_16x16x32_bf16 v[96:99], v[216:219], v[184:187], v[96:99]
	s_barrier
	v_readfirstlane_b32 s63, v156
	v_add_u32_e32 v171, 0x2000, v156
	v_lshl_add_u64 v[244:245], v[240:241], 0, s[44:45]
	s_mov_b32 m0, s63
	v_readfirstlane_b32 s63, v171
	global_load_lds_dwordx4 v[244:245], off
	v_lshl_add_u64 v[244:245], v[242:243], 0, s[44:45]
	s_mov_b32 m0, s63
	s_nop 0
	global_load_lds_dwordx4 v[244:245], off
	ds_read_b128 v[220:223], v153
	ds_read_b128 v[224:227], v153 offset:1024
	ds_read_b128 v[228:231], v153 offset:2048
	ds_read_b128 v[232:235], v153 offset:3072
	s_barrier
	s_waitcnt lgkmcnt(0)
	s_waitcnt lgkmcnt(0)
	v_mfma_f32_16x16x32_bf16 v[92:95], v[188:191], v[220:223], v[92:95]
	v_mfma_f32_16x16x32_bf16 v[88:91], v[188:191], v[228:231], v[88:91]
	v_mfma_f32_16x16x32_bf16 v[84:87], v[196:199], v[220:223], v[84:87]
	v_mfma_f32_16x16x32_bf16 v[80:83], v[196:199], v[228:231], v[80:83]
	v_mfma_f32_16x16x32_bf16 v[76:79], v[204:207], v[220:223], v[76:79]
	v_mfma_f32_16x16x32_bf16 v[72:75], v[204:207], v[228:231], v[72:75]
	v_mfma_f32_16x16x32_bf16 v[68:71], v[212:215], v[220:223], v[68:71]
	v_mfma_f32_16x16x32_bf16 v[64:67], v[212:215], v[228:231], v[64:67]
	v_mfma_f32_16x16x32_bf16 v[92:95], v[192:195], v[224:227], v[92:95]
	v_mfma_f32_16x16x32_bf16 v[88:91], v[192:195], v[232:235], v[88:91]
	v_mfma_f32_16x16x32_bf16 v[84:87], v[200:203], v[224:227], v[84:87]
	v_mfma_f32_16x16x32_bf16 v[80:83], v[200:203], v[232:235], v[80:83]
	v_mfma_f32_16x16x32_bf16 v[76:79], v[208:211], v[224:227], v[76:79]
	v_mfma_f32_16x16x32_bf16 v[72:75], v[208:211], v[232:235], v[72:75]
	v_mfma_f32_16x16x32_bf16 v[68:71], v[216:219], v[224:227], v[68:71]
	v_mfma_f32_16x16x32_bf16 v[64:67], v[216:219], v[232:235], v[64:67]
	v_readfirstlane_b32 s63, v157
	v_lshl_add_u64 v[236:237], v[236:237], 0, s[46:47]
	s_mov_b32 m0, s63
	v_readfirstlane_b32 s63, v158
	s_barrier
; #define STAGE(P, BASE, LD, br, kt) do { const char* _g = (const char*)((BASE) + (size_t)(br) * (LD) + (size_t)(kt) * 64); \
;     for (int _i = 0; _i < 2; ++_i) { int _b = tidx * 16 + _i * 8192; int _r, _c; stage_rc(_b, _r, _c); \
;       __builtin_amdgcn_global_load_lds((const unsigned*)(_g + (unsigned)((_r * (LD) + _c) * 2)), (unsigned*)((char*)(P) + _b), 16, 0, 0); } } while (0)
; #define LDA(dst, b, h) for (int m = 0; m < 4; ++m) for (int k = 0; k < 2; ++k) \
;     dst[m][k] = *reinterpret_cast<const bf16x8*>((char*)SA(b, h) + lds_byte(wr * 64 + m * 16 + fr, k * 32 + fq * 8))
; #define LDB(dst, b, h) for (int n = 0; n < 2; ++n) for (int k = 0; k < 2; ++k) \
;     dst[n][k] = *reinterpret_cast<const bf16x8*>((char*)SB(b, h) + lds_byte(wc * 32 + n * 16 + fr, k * 32 + fq * 8))
; #define MMA(ai, bj, At_, Bt_) do { __builtin_amdgcn_s_setprio(1); \
;     for (int k = 0; k < 2; ++k) for (int m = 0; m < 4; ++m) for (int n = 0; n < 2; ++n) \
;       acc[ai][bj][m][n] = __builtin_amdgcn_mfma_f32_16x16x32_bf16(At_[m][k], Bt_[n][k], acc[ai][bj][m][n], 0, 0, 0); \
;     __builtin_amdgcn_s_setprio(0); } while (0)
; #define WAIT_V(n) asm volatile("s_waitcnt vmcnt(" #n ")" ::: "memory")
; #define WAIT_L(n) asm volatile("s_waitcnt lgkmcnt(" #n ")" ::: "memory")
; #define BAR __builtin_amdgcn_s_barrier()
; #define SCHED __builtin_amdgcn_sched_barrier(0)
; template <int EPI, int lda, int ldb, int N, int K>
; __device__ __forceinline__ void gemm_phase(const u16* __restrict__ A, const u16* __restrict__ Bt, const GemmEpi ep, int wv) {
;     ...
;       LDA(At, 1, 1); STAGE(SA(1, 0), Ab, lda, brow, t + 3);
;       BAR; WAIT_L(0); MMA(1, 0, At, B0); BAR; SCHED;
;       STAGE(SB(1, 1), Bt, ldb, bcol + HALF, t + 3);
;       WAIT_V(6); BAR; MMA(1, 1, At, B1); BAR;
;     }
;     { LDB(B0, 0, 0); LDA(At, 0, 0); STAGE(SA(1, 1), Ab, lda, brow + HALF, nt - 1);
;       BAR; WAIT_L(0); MMA(0, 0, At, B0); BAR;
;       LDB(B1, 0, 1); BAR; WAIT_L(0); MMA(0, 1, At, B1); BAR;
	global_load_lds_dwordx4 v[236:237], off
	v_lshl_add_u64 v[236:237], v[238:239], 0, s[46:47]
	s_mov_b32 m0, s63
	s_nop 0
	global_load_lds_dwordx4 v[236:237], off
	ds_read_b128 v[188:191], v152 offset:49152
	ds_read_b128 v[192:195], v152 offset:50176
	ds_read_b128 v[196:199], v151 offset:49152
	ds_read_b128 v[200:203], v151 offset:50176
	ds_read_b128 v[204:207], v150 offset:49152
	ds_read_b128 v[208:211], v150 offset:50176
	ds_read_b128 v[212:215], v149 offset:49152
	ds_read_b128 v[216:219], v149 offset:50176
	s_barrier
	s_waitcnt lgkmcnt(0)
	s_waitcnt lgkmcnt(0)
	v_mfma_f32_16x16x32_bf16 v[60:63], v[188:191], v[172:175], v[60:63]
	v_mfma_f32_16x16x32_bf16 v[56:59], v[188:191], v[180:183], v[56:59]
	v_mfma_f32_16x16x32_bf16 v[52:55], v[196:199], v[172:175], v[52:55]
	v_mfma_f32_16x16x32_bf16 v[48:51], v[196:199], v[180:183], v[48:51]
	v_mfma_f32_16x16x32_bf16 v[44:47], v[204:207], v[172:175], v[44:47]
	v_mfma_f32_16x16x32_bf16 v[40:43], v[204:207], v[180:183], v[40:43]
	v_mfma_f32_16x16x32_bf16 v[36:39], v[212:215], v[172:175], v[36:39]
	v_mfma_f32_16x16x32_bf16 v[32:35], v[212:215], v[180:183], v[32:35]
	v_mfma_f32_16x16x32_bf16 v[60:63], v[192:195], v[176:179], v[60:63]
	v_mfma_f32_16x16x32_bf16 v[56:59], v[192:195], v[184:187], v[56:59]
	v_mfma_f32_16x16x32_bf16 v[52:55], v[200:203], v[176:179], v[52:55]
	v_mfma_f32_16x16x32_bf16 v[48:51], v[200:203], v[184:187], v[48:51]
	v_mfma_f32_16x16x32_bf16 v[44:47], v[208:211], v[176:179], v[44:47]
	v_mfma_f32_16x16x32_bf16 v[40:43], v[208:211], v[184:187], v[40:43]
	v_mfma_f32_16x16x32_bf16 v[36:39], v[216:219], v[176:179], v[36:39]
	v_mfma_f32_16x16x32_bf16 v[32:35], v[216:219], v[184:187], v[32:35]
	s_barrier
	v_readfirstlane_b32 s63, v159
	v_add_u32_e32 v171, 0x2000, v159
	v_lshl_add_u64 v[172:173], v[240:241], 0, s[48:49]
	s_mov_b32 m0, s63
	v_readfirstlane_b32 s63, v171
	global_load_lds_dwordx4 v[172:173], off
	v_lshl_add_u64 v[172:173], v[242:243], 0, s[48:49]
	s_mov_b32 m0, s63
	s_nop 0
	global_load_lds_dwordx4 v[172:173], off
	s_waitcnt vmcnt(6)
	s_barrier
	v_mfma_f32_16x16x32_bf16 v[28:31], v[188:191], v[220:223], v[28:31]
	v_mfma_f32_16x16x32_bf16 v[24:27], v[188:191], v[228:231], v[24:27]
	v_mfma_f32_16x16x32_bf16 v[20:23], v[196:199], v[220:223], v[20:23]
	v_mfma_f32_16x16x32_bf16 v[16:19], v[196:199], v[228:231], v[16:19]
	v_mfma_f32_16x16x32_bf16 v[12:15], v[204:207], v[220:223], v[12:15]
	v_mfma_f32_16x16x32_bf16 v[8:11], v[204:207], v[228:231], v[8:11]
	v_mfma_f32_16x16x32_bf16 v[4:7], v[212:215], v[220:223], v[4:7]
	v_mfma_f32_16x16x32_bf16 v[0:3], v[212:215], v[228:231], v[0:3]
	v_mfma_f32_16x16x32_bf16 v[28:31], v[192:195], v[224:227], v[28:31]
	v_mfma_f32_16x16x32_bf16 v[24:27], v[192:195], v[232:235], v[24:27]
	v_mfma_f32_16x16x32_bf16 v[20:23], v[200:203], v[224:227], v[20:23]
	v_mfma_f32_16x16x32_bf16 v[16:19], v[200:203], v[232:235], v[16:19]
	v_mfma_f32_16x16x32_bf16 v[12:15], v[208:211], v[224:227], v[12:15]
	v_mfma_f32_16x16x32_bf16 v[8:11], v[208:211], v[232:235], v[8:11]
	v_mfma_f32_16x16x32_bf16 v[4:7], v[216:219], v[224:227], v[4:7]
	v_mfma_f32_16x16x32_bf16 v[0:3], v[216:219], v[232:235], v[0:3]
	s_add_i32 s62, s62, 2
	s_add_u32 s60, s60, 0x100
	s_addc_u32 s61, s61, 0
	s_cmp_gt_u32 s62, 27
	s_barrier
	s_cbranch_scc0 .LBB0_1147
	s_add_i32 s60, s58, 0x80
	s_mul_hi_i32 s61, s60, 0x1080
	s_mulk_i32 s60, 0x1080
	s_add_u32 s60, s69, s60
	s_addc_u32 s61, s70, s61
	v_lshl_add_u64 v[208:209], s[60:61], 0, v[128:129]
	v_readfirstlane_b32 s62, v169
	v_lshl_add_u64 v[208:209], v[208:209], 0, s[50:51]
	s_mov_b32 m0, s62
	ds_read_b128 v[134:137], v161
	ds_read_b128 v[138:141], v161 offset:1024
	ds_read_b128 v[156:159], v161 offset:2048
	ds_read_b128 v[172:175], v161 offset:3072
	ds_read_b128 v[176:179], v152
	ds_read_b128 v[180:183], v152 offset:1024
	ds_read_b128 v[184:187], v151
	ds_read_b128 v[188:191], v151 offset:1024
	ds_read_b128 v[192:195], v150
	ds_read_b128 v[196:199], v150 offset:1024
	ds_read_b128 v[200:203], v149
	ds_read_b128 v[204:207], v149 offset:1024
	global_load_lds_dwordx4 v[208:209], off
	v_lshl_add_u64 v[208:209], s[60:61], 0, v[132:133]
	v_readfirstlane_b32 s60, v170
	v_lshl_add_u64 v[208:209], v[208:209], 0, s[50:51]
	s_mov_b32 m0, s60
	s_nop 0
	global_load_lds_dwordx4 v[208:209], off
	s_barrier
	s_waitcnt lgkmcnt(0)
	s_waitcnt lgkmcnt(0)
	v_mfma_f32_16x16x32_bf16 v[124:127], v[176:179], v[134:137], v[124:127]
	v_mfma_f32_16x16x32_bf16 v[120:123], v[176:179], v[156:159], v[120:123]
	v_mfma_f32_16x16x32_bf16 v[116:119], v[184:187], v[134:137], v[116:119]
	v_mfma_f32_16x16x32_bf16 v[112:115], v[184:187], v[156:159], v[112:115]
	v_mfma_f32_16x16x32_bf16 v[108:111], v[192:195], v[134:137], v[108:111]
	v_mfma_f32_16x16x32_bf16 v[104:107], v[192:195], v[156:159], v[104:107]
	v_mfma_f32_16x16x32_bf16 v[100:103], v[200:203], v[134:137], v[100:103]
	v_mfma_f32_16x16x32_bf16 v[96:99], v[200:203], v[156:159], v[96:99]
	v_mfma_f32_16x16x32_bf16 v[124:127], v[180:183], v[138:141], v[124:127]
	v_mfma_f32_16x16x32_bf16 v[120:123], v[180:183], v[172:175], v[120:123]
	v_mfma_f32_16x16x32_bf16 v[116:119], v[188:191], v[138:141], v[116:119]
	v_mfma_f32_16x16x32_bf16 v[112:115], v[188:191], v[172:175], v[112:115]
	v_mfma_f32_16x16x32_bf16 v[108:111], v[196:199], v[138:141], v[108:111]
	v_mfma_f32_16x16x32_bf16 v[104:107], v[196:199], v[172:175], v[104:107]
	v_mfma_f32_16x16x32_bf16 v[100:103], v[204:207], v[138:141], v[100:103]
	v_mfma_f32_16x16x32_bf16 v[96:99], v[204:207], v[172:175], v[96:99]
	s_barrier
	ds_read_b128 v[208:211], v160
	ds_read_b128 v[212:215], v160 offset:1024
	ds_read_b128 v[216:219], v160 offset:2048
	ds_read_b128 v[220:223], v160 offset:3072
	s_barrier
; #define LDA(dst, b, h) for (int m = 0; m < 4; ++m) for (int k = 0; k < 2; ++k) \
;     dst[m][k] = *reinterpret_cast<const bf16x8*>((char*)SA(b, h) + lds_byte(wr * 64 + m * 16 + fr, k * 32 + fq * 8))
; #define LDB(dst, b, h) for (int n = 0; n < 2; ++n) for (int k = 0; k < 2; ++k) \
;     dst[n][k] = *reinterpret_cast<const bf16x8*>((char*)SB(b, h) + lds_byte(wc * 32 + n * 16 + fr, k * 32 + fq * 8))
; #define MMA(ai, bj, At_, Bt_) do { __builtin_amdgcn_s_setprio(1); \
;     for (int k = 0; k < 2; ++k) for (int m = 0; m < 4; ++m) for (int n = 0; n < 2; ++n) \
;       acc[ai][bj][m][n] = __builtin_amdgcn_mfma_f32_16x16x32_bf16(At_[m][k], Bt_[n][k], acc[ai][bj][m][n], 0, 0, 0); \
;     __builtin_amdgcn_s_setprio(0); } while (0)
; #define WAIT_V(n) asm volatile("s_waitcnt vmcnt(" #n ")" ::: "memory")
; #define WAIT_L(n) asm volatile("s_waitcnt lgkmcnt(" #n ")" ::: "memory")
; #define BAR __builtin_amdgcn_s_barrier()
; template <int EPI, int lda, int ldb, int N, int K>
; __device__ __forceinline__ void gemm_phase(const u16* __restrict__ A, const u16* __restrict__ Bt, const GemmEpi ep, int wv) {
;     ...
;       LDB(B1, 0, 1); BAR; WAIT_L(0); MMA(0, 1, At, B1); BAR;
;       LDA(At, 0, 1); WAIT_V(4); BAR; WAIT_L(0); MMA(1, 0, At, B0); MMA(1, 1, At, B1); BAR; }
;     { LDB(B0, 1, 0); LDA(At, 1, 0); WAIT_V(2); BAR; WAIT_L(0); MMA(0, 0, At, B0); BAR;
	s_waitcnt lgkmcnt(0)
	s_waitcnt lgkmcnt(0)
	v_mfma_f32_16x16x32_bf16 v[92:95], v[176:179], v[208:211], v[92:95]
	v_mfma_f32_16x16x32_bf16 v[88:91], v[176:179], v[216:219], v[88:91]
	v_mfma_f32_16x16x32_bf16 v[76:79], v[192:195], v[208:211], v[76:79]
	v_mfma_f32_16x16x32_bf16 v[72:75], v[192:195], v[216:219], v[72:75]
	v_mfma_f32_16x16x32_bf16 v[84:87], v[184:187], v[208:211], v[84:87]
	v_mfma_f32_16x16x32_bf16 v[80:83], v[184:187], v[216:219], v[80:83]
	v_mfma_f32_16x16x32_bf16 v[68:71], v[200:203], v[208:211], v[68:71]
	v_mfma_f32_16x16x32_bf16 v[64:67], v[200:203], v[216:219], v[64:67]
	v_mfma_f32_16x16x32_bf16 v[92:95], v[180:183], v[212:215], v[92:95]
	v_mfma_f32_16x16x32_bf16 v[88:91], v[180:183], v[220:223], v[88:91]
	v_mfma_f32_16x16x32_bf16 v[76:79], v[196:199], v[212:215], v[76:79]
	v_mfma_f32_16x16x32_bf16 v[72:75], v[196:199], v[220:223], v[72:75]
	v_mfma_f32_16x16x32_bf16 v[176:179], v[188:191], v[212:215], v[84:87]
	v_mfma_f32_16x16x32_bf16 v[180:183], v[188:191], v[220:223], v[80:83]
	v_mfma_f32_16x16x32_bf16 v[184:187], v[204:207], v[212:215], v[68:71]
	v_mfma_f32_16x16x32_bf16 v[188:191], v[204:207], v[220:223], v[64:67]
	s_barrier
	s_nop 0
	ds_read_b128 v[64:67], v152 offset:16384
	ds_read_b128 v[68:71], v152 offset:17408
	ds_read_b128 v[80:83], v151 offset:16384
	ds_read_b128 v[84:87], v151 offset:17408
	ds_read_b128 v[192:195], v150 offset:16384
	ds_read_b128 v[196:199], v150 offset:17408
	ds_read_b128 v[200:203], v149 offset:16384
	ds_read_b128 v[204:207], v149 offset:17408
	s_waitcnt vmcnt(4)
	s_barrier
	s_waitcnt lgkmcnt(0)
	s_waitcnt lgkmcnt(0)
	v_mfma_f32_16x16x32_bf16 v[60:63], v[64:67], v[134:137], v[60:63]
	v_mfma_f32_16x16x32_bf16 v[56:59], v[64:67], v[156:159], v[56:59]
	v_mfma_f32_16x16x32_bf16 v[52:55], v[80:83], v[134:137], v[52:55]
	v_mfma_f32_16x16x32_bf16 v[48:51], v[80:83], v[156:159], v[48:51]
	v_mfma_f32_16x16x32_bf16 v[44:47], v[192:195], v[134:137], v[44:47]
	v_mfma_f32_16x16x32_bf16 v[40:43], v[192:195], v[156:159], v[40:43]
	v_mfma_f32_16x16x32_bf16 v[36:39], v[200:203], v[134:137], v[36:39]
	v_mfma_f32_16x16x32_bf16 v[32:35], v[200:203], v[156:159], v[32:35]
	v_mfma_f32_16x16x32_bf16 v[60:63], v[68:71], v[138:141], v[60:63]
	v_mfma_f32_16x16x32_bf16 v[56:59], v[68:71], v[172:175], v[56:59]
	v_mfma_f32_16x16x32_bf16 v[52:55], v[84:87], v[138:141], v[52:55]
	v_mfma_f32_16x16x32_bf16 v[48:51], v[84:87], v[172:175], v[48:51]
	v_mfma_f32_16x16x32_bf16 v[44:47], v[196:199], v[138:141], v[44:47]
	v_mfma_f32_16x16x32_bf16 v[40:43], v[196:199], v[172:175], v[40:43]
	v_mfma_f32_16x16x32_bf16 v[36:39], v[204:207], v[138:141], v[36:39]
	v_mfma_f32_16x16x32_bf16 v[32:35], v[204:207], v[172:175], v[32:35]
	v_mfma_f32_16x16x32_bf16 v[28:31], v[64:67], v[208:211], v[28:31]
	v_mfma_f32_16x16x32_bf16 v[24:27], v[64:67], v[216:219], v[24:27]
	v_mfma_f32_16x16x32_bf16 v[12:15], v[192:195], v[208:211], v[12:15]
	v_mfma_f32_16x16x32_bf16 v[8:11], v[192:195], v[216:219], v[8:11]
	v_mfma_f32_16x16x32_bf16 v[20:23], v[80:83], v[208:211], v[20:23]
	v_mfma_f32_16x16x32_bf16 v[16:19], v[80:83], v[216:219], v[16:19]
	v_mfma_f32_16x16x32_bf16 v[4:7], v[200:203], v[208:211], v[4:7]
	v_mfma_f32_16x16x32_bf16 v[0:3], v[200:203], v[216:219], v[0:3]
	v_mfma_f32_16x16x32_bf16 v[28:31], v[68:71], v[212:215], v[28:31]
	v_mfma_f32_16x16x32_bf16 v[24:27], v[68:71], v[220:223], v[24:27]
	v_mfma_f32_16x16x32_bf16 v[12:15], v[196:199], v[212:215], v[12:15]
	v_mfma_f32_16x16x32_bf16 v[8:11], v[196:199], v[220:223], v[8:11]
	v_mfma_f32_16x16x32_bf16 v[134:137], v[84:87], v[212:215], v[20:23]
	v_mfma_f32_16x16x32_bf16 v[138:141], v[84:87], v[220:223], v[16:19]
	v_mfma_f32_16x16x32_bf16 v[156:159], v[204:207], v[212:215], v[4:7]
	v_mfma_f32_16x16x32_bf16 v[170:173], v[204:207], v[220:223], v[0:3]
	s_barrier
	s_nop 0
	ds_read_b128 v[0:3], v155
	ds_read_b128 v[4:7], v155 offset:1024
	ds_read_b128 v[16:19], v155 offset:2048
	ds_read_b128 v[192:195], v155 offset:3072
	ds_read_b128 v[20:23], v152 offset:32768
	ds_read_b128 v[196:199], v152 offset:33792
	ds_read_b128 v[200:203], v151 offset:32768
	ds_read_b128 v[204:207], v151 offset:33792
	ds_read_b128 v[208:211], v150 offset:32768
	ds_read_b128 v[212:215], v150 offset:33792
	ds_read_b128 v[216:219], v149 offset:32768
	ds_read_b128 v[220:223], v149 offset:33792
	s_waitcnt vmcnt(2)
	s_barrier
; #define LDA(dst, b, h) for (int m = 0; m < 4; ++m) for (int k = 0; k < 2; ++k) \
;     dst[m][k] = *reinterpret_cast<const bf16x8*>((char*)SA(b, h) + lds_byte(wr * 64 + m * 16 + fr, k * 32 + fq * 8))
; #define LDB(dst, b, h) for (int n = 0; n < 2; ++n) for (int k = 0; k < 2; ++k) \
;     dst[n][k] = *reinterpret_cast<const bf16x8*>((char*)SB(b, h) + lds_byte(wc * 32 + n * 16 + fr, k * 32 + fq * 8))
; #define MMA(ai, bj, At_, Bt_) do { __builtin_amdgcn_s_setprio(1); \
;     for (int k = 0; k < 2; ++k) for (int m = 0; m < 4; ++m) for (int n = 0; n < 2; ++n) \
;       acc[ai][bj][m][n] = __builtin_amdgcn_mfma_f32_16x16x32_bf16(At_[m][k], Bt_[n][k], acc[ai][bj][m][n], 0, 0, 0); \
;     __builtin_amdgcn_s_setprio(0); } while (0)
; #define WAIT_V(n) asm volatile("s_waitcnt vmcnt(" #n ")" ::: "memory")
; #define WAIT_L(n) asm volatile("s_waitcnt lgkmcnt(" #n ")" ::: "memory")
; #define BAR __builtin_amdgcn_s_barrier()
; template <int EPI, int lda, int ldb, int N, int K>
; __device__ __forceinline__ void gemm_phase(const u16* __restrict__ A, const u16* __restrict__ Bt, const GemmEpi ep, int wv) {
;     ...
;     { LDB(B0, 1, 0); LDA(At, 1, 0); WAIT_V(2); BAR; WAIT_L(0); MMA(0, 0, At, B0); BAR;
;       LDB(B1, 1, 1); WAIT_V(0); BAR; WAIT_L(0); MMA(0, 1, At, B1); BAR;
;       LDA(At, 1, 1); BAR; WAIT_L(0); MMA(1, 0, At, B0); MMA(1, 1, At, B1); BAR; }
;     if (wr == 0) BAR;
	s_waitcnt lgkmcnt(0)
	s_waitcnt lgkmcnt(0)
	v_mfma_f32_16x16x32_bf16 v[64:67], v[20:23], v[0:3], v[124:127]
	v_mfma_f32_16x16x32_bf16 v[68:71], v[20:23], v[16:19], v[120:123]
	v_mfma_f32_16x16x32_bf16 v[80:83], v[200:203], v[0:3], v[116:119]
	v_mfma_f32_16x16x32_bf16 v[84:87], v[200:203], v[16:19], v[112:115]
	v_mfma_f32_16x16x32_bf16 v[108:111], v[208:211], v[0:3], v[108:111]
	v_mfma_f32_16x16x32_bf16 v[104:107], v[208:211], v[16:19], v[104:107]
	v_mfma_f32_16x16x32_bf16 v[120:123], v[216:219], v[0:3], v[100:103]
	v_mfma_f32_16x16x32_bf16 v[124:127], v[216:219], v[16:19], v[96:99]
	v_mfma_f32_16x16x32_bf16 v[116:119], v[196:199], v[4:7], v[64:67]
	v_mfma_f32_16x16x32_bf16 v[112:115], v[196:199], v[192:195], v[68:71]
	v_mfma_f32_16x16x32_bf16 v[100:103], v[204:207], v[4:7], v[80:83]
	v_mfma_f32_16x16x32_bf16 v[96:99], v[204:207], v[192:195], v[84:87]
	v_mfma_f32_16x16x32_bf16 v[84:87], v[212:215], v[4:7], v[108:111]
	v_mfma_f32_16x16x32_bf16 v[80:83], v[212:215], v[192:195], v[104:107]
	v_mfma_f32_16x16x32_bf16 v[68:71], v[220:223], v[4:7], v[120:123]
	v_mfma_f32_16x16x32_bf16 v[64:67], v[220:223], v[192:195], v[124:127]
	s_barrier
	ds_read_b128 v[224:227], v153
	ds_read_b128 v[228:231], v153 offset:1024
	ds_read_b128 v[232:235], v153 offset:2048
	ds_read_b128 v[236:239], v153 offset:3072
	s_waitcnt vmcnt(0)
	s_barrier
	s_waitcnt lgkmcnt(0)
	s_waitcnt lgkmcnt(0)
	v_mfma_f32_16x16x32_bf16 v[92:95], v[20:23], v[224:227], v[92:95]
	v_mfma_f32_16x16x32_bf16 v[20:23], v[20:23], v[232:235], v[88:91]
	v_mfma_f32_16x16x32_bf16 v[88:91], v[200:203], v[224:227], v[176:179]
	v_mfma_f32_16x16x32_bf16 v[104:107], v[200:203], v[232:235], v[180:183]
	v_mfma_f32_16x16x32_bf16 v[76:79], v[208:211], v[224:227], v[76:79]
	v_mfma_f32_16x16x32_bf16 v[72:75], v[208:211], v[232:235], v[72:75]
	v_mfma_f32_16x16x32_bf16 v[174:177], v[216:219], v[224:227], v[184:187]
	v_mfma_f32_16x16x32_bf16 v[178:181], v[216:219], v[232:235], v[188:191]
	v_mfma_f32_16x16x32_bf16 v[124:127], v[196:199], v[228:231], v[92:95]
	v_mfma_f32_16x16x32_bf16 v[120:123], v[196:199], v[236:239], v[20:23]
	v_mfma_f32_16x16x32_bf16 v[108:111], v[204:207], v[228:231], v[88:91]
	v_mfma_f32_16x16x32_bf16 v[104:107], v[204:207], v[236:239], v[104:107]
	v_mfma_f32_16x16x32_bf16 v[92:95], v[212:215], v[228:231], v[76:79]
	v_mfma_f32_16x16x32_bf16 v[88:91], v[212:215], v[236:239], v[72:75]
	v_mfma_f32_16x16x32_bf16 v[76:79], v[220:223], v[228:231], v[174:177]
	v_mfma_f32_16x16x32_bf16 v[72:75], v[220:223], v[236:239], v[178:181]
	s_barrier
	ds_read_b128 v[174:177], v152 offset:49152
	ds_read_b128 v[152:155], v152 offset:50176
	ds_read_b128 v[178:181], v151 offset:49152
	ds_read_b128 v[182:185], v151 offset:50176
	ds_read_b128 v[186:189], v150 offset:49152
	ds_read_b128 v[196:199], v150 offset:50176
	ds_read_b128 v[200:203], v149 offset:49152
	ds_read_b128 v[204:207], v149 offset:50176
	s_barrier
	s_waitcnt lgkmcnt(0)
	s_waitcnt lgkmcnt(0)
	v_mfma_f32_16x16x32_bf16 v[20:23], v[174:177], v[0:3], v[60:63]
	v_mfma_f32_16x16x32_bf16 v[56:59], v[174:177], v[16:19], v[56:59]
	v_mfma_f32_16x16x32_bf16 v[60:63], v[178:181], v[0:3], v[52:55]
	v_mfma_f32_16x16x32_bf16 v[208:211], v[178:181], v[16:19], v[48:51]
	v_mfma_f32_16x16x32_bf16 v[44:47], v[186:189], v[0:3], v[44:47]
	v_mfma_f32_16x16x32_bf16 v[40:43], v[186:189], v[16:19], v[40:43]
	v_mfma_f32_16x16x32_bf16 v[0:3], v[200:203], v[0:3], v[36:39]
	v_mfma_f32_16x16x32_bf16 v[212:215], v[200:203], v[16:19], v[32:35]
	v_mfma_f32_16x16x32_bf16 v[52:55], v[152:155], v[4:7], v[20:23]
	v_mfma_f32_16x16x32_bf16 v[48:51], v[152:155], v[192:195], v[56:59]
	v_mfma_f32_16x16x32_bf16 v[36:39], v[182:185], v[4:7], v[60:63]
	v_mfma_f32_16x16x32_bf16 v[32:35], v[182:185], v[192:195], v[208:211]
	v_mfma_f32_16x16x32_bf16 v[20:23], v[196:199], v[4:7], v[44:47]
	v_mfma_f32_16x16x32_bf16 v[16:19], v[196:199], v[192:195], v[40:43]
	v_mfma_f32_16x16x32_bf16 v[4:7], v[204:207], v[4:7], v[0:3]
	v_mfma_f32_16x16x32_bf16 v[0:3], v[204:207], v[192:195], v[212:215]
	v_mfma_f32_16x16x32_bf16 v[28:31], v[174:177], v[224:227], v[28:31]
	v_mfma_f32_16x16x32_bf16 v[24:27], v[174:177], v[232:235], v[24:27]
	v_mfma_f32_16x16x32_bf16 v[40:43], v[178:181], v[224:227], v[134:137]
	v_mfma_f32_16x16x32_bf16 v[134:137], v[178:181], v[232:235], v[138:141]
	v_mfma_f32_16x16x32_bf16 v[12:15], v[186:189], v[224:227], v[12:15]
	v_mfma_f32_16x16x32_bf16 v[8:11], v[186:189], v[232:235], v[8:11]
	v_mfma_f32_16x16x32_bf16 v[138:141], v[200:203], v[224:227], v[156:159]
	v_mfma_f32_16x16x32_bf16 v[156:159], v[200:203], v[232:235], v[170:173]
	v_mfma_f32_16x16x32_bf16 v[60:63], v[152:155], v[228:231], v[28:31]
	v_mfma_f32_16x16x32_bf16 v[56:59], v[152:155], v[236:239], v[24:27]
	v_mfma_f32_16x16x32_bf16 v[44:47], v[182:185], v[228:231], v[40:43]
	v_mfma_f32_16x16x32_bf16 v[40:43], v[182:185], v[236:239], v[134:137]
	v_mfma_f32_16x16x32_bf16 v[28:31], v[196:199], v[228:231], v[12:15]
	v_mfma_f32_16x16x32_bf16 v[24:27], v[196:199], v[236:239], v[8:11]
	v_mfma_f32_16x16x32_bf16 v[12:15], v[204:207], v[228:231], v[138:141]
	v_mfma_f32_16x16x32_bf16 v[8:11], v[204:207], v[236:239], v[156:159]
	v_cmp_gt_u32_e32 vcc, s80, v130
	s_barrier
	s_and_saveexec_b64 s[60:61], vcc
	s_cbranch_execz .LBB0_1150
	s_barrier

; #define STAGE(P, BASE, LD, br, kt) do { const char* _g = (const char*)((BASE) + (size_t)(br) * (LD) + (size_t)(kt) * 64); \
;     for (int _i = 0; _i < 2; ++_i) { int _b = tidx * 16 + _i * 8192; int _r, _c; stage_rc(_b, _r, _c); \
;       __builtin_amdgcn_global_load_lds((const unsigned*)(_g + (unsigned)((_r * (LD) + _c) * 2)), (unsigned*)((char*)(P) + _b), 16, 0, 0); } } while (0)
; #define LDA(dst, b, h) for (int m = 0; m < 4; ++m) for (int k = 0; k < 2; ++k) \
;     dst[m][k] = *reinterpret_cast<const bf16x8*>((char*)SA(b, h) + lds_byte(wr * 64 + m * 16 + fr, k * 32 + fq * 8))
; #define LDB(dst, b, h) for (int n = 0; n < 2; ++n) for (int k = 0; k < 2; ++k) \
;     dst[n][k] = *reinterpret_cast<const bf16x8*>((char*)SB(b, h) + lds_byte(wc * 32 + n * 16 + fr, k * 32 + fq * 8))
; #define MMA(ai, bj, At_, Bt_) do { __builtin_amdgcn_s_setprio(1); \
;     for (int k = 0; k < 2; ++k) for (int m = 0; m < 4; ++m) for (int n = 0; n < 2; ++n) \
;       acc[ai][bj][m][n] = __builtin_amdgcn_mfma_f32_16x16x32_bf16(At_[m][k], Bt_[n][k], acc[ai][bj][m][n], 0, 0, 0); \
;     __builtin_amdgcn_s_setprio(0); } while (0)
; #define WAIT_V(n) asm volatile("s_waitcnt vmcnt(" #n ")" ::: "memory")
; #define WAIT_L(n) asm volatile("s_waitcnt lgkmcnt(" #n ")" ::: "memory")
; #define BAR __builtin_amdgcn_s_barrier()
; template <int EPI, int lda, int ldb, int N, int K>
; __device__ __forceinline__ void gemm_phase(const u16* __restrict__ A, const u16* __restrict__ Bt, const GemmEpi ep, int wv) {
;     ...
;     if (wr == 1) BAR;
;     WAIT_V(4); BAR;
;     STAGE(SB(1, 0), Bt, ldb, bcol, 1); STAGE(SA(1, 0), Ab, lda, brow, 1); STAGE(SB(1, 1), Bt, ldb, bcol + HALF, 1);
;     WAIT_V(6); BAR;
;     for (int t = 0; t < nt - 2; t += 2) {
;       LDB(B0, 0, 0); SCHED; LDA(At, 0, 0); STAGE(SA(1, 1), Ab, lda, brow + HALF, t + 1);
;       WAIT_L(8); BAR; WAIT_L(0); MMA(0, 0, At, B0); BAR; SCHED;
;       LDB(B1, 0, 1); STAGE(SB(0, 0), Bt, ldb, bcol, t + 2);
;       BAR; WAIT_L(0); MMA(0, 1, At, B1); BAR;
;       LDA(At, 0, 1); STAGE(SA(0, 0), Ab, lda, brow, t + 2);
;       BAR; WAIT_L(0); MMA(1, 0, At, B0); BAR; SCHED;
;       STAGE(SB(0, 1), Bt, ldb, bcol + HALF, t + 2);
;       WAIT_V(6); BAR; MMA(1, 1, At, B1); BAR;
;       LDB(B0, 1, 0); SCHED; LDA(At, 1, 0); STAGE(SA(0, 1), Ab, lda, brow + HALF, t + 2);
;       WAIT_L(8); BAR; WAIT_L(0); MMA(0, 0, At, B0); BAR; SCHED;
.LBB0_1248:
	s_or_b64 exec, exec, s[54:55]
	v_mov_b32_e32 v1, v129
	v_add_u32_e32 v7, s60, v6
	v_lshl_add_u64 v[12:13], s[46:47], 0, v[128:129]
	v_lshl_add_u64 v[14:15], s[46:47], 0, v[0:1]
	v_lshl_add_u64 v[2:3], s[52:53], 0, v[128:129]
	v_lshl_add_u64 v[0:1], s[52:53], 0, v[0:1]
	v_readfirstlane_b32 s53, v7
	v_add_u32_e32 v7, 0x2000, v7
	v_mov_b32_e32 v5, v129
	v_mov_b32_e32 v17, v129
	v_lshl_add_u64 v[26:27], v[12:13], 0, s[40:41]
	s_mov_b32 m0, s53
	v_readfirstlane_b32 s52, v7
	v_add_u32_e32 v7, 0x8000, v23
	v_lshl_add_u64 v[8:9], s[50:51], 0, v[4:5]
	v_lshl_add_u64 v[10:11], s[50:51], 0, v[16:17]
	s_waitcnt vmcnt(4)
	s_barrier
	global_load_lds_dwordx4 v[26:27], off
	v_lshl_add_u64 v[26:27], v[14:15], 0, s[40:41]
	s_mov_b32 m0, s52
	v_readfirstlane_b32 s51, v7
	v_add_u32_e32 v7, 0xa000, v23
	global_load_lds_dwordx4 v[26:27], off
	v_lshl_add_u64 v[26:27], v[8:9], 0, s[40:41]
	s_mov_b32 m0, s51
	v_readfirstlane_b32 s50, v7
	v_add_u32_e32 v25, s61, v6
	global_load_lds_dwordx4 v[26:27], off
	v_lshl_add_u64 v[26:27], v[10:11], 0, s[40:41]
	s_mov_b32 m0, s50
	v_readfirstlane_b32 s13, v25
	v_add_u32_e32 v25, 0x2000, v25
	global_load_lds_dwordx4 v[26:27], off
	v_lshl_add_u64 v[26:27], v[2:3], 0, s[40:41]
	s_mov_b32 m0, s13
	v_readfirstlane_b32 s11, v25
	global_load_lds_dwordx4 v[26:27], off
	v_lshl_add_u64 v[6:7], v[0:1], 0, s[40:41]
	s_mov_b32 m0, s11
	v_and_b32_e32 v132, 15, v20
	global_load_lds_dwordx4 v[6:7], off
	v_bfe_u32 v128, v20, 4, 2
	v_lshlrev_b32_e32 v7, 2, v20
	v_bfe_u32 v131, v130, 6, 2
	v_lshlrev_b32_e32 v25, 4, v128
	v_lshlrev_b32_e32 v6, 6, v132
	v_and_b32_e32 v50, 32, v7
	v_lshlrev_b32_e32 v126, 12, v131
	v_bitop3_b32 v127, v25, v50, v6 bitop3:0x36
	v_add3_u32 v133, s58, v127, v126
	s_waitcnt vmcnt(6)
	s_barrier
	ds_read_b128 v[26:29], v133
	ds_read_b128 v[30:33], v133 offset:1024
	ds_read_b128 v[34:37], v133 offset:2048
	ds_read_b128 v[38:41], v133 offset:3072
	v_lshl_add_u64 v[6:7], s[48:49], 0, v[4:5]
	v_lshl_add_u64 v[4:5], s[48:49], 0, v[16:17]
	v_lshlrev_b32_e32 v17, 6, v20
	v_and_b32_e32 v17, 0x3c0, v17
	v_add_u32_e32 v20, 0xc000, v23
	v_lshlrev_b32_e32 v16, 13, v143
	v_bitop3_b32 v17, v17, v50, v25 bitop3:0x36
	v_readfirstlane_b32 s47, v20
	v_add_u32_e32 v20, 0xe000, v23
	v_add3_u32 v228, 0, v127, v16
	v_add3_u32 v229, 0, v17, v16
	v_lshl_add_u64 v[16:17], v[6:7], 0, s[40:41]
	s_mov_b32 m0, s47
	v_readfirstlane_b32 s46, v20
	ds_read_b128 v[42:45], v228
	ds_read_b128 v[46:49], v228 offset:1024
	ds_read_b128 v[50:53], v229 offset:2048
	ds_read_b128 v[54:57], v229 offset:3072
	ds_read_b128 v[58:61], v229 offset:4096
	ds_read_b128 v[62:65], v229 offset:5120
	ds_read_b128 v[66:69], v229 offset:6144
	ds_read_b128 v[70:73], v229 offset:7168
	global_load_lds_dwordx4 v[16:17], off
	v_lshl_add_u64 v[16:17], v[4:5], 0, s[40:41]
	s_mov_b32 m0, s46
	s_nop 0
	global_load_lds_dwordx4 v[16:17], off
	s_waitcnt lgkmcnt(8)
	s_barrier
	s_waitcnt lgkmcnt(0)
	s_waitcnt lgkmcnt(0)
	v_mfma_f32_16x16x32_bf16 v[74:77], v[42:45], v[26:29], 0
	v_mfma_f32_16x16x32_bf16 v[78:81], v[42:45], v[34:37], 0
	v_mfma_f32_16x16x32_bf16 v[82:85], v[50:53], v[26:29], 0
	v_mfma_f32_16x16x32_bf16 v[86:89], v[50:53], v[34:37], 0
	v_mfma_f32_16x16x32_bf16 v[90:93], v[58:61], v[26:29], 0
	v_mfma_f32_16x16x32_bf16 v[94:97], v[58:61], v[34:37], 0
	v_mfma_f32_16x16x32_bf16 v[98:101], v[66:69], v[26:29], 0
	v_mfma_f32_16x16x32_bf16 v[102:105], v[66:69], v[34:37], 0
	v_mfma_f32_16x16x32_bf16 v[74:77], v[46:49], v[30:33], v[74:77]
	v_mfma_f32_16x16x32_bf16 v[78:81], v[46:49], v[38:41], v[78:81]
	v_mfma_f32_16x16x32_bf16 v[82:85], v[54:57], v[30:33], v[82:85]
	v_mfma_f32_16x16x32_bf16 v[86:89], v[54:57], v[38:41], v[86:89]
	v_mfma_f32_16x16x32_bf16 v[90:93], v[62:65], v[30:33], v[90:93]
	v_mfma_f32_16x16x32_bf16 v[94:97], v[62:65], v[38:41], v[94:97]
	v_mfma_f32_16x16x32_bf16 v[98:101], v[70:73], v[30:33], v[98:101]
	v_mfma_f32_16x16x32_bf16 v[102:105], v[70:73], v[38:41], v[102:105]
	s_barrier
	v_readfirstlane_b32 s48, v21
	v_add_u32_e32 v20, 0x2000, v21
	v_add3_u32 v224, s59, v127, v126
	v_lshl_add_u64 v[16:17], v[12:13], 0, s[42:43]
	s_mov_b32 m0, s48
	v_readfirstlane_b32 s48, v20
	global_load_lds_dwordx4 v[16:17], off
	v_lshl_add_u64 v[16:17], v[14:15], 0, s[42:43]
	s_mov_b32 m0, s48
	s_nop 0
	global_load_lds_dwordx4 v[16:17], off
	ds_read_b128 v[106:109], v224
	ds_read_b128 v[110:113], v224 offset:1024
	ds_read_b128 v[114:117], v224 offset:2048
	ds_read_b128 v[118:121], v224 offset:3072
	s_barrier
	s_waitcnt lgkmcnt(0)
	s_waitcnt lgkmcnt(0)
	v_mfma_f32_16x16x32_bf16 v[122:125], v[42:45], v[106:109], 0
	v_mfma_f32_16x16x32_bf16 v[42:45], v[42:45], v[114:117], 0
	v_mfma_f32_16x16x32_bf16 v[134:137], v[50:53], v[106:109], 0
	v_mfma_f32_16x16x32_bf16 v[50:53], v[50:53], v[114:117], 0
	v_mfma_f32_16x16x32_bf16 v[144:147], v[58:61], v[106:109], 0
	v_mfma_f32_16x16x32_bf16 v[58:61], v[58:61], v[114:117], 0
	v_mfma_f32_16x16x32_bf16 v[148:151], v[66:69], v[106:109], 0
	v_mfma_f32_16x16x32_bf16 v[66:69], v[66:69], v[114:117], 0
	v_mfma_f32_16x16x32_bf16 v[122:125], v[46:49], v[110:113], v[122:125]
	v_mfma_f32_16x16x32_bf16 v[42:45], v[46:49], v[118:121], v[42:45]
	v_mfma_f32_16x16x32_bf16 v[46:49], v[54:57], v[110:113], v[134:137]
	v_mfma_f32_16x16x32_bf16 v[50:53], v[54:57], v[118:121], v[50:53]
	v_mfma_f32_16x16x32_bf16 v[54:57], v[62:65], v[110:113], v[144:147]
	v_mfma_f32_16x16x32_bf16 v[58:61], v[62:65], v[118:121], v[58:61]
	v_mfma_f32_16x16x32_bf16 v[62:65], v[70:73], v[110:113], v[148:151]
	v_mfma_f32_16x16x32_bf16 v[66:69], v[70:73], v[118:121], v[66:69]
	v_readfirstlane_b32 s48, v23
	v_lshl_add_u64 v[16:17], v[8:9], 0, s[42:43]
	s_mov_b32 m0, s48
	v_readfirstlane_b32 s48, v24
	s_barrier
; #define STAGE(P, BASE, LD, br, kt) do { const char* _g = (const char*)((BASE) + (size_t)(br) * (LD) + (size_t)(kt) * 64); \
;     for (int _i = 0; _i < 2; ++_i) { int _b = tidx * 16 + _i * 8192; int _r, _c; stage_rc(_b, _r, _c); \
;       __builtin_amdgcn_global_load_lds((const unsigned*)(_g + (unsigned)((_r * (LD) + _c) * 2)), (unsigned*)((char*)(P) + _b), 16, 0, 0); } } while (0)
; #define LDA(dst, b, h) for (int m = 0; m < 4; ++m) for (int k = 0; k < 2; ++k) \
;     dst[m][k] = *reinterpret_cast<const bf16x8*>((char*)SA(b, h) + lds_byte(wr * 64 + m * 16 + fr, k * 32 + fq * 8))
; #define LDB(dst, b, h) for (int n = 0; n < 2; ++n) for (int k = 0; k < 2; ++k) \
;     dst[n][k] = *reinterpret_cast<const bf16x8*>((char*)SB(b, h) + lds_byte(wc * 32 + n * 16 + fr, k * 32 + fq * 8))
; #define MMA(ai, bj, At_, Bt_) do { __builtin_amdgcn_s_setprio(1); \
;     for (int k = 0; k < 2; ++k) for (int m = 0; m < 4; ++m) for (int n = 0; n < 2; ++n) \
;       acc[ai][bj][m][n] = __builtin_amdgcn_mfma_f32_16x16x32_bf16(At_[m][k], Bt_[n][k], acc[ai][bj][m][n], 0, 0, 0); \
;     __builtin_amdgcn_s_setprio(0); } while (0)
; #define WAIT_V(n) asm volatile("s_waitcnt vmcnt(" #n ")" ::: "memory")
; #define WAIT_L(n) asm volatile("s_waitcnt lgkmcnt(" #n ")" ::: "memory")
; #define BAR __builtin_amdgcn_s_barrier()
; #define SCHED __builtin_amdgcn_sched_barrier(0)
; template <int EPI, int lda, int ldb, int N, int K>
; __device__ __forceinline__ void gemm_phase(const u16* __restrict__ A, const u16* __restrict__ Bt, const GemmEpi ep, int wv) {
;     ...
;       LDB(B1, 1, 1); STAGE(SB(1, 0), Bt, ldb, bcol, t + 3);
;       BAR; WAIT_L(0); MMA(0, 1, At, B1); BAR;
;       LDA(At, 1, 1); STAGE(SA(1, 0), Ab, lda, brow, t + 3);
;       BAR; WAIT_L(0); MMA(1, 0, At, B0); BAR; SCHED;
;       STAGE(SB(1, 1), Bt, ldb, bcol + HALF, t + 3);
;       WAIT_V(6); BAR; MMA(1, 1, At, B1); BAR;
	global_load_lds_dwordx4 v[16:17], off
	v_lshl_add_u64 v[16:17], v[10:11], 0, s[42:43]
	s_mov_b32 m0, s48
	s_nop 0
	global_load_lds_dwordx4 v[16:17], off
	ds_read_b128 v[70:73], v228 offset:16384
	ds_read_b128 v[134:137], v228 offset:17408
	ds_read_b128 v[144:147], v229 offset:18432
	ds_read_b128 v[148:151], v229 offset:19456
	ds_read_b128 v[152:155], v229 offset:20480
	ds_read_b128 v[156:159], v229 offset:21504
	ds_read_b128 v[160:163], v229 offset:22528
	ds_read_b128 v[164:167], v229 offset:23552
	s_barrier
	s_waitcnt lgkmcnt(0)
	s_waitcnt lgkmcnt(0)
	v_mfma_f32_16x16x32_bf16 v[168:171], v[70:73], v[26:29], 0
	v_mfma_f32_16x16x32_bf16 v[172:175], v[70:73], v[34:37], 0
	v_mfma_f32_16x16x32_bf16 v[176:179], v[144:147], v[26:29], 0
	v_mfma_f32_16x16x32_bf16 v[180:183], v[144:147], v[34:37], 0
	v_mfma_f32_16x16x32_bf16 v[184:187], v[152:155], v[26:29], 0
	v_mfma_f32_16x16x32_bf16 v[188:191], v[152:155], v[34:37], 0
	v_mfma_f32_16x16x32_bf16 v[24:27], v[160:163], v[26:29], 0
	v_mfma_f32_16x16x32_bf16 v[34:37], v[160:163], v[34:37], 0
	v_mfma_f32_16x16x32_bf16 v[168:171], v[134:137], v[30:33], v[168:171]
	v_mfma_f32_16x16x32_bf16 v[176:179], v[148:151], v[30:33], v[176:179]
	v_mfma_f32_16x16x32_bf16 v[184:187], v[156:159], v[30:33], v[184:187]
	v_mfma_f32_16x16x32_bf16 v[24:27], v[164:167], v[30:33], v[24:27]
	v_mfma_f32_16x16x32_bf16 v[28:31], v[164:167], v[38:41], v[34:37]
	v_mfma_f32_16x16x32_bf16 v[172:175], v[134:137], v[38:41], v[172:175]
	v_mfma_f32_16x16x32_bf16 v[180:183], v[148:151], v[38:41], v[180:183]
	v_mfma_f32_16x16x32_bf16 v[188:191], v[156:159], v[38:41], v[188:191]
	s_barrier
	v_readfirstlane_b32 s48, v22
	v_add_u32_e32 v20, 0x2000, v22
	v_lshl_add_u64 v[16:17], v[2:3], 0, s[42:43]
	s_mov_b32 m0, s48
	v_readfirstlane_b32 s48, v20
	global_load_lds_dwordx4 v[16:17], off
	v_lshl_add_u64 v[16:17], v[0:1], 0, s[42:43]
	s_mov_b32 m0, s48
	s_nop 0
	global_load_lds_dwordx4 v[16:17], off
	s_waitcnt vmcnt(6)
	s_barrier
	v_mfma_f32_16x16x32_bf16 v[20:23], v[70:73], v[106:109], 0
	v_mfma_f32_16x16x32_bf16 v[32:35], v[70:73], v[114:117], 0
	v_mfma_f32_16x16x32_bf16 v[36:39], v[144:147], v[106:109], 0
	v_mfma_f32_16x16x32_bf16 v[70:73], v[144:147], v[114:117], 0
	v_mfma_f32_16x16x32_bf16 v[144:147], v[152:155], v[106:109], 0
	v_mfma_f32_16x16x32_bf16 v[152:155], v[152:155], v[114:117], 0
	v_mfma_f32_16x16x32_bf16 v[106:109], v[160:163], v[106:109], 0
	v_mfma_f32_16x16x32_bf16 v[114:117], v[160:163], v[114:117], 0
	v_mfma_f32_16x16x32_bf16 v[20:23], v[134:137], v[110:113], v[20:23]
	v_mfma_f32_16x16x32_bf16 v[32:35], v[134:137], v[118:121], v[32:35]
	v_mfma_f32_16x16x32_bf16 v[36:39], v[148:151], v[110:113], v[36:39]
	v_mfma_f32_16x16x32_bf16 v[70:73], v[148:151], v[118:121], v[70:73]
	v_mfma_f32_16x16x32_bf16 v[134:137], v[156:159], v[110:113], v[144:147]
	v_mfma_f32_16x16x32_bf16 v[106:109], v[164:167], v[110:113], v[106:109]
	v_mfma_f32_16x16x32_bf16 v[110:113], v[164:167], v[118:121], v[114:117]
	v_mfma_f32_16x16x32_bf16 v[144:147], v[156:159], v[118:121], v[152:155]
	v_add3_u32 v225, s60, v127, v126
	s_barrier
	ds_read_b128 v[114:117], v225
	ds_read_b128 v[118:121], v225 offset:1024
	ds_read_b128 v[148:151], v225 offset:2048
	ds_read_b128 v[152:155], v225 offset:3072
	v_readfirstlane_b32 s48, v18
	v_lshl_add_u64 v[16:17], v[6:7], 0, s[42:43]
	s_mov_b32 m0, s48
	v_readfirstlane_b32 s48, v19
	global_load_lds_dwordx4 v[16:17], off
	v_lshl_add_u64 v[16:17], v[4:5], 0, s[42:43]
	s_mov_b32 m0, s48
	s_nop 0
	global_load_lds_dwordx4 v[16:17], off
	ds_read_b128 v[156:159], v228 offset:32768
	ds_read_b128 v[160:163], v228 offset:33792
	ds_read_b128 v[164:167], v229 offset:34816
	ds_read_b128 v[192:195], v229 offset:35840
	ds_read_b128 v[196:199], v229 offset:36864
	ds_read_b128 v[200:203], v229 offset:37888
	ds_read_b128 v[204:207], v229 offset:38912
	ds_read_b128 v[208:211], v229 offset:39936
	s_waitcnt lgkmcnt(8)
	s_barrier
	s_waitcnt lgkmcnt(0)
	s_waitcnt lgkmcnt(0)
	v_mfma_f32_16x16x32_bf16 v[16:19], v[156:159], v[114:117], v[74:77]
	v_mfma_f32_16x16x32_bf16 v[74:77], v[156:159], v[148:151], v[78:81]
	v_mfma_f32_16x16x32_bf16 v[78:81], v[164:167], v[114:117], v[82:85]
	v_mfma_f32_16x16x32_bf16 v[82:85], v[164:167], v[148:151], v[86:89]
	v_mfma_f32_16x16x32_bf16 v[86:89], v[196:199], v[114:117], v[90:93]
	v_mfma_f32_16x16x32_bf16 v[90:93], v[196:199], v[148:151], v[94:97]
	v_mfma_f32_16x16x32_bf16 v[94:97], v[204:207], v[114:117], v[98:101]
	v_mfma_f32_16x16x32_bf16 v[98:101], v[204:207], v[148:151], v[102:105]
	v_mfma_f32_16x16x32_bf16 v[16:19], v[160:163], v[118:121], v[16:19]
	v_mfma_f32_16x16x32_bf16 v[74:77], v[160:163], v[152:155], v[74:77]
	v_mfma_f32_16x16x32_bf16 v[78:81], v[192:195], v[118:121], v[78:81]
	v_mfma_f32_16x16x32_bf16 v[82:85], v[192:195], v[152:155], v[82:85]
	v_mfma_f32_16x16x32_bf16 v[86:89], v[200:203], v[118:121], v[86:89]
	v_mfma_f32_16x16x32_bf16 v[90:93], v[200:203], v[152:155], v[90:93]
	v_mfma_f32_16x16x32_bf16 v[94:97], v[208:211], v[118:121], v[94:97]
	v_mfma_f32_16x16x32_bf16 v[98:101], v[208:211], v[152:155], v[98:101]
	s_barrier
	s_mov_b32 m0, s53
	v_add3_u32 v226, s61, v127, v126
	v_lshl_add_u64 v[12:13], v[12:13], 0, s[44:45]
	global_load_lds_dwordx4 v[12:13], off
	v_lshl_add_u64 v[12:13], v[14:15], 0, s[44:45]
	s_mov_b32 m0, s52
	s_nop 0
	global_load_lds_dwordx4 v[12:13], off
	ds_read_b128 v[102:105], v226
	ds_read_b128 v[212:215], v226 offset:1024
	ds_read_b128 v[216:219], v226 offset:2048
	ds_read_b128 v[220:223], v226 offset:3072
	s_barrier
; #define STAGE(P, BASE, LD, br, kt) do { const char* _g = (const char*)((BASE) + (size_t)(br) * (LD) + (size_t)(kt) * 64); \
;     for (int _i = 0; _i < 2; ++_i) { int _b = tidx * 16 + _i * 8192; int _r, _c; stage_rc(_b, _r, _c); \
;       __builtin_amdgcn_global_load_lds((const unsigned*)(_g + (unsigned)((_r * (LD) + _c) * 2)), (unsigned*)((char*)(P) + _b), 16, 0, 0); } } while (0)
; #define LDA(dst, b, h) for (int m = 0; m < 4; ++m) for (int k = 0; k < 2; ++k) \
;     dst[m][k] = *reinterpret_cast<const bf16x8*>((char*)SA(b, h) + lds_byte(wr * 64 + m * 16 + fr, k * 32 + fq * 8))
; #define LDB(dst, b, h) for (int n = 0; n < 2; ++n) for (int k = 0; k < 2; ++k) \
;     dst[n][k] = *reinterpret_cast<const bf16x8*>((char*)SB(b, h) + lds_byte(wc * 32 + n * 16 + fr, k * 32 + fq * 8))
; #define MMA(ai, bj, At_, Bt_) do { __builtin_amdgcn_s_setprio(1); \
;     for (int k = 0; k < 2; ++k) for (int m = 0; m < 4; ++m) for (int n = 0; n < 2; ++n) \
;       acc[ai][bj][m][n] = __builtin_amdgcn_mfma_f32_16x16x32_bf16(At_[m][k], Bt_[n][k], acc[ai][bj][m][n], 0, 0, 0); \
;     __builtin_amdgcn_s_setprio(0); } while (0)
; #define WAIT_V(n) asm volatile("s_waitcnt vmcnt(" #n ")" ::: "memory")
; #define WAIT_L(n) asm volatile("s_waitcnt lgkmcnt(" #n ")" ::: "memory")
; #define BAR __builtin_amdgcn_s_barrier()
; template <int EPI, int lda, int ldb, int N, int K>
; __device__ __forceinline__ void gemm_phase(const u16* __restrict__ A, const u16* __restrict__ Bt, const GemmEpi ep, int wv) {
;     ...
;       WAIT_V(6); BAR; MMA(1, 1, At, B1); BAR;
;     }
;     { LDB(B0, 0, 0); LDA(At, 0, 0); STAGE(SA(1, 1), Ab, lda, brow + HALF, nt - 1);
;       BAR; WAIT_L(0); MMA(0, 0, At, B0); BAR;
;       LDB(B1, 0, 1); BAR; WAIT_L(0); MMA(0, 1, At, B1); BAR;
;       LDA(At, 0, 1); WAIT_V(4); BAR; WAIT_L(0); MMA(1, 0, At, B0); MMA(1, 1, At, B1); BAR; }
;     { LDB(B0, 1, 0); LDA(At, 1, 0); WAIT_V(2); BAR; WAIT_L(0); MMA(0, 0, At, B0); BAR;
	s_waitcnt lgkmcnt(0)
	s_waitcnt lgkmcnt(0)
	v_mfma_f32_16x16x32_bf16 v[12:15], v[156:159], v[102:105], v[122:125]
	v_mfma_f32_16x16x32_bf16 v[40:43], v[156:159], v[216:219], v[42:45]
	v_mfma_f32_16x16x32_bf16 v[44:47], v[164:167], v[102:105], v[46:49]
	v_mfma_f32_16x16x32_bf16 v[48:51], v[164:167], v[216:219], v[50:53]
	v_mfma_f32_16x16x32_bf16 v[52:55], v[196:199], v[102:105], v[54:57]
	v_mfma_f32_16x16x32_bf16 v[56:59], v[196:199], v[216:219], v[58:61]
	v_mfma_f32_16x16x32_bf16 v[60:63], v[204:207], v[102:105], v[62:65]
	v_mfma_f32_16x16x32_bf16 v[64:67], v[204:207], v[216:219], v[66:69]
	v_mfma_f32_16x16x32_bf16 v[12:15], v[160:163], v[212:215], v[12:15]
	v_mfma_f32_16x16x32_bf16 v[40:43], v[160:163], v[220:223], v[40:43]
	v_mfma_f32_16x16x32_bf16 v[44:47], v[192:195], v[212:215], v[44:47]
	v_mfma_f32_16x16x32_bf16 v[48:51], v[192:195], v[220:223], v[48:51]
	v_mfma_f32_16x16x32_bf16 v[52:55], v[200:203], v[212:215], v[52:55]
	v_mfma_f32_16x16x32_bf16 v[56:59], v[200:203], v[220:223], v[56:59]
	v_mfma_f32_16x16x32_bf16 v[60:63], v[208:211], v[212:215], v[60:63]
	v_mfma_f32_16x16x32_bf16 v[64:67], v[208:211], v[220:223], v[64:67]
	s_mov_b32 m0, s51
	v_lshl_add_u64 v[8:9], v[8:9], 0, s[44:45]
	s_barrier
	global_load_lds_dwordx4 v[8:9], off
	v_lshl_add_u64 v[8:9], v[10:11], 0, s[44:45]
	s_mov_b32 m0, s50
	s_nop 0
	global_load_lds_dwordx4 v[8:9], off
	ds_read_b128 v[122:125], v228 offset:49152
	ds_read_b128 v[156:159], v228 offset:50176
	ds_read_b128 v[160:163], v229 offset:51200
	ds_read_b128 v[164:167], v229 offset:52224
	ds_read_b128 v[192:195], v229 offset:53248
	ds_read_b128 v[196:199], v229 offset:54272
	ds_read_b128 v[200:203], v229 offset:55296
	ds_read_b128 v[204:207], v229 offset:56320
	s_barrier
	s_waitcnt lgkmcnt(0)
	s_waitcnt lgkmcnt(0)
	v_mfma_f32_16x16x32_bf16 v[8:11], v[122:125], v[114:117], v[168:171]
	v_mfma_f32_16x16x32_bf16 v[168:171], v[122:125], v[148:151], v[172:175]
	v_mfma_f32_16x16x32_bf16 v[24:27], v[200:203], v[114:117], v[24:27]
	v_mfma_f32_16x16x32_bf16 v[28:31], v[200:203], v[148:151], v[28:31]
	v_mfma_f32_16x16x32_bf16 v[172:175], v[160:163], v[114:117], v[176:179]
	v_mfma_f32_16x16x32_bf16 v[176:179], v[160:163], v[148:151], v[180:183]
	v_mfma_f32_16x16x32_bf16 v[180:183], v[192:195], v[114:117], v[184:187]
	v_mfma_f32_16x16x32_bf16 v[184:187], v[192:195], v[148:151], v[188:191]
	v_mfma_f32_16x16x32_bf16 v[8:11], v[156:159], v[118:121], v[8:11]
	v_mfma_f32_16x16x32_bf16 v[114:117], v[156:159], v[152:155], v[168:171]
	v_mfma_f32_16x16x32_bf16 v[24:27], v[204:207], v[118:121], v[24:27]
	v_mfma_f32_16x16x32_bf16 v[28:31], v[204:207], v[152:155], v[28:31]
	v_mfma_f32_16x16x32_bf16 v[148:151], v[164:167], v[118:121], v[172:175]
	v_mfma_f32_16x16x32_bf16 v[168:171], v[164:167], v[152:155], v[176:179]
	v_mfma_f32_16x16x32_bf16 v[172:175], v[196:199], v[118:121], v[180:183]
	v_mfma_f32_16x16x32_bf16 v[176:179], v[196:199], v[152:155], v[184:187]
	s_barrier
	s_mov_b32 m0, s13
	v_lshl_add_u64 v[2:3], v[2:3], 0, s[44:45]
	global_load_lds_dwordx4 v[2:3], off
	v_lshl_add_u64 v[0:1], v[0:1], 0, s[44:45]
	s_mov_b32 m0, s11
	s_nop 0
	global_load_lds_dwordx4 v[0:1], off
	s_waitcnt vmcnt(6)
	s_barrier
	v_mfma_f32_16x16x32_bf16 v[0:3], v[122:125], v[102:105], v[20:23]
	v_mfma_f32_16x16x32_bf16 v[20:23], v[122:125], v[216:219], v[32:35]
	v_mfma_f32_16x16x32_bf16 v[32:35], v[160:163], v[102:105], v[36:39]
	v_mfma_f32_16x16x32_bf16 v[36:39], v[160:163], v[216:219], v[70:73]
	v_mfma_f32_16x16x32_bf16 v[68:71], v[192:195], v[102:105], v[134:137]
	v_mfma_f32_16x16x32_bf16 v[118:121], v[192:195], v[216:219], v[144:147]
	v_mfma_f32_16x16x32_bf16 v[102:105], v[200:203], v[102:105], v[106:109]
	v_mfma_f32_16x16x32_bf16 v[106:109], v[200:203], v[216:219], v[110:113]
	v_mfma_f32_16x16x32_bf16 v[0:3], v[156:159], v[212:215], v[0:3]
	v_mfma_f32_16x16x32_bf16 v[20:23], v[156:159], v[220:223], v[20:23]
	v_mfma_f32_16x16x32_bf16 v[32:35], v[164:167], v[212:215], v[32:35]
	v_mfma_f32_16x16x32_bf16 v[36:39], v[164:167], v[220:223], v[36:39]
	v_mfma_f32_16x16x32_bf16 v[68:71], v[196:199], v[212:215], v[68:71]
	v_mfma_f32_16x16x32_bf16 v[110:113], v[196:199], v[220:223], v[118:121]
	v_mfma_f32_16x16x32_bf16 v[102:105], v[204:207], v[212:215], v[102:105]
	v_mfma_f32_16x16x32_bf16 v[106:109], v[204:207], v[220:223], v[106:109]
	s_mov_b32 m0, s47
	v_lshl_add_u64 v[6:7], v[6:7], 0, s[44:45]
	s_barrier
	ds_read_b128 v[118:121], v133
	ds_read_b128 v[122:125], v133 offset:1024
	ds_read_b128 v[134:137], v133 offset:2048
	ds_read_b128 v[144:147], v133 offset:3072
	ds_read_b128 v[152:155], v228
	ds_read_b128 v[156:159], v228 offset:1024
	ds_read_b128 v[160:163], v229 offset:2048
	ds_read_b128 v[164:167], v229 offset:3072
	ds_read_b128 v[180:183], v229 offset:4096
	ds_read_b128 v[184:187], v229 offset:5120
	ds_read_b128 v[188:191], v229 offset:6144
	ds_read_b128 v[192:195], v229 offset:7168
	global_load_lds_dwordx4 v[6:7], off
	v_lshl_add_u64 v[4:5], v[4:5], 0, s[44:45]
	s_mov_b32 m0, s46
	s_nop 0
	global_load_lds_dwordx4 v[4:5], off
	s_barrier
	s_waitcnt lgkmcnt(0)
	s_waitcnt lgkmcnt(0)
	v_mfma_f32_16x16x32_bf16 v[4:7], v[152:155], v[118:121], v[16:19]
	v_mfma_f32_16x16x32_bf16 v[16:19], v[152:155], v[134:137], v[74:77]
	v_mfma_f32_16x16x32_bf16 v[72:75], v[160:163], v[118:121], v[78:81]
	v_mfma_f32_16x16x32_bf16 v[76:79], v[160:163], v[134:137], v[82:85]
	v_mfma_f32_16x16x32_bf16 v[80:83], v[180:183], v[118:121], v[86:89]
	v_mfma_f32_16x16x32_bf16 v[84:87], v[180:183], v[134:137], v[90:93]
	v_mfma_f32_16x16x32_bf16 v[88:91], v[188:191], v[118:121], v[94:97]
	v_mfma_f32_16x16x32_bf16 v[92:95], v[188:191], v[134:137], v[98:101]
	v_mfma_f32_16x16x32_bf16 v[4:7], v[156:159], v[122:125], v[4:7]
	v_mfma_f32_16x16x32_bf16 v[16:19], v[156:159], v[144:147], v[16:19]
	v_mfma_f32_16x16x32_bf16 v[72:75], v[164:167], v[122:125], v[72:75]
	v_mfma_f32_16x16x32_bf16 v[76:79], v[164:167], v[144:147], v[76:79]
	v_mfma_f32_16x16x32_bf16 v[80:83], v[184:187], v[122:125], v[80:83]
	v_mfma_f32_16x16x32_bf16 v[84:87], v[184:187], v[144:147], v[84:87]
	v_mfma_f32_16x16x32_bf16 v[88:91], v[192:195], v[122:125], v[88:91]
	v_mfma_f32_16x16x32_bf16 v[92:95], v[192:195], v[144:147], v[92:95]
	s_barrier
; #define LDA(dst, b, h) for (int m = 0; m < 4; ++m) for (int k = 0; k < 2; ++k) \
;     dst[m][k] = *reinterpret_cast<const bf16x8*>((char*)SA(b, h) + lds_byte(wr * 64 + m * 16 + fr, k * 32 + fq * 8))
; #define LDB(dst, b, h) for (int n = 0; n < 2; ++n) for (int k = 0; k < 2; ++k) \
;     dst[n][k] = *reinterpret_cast<const bf16x8*>((char*)SB(b, h) + lds_byte(wc * 32 + n * 16 + fr, k * 32 + fq * 8))
; #define MMA(ai, bj, At_, Bt_) do { __builtin_amdgcn_s_setprio(1); \
;     for (int k = 0; k < 2; ++k) for (int m = 0; m < 4; ++m) for (int n = 0; n < 2; ++n) \
;       acc[ai][bj][m][n] = __builtin_amdgcn_mfma_f32_16x16x32_bf16(At_[m][k], Bt_[n][k], acc[ai][bj][m][n], 0, 0, 0); \
;     __builtin_amdgcn_s_setprio(0); } while (0)
; #define WAIT_V(n) asm volatile("s_waitcnt vmcnt(" #n ")" ::: "memory")
; #define WAIT_L(n) asm volatile("s_waitcnt lgkmcnt(" #n ")" ::: "memory")
; #define BAR __builtin_amdgcn_s_barrier()
; template <int EPI, int lda, int ldb, int N, int K>
; __device__ __forceinline__ void gemm_phase(const u16* __restrict__ A, const u16* __restrict__ Bt, const GemmEpi ep, int wv) {
;     ...
;       LDB(B1, 0, 1); BAR; WAIT_L(0); MMA(0, 1, At, B1); BAR;
;       LDA(At, 0, 1); WAIT_V(4); BAR; WAIT_L(0); MMA(1, 0, At, B0); MMA(1, 1, At, B1); BAR; }
;     { LDB(B0, 1, 0); LDA(At, 1, 0); WAIT_V(2); BAR; WAIT_L(0); MMA(0, 0, At, B0); BAR;
	ds_read_b128 v[96:99], v224
	ds_read_b128 v[196:199], v224 offset:1024
	ds_read_b128 v[200:203], v224 offset:2048
	ds_read_b128 v[204:207], v224 offset:3072
	s_barrier
	s_waitcnt lgkmcnt(0)
	s_waitcnt lgkmcnt(0)
	v_mfma_f32_16x16x32_bf16 v[12:15], v[152:155], v[96:99], v[12:15]
	v_mfma_f32_16x16x32_bf16 v[40:43], v[152:155], v[200:203], v[40:43]
	v_mfma_f32_16x16x32_bf16 v[52:55], v[180:183], v[96:99], v[52:55]
	v_mfma_f32_16x16x32_bf16 v[56:59], v[180:183], v[200:203], v[56:59]
	v_mfma_f32_16x16x32_bf16 v[64:67], v[188:191], v[200:203], v[64:67]
	v_mfma_f32_16x16x32_bf16 v[44:47], v[160:163], v[96:99], v[44:47]
	v_mfma_f32_16x16x32_bf16 v[48:51], v[160:163], v[200:203], v[48:51]
	v_mfma_f32_16x16x32_bf16 v[60:63], v[188:191], v[96:99], v[60:63]
	v_mfma_f32_16x16x32_bf16 v[12:15], v[156:159], v[196:199], v[12:15]
	v_mfma_f32_16x16x32_bf16 v[40:43], v[156:159], v[204:207], v[40:43]
	v_mfma_f32_16x16x32_bf16 v[52:55], v[184:187], v[196:199], v[52:55]
	v_mfma_f32_16x16x32_bf16 v[56:59], v[184:187], v[204:207], v[56:59]
	v_mfma_f32_16x16x32_bf16 v[64:67], v[192:195], v[204:207], v[64:67]
	v_mfma_f32_16x16x32_bf16 v[152:155], v[164:167], v[196:199], v[44:47]
	v_mfma_f32_16x16x32_bf16 v[156:159], v[164:167], v[204:207], v[48:51]
	v_mfma_f32_16x16x32_bf16 v[160:163], v[192:195], v[196:199], v[60:63]
	s_barrier
	ds_read_b128 v[44:47], v228 offset:16384
	ds_read_b128 v[48:51], v228 offset:17408
	ds_read_b128 v[60:63], v229 offset:18432
	ds_read_b128 v[164:167], v229 offset:19456
	ds_read_b128 v[180:183], v229 offset:20480
	ds_read_b128 v[184:187], v229 offset:21504
	ds_read_b128 v[188:191], v229 offset:22528
	ds_read_b128 v[192:195], v229 offset:23552
	s_waitcnt vmcnt(4)
	s_barrier
	s_waitcnt lgkmcnt(0)
	s_waitcnt lgkmcnt(0)
	v_mfma_f32_16x16x32_bf16 v[8:11], v[44:47], v[118:121], v[8:11]
	v_mfma_f32_16x16x32_bf16 v[24:27], v[188:191], v[118:121], v[24:27]
	v_mfma_f32_16x16x32_bf16 v[28:31], v[188:191], v[134:137], v[28:31]
	v_mfma_f32_16x16x32_bf16 v[114:117], v[44:47], v[134:137], v[114:117]
	v_mfma_f32_16x16x32_bf16 v[148:151], v[60:63], v[118:121], v[148:151]
	v_mfma_f32_16x16x32_bf16 v[168:171], v[60:63], v[134:137], v[168:171]
	v_mfma_f32_16x16x32_bf16 v[172:175], v[180:183], v[118:121], v[172:175]
	v_mfma_f32_16x16x32_bf16 v[176:179], v[180:183], v[134:137], v[176:179]
	v_mfma_f32_16x16x32_bf16 v[8:11], v[48:51], v[122:125], v[8:11]
	v_mfma_f32_16x16x32_bf16 v[24:27], v[192:195], v[122:125], v[24:27]
	v_mfma_f32_16x16x32_bf16 v[28:31], v[192:195], v[144:147], v[28:31]
	v_mfma_f32_16x16x32_bf16 v[134:137], v[48:51], v[144:147], v[114:117]
	v_mfma_f32_16x16x32_bf16 v[148:151], v[164:167], v[122:125], v[148:151]
	v_mfma_f32_16x16x32_bf16 v[168:171], v[164:167], v[144:147], v[168:171]
	v_mfma_f32_16x16x32_bf16 v[172:175], v[184:187], v[122:125], v[172:175]
	v_mfma_f32_16x16x32_bf16 v[176:179], v[184:187], v[144:147], v[176:179]
	v_mfma_f32_16x16x32_bf16 v[0:3], v[44:47], v[96:99], v[0:3]
	v_mfma_f32_16x16x32_bf16 v[20:23], v[44:47], v[200:203], v[20:23]
	v_mfma_f32_16x16x32_bf16 v[44:47], v[180:183], v[96:99], v[68:71]
	v_mfma_f32_16x16x32_bf16 v[68:71], v[188:191], v[96:99], v[102:105]
	v_mfma_f32_16x16x32_bf16 v[32:35], v[60:63], v[96:99], v[32:35]
	v_mfma_f32_16x16x32_bf16 v[36:39], v[60:63], v[200:203], v[36:39]
	v_mfma_f32_16x16x32_bf16 v[60:63], v[180:183], v[200:203], v[110:113]
	v_mfma_f32_16x16x32_bf16 v[96:99], v[188:191], v[200:203], v[106:109]
	v_mfma_f32_16x16x32_bf16 v[20:23], v[48:51], v[204:207], v[20:23]
	v_mfma_f32_16x16x32_bf16 v[68:71], v[192:195], v[196:199], v[68:71]
	v_mfma_f32_16x16x32_bf16 v[144:147], v[48:51], v[196:199], v[0:3]
	v_mfma_f32_16x16x32_bf16 v[180:183], v[164:167], v[196:199], v[32:35]
	v_mfma_f32_16x16x32_bf16 v[164:167], v[164:167], v[204:207], v[36:39]
	v_mfma_f32_16x16x32_bf16 v[188:191], v[184:187], v[196:199], v[44:47]
	v_mfma_f32_16x16x32_bf16 v[184:187], v[184:187], v[204:207], v[60:63]
	v_mfma_f32_16x16x32_bf16 v[192:195], v[192:195], v[204:207], v[96:99]
	s_barrier
	ds_read_b128 v[0:3], v225
	ds_read_b128 v[196:199], v225 offset:1024
	ds_read_b128 v[200:203], v225 offset:2048
	ds_read_b128 v[204:207], v225 offset:3072
	ds_read_b128 v[36:39], v228 offset:32768
	ds_read_b128 v[100:103], v228 offset:33792
	ds_read_b128 v[108:111], v229 offset:34816
	ds_read_b128 v[208:211], v229 offset:35840
	ds_read_b128 v[116:119], v229 offset:36864
	ds_read_b128 v[212:215], v229 offset:37888
	ds_read_b128 v[124:127], v229 offset:38912
	ds_read_b128 v[216:219], v229 offset:39936
	s_waitcnt vmcnt(2)
	s_barrier
; #define LDA(dst, b, h) for (int m = 0; m < 4; ++m) for (int k = 0; k < 2; ++k) \
;     dst[m][k] = *reinterpret_cast<const bf16x8*>((char*)SA(b, h) + lds_byte(wr * 64 + m * 16 + fr, k * 32 + fq * 8))
; #define LDB(dst, b, h) for (int n = 0; n < 2; ++n) for (int k = 0; k < 2; ++k) \
;     dst[n][k] = *reinterpret_cast<const bf16x8*>((char*)SB(b, h) + lds_byte(wc * 32 + n * 16 + fr, k * 32 + fq * 8))
; #define MMA(ai, bj, At_, Bt_) do { __builtin_amdgcn_s_setprio(1); \
;     for (int k = 0; k < 2; ++k) for (int m = 0; m < 4; ++m) for (int n = 0; n < 2; ++n) \
;       acc[ai][bj][m][n] = __builtin_amdgcn_mfma_f32_16x16x32_bf16(At_[m][k], Bt_[n][k], acc[ai][bj][m][n], 0, 0, 0); \
;     __builtin_amdgcn_s_setprio(0); } while (0)
; #define WAIT_V(n) asm volatile("s_waitcnt vmcnt(" #n ")" ::: "memory")
; #define WAIT_L(n) asm volatile("s_waitcnt lgkmcnt(" #n ")" ::: "memory")
; #define BAR __builtin_amdgcn_s_barrier()
; template <int EPI, int lda, int ldb, int N, int K>
; __device__ __forceinline__ void gemm_phase(const u16* __restrict__ A, const u16* __restrict__ Bt, const GemmEpi ep, int wv) {
;     ...
;     { LDB(B0, 1, 0); LDA(At, 1, 0); WAIT_V(2); BAR; WAIT_L(0); MMA(0, 0, At, B0); BAR;
;       LDB(B1, 1, 1); WAIT_V(0); BAR; WAIT_L(0); MMA(0, 1, At, B1); BAR;
;       LDA(At, 1, 1); BAR; WAIT_L(0); MMA(1, 0, At, B0); MMA(1, 1, At, B1); BAR; }
;     if (wr == 0) BAR;
	s_waitcnt lgkmcnt(0)
	s_waitcnt lgkmcnt(0)
	v_mfma_f32_16x16x32_bf16 v[4:7], v[36:39], v[0:3], v[4:7]
	v_mfma_f32_16x16x32_bf16 v[16:19], v[36:39], v[200:203], v[16:19]
	v_mfma_f32_16x16x32_bf16 v[32:35], v[108:111], v[0:3], v[72:75]
	v_mfma_f32_16x16x32_bf16 v[44:47], v[108:111], v[200:203], v[76:79]
	v_mfma_f32_16x16x32_bf16 v[72:75], v[116:119], v[0:3], v[80:83]
	v_mfma_f32_16x16x32_bf16 v[76:79], v[116:119], v[200:203], v[84:87]
	v_mfma_f32_16x16x32_bf16 v[80:83], v[124:127], v[0:3], v[88:91]
	v_mfma_f32_16x16x32_bf16 v[84:87], v[124:127], v[200:203], v[92:95]
	v_mfma_f32_16x16x32_bf16 v[120:123], v[100:103], v[196:199], v[4:7]
	v_mfma_f32_16x16x32_bf16 v[60:63], v[100:103], v[204:207], v[16:19]
	v_mfma_f32_16x16x32_bf16 v[112:115], v[208:211], v[196:199], v[32:35]
	v_mfma_f32_16x16x32_bf16 v[48:51], v[208:211], v[204:207], v[44:47]
	v_mfma_f32_16x16x32_bf16 v[104:107], v[212:215], v[196:199], v[72:75]
	v_mfma_f32_16x16x32_bf16 v[44:47], v[212:215], v[204:207], v[76:79]
	v_mfma_f32_16x16x32_bf16 v[96:99], v[216:219], v[196:199], v[80:83]
	v_mfma_f32_16x16x32_bf16 v[32:35], v[216:219], v[204:207], v[84:87]
	s_barrier
	ds_read_b128 v[4:7], v226
	ds_read_b128 v[220:223], v226 offset:1024
	ds_read_b128 v[76:79], v226 offset:2048
	ds_read_b128 v[224:227], v226 offset:3072
	s_waitcnt vmcnt(0)
	s_barrier
	s_waitcnt lgkmcnt(0)
	s_waitcnt lgkmcnt(0)
	v_mfma_f32_16x16x32_bf16 v[12:15], v[36:39], v[4:7], v[12:15]
	v_mfma_f32_16x16x32_bf16 v[16:19], v[36:39], v[76:79], v[40:43]
	v_mfma_f32_16x16x32_bf16 v[36:39], v[108:111], v[4:7], v[152:155]
	v_mfma_f32_16x16x32_bf16 v[40:43], v[108:111], v[76:79], v[156:159]
	v_mfma_f32_16x16x32_bf16 v[72:75], v[116:119], v[4:7], v[52:55]
	v_mfma_f32_16x16x32_bf16 v[80:83], v[116:119], v[76:79], v[56:59]
	v_mfma_f32_16x16x32_bf16 v[84:87], v[124:127], v[4:7], v[160:163]
	v_mfma_f32_16x16x32_bf16 v[64:67], v[124:127], v[76:79], v[64:67]
	v_mfma_f32_16x16x32_bf16 v[124:127], v[100:103], v[220:223], v[12:15]
	v_mfma_f32_16x16x32_bf16 v[56:59], v[100:103], v[224:227], v[16:19]
	v_mfma_f32_16x16x32_bf16 v[116:119], v[208:211], v[220:223], v[36:39]
	v_mfma_f32_16x16x32_bf16 v[52:55], v[208:211], v[224:227], v[40:43]
	v_mfma_f32_16x16x32_bf16 v[108:111], v[212:215], v[220:223], v[72:75]
	v_mfma_f32_16x16x32_bf16 v[40:43], v[212:215], v[224:227], v[80:83]
	v_mfma_f32_16x16x32_bf16 v[100:103], v[216:219], v[220:223], v[84:87]
	v_mfma_f32_16x16x32_bf16 v[36:39], v[216:219], v[224:227], v[64:67]
	s_barrier
	ds_read_b128 v[84:87], v228 offset:49152
	ds_read_b128 v[152:155], v228 offset:50176
	ds_read_b128 v[92:95], v229 offset:51200
	ds_read_b128 v[156:159], v229 offset:52224
	ds_read_b128 v[160:163], v229 offset:53248
	ds_read_b128 v[208:211], v229 offset:54272
	ds_read_b128 v[212:215], v229 offset:55296
	ds_read_b128 v[216:219], v229 offset:56320
	s_barrier
	s_waitcnt lgkmcnt(0)
	s_waitcnt lgkmcnt(0)
	v_mfma_f32_16x16x32_bf16 v[8:11], v[84:87], v[0:3], v[8:11]
	v_mfma_f32_16x16x32_bf16 v[12:15], v[84:87], v[200:203], v[134:137]
	v_mfma_f32_16x16x32_bf16 v[16:19], v[92:95], v[0:3], v[148:151]
	v_mfma_f32_16x16x32_bf16 v[64:67], v[92:95], v[200:203], v[168:171]
	v_mfma_f32_16x16x32_bf16 v[72:75], v[160:163], v[0:3], v[172:175]
	v_mfma_f32_16x16x32_bf16 v[134:137], v[160:163], v[200:203], v[176:179]
	v_mfma_f32_16x16x32_bf16 v[0:3], v[212:215], v[0:3], v[24:27]
	v_mfma_f32_16x16x32_bf16 v[24:27], v[212:215], v[200:203], v[28:31]
	v_mfma_f32_16x16x32_bf16 v[88:91], v[152:155], v[196:199], v[8:11]
	v_mfma_f32_16x16x32_bf16 v[28:31], v[152:155], v[204:207], v[12:15]
	v_mfma_f32_16x16x32_bf16 v[80:83], v[156:159], v[196:199], v[16:19]
	v_mfma_f32_16x16x32_bf16 v[16:19], v[156:159], v[204:207], v[64:67]
	v_mfma_f32_16x16x32_bf16 v[72:75], v[208:211], v[196:199], v[72:75]
	v_mfma_f32_16x16x32_bf16 v[12:15], v[208:211], v[204:207], v[134:137]
	v_mfma_f32_16x16x32_bf16 v[64:67], v[216:219], v[196:199], v[0:3]
	v_mfma_f32_16x16x32_bf16 v[0:3], v[216:219], v[204:207], v[24:27]
	v_mfma_f32_16x16x32_bf16 v[8:11], v[84:87], v[4:7], v[144:147]
	v_mfma_f32_16x16x32_bf16 v[20:23], v[84:87], v[76:79], v[20:23]
	v_mfma_f32_16x16x32_bf16 v[84:87], v[92:95], v[4:7], v[180:183]
	v_mfma_f32_16x16x32_bf16 v[134:137], v[92:95], v[76:79], v[164:167]
	v_mfma_f32_16x16x32_bf16 v[144:147], v[160:163], v[4:7], v[188:191]
	v_mfma_f32_16x16x32_bf16 v[148:151], v[160:163], v[76:79], v[184:187]
	v_mfma_f32_16x16x32_bf16 v[4:7], v[212:215], v[4:7], v[68:71]
	v_mfma_f32_16x16x32_bf16 v[160:163], v[212:215], v[76:79], v[192:195]
	v_mfma_f32_16x16x32_bf16 v[92:95], v[152:155], v[220:223], v[8:11]
	v_mfma_f32_16x16x32_bf16 v[24:27], v[152:155], v[224:227], v[20:23]
	v_mfma_f32_16x16x32_bf16 v[84:87], v[156:159], v[220:223], v[84:87]
	v_mfma_f32_16x16x32_bf16 v[20:23], v[156:159], v[224:227], v[134:137]
	v_mfma_f32_16x16x32_bf16 v[76:79], v[208:211], v[220:223], v[144:147]
	v_mfma_f32_16x16x32_bf16 v[8:11], v[208:211], v[224:227], v[148:151]
	v_mfma_f32_16x16x32_bf16 v[68:71], v[216:219], v[220:223], v[4:7]
	v_mfma_f32_16x16x32_bf16 v[4:7], v[216:219], v[224:227], v[160:163]
	v_cmp_gt_u32_e32 vcc, s62, v130
	s_barrier
	s_and_saveexec_b64 s[46:47], vcc
	s_cbranch_execz .LBB0_1245
	s_barrier
	s_branch .LBB0_1245

; #define STAGE(P, BASE, LD, br, kt) do { const char* _g = (const char*)((BASE) + (size_t)(br) * (LD) + (size_t)(kt) * 64); \
;     for (int _i = 0; _i < 2; ++_i) { int _b = tidx * 16 + _i * 8192; int _r, _c; stage_rc(_b, _r, _c); \
;       __builtin_amdgcn_global_load_lds((const unsigned*)(_g + (unsigned)((_r * (LD) + _c) * 2)), (unsigned*)((char*)(P) + _b), 16, 0, 0); } } while (0)
; #define LDA(dst, b, h) for (int m = 0; m < 4; ++m) for (int k = 0; k < 2; ++k) \
;     dst[m][k] = *reinterpret_cast<const bf16x8*>((char*)SA(b, h) + lds_byte(wr * 64 + m * 16 + fr, k * 32 + fq * 8))
; #define LDB(dst, b, h) for (int n = 0; n < 2; ++n) for (int k = 0; k < 2; ++k) \
;     dst[n][k] = *reinterpret_cast<const bf16x8*>((char*)SB(b, h) + lds_byte(wc * 32 + n * 16 + fr, k * 32 + fq * 8))
; #define MMA(ai, bj, At_, Bt_) do { __builtin_amdgcn_s_setprio(1); \
;     for (int k = 0; k < 2; ++k) for (int m = 0; m < 4; ++m) for (int n = 0; n < 2; ++n) \
;       acc[ai][bj][m][n] = __builtin_amdgcn_mfma_f32_16x16x32_bf16(At_[m][k], Bt_[n][k], acc[ai][bj][m][n], 0, 0, 0); \
;     __builtin_amdgcn_s_setprio(0); } while (0)
; #define WAIT_V(n) asm volatile("s_waitcnt vmcnt(" #n ")" ::: "memory")
; #define WAIT_L(n) asm volatile("s_waitcnt lgkmcnt(" #n ")" ::: "memory")
; template <int EPI, int lda, int ldb, int N, int K>
; __device__ __forceinline__ void gemm_phase(const u16* __restrict__ A, const u16* __restrict__ Bt, const GemmEpi ep, int wv) {
;     ...
;     if constexpr (!PF) { TILE_COORDS(tile, brow, bcol, pn); STAGE4(brow, bcol, pn); }
;     const int wid = tidx >> 6, lane = tidx & 63, wr = wid >> 2, wc = wid & 3, fr = lane & 15, fq = lane >> 4;
;     const u16* Ab = A + (EPI == EPI_RG ? (pn >> 1) * 256 : 0);
;     f32x4 acc[2][2][4][2] = {};
;     bf16x8 At[4][2], B0[2][2], B1[2][2];
;     constexpr int nt = K / 64;
;     if (wr == 1) BAR;
;     WAIT_V(4); BAR;
;     STAGE(SB(1, 0), Bt, ldb, bcol, 1); STAGE(SA(1, 0), Ab, lda, brow, 1); STAGE(SB(1, 1), Bt, ldb, bcol + HALF, 1);
;     WAIT_V(6); BAR;
;     for (int t = 0; t < nt - 2; t += 2) {
;       LDB(B0, 0, 0); SCHED; LDA(At, 0, 0); STAGE(SA(1, 1), Ab, lda, brow + HALF, t + 1);
;       WAIT_L(8); BAR; WAIT_L(0); MMA(0, 0, At, B0); BAR; SCHED;
;       LDB(B1, 0, 1); STAGE(SB(0, 0), Bt, ldb, bcol, t + 2);
;       BAR; WAIT_L(0); MMA(0, 1, At, B1); BAR;
;       LDA(At, 0, 1); STAGE(SA(0, 0), Ab, lda, brow, t + 2);
.LBB0_1349:
	s_or_b64 exec, exec, s[54:55]
	v_mov_b32_e32 v1, v129
	v_add_u32_e32 v7, s58, v6
	v_lshl_add_u64 v[12:13], s[46:47], 0, v[128:129]
	v_lshl_add_u64 v[14:15], s[46:47], 0, v[0:1]
	v_lshl_add_u64 v[2:3], s[52:53], 0, v[128:129]
	v_lshl_add_u64 v[0:1], s[52:53], 0, v[0:1]
	v_readfirstlane_b32 s53, v7
	v_add_u32_e32 v7, 0x2000, v7
	v_mov_b32_e32 v5, v129
	v_mov_b32_e32 v17, v129
	v_lshl_add_u64 v[26:27], v[12:13], 0, s[36:37]
	s_mov_b32 m0, s53
	v_readfirstlane_b32 s52, v7
	v_add_u32_e32 v7, 0x8000, v23
	v_lshl_add_u64 v[8:9], s[50:51], 0, v[4:5]
	v_lshl_add_u64 v[10:11], s[50:51], 0, v[16:17]
	s_waitcnt vmcnt(4)
	s_barrier
	global_load_lds_dwordx4 v[26:27], off
	v_lshl_add_u64 v[26:27], v[14:15], 0, s[36:37]
	s_mov_b32 m0, s52
	v_readfirstlane_b32 s51, v7
	v_add_u32_e32 v7, 0xa000, v23
	global_load_lds_dwordx4 v[26:27], off
	v_lshl_add_u64 v[26:27], v[8:9], 0, s[36:37]
	s_mov_b32 m0, s51
	v_readfirstlane_b32 s50, v7
	v_add_u32_e32 v25, s59, v6
	global_load_lds_dwordx4 v[26:27], off
	v_lshl_add_u64 v[26:27], v[10:11], 0, s[36:37]
	s_mov_b32 m0, s50
	v_readfirstlane_b32 s11, v25
	v_add_u32_e32 v25, 0x2000, v25
	global_load_lds_dwordx4 v[26:27], off
	v_lshl_add_u64 v[26:27], v[2:3], 0, s[36:37]
	s_mov_b32 m0, s11
	v_readfirstlane_b32 s5, v25
	global_load_lds_dwordx4 v[26:27], off
	v_lshl_add_u64 v[6:7], v[0:1], 0, s[36:37]
	s_mov_b32 m0, s5
	v_and_b32_e32 v132, 15, v20
	global_load_lds_dwordx4 v[6:7], off
	v_bfe_u32 v128, v20, 4, 2
	v_lshlrev_b32_e32 v7, 2, v20
	v_bfe_u32 v131, v130, 6, 2
	v_lshlrev_b32_e32 v25, 4, v128
	v_lshlrev_b32_e32 v6, 6, v132
	v_and_b32_e32 v50, 32, v7
	v_lshlrev_b32_e32 v126, 12, v131
	v_bitop3_b32 v127, v25, v50, v6 bitop3:0x36
	v_add3_u32 v133, s56, v127, v126
	s_waitcnt vmcnt(6)
	s_barrier
	ds_read_b128 v[26:29], v133
	ds_read_b128 v[30:33], v133 offset:1024
	ds_read_b128 v[34:37], v133 offset:2048
	ds_read_b128 v[38:41], v133 offset:3072
	v_lshl_add_u64 v[6:7], s[48:49], 0, v[4:5]
	v_lshl_add_u64 v[4:5], s[48:49], 0, v[16:17]
	v_lshlrev_b32_e32 v17, 6, v20
	v_and_b32_e32 v17, 0x3c0, v17
	v_add_u32_e32 v20, 0xc000, v23
	v_lshlrev_b32_e32 v16, 13, v139
	v_bitop3_b32 v17, v17, v50, v25 bitop3:0x36
	v_readfirstlane_b32 s47, v20
	v_add_u32_e32 v20, 0xe000, v23
	v_add3_u32 v228, 0, v127, v16
	v_add3_u32 v229, 0, v17, v16
	v_lshl_add_u64 v[16:17], v[6:7], 0, s[36:37]
	s_mov_b32 m0, s47
	v_readfirstlane_b32 s46, v20
	ds_read_b128 v[42:45], v228
	ds_read_b128 v[46:49], v228 offset:1024
	ds_read_b128 v[50:53], v229 offset:2048
	ds_read_b128 v[54:57], v229 offset:3072
	ds_read_b128 v[58:61], v229 offset:4096
	ds_read_b128 v[62:65], v229 offset:5120
	ds_read_b128 v[66:69], v229 offset:6144
	ds_read_b128 v[70:73], v229 offset:7168
	global_load_lds_dwordx4 v[16:17], off
	v_lshl_add_u64 v[16:17], v[4:5], 0, s[36:37]
	s_mov_b32 m0, s46
	s_nop 0
	global_load_lds_dwordx4 v[16:17], off
	s_waitcnt lgkmcnt(8)
	s_barrier
	s_waitcnt lgkmcnt(0)
	s_waitcnt lgkmcnt(0)
	v_mfma_f32_16x16x32_bf16 v[74:77], v[42:45], v[26:29], 0
	v_mfma_f32_16x16x32_bf16 v[78:81], v[42:45], v[34:37], 0
	v_mfma_f32_16x16x32_bf16 v[82:85], v[50:53], v[26:29], 0
	v_mfma_f32_16x16x32_bf16 v[86:89], v[50:53], v[34:37], 0
	v_mfma_f32_16x16x32_bf16 v[90:93], v[58:61], v[26:29], 0
	v_mfma_f32_16x16x32_bf16 v[94:97], v[58:61], v[34:37], 0
	v_mfma_f32_16x16x32_bf16 v[98:101], v[66:69], v[26:29], 0
	v_mfma_f32_16x16x32_bf16 v[102:105], v[66:69], v[34:37], 0
	v_mfma_f32_16x16x32_bf16 v[74:77], v[46:49], v[30:33], v[74:77]
	v_mfma_f32_16x16x32_bf16 v[78:81], v[46:49], v[38:41], v[78:81]
	v_mfma_f32_16x16x32_bf16 v[82:85], v[54:57], v[30:33], v[82:85]
	v_mfma_f32_16x16x32_bf16 v[86:89], v[54:57], v[38:41], v[86:89]
	v_mfma_f32_16x16x32_bf16 v[90:93], v[62:65], v[30:33], v[90:93]
	v_mfma_f32_16x16x32_bf16 v[94:97], v[62:65], v[38:41], v[94:97]
	v_mfma_f32_16x16x32_bf16 v[98:101], v[70:73], v[30:33], v[98:101]
	v_mfma_f32_16x16x32_bf16 v[102:105], v[70:73], v[38:41], v[102:105]
	s_barrier
	v_readfirstlane_b32 s48, v21
	v_add_u32_e32 v20, 0x2000, v21
	v_add3_u32 v224, s57, v127, v126
	v_lshl_add_u64 v[16:17], v[12:13], 0, s[38:39]
	s_mov_b32 m0, s48
	v_readfirstlane_b32 s48, v20
	global_load_lds_dwordx4 v[16:17], off
	v_lshl_add_u64 v[16:17], v[14:15], 0, s[38:39]
	s_mov_b32 m0, s48
	s_nop 0
	global_load_lds_dwordx4 v[16:17], off
	ds_read_b128 v[106:109], v224
	ds_read_b128 v[110:113], v224 offset:1024
	ds_read_b128 v[114:117], v224 offset:2048
	ds_read_b128 v[118:121], v224 offset:3072
	s_barrier
	s_waitcnt lgkmcnt(0)
	s_waitcnt lgkmcnt(0)
	v_mfma_f32_16x16x32_bf16 v[122:125], v[42:45], v[106:109], 0
	v_mfma_f32_16x16x32_bf16 v[42:45], v[42:45], v[114:117], 0
	v_mfma_f32_16x16x32_bf16 v[140:143], v[50:53], v[106:109], 0
	v_mfma_f32_16x16x32_bf16 v[50:53], v[50:53], v[114:117], 0
	v_mfma_f32_16x16x32_bf16 v[144:147], v[58:61], v[106:109], 0
	v_mfma_f32_16x16x32_bf16 v[58:61], v[58:61], v[114:117], 0
	v_mfma_f32_16x16x32_bf16 v[148:151], v[66:69], v[106:109], 0
	v_mfma_f32_16x16x32_bf16 v[66:69], v[66:69], v[114:117], 0
	v_mfma_f32_16x16x32_bf16 v[122:125], v[46:49], v[110:113], v[122:125]
	v_mfma_f32_16x16x32_bf16 v[42:45], v[46:49], v[118:121], v[42:45]
	v_mfma_f32_16x16x32_bf16 v[46:49], v[54:57], v[110:113], v[140:143]
	v_mfma_f32_16x16x32_bf16 v[50:53], v[54:57], v[118:121], v[50:53]
	v_mfma_f32_16x16x32_bf16 v[54:57], v[62:65], v[110:113], v[144:147]
	v_mfma_f32_16x16x32_bf16 v[58:61], v[62:65], v[118:121], v[58:61]
	v_mfma_f32_16x16x32_bf16 v[62:65], v[70:73], v[110:113], v[148:151]
	v_mfma_f32_16x16x32_bf16 v[66:69], v[70:73], v[118:121], v[66:69]
	v_readfirstlane_b32 s48, v23
	v_lshl_add_u64 v[16:17], v[8:9], 0, s[38:39]
	s_mov_b32 m0, s48
	v_readfirstlane_b32 s48, v24
	s_barrier
; #define STAGE(P, BASE, LD, br, kt) do { const char* _g = (const char*)((BASE) + (size_t)(br) * (LD) + (size_t)(kt) * 64); \
;     for (int _i = 0; _i < 2; ++_i) { int _b = tidx * 16 + _i * 8192; int _r, _c; stage_rc(_b, _r, _c); \
;       __builtin_amdgcn_global_load_lds((const unsigned*)(_g + (unsigned)((_r * (LD) + _c) * 2)), (unsigned*)((char*)(P) + _b), 16, 0, 0); } } while (0)
; #define LDA(dst, b, h) for (int m = 0; m < 4; ++m) for (int k = 0; k < 2; ++k) \
;     dst[m][k] = *reinterpret_cast<const bf16x8*>((char*)SA(b, h) + lds_byte(wr * 64 + m * 16 + fr, k * 32 + fq * 8))
; #define LDB(dst, b, h) for (int n = 0; n < 2; ++n) for (int k = 0; k < 2; ++k) \
;     dst[n][k] = *reinterpret_cast<const bf16x8*>((char*)SB(b, h) + lds_byte(wc * 32 + n * 16 + fr, k * 32 + fq * 8))
; #define MMA(ai, bj, At_, Bt_) do { __builtin_amdgcn_s_setprio(1); \
;     for (int k = 0; k < 2; ++k) for (int m = 0; m < 4; ++m) for (int n = 0; n < 2; ++n) \
;       acc[ai][bj][m][n] = __builtin_amdgcn_mfma_f32_16x16x32_bf16(At_[m][k], Bt_[n][k], acc[ai][bj][m][n], 0, 0, 0); \
;     __builtin_amdgcn_s_setprio(0); } while (0)
; #define WAIT_V(n) asm volatile("s_waitcnt vmcnt(" #n ")" ::: "memory")
; #define WAIT_L(n) asm volatile("s_waitcnt lgkmcnt(" #n ")" ::: "memory")
; #define BAR __builtin_amdgcn_s_barrier()
; #define SCHED __builtin_amdgcn_sched_barrier(0)
; template <int EPI, int lda, int ldb, int N, int K>
; __device__ __forceinline__ void gemm_phase(const u16* __restrict__ A, const u16* __restrict__ Bt, const GemmEpi ep, int wv) {
;     ...
;       LDA(At, 0, 1); STAGE(SA(0, 0), Ab, lda, brow, t + 2);
;       BAR; WAIT_L(0); MMA(1, 0, At, B0); BAR; SCHED;
;       STAGE(SB(0, 1), Bt, ldb, bcol + HALF, t + 2);
;       WAIT_V(6); BAR; MMA(1, 1, At, B1); BAR;
;       LDB(B0, 1, 0); SCHED; LDA(At, 1, 0); STAGE(SA(0, 1), Ab, lda, brow + HALF, t + 2);
;       WAIT_L(8); BAR; WAIT_L(0); MMA(0, 0, At, B0); BAR; SCHED;
;       LDB(B1, 1, 1); STAGE(SB(1, 0), Bt, ldb, bcol, t + 3);
	global_load_lds_dwordx4 v[16:17], off
	v_lshl_add_u64 v[16:17], v[10:11], 0, s[38:39]
	s_mov_b32 m0, s48
	s_nop 0
	global_load_lds_dwordx4 v[16:17], off
	ds_read_b128 v[70:73], v228 offset:16384
	ds_read_b128 v[140:143], v228 offset:17408
	ds_read_b128 v[144:147], v229 offset:18432
	ds_read_b128 v[148:151], v229 offset:19456
	ds_read_b128 v[152:155], v229 offset:20480
	ds_read_b128 v[156:159], v229 offset:21504
	ds_read_b128 v[160:163], v229 offset:22528
	ds_read_b128 v[164:167], v229 offset:23552
	s_barrier
	s_waitcnt lgkmcnt(0)
	s_waitcnt lgkmcnt(0)
	v_mfma_f32_16x16x32_bf16 v[168:171], v[70:73], v[26:29], 0
	v_mfma_f32_16x16x32_bf16 v[172:175], v[70:73], v[34:37], 0
	v_mfma_f32_16x16x32_bf16 v[176:179], v[144:147], v[26:29], 0
	v_mfma_f32_16x16x32_bf16 v[180:183], v[144:147], v[34:37], 0
	v_mfma_f32_16x16x32_bf16 v[184:187], v[152:155], v[26:29], 0
	v_mfma_f32_16x16x32_bf16 v[188:191], v[152:155], v[34:37], 0
	v_mfma_f32_16x16x32_bf16 v[24:27], v[160:163], v[26:29], 0
	v_mfma_f32_16x16x32_bf16 v[34:37], v[160:163], v[34:37], 0
	v_mfma_f32_16x16x32_bf16 v[168:171], v[140:143], v[30:33], v[168:171]
	v_mfma_f32_16x16x32_bf16 v[176:179], v[148:151], v[30:33], v[176:179]
	v_mfma_f32_16x16x32_bf16 v[184:187], v[156:159], v[30:33], v[184:187]
	v_mfma_f32_16x16x32_bf16 v[24:27], v[164:167], v[30:33], v[24:27]
	v_mfma_f32_16x16x32_bf16 v[28:31], v[164:167], v[38:41], v[34:37]
	v_mfma_f32_16x16x32_bf16 v[172:175], v[140:143], v[38:41], v[172:175]
	v_mfma_f32_16x16x32_bf16 v[180:183], v[148:151], v[38:41], v[180:183]
	v_mfma_f32_16x16x32_bf16 v[188:191], v[156:159], v[38:41], v[188:191]
	s_barrier
	v_readfirstlane_b32 s48, v22
	v_add_u32_e32 v20, 0x2000, v22
	v_lshl_add_u64 v[16:17], v[2:3], 0, s[38:39]
	s_mov_b32 m0, s48
	v_readfirstlane_b32 s48, v20
	global_load_lds_dwordx4 v[16:17], off
	v_lshl_add_u64 v[16:17], v[0:1], 0, s[38:39]
	s_mov_b32 m0, s48
	s_nop 0
	global_load_lds_dwordx4 v[16:17], off
	s_waitcnt vmcnt(6)
	s_barrier
	v_mfma_f32_16x16x32_bf16 v[20:23], v[70:73], v[106:109], 0
	v_mfma_f32_16x16x32_bf16 v[32:35], v[70:73], v[114:117], 0
	v_mfma_f32_16x16x32_bf16 v[36:39], v[144:147], v[106:109], 0
	v_mfma_f32_16x16x32_bf16 v[70:73], v[144:147], v[114:117], 0
	v_mfma_f32_16x16x32_bf16 v[144:147], v[152:155], v[106:109], 0
	v_mfma_f32_16x16x32_bf16 v[152:155], v[152:155], v[114:117], 0
	v_mfma_f32_16x16x32_bf16 v[106:109], v[160:163], v[106:109], 0
	v_mfma_f32_16x16x32_bf16 v[114:117], v[160:163], v[114:117], 0
	v_mfma_f32_16x16x32_bf16 v[20:23], v[140:143], v[110:113], v[20:23]
	v_mfma_f32_16x16x32_bf16 v[32:35], v[140:143], v[118:121], v[32:35]
	v_mfma_f32_16x16x32_bf16 v[36:39], v[148:151], v[110:113], v[36:39]
	v_mfma_f32_16x16x32_bf16 v[70:73], v[148:151], v[118:121], v[70:73]
	v_mfma_f32_16x16x32_bf16 v[140:143], v[156:159], v[110:113], v[144:147]
	v_mfma_f32_16x16x32_bf16 v[106:109], v[164:167], v[110:113], v[106:109]
	v_mfma_f32_16x16x32_bf16 v[110:113], v[164:167], v[118:121], v[114:117]
	v_mfma_f32_16x16x32_bf16 v[144:147], v[156:159], v[118:121], v[152:155]
	v_add3_u32 v225, s58, v127, v126
	s_barrier
	ds_read_b128 v[114:117], v225
	ds_read_b128 v[118:121], v225 offset:1024
	ds_read_b128 v[148:151], v225 offset:2048
	ds_read_b128 v[152:155], v225 offset:3072
	v_readfirstlane_b32 s48, v18
	v_lshl_add_u64 v[16:17], v[6:7], 0, s[38:39]
	s_mov_b32 m0, s48
	v_readfirstlane_b32 s48, v19
	global_load_lds_dwordx4 v[16:17], off
	v_lshl_add_u64 v[16:17], v[4:5], 0, s[38:39]
	s_mov_b32 m0, s48
	s_nop 0
	global_load_lds_dwordx4 v[16:17], off
	ds_read_b128 v[156:159], v228 offset:32768
	ds_read_b128 v[160:163], v228 offset:33792
	ds_read_b128 v[164:167], v229 offset:34816
	ds_read_b128 v[192:195], v229 offset:35840
	ds_read_b128 v[196:199], v229 offset:36864
	ds_read_b128 v[200:203], v229 offset:37888
	ds_read_b128 v[204:207], v229 offset:38912
	ds_read_b128 v[208:211], v229 offset:39936
	s_waitcnt lgkmcnt(8)
	s_barrier
	s_waitcnt lgkmcnt(0)
	s_waitcnt lgkmcnt(0)
	v_mfma_f32_16x16x32_bf16 v[16:19], v[156:159], v[114:117], v[74:77]
	v_mfma_f32_16x16x32_bf16 v[74:77], v[156:159], v[148:151], v[78:81]
	v_mfma_f32_16x16x32_bf16 v[78:81], v[164:167], v[114:117], v[82:85]
	v_mfma_f32_16x16x32_bf16 v[82:85], v[164:167], v[148:151], v[86:89]
	v_mfma_f32_16x16x32_bf16 v[86:89], v[196:199], v[114:117], v[90:93]
	v_mfma_f32_16x16x32_bf16 v[90:93], v[196:199], v[148:151], v[94:97]
	v_mfma_f32_16x16x32_bf16 v[94:97], v[204:207], v[114:117], v[98:101]
	v_mfma_f32_16x16x32_bf16 v[98:101], v[204:207], v[148:151], v[102:105]
	v_mfma_f32_16x16x32_bf16 v[16:19], v[160:163], v[118:121], v[16:19]
	v_mfma_f32_16x16x32_bf16 v[74:77], v[160:163], v[152:155], v[74:77]
	v_mfma_f32_16x16x32_bf16 v[78:81], v[192:195], v[118:121], v[78:81]
	v_mfma_f32_16x16x32_bf16 v[82:85], v[192:195], v[152:155], v[82:85]
	v_mfma_f32_16x16x32_bf16 v[86:89], v[200:203], v[118:121], v[86:89]
	v_mfma_f32_16x16x32_bf16 v[90:93], v[200:203], v[152:155], v[90:93]
	v_mfma_f32_16x16x32_bf16 v[94:97], v[208:211], v[118:121], v[94:97]
	v_mfma_f32_16x16x32_bf16 v[98:101], v[208:211], v[152:155], v[98:101]
	s_barrier
	s_mov_b32 m0, s53
	v_add3_u32 v226, s59, v127, v126
	v_lshl_add_u64 v[12:13], v[12:13], 0, s[40:41]
	global_load_lds_dwordx4 v[12:13], off
	v_lshl_add_u64 v[12:13], v[14:15], 0, s[40:41]
	s_mov_b32 m0, s52
	s_nop 0
	global_load_lds_dwordx4 v[12:13], off
	ds_read_b128 v[102:105], v226
	ds_read_b128 v[212:215], v226 offset:1024
	ds_read_b128 v[216:219], v226 offset:2048
	ds_read_b128 v[220:223], v226 offset:3072
	s_barrier
; #define STAGE(P, BASE, LD, br, kt) do { const char* _g = (const char*)((BASE) + (size_t)(br) * (LD) + (size_t)(kt) * 64); \
;     for (int _i = 0; _i < 2; ++_i) { int _b = tidx * 16 + _i * 8192; int _r, _c; stage_rc(_b, _r, _c); \
;       __builtin_amdgcn_global_load_lds((const unsigned*)(_g + (unsigned)((_r * (LD) + _c) * 2)), (unsigned*)((char*)(P) + _b), 16, 0, 0); } } while (0)
; #define LDA(dst, b, h) for (int m = 0; m < 4; ++m) for (int k = 0; k < 2; ++k) \
;     dst[m][k] = *reinterpret_cast<const bf16x8*>((char*)SA(b, h) + lds_byte(wr * 64 + m * 16 + fr, k * 32 + fq * 8))
; #define LDB(dst, b, h) for (int n = 0; n < 2; ++n) for (int k = 0; k < 2; ++k) \
;     dst[n][k] = *reinterpret_cast<const bf16x8*>((char*)SB(b, h) + lds_byte(wc * 32 + n * 16 + fr, k * 32 + fq * 8))
; #define MMA(ai, bj, At_, Bt_) do { __builtin_amdgcn_s_setprio(1); \
;     for (int k = 0; k < 2; ++k) for (int m = 0; m < 4; ++m) for (int n = 0; n < 2; ++n) \
;       acc[ai][bj][m][n] = __builtin_amdgcn_mfma_f32_16x16x32_bf16(At_[m][k], Bt_[n][k], acc[ai][bj][m][n], 0, 0, 0); \
;     __builtin_amdgcn_s_setprio(0); } while (0)
; #define WAIT_V(n) asm volatile("s_waitcnt vmcnt(" #n ")" ::: "memory")
; #define WAIT_L(n) asm volatile("s_waitcnt lgkmcnt(" #n ")" ::: "memory")
; #define BAR __builtin_amdgcn_s_barrier()
; #define SCHED __builtin_amdgcn_sched_barrier(0)
; template <int EPI, int lda, int ldb, int N, int K>
; __device__ __forceinline__ void gemm_phase(const u16* __restrict__ A, const u16* __restrict__ Bt, const GemmEpi ep, int wv) {
;     ...
;       LDB(B1, 1, 1); STAGE(SB(1, 0), Bt, ldb, bcol, t + 3);
;       BAR; WAIT_L(0); MMA(0, 1, At, B1); BAR;
;       LDA(At, 1, 1); STAGE(SA(1, 0), Ab, lda, brow, t + 3);
;       BAR; WAIT_L(0); MMA(1, 0, At, B0); BAR; SCHED;
;       STAGE(SB(1, 1), Bt, ldb, bcol + HALF, t + 3);
;       WAIT_V(6); BAR; MMA(1, 1, At, B1); BAR;
;     }
;     { LDB(B0, 0, 0); LDA(At, 0, 0); STAGE(SA(1, 1), Ab, lda, brow + HALF, nt - 1);
;       BAR; WAIT_L(0); MMA(0, 0, At, B0); BAR;
	s_waitcnt lgkmcnt(0)
	s_waitcnt lgkmcnt(0)
	v_mfma_f32_16x16x32_bf16 v[12:15], v[156:159], v[102:105], v[122:125]
	v_mfma_f32_16x16x32_bf16 v[40:43], v[156:159], v[216:219], v[42:45]
	v_mfma_f32_16x16x32_bf16 v[44:47], v[164:167], v[102:105], v[46:49]
	v_mfma_f32_16x16x32_bf16 v[48:51], v[164:167], v[216:219], v[50:53]
	v_mfma_f32_16x16x32_bf16 v[52:55], v[196:199], v[102:105], v[54:57]
	v_mfma_f32_16x16x32_bf16 v[56:59], v[196:199], v[216:219], v[58:61]
	v_mfma_f32_16x16x32_bf16 v[60:63], v[204:207], v[102:105], v[62:65]
	v_mfma_f32_16x16x32_bf16 v[64:67], v[204:207], v[216:219], v[66:69]
	v_mfma_f32_16x16x32_bf16 v[12:15], v[160:163], v[212:215], v[12:15]
	v_mfma_f32_16x16x32_bf16 v[40:43], v[160:163], v[220:223], v[40:43]
	v_mfma_f32_16x16x32_bf16 v[44:47], v[192:195], v[212:215], v[44:47]
	v_mfma_f32_16x16x32_bf16 v[48:51], v[192:195], v[220:223], v[48:51]
	v_mfma_f32_16x16x32_bf16 v[52:55], v[200:203], v[212:215], v[52:55]
	v_mfma_f32_16x16x32_bf16 v[56:59], v[200:203], v[220:223], v[56:59]
	v_mfma_f32_16x16x32_bf16 v[60:63], v[208:211], v[212:215], v[60:63]
	v_mfma_f32_16x16x32_bf16 v[64:67], v[208:211], v[220:223], v[64:67]
	s_mov_b32 m0, s51
	v_lshl_add_u64 v[8:9], v[8:9], 0, s[40:41]
	s_barrier
	global_load_lds_dwordx4 v[8:9], off
	v_lshl_add_u64 v[8:9], v[10:11], 0, s[40:41]
	s_mov_b32 m0, s50
	s_nop 0
	global_load_lds_dwordx4 v[8:9], off
	ds_read_b128 v[122:125], v228 offset:49152
	ds_read_b128 v[156:159], v228 offset:50176
	ds_read_b128 v[160:163], v229 offset:51200
	ds_read_b128 v[164:167], v229 offset:52224
	ds_read_b128 v[192:195], v229 offset:53248
	ds_read_b128 v[196:199], v229 offset:54272
	ds_read_b128 v[200:203], v229 offset:55296
	ds_read_b128 v[204:207], v229 offset:56320
	s_barrier
	s_waitcnt lgkmcnt(0)
	s_waitcnt lgkmcnt(0)
	v_mfma_f32_16x16x32_bf16 v[8:11], v[122:125], v[114:117], v[168:171]
	v_mfma_f32_16x16x32_bf16 v[168:171], v[122:125], v[148:151], v[172:175]
	v_mfma_f32_16x16x32_bf16 v[24:27], v[200:203], v[114:117], v[24:27]
	v_mfma_f32_16x16x32_bf16 v[28:31], v[200:203], v[148:151], v[28:31]
	v_mfma_f32_16x16x32_bf16 v[172:175], v[160:163], v[114:117], v[176:179]
	v_mfma_f32_16x16x32_bf16 v[176:179], v[160:163], v[148:151], v[180:183]
	v_mfma_f32_16x16x32_bf16 v[180:183], v[192:195], v[114:117], v[184:187]
	v_mfma_f32_16x16x32_bf16 v[184:187], v[192:195], v[148:151], v[188:191]
	v_mfma_f32_16x16x32_bf16 v[8:11], v[156:159], v[118:121], v[8:11]
	v_mfma_f32_16x16x32_bf16 v[114:117], v[156:159], v[152:155], v[168:171]
	v_mfma_f32_16x16x32_bf16 v[24:27], v[204:207], v[118:121], v[24:27]
	v_mfma_f32_16x16x32_bf16 v[28:31], v[204:207], v[152:155], v[28:31]
	v_mfma_f32_16x16x32_bf16 v[148:151], v[164:167], v[118:121], v[172:175]
	v_mfma_f32_16x16x32_bf16 v[168:171], v[164:167], v[152:155], v[176:179]
	v_mfma_f32_16x16x32_bf16 v[172:175], v[196:199], v[118:121], v[180:183]
	v_mfma_f32_16x16x32_bf16 v[176:179], v[196:199], v[152:155], v[184:187]
	s_barrier
	s_mov_b32 m0, s11
	v_lshl_add_u64 v[2:3], v[2:3], 0, s[40:41]
	global_load_lds_dwordx4 v[2:3], off
	v_lshl_add_u64 v[0:1], v[0:1], 0, s[40:41]
	s_mov_b32 m0, s5
	s_nop 0
	global_load_lds_dwordx4 v[0:1], off
	s_waitcnt vmcnt(6)
	s_barrier
	v_mfma_f32_16x16x32_bf16 v[0:3], v[122:125], v[102:105], v[20:23]
	v_mfma_f32_16x16x32_bf16 v[20:23], v[122:125], v[216:219], v[32:35]
	v_mfma_f32_16x16x32_bf16 v[32:35], v[160:163], v[102:105], v[36:39]
	v_mfma_f32_16x16x32_bf16 v[36:39], v[160:163], v[216:219], v[70:73]
	v_mfma_f32_16x16x32_bf16 v[68:71], v[192:195], v[102:105], v[140:143]
	v_mfma_f32_16x16x32_bf16 v[118:121], v[192:195], v[216:219], v[144:147]
	v_mfma_f32_16x16x32_bf16 v[102:105], v[200:203], v[102:105], v[106:109]
	v_mfma_f32_16x16x32_bf16 v[106:109], v[200:203], v[216:219], v[110:113]
	v_mfma_f32_16x16x32_bf16 v[0:3], v[156:159], v[212:215], v[0:3]
	v_mfma_f32_16x16x32_bf16 v[20:23], v[156:159], v[220:223], v[20:23]
	v_mfma_f32_16x16x32_bf16 v[32:35], v[164:167], v[212:215], v[32:35]
	v_mfma_f32_16x16x32_bf16 v[36:39], v[164:167], v[220:223], v[36:39]
	v_mfma_f32_16x16x32_bf16 v[68:71], v[196:199], v[212:215], v[68:71]
	v_mfma_f32_16x16x32_bf16 v[110:113], v[196:199], v[220:223], v[118:121]
	v_mfma_f32_16x16x32_bf16 v[102:105], v[204:207], v[212:215], v[102:105]
	v_mfma_f32_16x16x32_bf16 v[106:109], v[204:207], v[220:223], v[106:109]
	s_mov_b32 m0, s47
	v_lshl_add_u64 v[6:7], v[6:7], 0, s[40:41]
	s_barrier
	ds_read_b128 v[118:121], v133
	ds_read_b128 v[122:125], v133 offset:1024
	ds_read_b128 v[140:143], v133 offset:2048
	ds_read_b128 v[144:147], v133 offset:3072
	ds_read_b128 v[152:155], v228
	ds_read_b128 v[156:159], v228 offset:1024
	ds_read_b128 v[160:163], v229 offset:2048
	ds_read_b128 v[164:167], v229 offset:3072
	ds_read_b128 v[180:183], v229 offset:4096
	ds_read_b128 v[184:187], v229 offset:5120
	ds_read_b128 v[188:191], v229 offset:6144
	ds_read_b128 v[192:195], v229 offset:7168
	global_load_lds_dwordx4 v[6:7], off
	v_lshl_add_u64 v[4:5], v[4:5], 0, s[40:41]
	s_mov_b32 m0, s46
	s_nop 0
	global_load_lds_dwordx4 v[4:5], off
	s_barrier
	s_waitcnt lgkmcnt(0)
	s_waitcnt lgkmcnt(0)
	v_mfma_f32_16x16x32_bf16 v[4:7], v[152:155], v[118:121], v[16:19]
	v_mfma_f32_16x16x32_bf16 v[16:19], v[152:155], v[140:143], v[74:77]
	v_mfma_f32_16x16x32_bf16 v[72:75], v[160:163], v[118:121], v[78:81]
	v_mfma_f32_16x16x32_bf16 v[76:79], v[160:163], v[140:143], v[82:85]
	v_mfma_f32_16x16x32_bf16 v[80:83], v[180:183], v[118:121], v[86:89]
	v_mfma_f32_16x16x32_bf16 v[84:87], v[180:183], v[140:143], v[90:93]
	v_mfma_f32_16x16x32_bf16 v[88:91], v[188:191], v[118:121], v[94:97]
	v_mfma_f32_16x16x32_bf16 v[92:95], v[188:191], v[140:143], v[98:101]
	v_mfma_f32_16x16x32_bf16 v[4:7], v[156:159], v[122:125], v[4:7]
	v_mfma_f32_16x16x32_bf16 v[16:19], v[156:159], v[144:147], v[16:19]
	v_mfma_f32_16x16x32_bf16 v[72:75], v[164:167], v[122:125], v[72:75]
	v_mfma_f32_16x16x32_bf16 v[76:79], v[164:167], v[144:147], v[76:79]
	v_mfma_f32_16x16x32_bf16 v[80:83], v[184:187], v[122:125], v[80:83]
	v_mfma_f32_16x16x32_bf16 v[84:87], v[184:187], v[144:147], v[84:87]
	v_mfma_f32_16x16x32_bf16 v[88:91], v[192:195], v[122:125], v[88:91]
	v_mfma_f32_16x16x32_bf16 v[92:95], v[192:195], v[144:147], v[92:95]
	s_barrier
; #define LDA(dst, b, h) for (int m = 0; m < 4; ++m) for (int k = 0; k < 2; ++k) \
;     dst[m][k] = *reinterpret_cast<const bf16x8*>((char*)SA(b, h) + lds_byte(wr * 64 + m * 16 + fr, k * 32 + fq * 8))
; #define LDB(dst, b, h) for (int n = 0; n < 2; ++n) for (int k = 0; k < 2; ++k) \
;     dst[n][k] = *reinterpret_cast<const bf16x8*>((char*)SB(b, h) + lds_byte(wc * 32 + n * 16 + fr, k * 32 + fq * 8))
; #define MMA(ai, bj, At_, Bt_) do { __builtin_amdgcn_s_setprio(1); \
;     for (int k = 0; k < 2; ++k) for (int m = 0; m < 4; ++m) for (int n = 0; n < 2; ++n) \
;       acc[ai][bj][m][n] = __builtin_amdgcn_mfma_f32_16x16x32_bf16(At_[m][k], Bt_[n][k], acc[ai][bj][m][n], 0, 0, 0); \
;     __builtin_amdgcn_s_setprio(0); } while (0)
; #define WAIT_V(n) asm volatile("s_waitcnt vmcnt(" #n ")" ::: "memory")
; #define WAIT_L(n) asm volatile("s_waitcnt lgkmcnt(" #n ")" ::: "memory")
; #define BAR __builtin_amdgcn_s_barrier()
; template <int EPI, int lda, int ldb, int N, int K>
; __device__ __forceinline__ void gemm_phase(const u16* __restrict__ A, const u16* __restrict__ Bt, const GemmEpi ep, int wv) {
;     ...
;       LDB(B1, 0, 1); BAR; WAIT_L(0); MMA(0, 1, At, B1); BAR;
;       LDA(At, 0, 1); WAIT_V(4); BAR; WAIT_L(0); MMA(1, 0, At, B0); MMA(1, 1, At, B1); BAR; }
;     { LDB(B0, 1, 0); LDA(At, 1, 0); WAIT_V(2); BAR; WAIT_L(0); MMA(0, 0, At, B0); BAR;
	ds_read_b128 v[96:99], v224
	ds_read_b128 v[196:199], v224 offset:1024
	ds_read_b128 v[200:203], v224 offset:2048
	ds_read_b128 v[204:207], v224 offset:3072
	s_barrier
	s_waitcnt lgkmcnt(0)
	s_waitcnt lgkmcnt(0)
	v_mfma_f32_16x16x32_bf16 v[12:15], v[152:155], v[96:99], v[12:15]
	v_mfma_f32_16x16x32_bf16 v[40:43], v[152:155], v[200:203], v[40:43]
	v_mfma_f32_16x16x32_bf16 v[52:55], v[180:183], v[96:99], v[52:55]
	v_mfma_f32_16x16x32_bf16 v[56:59], v[180:183], v[200:203], v[56:59]
	v_mfma_f32_16x16x32_bf16 v[64:67], v[188:191], v[200:203], v[64:67]
	v_mfma_f32_16x16x32_bf16 v[44:47], v[160:163], v[96:99], v[44:47]
	v_mfma_f32_16x16x32_bf16 v[48:51], v[160:163], v[200:203], v[48:51]
	v_mfma_f32_16x16x32_bf16 v[60:63], v[188:191], v[96:99], v[60:63]
	v_mfma_f32_16x16x32_bf16 v[12:15], v[156:159], v[196:199], v[12:15]
	v_mfma_f32_16x16x32_bf16 v[40:43], v[156:159], v[204:207], v[40:43]
	v_mfma_f32_16x16x32_bf16 v[52:55], v[184:187], v[196:199], v[52:55]
	v_mfma_f32_16x16x32_bf16 v[56:59], v[184:187], v[204:207], v[56:59]
	v_mfma_f32_16x16x32_bf16 v[64:67], v[192:195], v[204:207], v[64:67]
	v_mfma_f32_16x16x32_bf16 v[152:155], v[164:167], v[196:199], v[44:47]
	v_mfma_f32_16x16x32_bf16 v[156:159], v[164:167], v[204:207], v[48:51]
	v_mfma_f32_16x16x32_bf16 v[160:163], v[192:195], v[196:199], v[60:63]
	s_barrier
	ds_read_b128 v[44:47], v228 offset:16384
	ds_read_b128 v[48:51], v228 offset:17408
	ds_read_b128 v[60:63], v229 offset:18432
	ds_read_b128 v[164:167], v229 offset:19456
	ds_read_b128 v[180:183], v229 offset:20480
	ds_read_b128 v[184:187], v229 offset:21504
	ds_read_b128 v[188:191], v229 offset:22528
	ds_read_b128 v[192:195], v229 offset:23552
	s_waitcnt vmcnt(4)
	s_barrier
	s_waitcnt lgkmcnt(0)
	s_waitcnt lgkmcnt(0)
	v_mfma_f32_16x16x32_bf16 v[8:11], v[44:47], v[118:121], v[8:11]
	v_mfma_f32_16x16x32_bf16 v[24:27], v[188:191], v[118:121], v[24:27]
	v_mfma_f32_16x16x32_bf16 v[28:31], v[188:191], v[140:143], v[28:31]
	v_mfma_f32_16x16x32_bf16 v[114:117], v[44:47], v[140:143], v[114:117]
	v_mfma_f32_16x16x32_bf16 v[148:151], v[60:63], v[118:121], v[148:151]
	v_mfma_f32_16x16x32_bf16 v[168:171], v[60:63], v[140:143], v[168:171]
	v_mfma_f32_16x16x32_bf16 v[172:175], v[180:183], v[118:121], v[172:175]
	v_mfma_f32_16x16x32_bf16 v[176:179], v[180:183], v[140:143], v[176:179]
	v_mfma_f32_16x16x32_bf16 v[8:11], v[48:51], v[122:125], v[8:11]
	v_mfma_f32_16x16x32_bf16 v[24:27], v[192:195], v[122:125], v[24:27]
	v_mfma_f32_16x16x32_bf16 v[28:31], v[192:195], v[144:147], v[28:31]
	v_mfma_f32_16x16x32_bf16 v[140:143], v[48:51], v[144:147], v[114:117]
	v_mfma_f32_16x16x32_bf16 v[148:151], v[164:167], v[122:125], v[148:151]
	v_mfma_f32_16x16x32_bf16 v[168:171], v[164:167], v[144:147], v[168:171]
	v_mfma_f32_16x16x32_bf16 v[172:175], v[184:187], v[122:125], v[172:175]
	v_mfma_f32_16x16x32_bf16 v[176:179], v[184:187], v[144:147], v[176:179]
	v_mfma_f32_16x16x32_bf16 v[0:3], v[44:47], v[96:99], v[0:3]
	v_mfma_f32_16x16x32_bf16 v[20:23], v[44:47], v[200:203], v[20:23]
	v_mfma_f32_16x16x32_bf16 v[44:47], v[180:183], v[96:99], v[68:71]
	v_mfma_f32_16x16x32_bf16 v[68:71], v[188:191], v[96:99], v[102:105]
	v_mfma_f32_16x16x32_bf16 v[32:35], v[60:63], v[96:99], v[32:35]
	v_mfma_f32_16x16x32_bf16 v[36:39], v[60:63], v[200:203], v[36:39]
	v_mfma_f32_16x16x32_bf16 v[60:63], v[180:183], v[200:203], v[110:113]
	v_mfma_f32_16x16x32_bf16 v[96:99], v[188:191], v[200:203], v[106:109]
	v_mfma_f32_16x16x32_bf16 v[20:23], v[48:51], v[204:207], v[20:23]
	v_mfma_f32_16x16x32_bf16 v[68:71], v[192:195], v[196:199], v[68:71]
	v_mfma_f32_16x16x32_bf16 v[144:147], v[48:51], v[196:199], v[0:3]
	v_mfma_f32_16x16x32_bf16 v[180:183], v[164:167], v[196:199], v[32:35]
	v_mfma_f32_16x16x32_bf16 v[164:167], v[164:167], v[204:207], v[36:39]
	v_mfma_f32_16x16x32_bf16 v[188:191], v[184:187], v[196:199], v[44:47]
	v_mfma_f32_16x16x32_bf16 v[184:187], v[184:187], v[204:207], v[60:63]
	v_mfma_f32_16x16x32_bf16 v[192:195], v[192:195], v[204:207], v[96:99]
	s_barrier
	ds_read_b128 v[0:3], v225
	ds_read_b128 v[196:199], v225 offset:1024
	ds_read_b128 v[200:203], v225 offset:2048
	ds_read_b128 v[204:207], v225 offset:3072
	ds_read_b128 v[36:39], v228 offset:32768
	ds_read_b128 v[100:103], v228 offset:33792
	ds_read_b128 v[108:111], v229 offset:34816
	ds_read_b128 v[208:211], v229 offset:35840
	ds_read_b128 v[116:119], v229 offset:36864
	ds_read_b128 v[212:215], v229 offset:37888
	ds_read_b128 v[124:127], v229 offset:38912
	ds_read_b128 v[216:219], v229 offset:39936
	s_waitcnt vmcnt(2)
	s_barrier
; #define LDA(dst, b, h) for (int m = 0; m < 4; ++m) for (int k = 0; k < 2; ++k) \
;     dst[m][k] = *reinterpret_cast<const bf16x8*>((char*)SA(b, h) + lds_byte(wr * 64 + m * 16 + fr, k * 32 + fq * 8))
; #define LDB(dst, b, h) for (int n = 0; n < 2; ++n) for (int k = 0; k < 2; ++k) \
;     dst[n][k] = *reinterpret_cast<const bf16x8*>((char*)SB(b, h) + lds_byte(wc * 32 + n * 16 + fr, k * 32 + fq * 8))
; #define MMA(ai, bj, At_, Bt_) do { __builtin_amdgcn_s_setprio(1); \
;     for (int k = 0; k < 2; ++k) for (int m = 0; m < 4; ++m) for (int n = 0; n < 2; ++n) \
;       acc[ai][bj][m][n] = __builtin_amdgcn_mfma_f32_16x16x32_bf16(At_[m][k], Bt_[n][k], acc[ai][bj][m][n], 0, 0, 0); \
;     __builtin_amdgcn_s_setprio(0); } while (0)
; #define WAIT_V(n) asm volatile("s_waitcnt vmcnt(" #n ")" ::: "memory")
; #define WAIT_L(n) asm volatile("s_waitcnt lgkmcnt(" #n ")" ::: "memory")
; #define BAR __builtin_amdgcn_s_barrier()
; template <int EPI, int lda, int ldb, int N, int K>
; __device__ __forceinline__ void gemm_phase(const u16* __restrict__ A, const u16* __restrict__ Bt, const GemmEpi ep, int wv) {
;     ...
;     { LDB(B0, 1, 0); LDA(At, 1, 0); WAIT_V(2); BAR; WAIT_L(0); MMA(0, 0, At, B0); BAR;
;       LDB(B1, 1, 1); WAIT_V(0); BAR; WAIT_L(0); MMA(0, 1, At, B1); BAR;
;       LDA(At, 1, 1); BAR; WAIT_L(0); MMA(1, 0, At, B0); MMA(1, 1, At, B1); BAR; }
;     if (wr == 0) BAR;
	s_waitcnt lgkmcnt(0)
	s_waitcnt lgkmcnt(0)
	v_mfma_f32_16x16x32_bf16 v[4:7], v[36:39], v[0:3], v[4:7]
	v_mfma_f32_16x16x32_bf16 v[16:19], v[36:39], v[200:203], v[16:19]
	v_mfma_f32_16x16x32_bf16 v[32:35], v[108:111], v[0:3], v[72:75]
	v_mfma_f32_16x16x32_bf16 v[44:47], v[108:111], v[200:203], v[76:79]
	v_mfma_f32_16x16x32_bf16 v[72:75], v[116:119], v[0:3], v[80:83]
	v_mfma_f32_16x16x32_bf16 v[76:79], v[116:119], v[200:203], v[84:87]
	v_mfma_f32_16x16x32_bf16 v[80:83], v[124:127], v[0:3], v[88:91]
	v_mfma_f32_16x16x32_bf16 v[84:87], v[124:127], v[200:203], v[92:95]
	v_mfma_f32_16x16x32_bf16 v[120:123], v[100:103], v[196:199], v[4:7]
	v_mfma_f32_16x16x32_bf16 v[60:63], v[100:103], v[204:207], v[16:19]
	v_mfma_f32_16x16x32_bf16 v[112:115], v[208:211], v[196:199], v[32:35]
	v_mfma_f32_16x16x32_bf16 v[48:51], v[208:211], v[204:207], v[44:47]
	v_mfma_f32_16x16x32_bf16 v[104:107], v[212:215], v[196:199], v[72:75]
	v_mfma_f32_16x16x32_bf16 v[44:47], v[212:215], v[204:207], v[76:79]
	v_mfma_f32_16x16x32_bf16 v[96:99], v[216:219], v[196:199], v[80:83]
	v_mfma_f32_16x16x32_bf16 v[32:35], v[216:219], v[204:207], v[84:87]
	s_barrier
	ds_read_b128 v[4:7], v226
	ds_read_b128 v[220:223], v226 offset:1024
	ds_read_b128 v[76:79], v226 offset:2048
	ds_read_b128 v[224:227], v226 offset:3072
	s_waitcnt vmcnt(0)
	s_barrier
	s_waitcnt lgkmcnt(0)
	s_waitcnt lgkmcnt(0)
	v_mfma_f32_16x16x32_bf16 v[12:15], v[36:39], v[4:7], v[12:15]
	v_mfma_f32_16x16x32_bf16 v[16:19], v[36:39], v[76:79], v[40:43]
	v_mfma_f32_16x16x32_bf16 v[36:39], v[108:111], v[4:7], v[152:155]
	v_mfma_f32_16x16x32_bf16 v[40:43], v[108:111], v[76:79], v[156:159]
	v_mfma_f32_16x16x32_bf16 v[72:75], v[116:119], v[4:7], v[52:55]
	v_mfma_f32_16x16x32_bf16 v[80:83], v[116:119], v[76:79], v[56:59]
	v_mfma_f32_16x16x32_bf16 v[84:87], v[124:127], v[4:7], v[160:163]
	v_mfma_f32_16x16x32_bf16 v[64:67], v[124:127], v[76:79], v[64:67]
	v_mfma_f32_16x16x32_bf16 v[124:127], v[100:103], v[220:223], v[12:15]
	v_mfma_f32_16x16x32_bf16 v[56:59], v[100:103], v[224:227], v[16:19]
	v_mfma_f32_16x16x32_bf16 v[116:119], v[208:211], v[220:223], v[36:39]
	v_mfma_f32_16x16x32_bf16 v[52:55], v[208:211], v[224:227], v[40:43]
	v_mfma_f32_16x16x32_bf16 v[108:111], v[212:215], v[220:223], v[72:75]
	v_mfma_f32_16x16x32_bf16 v[40:43], v[212:215], v[224:227], v[80:83]
	v_mfma_f32_16x16x32_bf16 v[100:103], v[216:219], v[220:223], v[84:87]
	v_mfma_f32_16x16x32_bf16 v[36:39], v[216:219], v[224:227], v[64:67]
	s_barrier
	ds_read_b128 v[84:87], v228 offset:49152
	ds_read_b128 v[152:155], v228 offset:50176
	ds_read_b128 v[92:95], v229 offset:51200
	ds_read_b128 v[156:159], v229 offset:52224
	ds_read_b128 v[160:163], v229 offset:53248
	ds_read_b128 v[208:211], v229 offset:54272
	ds_read_b128 v[212:215], v229 offset:55296
	ds_read_b128 v[216:219], v229 offset:56320
	s_barrier
	s_waitcnt lgkmcnt(0)
	s_waitcnt lgkmcnt(0)
	v_mfma_f32_16x16x32_bf16 v[8:11], v[84:87], v[0:3], v[8:11]
	v_mfma_f32_16x16x32_bf16 v[12:15], v[84:87], v[200:203], v[140:143]
	v_mfma_f32_16x16x32_bf16 v[16:19], v[92:95], v[0:3], v[148:151]
	v_mfma_f32_16x16x32_bf16 v[64:67], v[92:95], v[200:203], v[168:171]
	v_mfma_f32_16x16x32_bf16 v[72:75], v[160:163], v[0:3], v[172:175]
	v_mfma_f32_16x16x32_bf16 v[140:143], v[160:163], v[200:203], v[176:179]
	v_mfma_f32_16x16x32_bf16 v[0:3], v[212:215], v[0:3], v[24:27]
	v_mfma_f32_16x16x32_bf16 v[24:27], v[212:215], v[200:203], v[28:31]
	v_mfma_f32_16x16x32_bf16 v[88:91], v[152:155], v[196:199], v[8:11]
	v_mfma_f32_16x16x32_bf16 v[28:31], v[152:155], v[204:207], v[12:15]
	v_mfma_f32_16x16x32_bf16 v[80:83], v[156:159], v[196:199], v[16:19]
	v_mfma_f32_16x16x32_bf16 v[16:19], v[156:159], v[204:207], v[64:67]
	v_mfma_f32_16x16x32_bf16 v[72:75], v[208:211], v[196:199], v[72:75]
	v_mfma_f32_16x16x32_bf16 v[12:15], v[208:211], v[204:207], v[140:143]
	v_mfma_f32_16x16x32_bf16 v[64:67], v[216:219], v[196:199], v[0:3]
	v_mfma_f32_16x16x32_bf16 v[0:3], v[216:219], v[204:207], v[24:27]
	v_mfma_f32_16x16x32_bf16 v[8:11], v[84:87], v[4:7], v[144:147]
	v_mfma_f32_16x16x32_bf16 v[20:23], v[84:87], v[76:79], v[20:23]
	v_mfma_f32_16x16x32_bf16 v[84:87], v[92:95], v[4:7], v[180:183]
	v_mfma_f32_16x16x32_bf16 v[140:143], v[92:95], v[76:79], v[164:167]
	v_mfma_f32_16x16x32_bf16 v[144:147], v[160:163], v[4:7], v[188:191]
	v_mfma_f32_16x16x32_bf16 v[148:151], v[160:163], v[76:79], v[184:187]
	v_mfma_f32_16x16x32_bf16 v[4:7], v[212:215], v[4:7], v[68:71]
	v_mfma_f32_16x16x32_bf16 v[160:163], v[212:215], v[76:79], v[192:195]
	v_mfma_f32_16x16x32_bf16 v[92:95], v[152:155], v[220:223], v[8:11]
	v_mfma_f32_16x16x32_bf16 v[24:27], v[152:155], v[224:227], v[20:23]
	v_mfma_f32_16x16x32_bf16 v[84:87], v[156:159], v[220:223], v[84:87]
	v_mfma_f32_16x16x32_bf16 v[20:23], v[156:159], v[224:227], v[140:143]
	v_mfma_f32_16x16x32_bf16 v[76:79], v[208:211], v[220:223], v[144:147]
	v_mfma_f32_16x16x32_bf16 v[8:11], v[208:211], v[224:227], v[148:151]
	v_mfma_f32_16x16x32_bf16 v[68:71], v[216:219], v[220:223], v[4:7]
	v_mfma_f32_16x16x32_bf16 v[4:7], v[216:219], v[224:227], v[160:163]
	v_cmp_gt_u32_e32 vcc, s60, v130
	s_barrier
	s_and_saveexec_b64 s[46:47], vcc
	s_cbranch_execz .LBB0_1346
	s_barrier
	s_branch .LBB0_1346

; #define STAGE(P, BASE, LD, br, kt) do { const char* _g = (const char*)((BASE) + (size_t)(br) * (LD) + (size_t)(kt) * 64); \
;     for (int _i = 0; _i < 2; ++_i) { int _b = tidx * 16 + _i * 8192; int _r, _c; stage_rc(_b, _r, _c); \
;       __builtin_amdgcn_global_load_lds((const unsigned*)(_g + (unsigned)((_r * (LD) + _c) * 2)), (unsigned*)((char*)(P) + _b), 16, 0, 0); } } while (0)
; #define LDA(dst, b, h) for (int m = 0; m < 4; ++m) for (int k = 0; k < 2; ++k) \
;     dst[m][k] = *reinterpret_cast<const bf16x8*>((char*)SA(b, h) + lds_byte(wr * 64 + m * 16 + fr, k * 32 + fq * 8))
; #define LDB(dst, b, h) for (int n = 0; n < 2; ++n) for (int k = 0; k < 2; ++k) \
;     dst[n][k] = *reinterpret_cast<const bf16x8*>((char*)SB(b, h) + lds_byte(wc * 32 + n * 16 + fr, k * 32 + fq * 8))
; #define MMA(ai, bj, At_, Bt_) do { __builtin_amdgcn_s_setprio(1); \
;     for (int k = 0; k < 2; ++k) for (int m = 0; m < 4; ++m) for (int n = 0; n < 2; ++n) \
;       acc[ai][bj][m][n] = __builtin_amdgcn_mfma_f32_16x16x32_bf16(At_[m][k], Bt_[n][k], acc[ai][bj][m][n], 0, 0, 0); \
;     __builtin_amdgcn_s_setprio(0); } while (0)
; #define WAIT_L(n) asm volatile("s_waitcnt lgkmcnt(" #n ")" ::: "memory")
; #define BAR __builtin_amdgcn_s_barrier()
; #define SCHED __builtin_amdgcn_sched_barrier(0)
; template <int EPI, int lda, int ldb, int N, int K>
; __device__ __forceinline__ void gemm_phase(const u16* __restrict__ A, const u16* __restrict__ Bt, const GemmEpi ep, int wv) {
;     ...
;       LDB(B0, 0, 0); SCHED; LDA(At, 0, 0); STAGE(SA(1, 1), Ab, lda, brow + HALF, t + 1);
;       WAIT_L(8); BAR; WAIT_L(0); MMA(0, 0, At, B0); BAR; SCHED;
;       LDB(B1, 0, 1); STAGE(SB(0, 0), Bt, ldb, bcol, t + 2);
;       BAR; WAIT_L(0); MMA(0, 1, At, B1); BAR;
;       LDA(At, 0, 1); STAGE(SA(0, 0), Ab, lda, brow, t + 2);
;       BAR; WAIT_L(0); MMA(1, 0, At, B0); BAR; SCHED;
;       STAGE(SB(0, 1), Bt, ldb, bcol + HALF, t + 2);
.LBB0_1448:
	ds_read_b128 v[164:167], v160
	ds_read_b128 v[170:173], v160 offset:1024
	ds_read_b128 v[174:177], v160 offset:2048
	ds_read_b128 v[178:181], v160 offset:3072
	v_add_u32_e32 v168, 0xc000, v143
	v_lshl_add_u64 v[234:235], v[138:139], 0, s[44:45]
	v_readfirstlane_b32 s47, v168
	v_add_u32_e32 v169, 0xe000, v143
	v_lshl_add_u64 v[162:163], v[234:235], 0, s[20:21]
	s_mov_b32 m0, s47
	v_lshl_add_u64 v[236:237], v[140:141], 0, s[44:45]
	v_readfirstlane_b32 s47, v169
	global_load_lds_dwordx4 v[162:163], off
	v_lshl_add_u64 v[162:163], v[236:237], 0, s[20:21]
	s_mov_b32 m0, s47
	s_nop 0
	global_load_lds_dwordx4 v[162:163], off
	ds_read_b128 v[182:185], v151
	ds_read_b128 v[186:189], v151 offset:1024
	ds_read_b128 v[190:193], v150
	ds_read_b128 v[194:197], v150 offset:1024
	ds_read_b128 v[198:201], v149
	ds_read_b128 v[202:205], v149 offset:1024
	ds_read_b128 v[206:209], v148
	ds_read_b128 v[210:213], v148 offset:1024
	s_waitcnt lgkmcnt(8)
	s_barrier
	s_waitcnt lgkmcnt(0)
	s_waitcnt lgkmcnt(0)
	v_mfma_f32_16x16x32_bf16 v[124:127], v[164:167], v[182:185], v[124:127]
	v_mfma_f32_16x16x32_bf16 v[120:123], v[174:177], v[182:185], v[120:123]
	v_mfma_f32_16x16x32_bf16 v[116:119], v[164:167], v[190:193], v[116:119]
	v_mfma_f32_16x16x32_bf16 v[112:115], v[174:177], v[190:193], v[112:115]
	v_mfma_f32_16x16x32_bf16 v[108:111], v[164:167], v[198:201], v[108:111]
	v_mfma_f32_16x16x32_bf16 v[104:107], v[174:177], v[198:201], v[104:107]
	v_mfma_f32_16x16x32_bf16 v[100:103], v[164:167], v[206:209], v[100:103]
	v_mfma_f32_16x16x32_bf16 v[96:99], v[174:177], v[206:209], v[96:99]
	v_mfma_f32_16x16x32_bf16 v[124:127], v[170:173], v[186:189], v[124:127]
	v_mfma_f32_16x16x32_bf16 v[120:123], v[178:181], v[186:189], v[120:123]
	v_mfma_f32_16x16x32_bf16 v[116:119], v[170:173], v[194:197], v[116:119]
	v_mfma_f32_16x16x32_bf16 v[112:115], v[178:181], v[194:197], v[112:115]
	v_mfma_f32_16x16x32_bf16 v[108:111], v[170:173], v[202:205], v[108:111]
	v_mfma_f32_16x16x32_bf16 v[104:107], v[178:181], v[202:205], v[104:107]
	v_mfma_f32_16x16x32_bf16 v[100:103], v[170:173], v[210:213], v[100:103]
	v_mfma_f32_16x16x32_bf16 v[96:99], v[178:181], v[210:213], v[96:99]
	s_barrier
	v_add_u32_e32 v161, s55, v153
	v_lshl_add_u64 v[238:239], v[134:135], 0, s[44:45]
	v_readfirstlane_b32 s47, v161
	v_lshl_add_u64 v[162:163], v[238:239], 0, s[22:23]
	s_mov_b32 m0, s47
	global_load_lds_dwordx4 v[162:163], off
	v_add_u32_e32 v162, 0x2000, v161
	v_lshl_add_u64 v[240:241], v[136:137], 0, s[44:45]
	v_readfirstlane_b32 s47, v162
	v_lshl_add_u64 v[230:231], v[240:241], 0, s[22:23]
	s_mov_b32 m0, s47
	s_nop 0
	global_load_lds_dwordx4 v[230:231], off
	ds_read_b128 v[214:217], v159
	ds_read_b128 v[218:221], v159 offset:1024
	ds_read_b128 v[222:225], v159 offset:2048
	ds_read_b128 v[226:229], v159 offset:3072
	s_barrier
	s_waitcnt lgkmcnt(0)
	s_waitcnt lgkmcnt(0)
	v_mfma_f32_16x16x32_bf16 v[92:95], v[214:217], v[182:185], v[92:95]
	v_mfma_f32_16x16x32_bf16 v[88:91], v[222:225], v[182:185], v[88:91]
	v_mfma_f32_16x16x32_bf16 v[84:87], v[214:217], v[190:193], v[84:87]
	v_mfma_f32_16x16x32_bf16 v[80:83], v[222:225], v[190:193], v[80:83]
	v_mfma_f32_16x16x32_bf16 v[76:79], v[214:217], v[198:201], v[76:79]
	v_mfma_f32_16x16x32_bf16 v[72:75], v[222:225], v[198:201], v[72:75]
	v_mfma_f32_16x16x32_bf16 v[68:71], v[214:217], v[206:209], v[68:71]
	v_mfma_f32_16x16x32_bf16 v[64:67], v[222:225], v[206:209], v[64:67]
	v_mfma_f32_16x16x32_bf16 v[92:95], v[218:221], v[186:189], v[92:95]
	v_mfma_f32_16x16x32_bf16 v[88:91], v[226:229], v[186:189], v[88:91]
	v_mfma_f32_16x16x32_bf16 v[84:87], v[218:221], v[194:197], v[84:87]
	v_mfma_f32_16x16x32_bf16 v[80:83], v[226:229], v[194:197], v[80:83]
	v_mfma_f32_16x16x32_bf16 v[76:79], v[218:221], v[202:205], v[76:79]
	v_mfma_f32_16x16x32_bf16 v[72:75], v[226:229], v[202:205], v[72:75]
	v_mfma_f32_16x16x32_bf16 v[68:71], v[218:221], v[210:213], v[68:71]
	v_mfma_f32_16x16x32_bf16 v[64:67], v[226:229], v[210:213], v[64:67]
	v_readfirstlane_b32 s47, v143
	v_add_u32_e32 v163, 0x2000, v143
	v_lshl_add_u64 v[230:231], v[234:235], 0, s[24:25]
	s_mov_b32 m0, s47
	v_readfirstlane_b32 s47, v163
	s_barrier
	global_load_lds_dwordx4 v[230:231], off
	v_lshl_add_u64 v[230:231], v[236:237], 0, s[24:25]
	s_mov_b32 m0, s47
	s_nop 0
	global_load_lds_dwordx4 v[230:231], off
	ds_read_b128 v[182:185], v151 offset:16384
	ds_read_b128 v[186:189], v151 offset:17408
	ds_read_b128 v[190:193], v150 offset:16384
	ds_read_b128 v[194:197], v150 offset:17408
	ds_read_b128 v[198:201], v149 offset:16384
	ds_read_b128 v[202:205], v149 offset:17408
	ds_read_b128 v[206:209], v148 offset:16384
	ds_read_b128 v[210:213], v148 offset:17408
	s_barrier
	s_waitcnt lgkmcnt(0)
	s_waitcnt lgkmcnt(0)
	v_mfma_f32_16x16x32_bf16 v[60:63], v[164:167], v[182:185], v[60:63]
	v_mfma_f32_16x16x32_bf16 v[56:59], v[174:177], v[182:185], v[56:59]
	v_mfma_f32_16x16x32_bf16 v[52:55], v[164:167], v[190:193], v[52:55]
	v_mfma_f32_16x16x32_bf16 v[48:51], v[174:177], v[190:193], v[48:51]
	v_mfma_f32_16x16x32_bf16 v[44:47], v[164:167], v[198:201], v[44:47]
	v_mfma_f32_16x16x32_bf16 v[40:43], v[174:177], v[198:201], v[40:43]
	v_mfma_f32_16x16x32_bf16 v[36:39], v[164:167], v[206:209], v[36:39]
	v_mfma_f32_16x16x32_bf16 v[32:35], v[174:177], v[206:209], v[32:35]
	v_mfma_f32_16x16x32_bf16 v[60:63], v[170:173], v[186:189], v[60:63]
	v_mfma_f32_16x16x32_bf16 v[56:59], v[178:181], v[186:189], v[56:59]
	v_mfma_f32_16x16x32_bf16 v[52:55], v[170:173], v[194:197], v[52:55]
	v_mfma_f32_16x16x32_bf16 v[48:51], v[178:181], v[194:197], v[48:51]
	v_mfma_f32_16x16x32_bf16 v[44:47], v[170:173], v[202:205], v[44:47]
	v_mfma_f32_16x16x32_bf16 v[40:43], v[178:181], v[202:205], v[40:43]
	v_mfma_f32_16x16x32_bf16 v[36:39], v[170:173], v[210:213], v[36:39]
	v_mfma_f32_16x16x32_bf16 v[32:35], v[178:181], v[210:213], v[32:35]
	s_barrier
; #define STAGE(P, BASE, LD, br, kt) do { const char* _g = (const char*)((BASE) + (size_t)(br) * (LD) + (size_t)(kt) * 64); \
;     for (int _i = 0; _i < 2; ++_i) { int _b = tidx * 16 + _i * 8192; int _r, _c; stage_rc(_b, _r, _c); \
;       __builtin_amdgcn_global_load_lds((const unsigned*)(_g + (unsigned)((_r * (LD) + _c) * 2)), (unsigned*)((char*)(P) + _b), 16, 0, 0); } } while (0)
; #define LDA(dst, b, h) for (int m = 0; m < 4; ++m) for (int k = 0; k < 2; ++k) \
;     dst[m][k] = *reinterpret_cast<const bf16x8*>((char*)SA(b, h) + lds_byte(wr * 64 + m * 16 + fr, k * 32 + fq * 8))
; #define LDB(dst, b, h) for (int n = 0; n < 2; ++n) for (int k = 0; k < 2; ++k) \
;     dst[n][k] = *reinterpret_cast<const bf16x8*>((char*)SB(b, h) + lds_byte(wc * 32 + n * 16 + fr, k * 32 + fq * 8))
; #define MMA(ai, bj, At_, Bt_) do { __builtin_amdgcn_s_setprio(1); \
;     for (int k = 0; k < 2; ++k) for (int m = 0; m < 4; ++m) for (int n = 0; n < 2; ++n) \
;       acc[ai][bj][m][n] = __builtin_amdgcn_mfma_f32_16x16x32_bf16(At_[m][k], Bt_[n][k], acc[ai][bj][m][n], 0, 0, 0); \
;     __builtin_amdgcn_s_setprio(0); } while (0)
; #define WAIT_V(n) asm volatile("s_waitcnt vmcnt(" #n ")" ::: "memory")
; #define WAIT_L(n) asm volatile("s_waitcnt lgkmcnt(" #n ")" ::: "memory")
; #define BAR __builtin_amdgcn_s_barrier()
; #define SCHED __builtin_amdgcn_sched_barrier(0)
; template <int EPI, int lda, int ldb, int N, int K>
; __device__ __forceinline__ void gemm_phase(const u16* __restrict__ A, const u16* __restrict__ Bt, const GemmEpi ep, int wv) {
;     ...
;       STAGE(SB(0, 1), Bt, ldb, bcol + HALF, t + 2);
;       WAIT_V(6); BAR; MMA(1, 1, At, B1); BAR;
;       LDB(B0, 1, 0); SCHED; LDA(At, 1, 0); STAGE(SA(0, 1), Ab, lda, brow + HALF, t + 2);
;       WAIT_L(8); BAR; WAIT_L(0); MMA(0, 0, At, B0); BAR; SCHED;
;       LDB(B1, 1, 1); STAGE(SB(1, 0), Bt, ldb, bcol, t + 3);
;       BAR; WAIT_L(0); MMA(0, 1, At, B1); BAR;
;       LDA(At, 1, 1); STAGE(SA(1, 0), Ab, lda, brow, t + 3);
	v_add_u32_e32 v164, s56, v153
	v_add_u32_e32 v165, 0x2000, v164
	v_readfirstlane_b32 s47, v164
	v_lshl_add_u64 v[166:167], v[238:239], 0, s[26:27]
	s_mov_b32 m0, s47
	v_readfirstlane_b32 s47, v165
	global_load_lds_dwordx4 v[166:167], off
	v_lshl_add_u64 v[166:167], v[240:241], 0, s[26:27]
	s_mov_b32 m0, s47
	s_nop 0
	global_load_lds_dwordx4 v[166:167], off
	s_waitcnt vmcnt(6)
	s_barrier
	v_mfma_f32_16x16x32_bf16 v[28:31], v[214:217], v[182:185], v[28:31]
	v_mfma_f32_16x16x32_bf16 v[24:27], v[222:225], v[182:185], v[24:27]
	v_mfma_f32_16x16x32_bf16 v[20:23], v[214:217], v[190:193], v[20:23]
	v_mfma_f32_16x16x32_bf16 v[16:19], v[222:225], v[190:193], v[16:19]
	v_mfma_f32_16x16x32_bf16 v[12:15], v[214:217], v[198:201], v[12:15]
	v_mfma_f32_16x16x32_bf16 v[8:11], v[222:225], v[198:201], v[8:11]
	v_mfma_f32_16x16x32_bf16 v[4:7], v[214:217], v[206:209], v[4:7]
	v_mfma_f32_16x16x32_bf16 v[0:3], v[222:225], v[206:209], v[0:3]
	v_mfma_f32_16x16x32_bf16 v[28:31], v[218:221], v[186:189], v[28:31]
	v_mfma_f32_16x16x32_bf16 v[24:27], v[226:229], v[186:189], v[24:27]
	v_mfma_f32_16x16x32_bf16 v[20:23], v[218:221], v[194:197], v[20:23]
	v_mfma_f32_16x16x32_bf16 v[16:19], v[226:229], v[194:197], v[16:19]
	v_mfma_f32_16x16x32_bf16 v[12:15], v[218:221], v[202:205], v[12:15]
	v_mfma_f32_16x16x32_bf16 v[8:11], v[226:229], v[202:205], v[8:11]
	v_mfma_f32_16x16x32_bf16 v[4:7], v[218:221], v[210:213], v[4:7]
	v_mfma_f32_16x16x32_bf16 v[0:3], v[226:229], v[210:213], v[0:3]
	s_barrier
	ds_read_b128 v[170:173], v154
	ds_read_b128 v[174:177], v154 offset:1024
	ds_read_b128 v[178:181], v154 offset:2048
	ds_read_b128 v[182:185], v154 offset:3072
	v_add_u32_e32 v166, 0x4000, v143
	v_add_u32_e32 v167, 0x6000, v143
	v_readfirstlane_b32 s47, v166
	v_lshl_add_u64 v[218:219], v[234:235], 0, s[34:35]
	s_mov_b32 m0, s47
	v_readfirstlane_b32 s47, v167
	global_load_lds_dwordx4 v[218:219], off
	v_lshl_add_u64 v[218:219], v[236:237], 0, s[34:35]
	s_mov_b32 m0, s47
	s_nop 0
	global_load_lds_dwordx4 v[218:219], off
	ds_read_b128 v[186:189], v151 offset:32768
	ds_read_b128 v[190:193], v151 offset:33792
	ds_read_b128 v[194:197], v150 offset:32768
	ds_read_b128 v[198:201], v150 offset:33792
	ds_read_b128 v[202:205], v149 offset:32768
	ds_read_b128 v[206:209], v149 offset:33792
	ds_read_b128 v[210:213], v148 offset:32768
	ds_read_b128 v[214:217], v148 offset:33792
	s_waitcnt lgkmcnt(8)
	s_barrier
	s_waitcnt lgkmcnt(0)
	s_waitcnt lgkmcnt(0)
	v_mfma_f32_16x16x32_bf16 v[124:127], v[170:173], v[186:189], v[124:127]
	v_mfma_f32_16x16x32_bf16 v[120:123], v[178:181], v[186:189], v[120:123]
	v_mfma_f32_16x16x32_bf16 v[116:119], v[170:173], v[194:197], v[116:119]
	v_mfma_f32_16x16x32_bf16 v[112:115], v[178:181], v[194:197], v[112:115]
	v_mfma_f32_16x16x32_bf16 v[108:111], v[170:173], v[202:205], v[108:111]
	v_mfma_f32_16x16x32_bf16 v[104:107], v[178:181], v[202:205], v[104:107]
	v_mfma_f32_16x16x32_bf16 v[100:103], v[170:173], v[210:213], v[100:103]
	v_mfma_f32_16x16x32_bf16 v[96:99], v[178:181], v[210:213], v[96:99]
	v_mfma_f32_16x16x32_bf16 v[124:127], v[174:177], v[190:193], v[124:127]
	v_mfma_f32_16x16x32_bf16 v[120:123], v[182:185], v[190:193], v[120:123]
	v_mfma_f32_16x16x32_bf16 v[116:119], v[174:177], v[198:201], v[116:119]
	v_mfma_f32_16x16x32_bf16 v[112:115], v[182:185], v[198:201], v[112:115]
	v_mfma_f32_16x16x32_bf16 v[108:111], v[174:177], v[206:209], v[108:111]
	v_mfma_f32_16x16x32_bf16 v[104:107], v[182:185], v[206:209], v[104:107]
	v_mfma_f32_16x16x32_bf16 v[100:103], v[174:177], v[214:217], v[100:103]
	v_mfma_f32_16x16x32_bf16 v[96:99], v[182:185], v[214:217], v[96:99]
	s_barrier
	v_readfirstlane_b32 s47, v155
	v_add_u32_e32 v244, 0x2000, v155
	v_lshl_add_u64 v[242:243], v[238:239], 0, s[36:37]
	s_mov_b32 m0, s47
	v_readfirstlane_b32 s47, v244
	global_load_lds_dwordx4 v[242:243], off
	v_lshl_add_u64 v[242:243], v[240:241], 0, s[36:37]
	s_mov_b32 m0, s47
	s_nop 0
	global_load_lds_dwordx4 v[242:243], off
	ds_read_b128 v[218:221], v152
	ds_read_b128 v[222:225], v152 offset:1024
	ds_read_b128 v[226:229], v152 offset:2048
	ds_read_b128 v[230:233], v152 offset:3072
	s_barrier
	s_waitcnt lgkmcnt(0)
	s_waitcnt lgkmcnt(0)
	v_mfma_f32_16x16x32_bf16 v[92:95], v[218:221], v[186:189], v[92:95]
	v_mfma_f32_16x16x32_bf16 v[88:91], v[226:229], v[186:189], v[88:91]
	v_mfma_f32_16x16x32_bf16 v[84:87], v[218:221], v[194:197], v[84:87]
	v_mfma_f32_16x16x32_bf16 v[80:83], v[226:229], v[194:197], v[80:83]
	v_mfma_f32_16x16x32_bf16 v[76:79], v[218:221], v[202:205], v[76:79]
	v_mfma_f32_16x16x32_bf16 v[72:75], v[226:229], v[202:205], v[72:75]
	v_mfma_f32_16x16x32_bf16 v[68:71], v[218:221], v[210:213], v[68:71]
	v_mfma_f32_16x16x32_bf16 v[64:67], v[226:229], v[210:213], v[64:67]
	v_mfma_f32_16x16x32_bf16 v[92:95], v[222:225], v[190:193], v[92:95]
	v_mfma_f32_16x16x32_bf16 v[88:91], v[230:233], v[190:193], v[88:91]
	v_mfma_f32_16x16x32_bf16 v[84:87], v[222:225], v[198:201], v[84:87]
	v_mfma_f32_16x16x32_bf16 v[80:83], v[230:233], v[198:201], v[80:83]
	v_mfma_f32_16x16x32_bf16 v[76:79], v[222:225], v[206:209], v[76:79]
	v_mfma_f32_16x16x32_bf16 v[72:75], v[230:233], v[206:209], v[72:75]
	v_mfma_f32_16x16x32_bf16 v[68:71], v[222:225], v[214:217], v[68:71]
	v_mfma_f32_16x16x32_bf16 v[64:67], v[230:233], v[214:217], v[64:67]
	v_readfirstlane_b32 s47, v156
	v_lshl_add_u64 v[234:235], v[234:235], 0, s[38:39]
	s_mov_b32 m0, s47
	v_readfirstlane_b32 s47, v157
	s_barrier
; #define STAGE(P, BASE, LD, br, kt) do { const char* _g = (const char*)((BASE) + (size_t)(br) * (LD) + (size_t)(kt) * 64); \
;     for (int _i = 0; _i < 2; ++_i) { int _b = tidx * 16 + _i * 8192; int _r, _c; stage_rc(_b, _r, _c); \
;       __builtin_amdgcn_global_load_lds((const unsigned*)(_g + (unsigned)((_r * (LD) + _c) * 2)), (unsigned*)((char*)(P) + _b), 16, 0, 0); } } while (0)
; #define LDA(dst, b, h) for (int m = 0; m < 4; ++m) for (int k = 0; k < 2; ++k) \
;     dst[m][k] = *reinterpret_cast<const bf16x8*>((char*)SA(b, h) + lds_byte(wr * 64 + m * 16 + fr, k * 32 + fq * 8))
; #define LDB(dst, b, h) for (int n = 0; n < 2; ++n) for (int k = 0; k < 2; ++k) \
;     dst[n][k] = *reinterpret_cast<const bf16x8*>((char*)SB(b, h) + lds_byte(wc * 32 + n * 16 + fr, k * 32 + fq * 8))
; #define MMA(ai, bj, At_, Bt_) do { __builtin_amdgcn_s_setprio(1); \
;     for (int k = 0; k < 2; ++k) for (int m = 0; m < 4; ++m) for (int n = 0; n < 2; ++n) \
;       acc[ai][bj][m][n] = __builtin_amdgcn_mfma_f32_16x16x32_bf16(At_[m][k], Bt_[n][k], acc[ai][bj][m][n], 0, 0, 0); \
;     __builtin_amdgcn_s_setprio(0); } while (0)
; #define WAIT_V(n) asm volatile("s_waitcnt vmcnt(" #n ")" ::: "memory")
; #define WAIT_L(n) asm volatile("s_waitcnt lgkmcnt(" #n ")" ::: "memory")
; #define BAR __builtin_amdgcn_s_barrier()
; #define SCHED __builtin_amdgcn_sched_barrier(0)
; template <int EPI, int lda, int ldb, int N, int K>
; __device__ __forceinline__ void gemm_phase(const u16* __restrict__ A, const u16* __restrict__ Bt, const GemmEpi ep, int wv) {
;     ...
;       LDA(At, 1, 1); STAGE(SA(1, 0), Ab, lda, brow, t + 3);
;       BAR; WAIT_L(0); MMA(1, 0, At, B0); BAR; SCHED;
;       STAGE(SB(1, 1), Bt, ldb, bcol + HALF, t + 3);
;       WAIT_V(6); BAR; MMA(1, 1, At, B1); BAR;
;     }
;     { LDB(B0, 0, 0); LDA(At, 0, 0); STAGE(SA(1, 1), Ab, lda, brow + HALF, nt - 1);
;       BAR; WAIT_L(0); MMA(0, 0, At, B0); BAR;
	global_load_lds_dwordx4 v[234:235], off
	v_lshl_add_u64 v[234:235], v[236:237], 0, s[38:39]
	s_mov_b32 m0, s47
	s_nop 0
	global_load_lds_dwordx4 v[234:235], off
	ds_read_b128 v[186:189], v151 offset:49152
	ds_read_b128 v[190:193], v151 offset:50176
	ds_read_b128 v[194:197], v150 offset:49152
	ds_read_b128 v[198:201], v150 offset:50176
	ds_read_b128 v[202:205], v149 offset:49152
	ds_read_b128 v[206:209], v149 offset:50176
	ds_read_b128 v[210:213], v148 offset:49152
	ds_read_b128 v[214:217], v148 offset:50176
	s_barrier
	s_waitcnt lgkmcnt(0)
	s_waitcnt lgkmcnt(0)
	v_mfma_f32_16x16x32_bf16 v[60:63], v[170:173], v[186:189], v[60:63]
	v_mfma_f32_16x16x32_bf16 v[56:59], v[178:181], v[186:189], v[56:59]
	v_mfma_f32_16x16x32_bf16 v[52:55], v[170:173], v[194:197], v[52:55]
	v_mfma_f32_16x16x32_bf16 v[48:51], v[178:181], v[194:197], v[48:51]
	v_mfma_f32_16x16x32_bf16 v[44:47], v[170:173], v[202:205], v[44:47]
	v_mfma_f32_16x16x32_bf16 v[40:43], v[178:181], v[202:205], v[40:43]
	v_mfma_f32_16x16x32_bf16 v[36:39], v[170:173], v[210:213], v[36:39]
	v_mfma_f32_16x16x32_bf16 v[32:35], v[178:181], v[210:213], v[32:35]
	v_mfma_f32_16x16x32_bf16 v[60:63], v[174:177], v[190:193], v[60:63]
	v_mfma_f32_16x16x32_bf16 v[56:59], v[182:185], v[190:193], v[56:59]
	v_mfma_f32_16x16x32_bf16 v[52:55], v[174:177], v[198:201], v[52:55]
	v_mfma_f32_16x16x32_bf16 v[48:51], v[182:185], v[198:201], v[48:51]
	v_mfma_f32_16x16x32_bf16 v[44:47], v[174:177], v[206:209], v[44:47]
	v_mfma_f32_16x16x32_bf16 v[40:43], v[182:185], v[206:209], v[40:43]
	v_mfma_f32_16x16x32_bf16 v[36:39], v[174:177], v[214:217], v[36:39]
	v_mfma_f32_16x16x32_bf16 v[32:35], v[182:185], v[214:217], v[32:35]
	s_barrier
	v_readfirstlane_b32 s47, v158
	v_add_u32_e32 v172, 0x2000, v158
	v_lshl_add_u64 v[170:171], v[238:239], 0, s[40:41]
	s_mov_b32 m0, s47
	v_readfirstlane_b32 s47, v172
	global_load_lds_dwordx4 v[170:171], off
	v_lshl_add_u64 v[170:171], v[240:241], 0, s[40:41]
	s_mov_b32 m0, s47
	s_nop 0
	global_load_lds_dwordx4 v[170:171], off
	s_waitcnt vmcnt(6)
	s_barrier
	v_mfma_f32_16x16x32_bf16 v[28:31], v[218:221], v[186:189], v[28:31]
	v_mfma_f32_16x16x32_bf16 v[24:27], v[226:229], v[186:189], v[24:27]
	v_mfma_f32_16x16x32_bf16 v[20:23], v[218:221], v[194:197], v[20:23]
	v_mfma_f32_16x16x32_bf16 v[16:19], v[226:229], v[194:197], v[16:19]
	v_mfma_f32_16x16x32_bf16 v[12:15], v[218:221], v[202:205], v[12:15]
	v_mfma_f32_16x16x32_bf16 v[8:11], v[226:229], v[202:205], v[8:11]
	v_mfma_f32_16x16x32_bf16 v[4:7], v[218:221], v[210:213], v[4:7]
	v_mfma_f32_16x16x32_bf16 v[0:3], v[226:229], v[210:213], v[0:3]
	v_mfma_f32_16x16x32_bf16 v[28:31], v[222:225], v[190:193], v[28:31]
	v_mfma_f32_16x16x32_bf16 v[24:27], v[230:233], v[190:193], v[24:27]
	v_mfma_f32_16x16x32_bf16 v[20:23], v[222:225], v[198:201], v[20:23]
	v_mfma_f32_16x16x32_bf16 v[16:19], v[230:233], v[198:201], v[16:19]
	v_mfma_f32_16x16x32_bf16 v[12:15], v[222:225], v[206:209], v[12:15]
	v_mfma_f32_16x16x32_bf16 v[8:11], v[230:233], v[206:209], v[8:11]
	v_mfma_f32_16x16x32_bf16 v[4:7], v[222:225], v[214:217], v[4:7]
	v_mfma_f32_16x16x32_bf16 v[0:3], v[230:233], v[214:217], v[0:3]
	s_add_i32 s46, s46, 2
	s_add_u32 s44, s44, 0x100
	s_addc_u32 s45, s45, 0
	s_cmp_gt_u32 s46, 27
	s_barrier
	s_cbranch_scc0 .LBB0_1448
	s_lshl_b64 s[44:45], s[16:17], 12
	s_add_u32 s44, s14, s44
	s_addc_u32 s45, s15, s45
	s_add_u32 s44, s44, 0x80000
	s_addc_u32 s45, s45, 0
	v_lshl_add_u64 v[156:157], s[44:45], 0, v[128:129]
	v_readfirstlane_b32 s46, v168
	v_lshl_add_u64 v[156:157], v[156:157], 0, s[42:43]
	s_mov_b32 m0, s46
	ds_read_b128 v[134:137], v160
	ds_read_b128 v[138:141], v160 offset:1024
	ds_read_b128 v[170:173], v160 offset:2048
	ds_read_b128 v[174:177], v160 offset:3072
	ds_read_b128 v[178:181], v151
	ds_read_b128 v[182:185], v151 offset:1024
	ds_read_b128 v[186:189], v150
	ds_read_b128 v[190:193], v150 offset:1024
	ds_read_b128 v[194:197], v149
	ds_read_b128 v[198:201], v149 offset:1024
	ds_read_b128 v[202:205], v148
	ds_read_b128 v[206:209], v148 offset:1024
	global_load_lds_dwordx4 v[156:157], off
	v_lshl_add_u64 v[156:157], s[44:45], 0, v[132:133]
	v_readfirstlane_b32 s44, v169
	v_lshl_add_u64 v[156:157], v[156:157], 0, s[42:43]
	s_mov_b32 m0, s44
	s_nop 0
	global_load_lds_dwordx4 v[156:157], off
	s_barrier
	s_waitcnt lgkmcnt(0)
	s_waitcnt lgkmcnt(0)
	v_mfma_f32_16x16x32_bf16 v[124:127], v[134:137], v[178:181], v[124:127]
	v_mfma_f32_16x16x32_bf16 v[120:123], v[170:173], v[178:181], v[120:123]
	v_mfma_f32_16x16x32_bf16 v[116:119], v[134:137], v[186:189], v[116:119]
	v_mfma_f32_16x16x32_bf16 v[112:115], v[170:173], v[186:189], v[112:115]
	v_mfma_f32_16x16x32_bf16 v[108:111], v[134:137], v[194:197], v[108:111]
	v_mfma_f32_16x16x32_bf16 v[104:107], v[170:173], v[194:197], v[104:107]
	v_mfma_f32_16x16x32_bf16 v[100:103], v[134:137], v[202:205], v[100:103]
	v_mfma_f32_16x16x32_bf16 v[96:99], v[170:173], v[202:205], v[96:99]
	v_mfma_f32_16x16x32_bf16 v[124:127], v[138:141], v[182:185], v[124:127]
	v_mfma_f32_16x16x32_bf16 v[120:123], v[174:177], v[182:185], v[120:123]
	v_mfma_f32_16x16x32_bf16 v[116:119], v[138:141], v[190:193], v[116:119]
	v_mfma_f32_16x16x32_bf16 v[112:115], v[174:177], v[190:193], v[112:115]
	v_mfma_f32_16x16x32_bf16 v[108:111], v[138:141], v[198:201], v[108:111]
	v_mfma_f32_16x16x32_bf16 v[104:107], v[174:177], v[198:201], v[104:107]
	v_mfma_f32_16x16x32_bf16 v[100:103], v[138:141], v[206:209], v[100:103]
	v_mfma_f32_16x16x32_bf16 v[96:99], v[174:177], v[206:209], v[96:99]
	s_barrier
	ds_read_b128 v[210:213], v159
	ds_read_b128 v[214:217], v159 offset:1024
	ds_read_b128 v[218:221], v159 offset:2048
	ds_read_b128 v[156:159], v159 offset:3072
	s_barrier
; #define LDA(dst, b, h) for (int m = 0; m < 4; ++m) for (int k = 0; k < 2; ++k) \
;     dst[m][k] = *reinterpret_cast<const bf16x8*>((char*)SA(b, h) + lds_byte(wr * 64 + m * 16 + fr, k * 32 + fq * 8))
; #define LDB(dst, b, h) for (int n = 0; n < 2; ++n) for (int k = 0; k < 2; ++k) \
;     dst[n][k] = *reinterpret_cast<const bf16x8*>((char*)SB(b, h) + lds_byte(wc * 32 + n * 16 + fr, k * 32 + fq * 8))
; #define MMA(ai, bj, At_, Bt_) do { __builtin_amdgcn_s_setprio(1); \
;     for (int k = 0; k < 2; ++k) for (int m = 0; m < 4; ++m) for (int n = 0; n < 2; ++n) \
;       acc[ai][bj][m][n] = __builtin_amdgcn_mfma_f32_16x16x32_bf16(At_[m][k], Bt_[n][k], acc[ai][bj][m][n], 0, 0, 0); \
;     __builtin_amdgcn_s_setprio(0); } while (0)
; #define WAIT_V(n) asm volatile("s_waitcnt vmcnt(" #n ")" ::: "memory")
; #define WAIT_L(n) asm volatile("s_waitcnt lgkmcnt(" #n ")" ::: "memory")
; #define BAR __builtin_amdgcn_s_barrier()
; template <int EPI, int lda, int ldb, int N, int K>
; __device__ __forceinline__ void gemm_phase(const u16* __restrict__ A, const u16* __restrict__ Bt, const GemmEpi ep, int wv) {
;     ...
;       BAR; WAIT_L(0); MMA(0, 0, At, B0); BAR;
;       LDB(B1, 0, 1); BAR; WAIT_L(0); MMA(0, 1, At, B1); BAR;
;       LDA(At, 0, 1); WAIT_V(4); BAR; WAIT_L(0); MMA(1, 0, At, B0); MMA(1, 1, At, B1); BAR; }
;     { LDB(B0, 1, 0); LDA(At, 1, 0); WAIT_V(2); BAR; WAIT_L(0); MMA(0, 0, At, B0); BAR;
	s_waitcnt lgkmcnt(0)
	s_waitcnt lgkmcnt(0)
	v_mfma_f32_16x16x32_bf16 v[92:95], v[210:213], v[178:181], v[92:95]
	v_mfma_f32_16x16x32_bf16 v[88:91], v[218:221], v[178:181], v[88:91]
	v_mfma_f32_16x16x32_bf16 v[76:79], v[210:213], v[194:197], v[76:79]
	v_mfma_f32_16x16x32_bf16 v[72:75], v[218:221], v[194:197], v[72:75]
	v_mfma_f32_16x16x32_bf16 v[84:87], v[210:213], v[186:189], v[84:87]
	v_mfma_f32_16x16x32_bf16 v[80:83], v[218:221], v[186:189], v[80:83]
	v_mfma_f32_16x16x32_bf16 v[68:71], v[210:213], v[202:205], v[68:71]
	v_mfma_f32_16x16x32_bf16 v[64:67], v[218:221], v[202:205], v[64:67]
	v_mfma_f32_16x16x32_bf16 v[92:95], v[214:217], v[182:185], v[92:95]
	v_mfma_f32_16x16x32_bf16 v[88:91], v[156:159], v[182:185], v[88:91]
	v_mfma_f32_16x16x32_bf16 v[76:79], v[214:217], v[198:201], v[76:79]
	v_mfma_f32_16x16x32_bf16 v[72:75], v[156:159], v[198:201], v[72:75]
	v_mfma_f32_16x16x32_bf16 v[178:181], v[214:217], v[190:193], v[84:87]
	v_mfma_f32_16x16x32_bf16 v[182:185], v[156:159], v[190:193], v[80:83]
	v_mfma_f32_16x16x32_bf16 v[186:189], v[214:217], v[206:209], v[68:71]
	v_mfma_f32_16x16x32_bf16 v[190:193], v[156:159], v[206:209], v[64:67]
	s_barrier
	s_nop 0
	ds_read_b128 v[64:67], v151 offset:16384
	ds_read_b128 v[68:71], v151 offset:17408
	ds_read_b128 v[80:83], v150 offset:16384
	ds_read_b128 v[84:87], v150 offset:17408
	ds_read_b128 v[194:197], v149 offset:16384
	ds_read_b128 v[198:201], v149 offset:17408
	ds_read_b128 v[202:205], v148 offset:16384
	ds_read_b128 v[206:209], v148 offset:17408
	s_waitcnt vmcnt(4)
	s_barrier
	s_waitcnt lgkmcnt(0)
	s_waitcnt lgkmcnt(0)
	v_mfma_f32_16x16x32_bf16 v[60:63], v[134:137], v[64:67], v[60:63]
	v_mfma_f32_16x16x32_bf16 v[56:59], v[170:173], v[64:67], v[56:59]
	v_mfma_f32_16x16x32_bf16 v[52:55], v[134:137], v[80:83], v[52:55]
	v_mfma_f32_16x16x32_bf16 v[48:51], v[170:173], v[80:83], v[48:51]
	v_mfma_f32_16x16x32_bf16 v[44:47], v[134:137], v[194:197], v[44:47]
	v_mfma_f32_16x16x32_bf16 v[40:43], v[170:173], v[194:197], v[40:43]
	v_mfma_f32_16x16x32_bf16 v[36:39], v[134:137], v[202:205], v[36:39]
	v_mfma_f32_16x16x32_bf16 v[32:35], v[170:173], v[202:205], v[32:35]
	v_mfma_f32_16x16x32_bf16 v[60:63], v[138:141], v[68:71], v[60:63]
	v_mfma_f32_16x16x32_bf16 v[56:59], v[174:177], v[68:71], v[56:59]
	v_mfma_f32_16x16x32_bf16 v[52:55], v[138:141], v[84:87], v[52:55]
	v_mfma_f32_16x16x32_bf16 v[48:51], v[174:177], v[84:87], v[48:51]
	v_mfma_f32_16x16x32_bf16 v[44:47], v[138:141], v[198:201], v[44:47]
	v_mfma_f32_16x16x32_bf16 v[40:43], v[174:177], v[198:201], v[40:43]
	v_mfma_f32_16x16x32_bf16 v[36:39], v[138:141], v[206:209], v[36:39]
	v_mfma_f32_16x16x32_bf16 v[32:35], v[174:177], v[206:209], v[32:35]
	v_mfma_f32_16x16x32_bf16 v[28:31], v[210:213], v[64:67], v[28:31]
	v_mfma_f32_16x16x32_bf16 v[20:23], v[210:213], v[80:83], v[20:23]
	v_mfma_f32_16x16x32_bf16 v[12:15], v[210:213], v[194:197], v[12:15]
	v_mfma_f32_16x16x32_bf16 v[4:7], v[210:213], v[202:205], v[4:7]
	v_mfma_f32_16x16x32_bf16 v[24:27], v[218:221], v[64:67], v[24:27]
	v_mfma_f32_16x16x32_bf16 v[16:19], v[218:221], v[80:83], v[16:19]
	v_mfma_f32_16x16x32_bf16 v[8:11], v[218:221], v[194:197], v[8:11]
	v_mfma_f32_16x16x32_bf16 v[0:3], v[218:221], v[202:205], v[0:3]
	v_mfma_f32_16x16x32_bf16 v[28:31], v[214:217], v[68:71], v[28:31]
	v_mfma_f32_16x16x32_bf16 v[20:23], v[214:217], v[84:87], v[20:23]
	v_mfma_f32_16x16x32_bf16 v[12:15], v[214:217], v[198:201], v[12:15]
	v_mfma_f32_16x16x32_bf16 v[4:7], v[214:217], v[206:209], v[4:7]
	v_mfma_f32_16x16x32_bf16 v[134:137], v[156:159], v[68:71], v[24:27]
	v_mfma_f32_16x16x32_bf16 v[138:141], v[156:159], v[84:87], v[16:19]
	v_mfma_f32_16x16x32_bf16 v[168:171], v[156:159], v[198:201], v[8:11]
	v_mfma_f32_16x16x32_bf16 v[156:159], v[156:159], v[206:209], v[0:3]
	s_barrier
	s_nop 0
	ds_read_b128 v[0:3], v154
	ds_read_b128 v[8:11], v154 offset:1024
	ds_read_b128 v[16:19], v154 offset:2048
	ds_read_b128 v[172:175], v154 offset:3072
	ds_read_b128 v[24:27], v151 offset:32768
	ds_read_b128 v[194:197], v151 offset:33792
	ds_read_b128 v[198:201], v150 offset:32768
	ds_read_b128 v[202:205], v150 offset:33792
	ds_read_b128 v[206:209], v149 offset:32768
	ds_read_b128 v[210:213], v149 offset:33792
	ds_read_b128 v[214:217], v148 offset:32768
	ds_read_b128 v[218:221], v148 offset:33792
	s_waitcnt vmcnt(2)
	s_barrier
; #define LDA(dst, b, h) for (int m = 0; m < 4; ++m) for (int k = 0; k < 2; ++k) \
;     dst[m][k] = *reinterpret_cast<const bf16x8*>((char*)SA(b, h) + lds_byte(wr * 64 + m * 16 + fr, k * 32 + fq * 8))
; #define LDB(dst, b, h) for (int n = 0; n < 2; ++n) for (int k = 0; k < 2; ++k) \
;     dst[n][k] = *reinterpret_cast<const bf16x8*>((char*)SB(b, h) + lds_byte(wc * 32 + n * 16 + fr, k * 32 + fq * 8))
; #define MMA(ai, bj, At_, Bt_) do { __builtin_amdgcn_s_setprio(1); \
;     for (int k = 0; k < 2; ++k) for (int m = 0; m < 4; ++m) for (int n = 0; n < 2; ++n) \
;       acc[ai][bj][m][n] = __builtin_amdgcn_mfma_f32_16x16x32_bf16(At_[m][k], Bt_[n][k], acc[ai][bj][m][n], 0, 0, 0); \
;     __builtin_amdgcn_s_setprio(0); } while (0)
; #define WAIT_V(n) asm volatile("s_waitcnt vmcnt(" #n ")" ::: "memory")
; #define WAIT_L(n) asm volatile("s_waitcnt lgkmcnt(" #n ")" ::: "memory")
; #define BAR __builtin_amdgcn_s_barrier()
; template <int EPI, int lda, int ldb, int N, int K>
; __device__ __forceinline__ void gemm_phase(const u16* __restrict__ A, const u16* __restrict__ Bt, const GemmEpi ep, int wv) {
;     ...
;     { LDB(B0, 1, 0); LDA(At, 1, 0); WAIT_V(2); BAR; WAIT_L(0); MMA(0, 0, At, B0); BAR;
;       LDB(B1, 1, 1); WAIT_V(0); BAR; WAIT_L(0); MMA(0, 1, At, B1); BAR;
;       LDA(At, 1, 1); BAR; WAIT_L(0); MMA(1, 0, At, B0); MMA(1, 1, At, B1); BAR; }
;     if (wr == 0) BAR;
	s_waitcnt lgkmcnt(0)
	s_waitcnt lgkmcnt(0)
	v_mfma_f32_16x16x32_bf16 v[64:67], v[0:3], v[24:27], v[124:127]
	v_mfma_f32_16x16x32_bf16 v[68:71], v[16:19], v[24:27], v[120:123]
	v_mfma_f32_16x16x32_bf16 v[80:83], v[0:3], v[198:201], v[116:119]
	v_mfma_f32_16x16x32_bf16 v[84:87], v[16:19], v[198:201], v[112:115]
	v_mfma_f32_16x16x32_bf16 v[108:111], v[0:3], v[206:209], v[108:111]
	v_mfma_f32_16x16x32_bf16 v[104:107], v[16:19], v[206:209], v[104:107]
	v_mfma_f32_16x16x32_bf16 v[120:123], v[0:3], v[214:217], v[100:103]
	v_mfma_f32_16x16x32_bf16 v[124:127], v[16:19], v[214:217], v[96:99]
	v_mfma_f32_16x16x32_bf16 v[116:119], v[8:11], v[194:197], v[64:67]
	v_mfma_f32_16x16x32_bf16 v[112:115], v[172:175], v[194:197], v[68:71]
	v_mfma_f32_16x16x32_bf16 v[100:103], v[8:11], v[202:205], v[80:83]
	v_mfma_f32_16x16x32_bf16 v[96:99], v[172:175], v[202:205], v[84:87]
	v_mfma_f32_16x16x32_bf16 v[84:87], v[8:11], v[210:213], v[108:111]
	v_mfma_f32_16x16x32_bf16 v[80:83], v[172:175], v[210:213], v[104:107]
	v_mfma_f32_16x16x32_bf16 v[68:71], v[8:11], v[218:221], v[120:123]
	v_mfma_f32_16x16x32_bf16 v[64:67], v[172:175], v[218:221], v[124:127]
	s_barrier
	ds_read_b128 v[222:225], v152
	ds_read_b128 v[226:229], v152 offset:1024
	ds_read_b128 v[230:233], v152 offset:2048
	ds_read_b128 v[152:155], v152 offset:3072
	s_waitcnt vmcnt(0)
	s_barrier
	s_waitcnt lgkmcnt(0)
	s_waitcnt lgkmcnt(0)
	v_mfma_f32_16x16x32_bf16 v[92:95], v[222:225], v[24:27], v[92:95]
	v_mfma_f32_16x16x32_bf16 v[24:27], v[230:233], v[24:27], v[88:91]
	v_mfma_f32_16x16x32_bf16 v[88:91], v[222:225], v[198:201], v[178:181]
	v_mfma_f32_16x16x32_bf16 v[104:107], v[230:233], v[198:201], v[182:185]
	v_mfma_f32_16x16x32_bf16 v[76:79], v[222:225], v[206:209], v[76:79]
	v_mfma_f32_16x16x32_bf16 v[72:75], v[230:233], v[206:209], v[72:75]
	v_mfma_f32_16x16x32_bf16 v[176:179], v[222:225], v[214:217], v[186:189]
	v_mfma_f32_16x16x32_bf16 v[180:183], v[230:233], v[214:217], v[190:193]
	v_mfma_f32_16x16x32_bf16 v[124:127], v[226:229], v[194:197], v[92:95]
	v_mfma_f32_16x16x32_bf16 v[120:123], v[152:155], v[194:197], v[24:27]
	v_mfma_f32_16x16x32_bf16 v[108:111], v[226:229], v[202:205], v[88:91]
	v_mfma_f32_16x16x32_bf16 v[104:107], v[152:155], v[202:205], v[104:107]
	v_mfma_f32_16x16x32_bf16 v[92:95], v[226:229], v[210:213], v[76:79]
	v_mfma_f32_16x16x32_bf16 v[88:91], v[152:155], v[210:213], v[72:75]
	v_mfma_f32_16x16x32_bf16 v[76:79], v[226:229], v[218:221], v[176:179]
	v_mfma_f32_16x16x32_bf16 v[72:75], v[152:155], v[218:221], v[180:183]
	s_barrier
	ds_read_b128 v[176:179], v151 offset:49152
	ds_read_b128 v[180:183], v151 offset:50176
	ds_read_b128 v[184:187], v150 offset:49152
	ds_read_b128 v[188:191], v150 offset:50176
	ds_read_b128 v[192:195], v149 offset:49152
	ds_read_b128 v[196:199], v149 offset:50176
	ds_read_b128 v[200:203], v148 offset:49152
	ds_read_b128 v[148:151], v148 offset:50176
	s_barrier
	s_waitcnt lgkmcnt(0)
	s_waitcnt lgkmcnt(0)
	v_mfma_f32_16x16x32_bf16 v[24:27], v[0:3], v[176:179], v[60:63]
	v_mfma_f32_16x16x32_bf16 v[60:63], v[16:19], v[176:179], v[56:59]
	v_mfma_f32_16x16x32_bf16 v[52:55], v[0:3], v[184:187], v[52:55]
	v_mfma_f32_16x16x32_bf16 v[204:207], v[16:19], v[184:187], v[48:51]
	v_mfma_f32_16x16x32_bf16 v[44:47], v[0:3], v[192:195], v[44:47]
	v_mfma_f32_16x16x32_bf16 v[208:211], v[16:19], v[192:195], v[40:43]
	v_mfma_f32_16x16x32_bf16 v[0:3], v[0:3], v[200:203], v[36:39]
	v_mfma_f32_16x16x32_bf16 v[36:39], v[16:19], v[200:203], v[32:35]
	v_mfma_f32_16x16x32_bf16 v[56:59], v[8:11], v[180:183], v[24:27]
	v_mfma_f32_16x16x32_bf16 v[48:51], v[172:175], v[180:183], v[60:63]
	v_mfma_f32_16x16x32_bf16 v[40:43], v[8:11], v[188:191], v[52:55]
	v_mfma_f32_16x16x32_bf16 v[32:35], v[172:175], v[188:191], v[204:207]
	v_mfma_f32_16x16x32_bf16 v[24:27], v[8:11], v[196:199], v[44:47]
	v_mfma_f32_16x16x32_bf16 v[16:19], v[172:175], v[196:199], v[208:211]
	v_mfma_f32_16x16x32_bf16 v[8:11], v[8:11], v[148:151], v[0:3]
	v_mfma_f32_16x16x32_bf16 v[0:3], v[172:175], v[148:151], v[36:39]
	v_mfma_f32_16x16x32_bf16 v[28:31], v[222:225], v[176:179], v[28:31]
	v_mfma_f32_16x16x32_bf16 v[36:39], v[230:233], v[176:179], v[134:137]
	v_mfma_f32_16x16x32_bf16 v[20:23], v[222:225], v[184:187], v[20:23]
	v_mfma_f32_16x16x32_bf16 v[134:137], v[230:233], v[184:187], v[138:141]
	v_mfma_f32_16x16x32_bf16 v[12:15], v[222:225], v[192:195], v[12:15]
	v_mfma_f32_16x16x32_bf16 v[138:141], v[230:233], v[192:195], v[168:171]
	v_mfma_f32_16x16x32_bf16 v[4:7], v[222:225], v[200:203], v[4:7]
	v_mfma_f32_16x16x32_bf16 v[156:159], v[230:233], v[200:203], v[156:159]
	v_mfma_f32_16x16x32_bf16 v[60:63], v[226:229], v[180:183], v[28:31]
	v_mfma_f32_16x16x32_bf16 v[52:55], v[152:155], v[180:183], v[36:39]
	v_mfma_f32_16x16x32_bf16 v[44:47], v[226:229], v[188:191], v[20:23]
	v_mfma_f32_16x16x32_bf16 v[36:39], v[152:155], v[188:191], v[134:137]
	v_mfma_f32_16x16x32_bf16 v[28:31], v[226:229], v[196:199], v[12:15]
	v_mfma_f32_16x16x32_bf16 v[20:23], v[152:155], v[196:199], v[138:141]
	v_mfma_f32_16x16x32_bf16 v[12:15], v[226:229], v[148:151], v[4:7]
	v_mfma_f32_16x16x32_bf16 v[4:7], v[152:155], v[148:151], v[156:159]
	v_cmp_gt_u32_e32 vcc, s60, v130
	s_barrier
	s_and_saveexec_b64 s[44:45], vcc
	s_cbranch_execz .LBB0_1451
	s_barrier

; #define STAGE(P, BASE, LD, br, kt) do { const char* _g = (const char*)((BASE) + (size_t)(br) * (LD) + (size_t)(kt) * 64); \
;     for (int _i = 0; _i < 2; ++_i) { int _b = tidx * 16 + _i * 8192; int _r, _c; stage_rc(_b, _r, _c); \
;       __builtin_amdgcn_global_load_lds((const unsigned*)(_g + (unsigned)((_r * (LD) + _c) * 2)), (unsigned*)((char*)(P) + _b), 16, 0, 0); } } while (0)
; #define LDA(dst, b, h) for (int m = 0; m < 4; ++m) for (int k = 0; k < 2; ++k) \
;     dst[m][k] = *reinterpret_cast<const bf16x8*>((char*)SA(b, h) + lds_byte(wr * 64 + m * 16 + fr, k * 32 + fq * 8))
; #define LDB(dst, b, h) for (int n = 0; n < 2; ++n) for (int k = 0; k < 2; ++k) \
;     dst[n][k] = *reinterpret_cast<const bf16x8*>((char*)SB(b, h) + lds_byte(wc * 32 + n * 16 + fr, k * 32 + fq * 8))
; #define MMA(ai, bj, At_, Bt_) do { __builtin_amdgcn_s_setprio(1); \
;     for (int k = 0; k < 2; ++k) for (int m = 0; m < 4; ++m) for (int n = 0; n < 2; ++n) \
;       acc[ai][bj][m][n] = __builtin_amdgcn_mfma_f32_16x16x32_bf16(At_[m][k], Bt_[n][k], acc[ai][bj][m][n], 0, 0, 0); \
;     __builtin_amdgcn_s_setprio(0); } while (0)
; #define WAIT_L(n) asm volatile("s_waitcnt lgkmcnt(" #n ")" ::: "memory")
; #define BAR __builtin_amdgcn_s_barrier()
; #define SCHED __builtin_amdgcn_sched_barrier(0)
; template <int EPI, int lda, int ldb, int N, int K>
; __device__ __forceinline__ void gemm_phase(const u16* __restrict__ A, const u16* __restrict__ Bt, const GemmEpi ep, int wv) {
;     ...
;       LDB(B0, 0, 0); SCHED; LDA(At, 0, 0); STAGE(SA(1, 1), Ab, lda, brow + HALF, t + 1);
;       WAIT_L(8); BAR; WAIT_L(0); MMA(0, 0, At, B0); BAR; SCHED;
;       LDB(B1, 0, 1); STAGE(SB(0, 0), Bt, ldb, bcol, t + 2);
;       BAR; WAIT_L(0); MMA(0, 1, At, B1); BAR;
;       LDA(At, 0, 1); STAGE(SA(0, 0), Ab, lda, brow, t + 2);
;       BAR; WAIT_L(0); MMA(1, 0, At, B0); BAR; SCHED;
;       STAGE(SB(0, 1), Bt, ldb, bcol + HALF, t + 2);
.LBB0_1564:
	ds_read_b128 v[172:175], v161
	ds_read_b128 v[176:179], v161 offset:1024
	ds_read_b128 v[180:183], v161 offset:2048
	ds_read_b128 v[184:187], v161 offset:3072
	v_add_u32_e32 v169, 0xc000, v148
	v_lshl_add_u64 v[236:237], v[136:137], 0, s[40:41]
	v_readfirstlane_b32 s43, v169
	v_add_u32_e32 v170, 0xe000, v148
	v_lshl_add_u64 v[162:163], v[236:237], 0, s[14:15]
	s_mov_b32 m0, s43
	v_lshl_add_u64 v[238:239], v[134:135], 0, s[40:41]
	v_readfirstlane_b32 s43, v170
	global_load_lds_dwordx4 v[162:163], off
	v_lshl_add_u64 v[162:163], v[238:239], 0, s[14:15]
	s_mov_b32 m0, s43
	s_nop 0
	global_load_lds_dwordx4 v[162:163], off
	ds_read_b128 v[164:167], v152
	ds_read_b128 v[188:191], v152 offset:1024
	ds_read_b128 v[192:195], v151
	ds_read_b128 v[196:199], v151 offset:1024
	ds_read_b128 v[200:203], v150
	ds_read_b128 v[204:207], v150 offset:1024
	ds_read_b128 v[208:211], v149
	ds_read_b128 v[212:215], v149 offset:1024
	s_waitcnt lgkmcnt(8)
	s_barrier
	s_waitcnt lgkmcnt(0)
	s_waitcnt lgkmcnt(0)
	v_mfma_f32_16x16x32_bf16 v[124:127], v[172:175], v[164:167], v[124:127]
	v_mfma_f32_16x16x32_bf16 v[120:123], v[180:183], v[164:167], v[120:123]
	v_mfma_f32_16x16x32_bf16 v[116:119], v[172:175], v[192:195], v[116:119]
	v_mfma_f32_16x16x32_bf16 v[112:115], v[180:183], v[192:195], v[112:115]
	v_mfma_f32_16x16x32_bf16 v[108:111], v[172:175], v[200:203], v[108:111]
	v_mfma_f32_16x16x32_bf16 v[104:107], v[180:183], v[200:203], v[104:107]
	v_mfma_f32_16x16x32_bf16 v[100:103], v[172:175], v[208:211], v[100:103]
	v_mfma_f32_16x16x32_bf16 v[96:99], v[180:183], v[208:211], v[96:99]
	v_mfma_f32_16x16x32_bf16 v[124:127], v[176:179], v[188:191], v[124:127]
	v_mfma_f32_16x16x32_bf16 v[120:123], v[184:187], v[188:191], v[120:123]
	v_mfma_f32_16x16x32_bf16 v[116:119], v[176:179], v[196:199], v[116:119]
	v_mfma_f32_16x16x32_bf16 v[112:115], v[184:187], v[196:199], v[112:115]
	v_mfma_f32_16x16x32_bf16 v[108:111], v[176:179], v[204:207], v[108:111]
	v_mfma_f32_16x16x32_bf16 v[104:107], v[184:187], v[204:207], v[104:107]
	v_mfma_f32_16x16x32_bf16 v[100:103], v[176:179], v[212:215], v[100:103]
	v_mfma_f32_16x16x32_bf16 v[96:99], v[184:187], v[212:215], v[96:99]
	s_barrier
	v_add_u32_e32 v162, s52, v153
	v_lshl_add_u64 v[240:241], v[140:141], 0, s[40:41]
	v_readfirstlane_b32 s43, v162
	v_add_u32_e32 v163, 0x2000, v162
	v_lshl_add_u64 v[232:233], v[240:241], 0, s[16:17]
	s_mov_b32 m0, s43
	v_lshl_add_u64 v[242:243], v[138:139], 0, s[40:41]
	v_readfirstlane_b32 s43, v163
	global_load_lds_dwordx4 v[232:233], off
	v_lshl_add_u64 v[232:233], v[242:243], 0, s[16:17]
	s_mov_b32 m0, s43
	s_nop 0
	global_load_lds_dwordx4 v[232:233], off
	ds_read_b128 v[216:219], v160
	ds_read_b128 v[220:223], v160 offset:1024
	ds_read_b128 v[224:227], v160 offset:2048
	ds_read_b128 v[228:231], v160 offset:3072
	s_barrier
	s_waitcnt lgkmcnt(0)
	s_waitcnt lgkmcnt(0)
	v_mfma_f32_16x16x32_bf16 v[92:95], v[216:219], v[164:167], v[92:95]
	v_mfma_f32_16x16x32_bf16 v[88:91], v[224:227], v[164:167], v[88:91]
	v_mfma_f32_16x16x32_bf16 v[84:87], v[216:219], v[192:195], v[84:87]
	v_mfma_f32_16x16x32_bf16 v[80:83], v[224:227], v[192:195], v[80:83]
	v_mfma_f32_16x16x32_bf16 v[76:79], v[216:219], v[200:203], v[76:79]
	v_mfma_f32_16x16x32_bf16 v[72:75], v[224:227], v[200:203], v[72:75]
	v_mfma_f32_16x16x32_bf16 v[68:71], v[216:219], v[208:211], v[68:71]
	v_mfma_f32_16x16x32_bf16 v[64:67], v[224:227], v[208:211], v[64:67]
	v_mfma_f32_16x16x32_bf16 v[92:95], v[220:223], v[188:191], v[92:95]
	v_mfma_f32_16x16x32_bf16 v[88:91], v[228:231], v[188:191], v[88:91]
	v_mfma_f32_16x16x32_bf16 v[84:87], v[220:223], v[196:199], v[84:87]
	v_mfma_f32_16x16x32_bf16 v[80:83], v[228:231], v[196:199], v[80:83]
	v_mfma_f32_16x16x32_bf16 v[76:79], v[220:223], v[204:207], v[76:79]
	v_mfma_f32_16x16x32_bf16 v[72:75], v[228:231], v[204:207], v[72:75]
	v_mfma_f32_16x16x32_bf16 v[68:71], v[220:223], v[212:215], v[68:71]
	v_mfma_f32_16x16x32_bf16 v[64:67], v[228:231], v[212:215], v[64:67]
	v_readfirstlane_b32 s43, v148
	v_lshl_add_u64 v[164:165], v[236:237], 0, s[18:19]
	s_mov_b32 m0, s43
	s_barrier
	global_load_lds_dwordx4 v[164:165], off
	v_add_u32_e32 v164, 0x2000, v148
	v_lshl_add_u64 v[166:167], v[238:239], 0, s[18:19]
	v_readfirstlane_b32 s43, v164
	s_mov_b32 m0, s43
	s_nop 0
	global_load_lds_dwordx4 v[166:167], off
	ds_read_b128 v[188:191], v152 offset:16384
	ds_read_b128 v[192:195], v152 offset:17408
	ds_read_b128 v[196:199], v151 offset:16384
	ds_read_b128 v[200:203], v151 offset:17408
	ds_read_b128 v[204:207], v150 offset:16384
	ds_read_b128 v[208:211], v150 offset:17408
	ds_read_b128 v[212:215], v149 offset:16384
	ds_read_b128 v[232:235], v149 offset:17408
	s_barrier
	s_waitcnt lgkmcnt(0)
	s_waitcnt lgkmcnt(0)
	v_mfma_f32_16x16x32_bf16 v[60:63], v[172:175], v[188:191], v[60:63]
	v_mfma_f32_16x16x32_bf16 v[56:59], v[180:183], v[188:191], v[56:59]
	v_mfma_f32_16x16x32_bf16 v[52:55], v[172:175], v[196:199], v[52:55]
	v_mfma_f32_16x16x32_bf16 v[48:51], v[180:183], v[196:199], v[48:51]
	v_mfma_f32_16x16x32_bf16 v[44:47], v[172:175], v[204:207], v[44:47]
	v_mfma_f32_16x16x32_bf16 v[40:43], v[180:183], v[204:207], v[40:43]
	v_mfma_f32_16x16x32_bf16 v[36:39], v[172:175], v[212:215], v[36:39]
	v_mfma_f32_16x16x32_bf16 v[32:35], v[180:183], v[212:215], v[32:35]
	v_mfma_f32_16x16x32_bf16 v[60:63], v[176:179], v[192:195], v[60:63]
	v_mfma_f32_16x16x32_bf16 v[56:59], v[184:187], v[192:195], v[56:59]
	v_mfma_f32_16x16x32_bf16 v[52:55], v[176:179], v[200:203], v[52:55]
	v_mfma_f32_16x16x32_bf16 v[48:51], v[184:187], v[200:203], v[48:51]
	v_mfma_f32_16x16x32_bf16 v[44:47], v[176:179], v[208:211], v[44:47]
	v_mfma_f32_16x16x32_bf16 v[40:43], v[184:187], v[208:211], v[40:43]
	v_mfma_f32_16x16x32_bf16 v[36:39], v[176:179], v[232:235], v[36:39]
	v_mfma_f32_16x16x32_bf16 v[32:35], v[184:187], v[232:235], v[32:35]
	s_barrier
; #define STAGE(P, BASE, LD, br, kt) do { const char* _g = (const char*)((BASE) + (size_t)(br) * (LD) + (size_t)(kt) * 64); \
;     for (int _i = 0; _i < 2; ++_i) { int _b = tidx * 16 + _i * 8192; int _r, _c; stage_rc(_b, _r, _c); \
;       __builtin_amdgcn_global_load_lds((const unsigned*)(_g + (unsigned)((_r * (LD) + _c) * 2)), (unsigned*)((char*)(P) + _b), 16, 0, 0); } } while (0)
; #define LDA(dst, b, h) for (int m = 0; m < 4; ++m) for (int k = 0; k < 2; ++k) \
;     dst[m][k] = *reinterpret_cast<const bf16x8*>((char*)SA(b, h) + lds_byte(wr * 64 + m * 16 + fr, k * 32 + fq * 8))
; #define LDB(dst, b, h) for (int n = 0; n < 2; ++n) for (int k = 0; k < 2; ++k) \
;     dst[n][k] = *reinterpret_cast<const bf16x8*>((char*)SB(b, h) + lds_byte(wc * 32 + n * 16 + fr, k * 32 + fq * 8))
; #define MMA(ai, bj, At_, Bt_) do { __builtin_amdgcn_s_setprio(1); \
;     for (int k = 0; k < 2; ++k) for (int m = 0; m < 4; ++m) for (int n = 0; n < 2; ++n) \
;       acc[ai][bj][m][n] = __builtin_amdgcn_mfma_f32_16x16x32_bf16(At_[m][k], Bt_[n][k], acc[ai][bj][m][n], 0, 0, 0); \
;     __builtin_amdgcn_s_setprio(0); } while (0)
; #define WAIT_V(n) asm volatile("s_waitcnt vmcnt(" #n ")" ::: "memory")
; #define WAIT_L(n) asm volatile("s_waitcnt lgkmcnt(" #n ")" ::: "memory")
; #define BAR __builtin_amdgcn_s_barrier()
; #define SCHED __builtin_amdgcn_sched_barrier(0)
; template <int EPI, int lda, int ldb, int N, int K>
; __device__ __forceinline__ void gemm_phase(const u16* __restrict__ A, const u16* __restrict__ Bt, const GemmEpi ep, int wv) {
;     ...
;       STAGE(SB(0, 1), Bt, ldb, bcol + HALF, t + 2);
;       WAIT_V(6); BAR; MMA(1, 1, At, B1); BAR;
;       LDB(B0, 1, 0); SCHED; LDA(At, 1, 0); STAGE(SA(0, 1), Ab, lda, brow + HALF, t + 2);
;       WAIT_L(8); BAR; WAIT_L(0); MMA(0, 0, At, B0); BAR; SCHED;
;       LDB(B1, 1, 1); STAGE(SB(1, 0), Bt, ldb, bcol, t + 3);
;       BAR; WAIT_L(0); MMA(0, 1, At, B1); BAR;
;       LDA(At, 1, 1); STAGE(SA(1, 0), Ab, lda, brow, t + 3);
	v_add_u32_e32 v165, s53, v153
	v_lshl_add_u64 v[166:167], v[240:241], 0, s[20:21]
	v_readfirstlane_b32 s43, v165
	s_mov_b32 m0, s43
	v_lshl_add_u64 v[172:173], v[242:243], 0, s[20:21]
	global_load_lds_dwordx4 v[166:167], off
	v_add_u32_e32 v166, 0x2000, v165
	s_nop 0
	v_readfirstlane_b32 s43, v166
	s_mov_b32 m0, s43
	s_nop 0
	global_load_lds_dwordx4 v[172:173], off
	s_waitcnt vmcnt(6)
	s_barrier
	v_mfma_f32_16x16x32_bf16 v[28:31], v[216:219], v[188:191], v[28:31]
	v_mfma_f32_16x16x32_bf16 v[24:27], v[224:227], v[188:191], v[24:27]
	v_mfma_f32_16x16x32_bf16 v[20:23], v[216:219], v[196:199], v[20:23]
	v_mfma_f32_16x16x32_bf16 v[16:19], v[224:227], v[196:199], v[16:19]
	v_mfma_f32_16x16x32_bf16 v[12:15], v[216:219], v[204:207], v[12:15]
	v_mfma_f32_16x16x32_bf16 v[8:11], v[224:227], v[204:207], v[8:11]
	v_mfma_f32_16x16x32_bf16 v[4:7], v[216:219], v[212:215], v[4:7]
	v_mfma_f32_16x16x32_bf16 v[0:3], v[224:227], v[212:215], v[0:3]
	v_mfma_f32_16x16x32_bf16 v[28:31], v[220:223], v[192:195], v[28:31]
	v_mfma_f32_16x16x32_bf16 v[24:27], v[228:231], v[192:195], v[24:27]
	v_mfma_f32_16x16x32_bf16 v[20:23], v[220:223], v[200:203], v[20:23]
	v_mfma_f32_16x16x32_bf16 v[16:19], v[228:231], v[200:203], v[16:19]
	v_mfma_f32_16x16x32_bf16 v[12:15], v[220:223], v[208:211], v[12:15]
	v_mfma_f32_16x16x32_bf16 v[8:11], v[228:231], v[208:211], v[8:11]
	v_mfma_f32_16x16x32_bf16 v[4:7], v[220:223], v[232:235], v[4:7]
	v_mfma_f32_16x16x32_bf16 v[0:3], v[228:231], v[232:235], v[0:3]
	s_barrier
	ds_read_b128 v[172:175], v156
	ds_read_b128 v[176:179], v156 offset:1024
	ds_read_b128 v[180:183], v156 offset:2048
	ds_read_b128 v[184:187], v156 offset:3072
	v_add_u32_e32 v167, 0x4000, v148
	v_add_u32_e32 v168, 0x6000, v148
	v_readfirstlane_b32 s43, v167
	v_lshl_add_u64 v[220:221], v[236:237], 0, s[22:23]
	s_mov_b32 m0, s43
	v_readfirstlane_b32 s43, v168
	global_load_lds_dwordx4 v[220:221], off
	v_lshl_add_u64 v[220:221], v[238:239], 0, s[22:23]
	s_mov_b32 m0, s43
	s_nop 0
	global_load_lds_dwordx4 v[220:221], off
	ds_read_b128 v[188:191], v152 offset:32768
	ds_read_b128 v[192:195], v152 offset:33792
	ds_read_b128 v[196:199], v151 offset:32768
	ds_read_b128 v[200:203], v151 offset:33792
	ds_read_b128 v[204:207], v150 offset:32768
	ds_read_b128 v[208:211], v150 offset:33792
	ds_read_b128 v[212:215], v149 offset:32768
	ds_read_b128 v[216:219], v149 offset:33792
	s_waitcnt lgkmcnt(8)
	s_barrier
	s_waitcnt lgkmcnt(0)
	s_waitcnt lgkmcnt(0)
	v_mfma_f32_16x16x32_bf16 v[124:127], v[172:175], v[188:191], v[124:127]
	v_mfma_f32_16x16x32_bf16 v[120:123], v[180:183], v[188:191], v[120:123]
	v_mfma_f32_16x16x32_bf16 v[116:119], v[172:175], v[196:199], v[116:119]
	v_mfma_f32_16x16x32_bf16 v[112:115], v[180:183], v[196:199], v[112:115]
	v_mfma_f32_16x16x32_bf16 v[108:111], v[172:175], v[204:207], v[108:111]
	v_mfma_f32_16x16x32_bf16 v[104:107], v[180:183], v[204:207], v[104:107]
	v_mfma_f32_16x16x32_bf16 v[100:103], v[172:175], v[212:215], v[100:103]
	v_mfma_f32_16x16x32_bf16 v[96:99], v[180:183], v[212:215], v[96:99]
	v_mfma_f32_16x16x32_bf16 v[124:127], v[176:179], v[192:195], v[124:127]
	v_mfma_f32_16x16x32_bf16 v[120:123], v[184:187], v[192:195], v[120:123]
	v_mfma_f32_16x16x32_bf16 v[116:119], v[176:179], v[200:203], v[116:119]
	v_mfma_f32_16x16x32_bf16 v[112:115], v[184:187], v[200:203], v[112:115]
	v_mfma_f32_16x16x32_bf16 v[108:111], v[176:179], v[208:211], v[108:111]
	v_mfma_f32_16x16x32_bf16 v[104:107], v[184:187], v[208:211], v[104:107]
	v_mfma_f32_16x16x32_bf16 v[100:103], v[176:179], v[216:219], v[100:103]
	v_mfma_f32_16x16x32_bf16 v[96:99], v[184:187], v[216:219], v[96:99]
	s_barrier
	v_readfirstlane_b32 s43, v155
	v_add_u32_e32 v171, 0x2000, v155
	v_lshl_add_u64 v[244:245], v[240:241], 0, s[24:25]
	s_mov_b32 m0, s43
	v_readfirstlane_b32 s43, v171
	global_load_lds_dwordx4 v[244:245], off
	v_lshl_add_u64 v[244:245], v[242:243], 0, s[24:25]
	s_mov_b32 m0, s43
	s_nop 0
	global_load_lds_dwordx4 v[244:245], off
	ds_read_b128 v[220:223], v154
	ds_read_b128 v[224:227], v154 offset:1024
	ds_read_b128 v[228:231], v154 offset:2048
	ds_read_b128 v[232:235], v154 offset:3072
	s_barrier
	s_waitcnt lgkmcnt(0)
	s_waitcnt lgkmcnt(0)
	v_mfma_f32_16x16x32_bf16 v[92:95], v[220:223], v[188:191], v[92:95]
	v_mfma_f32_16x16x32_bf16 v[88:91], v[228:231], v[188:191], v[88:91]
	v_mfma_f32_16x16x32_bf16 v[84:87], v[220:223], v[196:199], v[84:87]
	v_mfma_f32_16x16x32_bf16 v[80:83], v[228:231], v[196:199], v[80:83]
	v_mfma_f32_16x16x32_bf16 v[76:79], v[220:223], v[204:207], v[76:79]
	v_mfma_f32_16x16x32_bf16 v[72:75], v[228:231], v[204:207], v[72:75]
	v_mfma_f32_16x16x32_bf16 v[68:71], v[220:223], v[212:215], v[68:71]
	v_mfma_f32_16x16x32_bf16 v[64:67], v[228:231], v[212:215], v[64:67]
	v_mfma_f32_16x16x32_bf16 v[92:95], v[224:227], v[192:195], v[92:95]
	v_mfma_f32_16x16x32_bf16 v[88:91], v[232:235], v[192:195], v[88:91]
	v_mfma_f32_16x16x32_bf16 v[84:87], v[224:227], v[200:203], v[84:87]
	v_mfma_f32_16x16x32_bf16 v[80:83], v[232:235], v[200:203], v[80:83]
	v_mfma_f32_16x16x32_bf16 v[76:79], v[224:227], v[208:211], v[76:79]
	v_mfma_f32_16x16x32_bf16 v[72:75], v[232:235], v[208:211], v[72:75]
	v_mfma_f32_16x16x32_bf16 v[68:71], v[224:227], v[216:219], v[68:71]
	v_mfma_f32_16x16x32_bf16 v[64:67], v[232:235], v[216:219], v[64:67]
	v_readfirstlane_b32 s43, v157
	v_lshl_add_u64 v[236:237], v[236:237], 0, s[26:27]
	s_mov_b32 m0, s43
	v_readfirstlane_b32 s43, v158
	s_barrier
; #define STAGE(P, BASE, LD, br, kt) do { const char* _g = (const char*)((BASE) + (size_t)(br) * (LD) + (size_t)(kt) * 64); \
;     for (int _i = 0; _i < 2; ++_i) { int _b = tidx * 16 + _i * 8192; int _r, _c; stage_rc(_b, _r, _c); \
;       __builtin_amdgcn_global_load_lds((const unsigned*)(_g + (unsigned)((_r * (LD) + _c) * 2)), (unsigned*)((char*)(P) + _b), 16, 0, 0); } } while (0)
; #define LDA(dst, b, h) for (int m = 0; m < 4; ++m) for (int k = 0; k < 2; ++k) \
;     dst[m][k] = *reinterpret_cast<const bf16x8*>((char*)SA(b, h) + lds_byte(wr * 64 + m * 16 + fr, k * 32 + fq * 8))
; #define LDB(dst, b, h) for (int n = 0; n < 2; ++n) for (int k = 0; k < 2; ++k) \
;     dst[n][k] = *reinterpret_cast<const bf16x8*>((char*)SB(b, h) + lds_byte(wc * 32 + n * 16 + fr, k * 32 + fq * 8))
; #define MMA(ai, bj, At_, Bt_) do { __builtin_amdgcn_s_setprio(1); \
;     for (int k = 0; k < 2; ++k) for (int m = 0; m < 4; ++m) for (int n = 0; n < 2; ++n) \
;       acc[ai][bj][m][n] = __builtin_amdgcn_mfma_f32_16x16x32_bf16(At_[m][k], Bt_[n][k], acc[ai][bj][m][n], 0, 0, 0); \
;     __builtin_amdgcn_s_setprio(0); } while (0)
; #define WAIT_V(n) asm volatile("s_waitcnt vmcnt(" #n ")" ::: "memory")
; #define WAIT_L(n) asm volatile("s_waitcnt lgkmcnt(" #n ")" ::: "memory")
; #define BAR __builtin_amdgcn_s_barrier()
; #define SCHED __builtin_amdgcn_sched_barrier(0)
; template <int EPI, int lda, int ldb, int N, int K>
; __device__ __forceinline__ void gemm_phase(const u16* __restrict__ A, const u16* __restrict__ Bt, const GemmEpi ep, int wv) {
;     ...
;       LDA(At, 1, 1); STAGE(SA(1, 0), Ab, lda, brow, t + 3);
;       BAR; WAIT_L(0); MMA(1, 0, At, B0); BAR; SCHED;
;       STAGE(SB(1, 1), Bt, ldb, bcol + HALF, t + 3);
;       WAIT_V(6); BAR; MMA(1, 1, At, B1); BAR;
;     }
;     { LDB(B0, 0, 0); LDA(At, 0, 0); STAGE(SA(1, 1), Ab, lda, brow + HALF, nt - 1);
;       BAR; WAIT_L(0); MMA(0, 0, At, B0); BAR;
	global_load_lds_dwordx4 v[236:237], off
	v_lshl_add_u64 v[236:237], v[238:239], 0, s[26:27]
	s_mov_b32 m0, s43
	s_nop 0
	global_load_lds_dwordx4 v[236:237], off
	ds_read_b128 v[188:191], v152 offset:49152
	ds_read_b128 v[192:195], v152 offset:50176
	ds_read_b128 v[196:199], v151 offset:49152
	ds_read_b128 v[200:203], v151 offset:50176
	ds_read_b128 v[204:207], v150 offset:49152
	ds_read_b128 v[208:211], v150 offset:50176
	ds_read_b128 v[212:215], v149 offset:49152
	ds_read_b128 v[216:219], v149 offset:50176
	s_barrier
	s_waitcnt lgkmcnt(0)
	s_waitcnt lgkmcnt(0)
	v_mfma_f32_16x16x32_bf16 v[60:63], v[172:175], v[188:191], v[60:63]
	v_mfma_f32_16x16x32_bf16 v[56:59], v[180:183], v[188:191], v[56:59]
	v_mfma_f32_16x16x32_bf16 v[52:55], v[172:175], v[196:199], v[52:55]
	v_mfma_f32_16x16x32_bf16 v[48:51], v[180:183], v[196:199], v[48:51]
	v_mfma_f32_16x16x32_bf16 v[44:47], v[172:175], v[204:207], v[44:47]
	v_mfma_f32_16x16x32_bf16 v[40:43], v[180:183], v[204:207], v[40:43]
	v_mfma_f32_16x16x32_bf16 v[36:39], v[172:175], v[212:215], v[36:39]
	v_mfma_f32_16x16x32_bf16 v[32:35], v[180:183], v[212:215], v[32:35]
	v_mfma_f32_16x16x32_bf16 v[60:63], v[176:179], v[192:195], v[60:63]
	v_mfma_f32_16x16x32_bf16 v[56:59], v[184:187], v[192:195], v[56:59]
	v_mfma_f32_16x16x32_bf16 v[52:55], v[176:179], v[200:203], v[52:55]
	v_mfma_f32_16x16x32_bf16 v[48:51], v[184:187], v[200:203], v[48:51]
	v_mfma_f32_16x16x32_bf16 v[44:47], v[176:179], v[208:211], v[44:47]
	v_mfma_f32_16x16x32_bf16 v[40:43], v[184:187], v[208:211], v[40:43]
	v_mfma_f32_16x16x32_bf16 v[36:39], v[176:179], v[216:219], v[36:39]
	v_mfma_f32_16x16x32_bf16 v[32:35], v[184:187], v[216:219], v[32:35]
	s_barrier
	v_readfirstlane_b32 s43, v159
	v_add_u32_e32 v171, 0x2000, v159
	v_lshl_add_u64 v[172:173], v[240:241], 0, s[34:35]
	s_mov_b32 m0, s43
	v_readfirstlane_b32 s43, v171
	global_load_lds_dwordx4 v[172:173], off
	v_lshl_add_u64 v[172:173], v[242:243], 0, s[34:35]
	s_mov_b32 m0, s43
	s_nop 0
	global_load_lds_dwordx4 v[172:173], off
	s_waitcnt vmcnt(6)
	s_barrier
	v_mfma_f32_16x16x32_bf16 v[28:31], v[220:223], v[188:191], v[28:31]
	v_mfma_f32_16x16x32_bf16 v[24:27], v[228:231], v[188:191], v[24:27]
	v_mfma_f32_16x16x32_bf16 v[20:23], v[220:223], v[196:199], v[20:23]
	v_mfma_f32_16x16x32_bf16 v[16:19], v[228:231], v[196:199], v[16:19]
	v_mfma_f32_16x16x32_bf16 v[12:15], v[220:223], v[204:207], v[12:15]
	v_mfma_f32_16x16x32_bf16 v[8:11], v[228:231], v[204:207], v[8:11]
	v_mfma_f32_16x16x32_bf16 v[4:7], v[220:223], v[212:215], v[4:7]
	v_mfma_f32_16x16x32_bf16 v[0:3], v[228:231], v[212:215], v[0:3]
	v_mfma_f32_16x16x32_bf16 v[28:31], v[224:227], v[192:195], v[28:31]
	v_mfma_f32_16x16x32_bf16 v[24:27], v[232:235], v[192:195], v[24:27]
	v_mfma_f32_16x16x32_bf16 v[20:23], v[224:227], v[200:203], v[20:23]
	v_mfma_f32_16x16x32_bf16 v[16:19], v[232:235], v[200:203], v[16:19]
	v_mfma_f32_16x16x32_bf16 v[12:15], v[224:227], v[208:211], v[12:15]
	v_mfma_f32_16x16x32_bf16 v[8:11], v[232:235], v[208:211], v[8:11]
	v_mfma_f32_16x16x32_bf16 v[4:7], v[224:227], v[216:219], v[4:7]
	v_mfma_f32_16x16x32_bf16 v[0:3], v[232:235], v[216:219], v[0:3]
	s_add_i32 s42, s42, 2
	s_add_u32 s40, s40, 0x100
	s_addc_u32 s41, s41, 0
	s_cmp_gt_u32 s42, 27
	s_barrier
	s_cbranch_scc0 .LBB0_1564
	s_add_i32 s40, s38, 0x80
	s_mul_hi_i32 s41, s40, 0x1080
	s_mulk_i32 s40, 0x1080
	s_add_u32 s40, s49, s40
	s_addc_u32 s41, s50, s41
	v_lshl_add_u64 v[158:159], s[40:41], 0, v[128:129]
	v_readfirstlane_b32 s42, v169
	v_lshl_add_u64 v[158:159], v[158:159], 0, s[36:37]
	s_mov_b32 m0, s42
	ds_read_b128 v[134:137], v161
	ds_read_b128 v[138:141], v161 offset:1024
	ds_read_b128 v[172:175], v161 offset:2048
	ds_read_b128 v[176:179], v161 offset:3072
	ds_read_b128 v[180:183], v152
	ds_read_b128 v[184:187], v152 offset:1024
	ds_read_b128 v[188:191], v151
	ds_read_b128 v[192:195], v151 offset:1024
	ds_read_b128 v[196:199], v150
	ds_read_b128 v[200:203], v150 offset:1024
	ds_read_b128 v[204:207], v149
	ds_read_b128 v[208:211], v149 offset:1024
	global_load_lds_dwordx4 v[158:159], off
	v_lshl_add_u64 v[158:159], s[40:41], 0, v[132:133]
	v_readfirstlane_b32 s40, v170
	v_lshl_add_u64 v[158:159], v[158:159], 0, s[36:37]
	s_mov_b32 m0, s40
	s_nop 0
	global_load_lds_dwordx4 v[158:159], off
	s_barrier
	s_waitcnt lgkmcnt(0)
	s_waitcnt lgkmcnt(0)
	v_mfma_f32_16x16x32_bf16 v[124:127], v[134:137], v[180:183], v[124:127]
	v_mfma_f32_16x16x32_bf16 v[120:123], v[172:175], v[180:183], v[120:123]
	v_mfma_f32_16x16x32_bf16 v[116:119], v[134:137], v[188:191], v[116:119]
	v_mfma_f32_16x16x32_bf16 v[112:115], v[172:175], v[188:191], v[112:115]
	v_mfma_f32_16x16x32_bf16 v[108:111], v[134:137], v[196:199], v[108:111]
	v_mfma_f32_16x16x32_bf16 v[104:107], v[172:175], v[196:199], v[104:107]
	v_mfma_f32_16x16x32_bf16 v[100:103], v[134:137], v[204:207], v[100:103]
	v_mfma_f32_16x16x32_bf16 v[96:99], v[172:175], v[204:207], v[96:99]
	v_mfma_f32_16x16x32_bf16 v[124:127], v[138:141], v[184:187], v[124:127]
	v_mfma_f32_16x16x32_bf16 v[120:123], v[176:179], v[184:187], v[120:123]
	v_mfma_f32_16x16x32_bf16 v[116:119], v[138:141], v[192:195], v[116:119]
	v_mfma_f32_16x16x32_bf16 v[112:115], v[176:179], v[192:195], v[112:115]
	v_mfma_f32_16x16x32_bf16 v[108:111], v[138:141], v[200:203], v[108:111]
	v_mfma_f32_16x16x32_bf16 v[104:107], v[176:179], v[200:203], v[104:107]
	v_mfma_f32_16x16x32_bf16 v[100:103], v[138:141], v[208:211], v[100:103]
	v_mfma_f32_16x16x32_bf16 v[96:99], v[176:179], v[208:211], v[96:99]
	s_barrier
	ds_read_b128 v[212:215], v160
	ds_read_b128 v[216:219], v160 offset:1024
	ds_read_b128 v[220:223], v160 offset:2048
	ds_read_b128 v[158:161], v160 offset:3072
	s_barrier
; #define LDA(dst, b, h) for (int m = 0; m < 4; ++m) for (int k = 0; k < 2; ++k) \
;     dst[m][k] = *reinterpret_cast<const bf16x8*>((char*)SA(b, h) + lds_byte(wr * 64 + m * 16 + fr, k * 32 + fq * 8))
; #define LDB(dst, b, h) for (int n = 0; n < 2; ++n) for (int k = 0; k < 2; ++k) \
;     dst[n][k] = *reinterpret_cast<const bf16x8*>((char*)SB(b, h) + lds_byte(wc * 32 + n * 16 + fr, k * 32 + fq * 8))
; #define MMA(ai, bj, At_, Bt_) do { __builtin_amdgcn_s_setprio(1); \
;     for (int k = 0; k < 2; ++k) for (int m = 0; m < 4; ++m) for (int n = 0; n < 2; ++n) \
;       acc[ai][bj][m][n] = __builtin_amdgcn_mfma_f32_16x16x32_bf16(At_[m][k], Bt_[n][k], acc[ai][bj][m][n], 0, 0, 0); \
;     __builtin_amdgcn_s_setprio(0); } while (0)
; #define WAIT_V(n) asm volatile("s_waitcnt vmcnt(" #n ")" ::: "memory")
; #define WAIT_L(n) asm volatile("s_waitcnt lgkmcnt(" #n ")" ::: "memory")
; #define BAR __builtin_amdgcn_s_barrier()
; template <int EPI, int lda, int ldb, int N, int K>
; __device__ __forceinline__ void gemm_phase(const u16* __restrict__ A, const u16* __restrict__ Bt, const GemmEpi ep, int wv) {
;     ...
;       BAR; WAIT_L(0); MMA(0, 0, At, B0); BAR;
;       LDB(B1, 0, 1); BAR; WAIT_L(0); MMA(0, 1, At, B1); BAR;
;       LDA(At, 0, 1); WAIT_V(4); BAR; WAIT_L(0); MMA(1, 0, At, B0); MMA(1, 1, At, B1); BAR; }
;     { LDB(B0, 1, 0); LDA(At, 1, 0); WAIT_V(2); BAR; WAIT_L(0); MMA(0, 0, At, B0); BAR;
	s_waitcnt lgkmcnt(0)
	s_waitcnt lgkmcnt(0)
	v_mfma_f32_16x16x32_bf16 v[92:95], v[212:215], v[180:183], v[92:95]
	v_mfma_f32_16x16x32_bf16 v[88:91], v[220:223], v[180:183], v[88:91]
	v_mfma_f32_16x16x32_bf16 v[76:79], v[212:215], v[196:199], v[76:79]
	v_mfma_f32_16x16x32_bf16 v[72:75], v[220:223], v[196:199], v[72:75]
	v_mfma_f32_16x16x32_bf16 v[84:87], v[212:215], v[188:191], v[84:87]
	v_mfma_f32_16x16x32_bf16 v[80:83], v[220:223], v[188:191], v[80:83]
	v_mfma_f32_16x16x32_bf16 v[68:71], v[212:215], v[204:207], v[68:71]
	v_mfma_f32_16x16x32_bf16 v[64:67], v[220:223], v[204:207], v[64:67]
	v_mfma_f32_16x16x32_bf16 v[92:95], v[216:219], v[184:187], v[92:95]
	v_mfma_f32_16x16x32_bf16 v[88:91], v[158:161], v[184:187], v[88:91]
	v_mfma_f32_16x16x32_bf16 v[76:79], v[216:219], v[200:203], v[76:79]
	v_mfma_f32_16x16x32_bf16 v[72:75], v[158:161], v[200:203], v[72:75]
	v_mfma_f32_16x16x32_bf16 v[180:183], v[216:219], v[192:195], v[84:87]
	v_mfma_f32_16x16x32_bf16 v[184:187], v[158:161], v[192:195], v[80:83]
	v_mfma_f32_16x16x32_bf16 v[188:191], v[216:219], v[208:211], v[68:71]
	v_mfma_f32_16x16x32_bf16 v[192:195], v[158:161], v[208:211], v[64:67]
	s_barrier
	s_nop 0
	ds_read_b128 v[64:67], v152 offset:16384
	ds_read_b128 v[68:71], v152 offset:17408
	ds_read_b128 v[80:83], v151 offset:16384
	ds_read_b128 v[84:87], v151 offset:17408
	ds_read_b128 v[196:199], v150 offset:16384
	ds_read_b128 v[200:203], v150 offset:17408
	ds_read_b128 v[204:207], v149 offset:16384
	ds_read_b128 v[208:211], v149 offset:17408
	s_waitcnt vmcnt(4)
	s_barrier
	s_waitcnt lgkmcnt(0)
	s_waitcnt lgkmcnt(0)
	v_mfma_f32_16x16x32_bf16 v[60:63], v[134:137], v[64:67], v[60:63]
	v_mfma_f32_16x16x32_bf16 v[56:59], v[172:175], v[64:67], v[56:59]
	v_mfma_f32_16x16x32_bf16 v[52:55], v[134:137], v[80:83], v[52:55]
	v_mfma_f32_16x16x32_bf16 v[48:51], v[172:175], v[80:83], v[48:51]
	v_mfma_f32_16x16x32_bf16 v[44:47], v[134:137], v[196:199], v[44:47]
	v_mfma_f32_16x16x32_bf16 v[40:43], v[172:175], v[196:199], v[40:43]
	v_mfma_f32_16x16x32_bf16 v[36:39], v[134:137], v[204:207], v[36:39]
	v_mfma_f32_16x16x32_bf16 v[32:35], v[172:175], v[204:207], v[32:35]
	v_mfma_f32_16x16x32_bf16 v[60:63], v[138:141], v[68:71], v[60:63]
	v_mfma_f32_16x16x32_bf16 v[56:59], v[176:179], v[68:71], v[56:59]
	v_mfma_f32_16x16x32_bf16 v[52:55], v[138:141], v[84:87], v[52:55]
	v_mfma_f32_16x16x32_bf16 v[48:51], v[176:179], v[84:87], v[48:51]
	v_mfma_f32_16x16x32_bf16 v[44:47], v[138:141], v[200:203], v[44:47]
	v_mfma_f32_16x16x32_bf16 v[40:43], v[176:179], v[200:203], v[40:43]
	v_mfma_f32_16x16x32_bf16 v[36:39], v[138:141], v[208:211], v[36:39]
	v_mfma_f32_16x16x32_bf16 v[32:35], v[176:179], v[208:211], v[32:35]
	v_mfma_f32_16x16x32_bf16 v[28:31], v[212:215], v[64:67], v[28:31]
	v_mfma_f32_16x16x32_bf16 v[24:27], v[220:223], v[64:67], v[24:27]
	v_mfma_f32_16x16x32_bf16 v[12:15], v[212:215], v[196:199], v[12:15]
	v_mfma_f32_16x16x32_bf16 v[8:11], v[220:223], v[196:199], v[8:11]
	v_mfma_f32_16x16x32_bf16 v[20:23], v[212:215], v[80:83], v[20:23]
	v_mfma_f32_16x16x32_bf16 v[16:19], v[220:223], v[80:83], v[16:19]
	v_mfma_f32_16x16x32_bf16 v[4:7], v[212:215], v[204:207], v[4:7]
	v_mfma_f32_16x16x32_bf16 v[0:3], v[220:223], v[204:207], v[0:3]
	v_mfma_f32_16x16x32_bf16 v[28:31], v[216:219], v[68:71], v[28:31]
	v_mfma_f32_16x16x32_bf16 v[24:27], v[158:161], v[68:71], v[24:27]
	v_mfma_f32_16x16x32_bf16 v[12:15], v[216:219], v[200:203], v[12:15]
	v_mfma_f32_16x16x32_bf16 v[8:11], v[158:161], v[200:203], v[8:11]
	v_mfma_f32_16x16x32_bf16 v[134:137], v[216:219], v[84:87], v[20:23]
	v_mfma_f32_16x16x32_bf16 v[138:141], v[158:161], v[84:87], v[16:19]
	v_mfma_f32_16x16x32_bf16 v[170:173], v[216:219], v[208:211], v[4:7]
	v_mfma_f32_16x16x32_bf16 v[158:161], v[158:161], v[208:211], v[0:3]
	s_barrier
	s_nop 0
	ds_read_b128 v[0:3], v156
	ds_read_b128 v[4:7], v156 offset:1024
	ds_read_b128 v[16:19], v156 offset:2048
	ds_read_b128 v[174:177], v156 offset:3072
	ds_read_b128 v[20:23], v152 offset:32768
	ds_read_b128 v[196:199], v152 offset:33792
	ds_read_b128 v[200:203], v151 offset:32768
	ds_read_b128 v[204:207], v151 offset:33792
	ds_read_b128 v[208:211], v150 offset:32768
	ds_read_b128 v[212:215], v150 offset:33792
	ds_read_b128 v[216:219], v149 offset:32768
	ds_read_b128 v[220:223], v149 offset:33792
	s_waitcnt vmcnt(2)
	s_barrier
; #define LDA(dst, b, h) for (int m = 0; m < 4; ++m) for (int k = 0; k < 2; ++k) \
;     dst[m][k] = *reinterpret_cast<const bf16x8*>((char*)SA(b, h) + lds_byte(wr * 64 + m * 16 + fr, k * 32 + fq * 8))
; #define LDB(dst, b, h) for (int n = 0; n < 2; ++n) for (int k = 0; k < 2; ++k) \
;     dst[n][k] = *reinterpret_cast<const bf16x8*>((char*)SB(b, h) + lds_byte(wc * 32 + n * 16 + fr, k * 32 + fq * 8))
; #define MMA(ai, bj, At_, Bt_) do { __builtin_amdgcn_s_setprio(1); \
;     for (int k = 0; k < 2; ++k) for (int m = 0; m < 4; ++m) for (int n = 0; n < 2; ++n) \
;       acc[ai][bj][m][n] = __builtin_amdgcn_mfma_f32_16x16x32_bf16(At_[m][k], Bt_[n][k], acc[ai][bj][m][n], 0, 0, 0); \
;     __builtin_amdgcn_s_setprio(0); } while (0)
; #define WAIT_V(n) asm volatile("s_waitcnt vmcnt(" #n ")" ::: "memory")
; #define WAIT_L(n) asm volatile("s_waitcnt lgkmcnt(" #n ")" ::: "memory")
; #define BAR __builtin_amdgcn_s_barrier()
; template <int EPI, int lda, int ldb, int N, int K>
; __device__ __forceinline__ void gemm_phase(const u16* __restrict__ A, const u16* __restrict__ Bt, const GemmEpi ep, int wv) {
;     ...
;     { LDB(B0, 1, 0); LDA(At, 1, 0); WAIT_V(2); BAR; WAIT_L(0); MMA(0, 0, At, B0); BAR;
;       LDB(B1, 1, 1); WAIT_V(0); BAR; WAIT_L(0); MMA(0, 1, At, B1); BAR;
;       LDA(At, 1, 1); BAR; WAIT_L(0); MMA(1, 0, At, B0); MMA(1, 1, At, B1); BAR; }
;     if (wr == 0) BAR;
	s_waitcnt lgkmcnt(0)
	s_waitcnt lgkmcnt(0)
	v_mfma_f32_16x16x32_bf16 v[64:67], v[0:3], v[20:23], v[124:127]
	v_mfma_f32_16x16x32_bf16 v[68:71], v[16:19], v[20:23], v[120:123]
	v_mfma_f32_16x16x32_bf16 v[80:83], v[0:3], v[200:203], v[116:119]
	v_mfma_f32_16x16x32_bf16 v[84:87], v[16:19], v[200:203], v[112:115]
	v_mfma_f32_16x16x32_bf16 v[108:111], v[0:3], v[208:211], v[108:111]
	v_mfma_f32_16x16x32_bf16 v[104:107], v[16:19], v[208:211], v[104:107]
	v_mfma_f32_16x16x32_bf16 v[120:123], v[0:3], v[216:219], v[100:103]
	v_mfma_f32_16x16x32_bf16 v[124:127], v[16:19], v[216:219], v[96:99]
	v_mfma_f32_16x16x32_bf16 v[116:119], v[4:7], v[196:199], v[64:67]
	v_mfma_f32_16x16x32_bf16 v[112:115], v[174:177], v[196:199], v[68:71]
	v_mfma_f32_16x16x32_bf16 v[100:103], v[4:7], v[204:207], v[80:83]
	v_mfma_f32_16x16x32_bf16 v[96:99], v[174:177], v[204:207], v[84:87]
	v_mfma_f32_16x16x32_bf16 v[84:87], v[4:7], v[212:215], v[108:111]
	v_mfma_f32_16x16x32_bf16 v[80:83], v[174:177], v[212:215], v[104:107]
	v_mfma_f32_16x16x32_bf16 v[68:71], v[4:7], v[220:223], v[120:123]
	v_mfma_f32_16x16x32_bf16 v[64:67], v[174:177], v[220:223], v[124:127]
	s_barrier
	ds_read_b128 v[224:227], v154
	ds_read_b128 v[228:231], v154 offset:1024
	ds_read_b128 v[232:235], v154 offset:2048
	ds_read_b128 v[154:157], v154 offset:3072
	s_waitcnt vmcnt(0)
	s_barrier
	s_waitcnt lgkmcnt(0)
	s_waitcnt lgkmcnt(0)
	v_mfma_f32_16x16x32_bf16 v[92:95], v[224:227], v[20:23], v[92:95]
	v_mfma_f32_16x16x32_bf16 v[20:23], v[232:235], v[20:23], v[88:91]
	v_mfma_f32_16x16x32_bf16 v[88:91], v[224:227], v[200:203], v[180:183]
	v_mfma_f32_16x16x32_bf16 v[104:107], v[232:235], v[200:203], v[184:187]
	v_mfma_f32_16x16x32_bf16 v[76:79], v[224:227], v[208:211], v[76:79]
	v_mfma_f32_16x16x32_bf16 v[72:75], v[232:235], v[208:211], v[72:75]
	v_mfma_f32_16x16x32_bf16 v[178:181], v[224:227], v[216:219], v[188:191]
	v_mfma_f32_16x16x32_bf16 v[182:185], v[232:235], v[216:219], v[192:195]
	v_mfma_f32_16x16x32_bf16 v[124:127], v[228:231], v[196:199], v[92:95]
	v_mfma_f32_16x16x32_bf16 v[120:123], v[154:157], v[196:199], v[20:23]
	v_mfma_f32_16x16x32_bf16 v[108:111], v[228:231], v[204:207], v[88:91]
	v_mfma_f32_16x16x32_bf16 v[104:107], v[154:157], v[204:207], v[104:107]
	v_mfma_f32_16x16x32_bf16 v[92:95], v[228:231], v[212:215], v[76:79]
	v_mfma_f32_16x16x32_bf16 v[88:91], v[154:157], v[212:215], v[72:75]
	v_mfma_f32_16x16x32_bf16 v[76:79], v[228:231], v[220:223], v[178:181]
	v_mfma_f32_16x16x32_bf16 v[72:75], v[154:157], v[220:223], v[182:185]
	s_barrier
	ds_read_b128 v[178:181], v152 offset:49152
	ds_read_b128 v[182:185], v152 offset:50176
	ds_read_b128 v[186:189], v151 offset:49152
	ds_read_b128 v[190:193], v151 offset:50176
	ds_read_b128 v[194:197], v150 offset:49152
	ds_read_b128 v[150:153], v150 offset:50176
	ds_read_b128 v[198:201], v149 offset:49152
	ds_read_b128 v[202:205], v149 offset:50176
	s_barrier
	s_waitcnt lgkmcnt(0)
	s_waitcnt lgkmcnt(0)
	v_mfma_f32_16x16x32_bf16 v[20:23], v[0:3], v[178:181], v[60:63]
	v_mfma_f32_16x16x32_bf16 v[56:59], v[16:19], v[178:181], v[56:59]
	v_mfma_f32_16x16x32_bf16 v[60:63], v[0:3], v[186:189], v[52:55]
	v_mfma_f32_16x16x32_bf16 v[206:209], v[16:19], v[186:189], v[48:51]
	v_mfma_f32_16x16x32_bf16 v[44:47], v[0:3], v[194:197], v[44:47]
	v_mfma_f32_16x16x32_bf16 v[40:43], v[16:19], v[194:197], v[40:43]
	v_mfma_f32_16x16x32_bf16 v[0:3], v[0:3], v[198:201], v[36:39]
	v_mfma_f32_16x16x32_bf16 v[210:213], v[16:19], v[198:201], v[32:35]
	v_mfma_f32_16x16x32_bf16 v[52:55], v[4:7], v[182:185], v[20:23]
	v_mfma_f32_16x16x32_bf16 v[48:51], v[174:177], v[182:185], v[56:59]
	v_mfma_f32_16x16x32_bf16 v[36:39], v[4:7], v[190:193], v[60:63]
	v_mfma_f32_16x16x32_bf16 v[32:35], v[174:177], v[190:193], v[206:209]
	v_mfma_f32_16x16x32_bf16 v[20:23], v[4:7], v[150:153], v[44:47]
	v_mfma_f32_16x16x32_bf16 v[16:19], v[174:177], v[150:153], v[40:43]
	v_mfma_f32_16x16x32_bf16 v[4:7], v[4:7], v[202:205], v[0:3]
	v_mfma_f32_16x16x32_bf16 v[0:3], v[174:177], v[202:205], v[210:213]
	v_mfma_f32_16x16x32_bf16 v[28:31], v[224:227], v[178:181], v[28:31]
	v_mfma_f32_16x16x32_bf16 v[24:27], v[232:235], v[178:181], v[24:27]
	v_mfma_f32_16x16x32_bf16 v[40:43], v[224:227], v[186:189], v[134:137]
	v_mfma_f32_16x16x32_bf16 v[134:137], v[232:235], v[186:189], v[138:141]
	v_mfma_f32_16x16x32_bf16 v[12:15], v[224:227], v[194:197], v[12:15]
	v_mfma_f32_16x16x32_bf16 v[8:11], v[232:235], v[194:197], v[8:11]
	v_mfma_f32_16x16x32_bf16 v[138:141], v[224:227], v[198:201], v[170:173]
	v_mfma_f32_16x16x32_bf16 v[158:161], v[232:235], v[198:201], v[158:161]
	v_mfma_f32_16x16x32_bf16 v[60:63], v[228:231], v[182:185], v[28:31]
	v_mfma_f32_16x16x32_bf16 v[56:59], v[154:157], v[182:185], v[24:27]
	v_mfma_f32_16x16x32_bf16 v[44:47], v[228:231], v[190:193], v[40:43]
	v_mfma_f32_16x16x32_bf16 v[40:43], v[154:157], v[190:193], v[134:137]
	v_mfma_f32_16x16x32_bf16 v[28:31], v[228:231], v[150:153], v[12:15]
	v_mfma_f32_16x16x32_bf16 v[24:27], v[154:157], v[150:153], v[8:11]
	v_mfma_f32_16x16x32_bf16 v[12:15], v[228:231], v[202:205], v[138:141]
	v_mfma_f32_16x16x32_bf16 v[8:11], v[154:157], v[202:205], v[158:161]
	v_cmp_gt_u32_e32 vcc, s54, v130
	s_barrier
	s_and_saveexec_b64 s[40:41], vcc
	s_cbranch_execz .LBB0_1567
	s_barrier

; #define STAGE(P, BASE, LD, br, kt) do { const char* _g = (const char*)((BASE) + (size_t)(br) * (LD) + (size_t)(kt) * 64); \
;     for (int _i = 0; _i < 2; ++_i) { int _b = tidx * 16 + _i * 8192; int _r, _c; stage_rc(_b, _r, _c); \
;       __builtin_amdgcn_global_load_lds((const unsigned*)(_g + (unsigned)((_r * (LD) + _c) * 2)), (unsigned*)((char*)(P) + _b), 16, 0, 0); } } while (0)
; #define LDA(dst, b, h) for (int m = 0; m < 4; ++m) for (int k = 0; k < 2; ++k) \
;     dst[m][k] = *reinterpret_cast<const bf16x8*>((char*)SA(b, h) + lds_byte(wr * 64 + m * 16 + fr, k * 32 + fq * 8))
; #define LDB(dst, b, h) for (int n = 0; n < 2; ++n) for (int k = 0; k < 2; ++k) \
;     dst[n][k] = *reinterpret_cast<const bf16x8*>((char*)SB(b, h) + lds_byte(wc * 32 + n * 16 + fr, k * 32 + fq * 8))
; #define MMA(ai, bj, At_, Bt_) do { __builtin_amdgcn_s_setprio(1); \
;     for (int k = 0; k < 2; ++k) for (int m = 0; m < 4; ++m) for (int n = 0; n < 2; ++n) \
;       acc[ai][bj][m][n] = __builtin_amdgcn_mfma_f32_16x16x32_bf16(At_[m][k], Bt_[n][k], acc[ai][bj][m][n], 0, 0, 0); \
;     __builtin_amdgcn_s_setprio(0); } while (0)
; #define WAIT_L(n) asm volatile("s_waitcnt lgkmcnt(" #n ")" ::: "memory")
; #define BAR __builtin_amdgcn_s_barrier()
; #define SCHED __builtin_amdgcn_sched_barrier(0)
; template <int EPI, int lda, int ldb, int N, int K>
; __device__ __forceinline__ void gemm_phase(const u16* __restrict__ A, const u16* __restrict__ Bt, const GemmEpi ep, int wv) {
;     ...
;       LDB(B0, 0, 0); SCHED; LDA(At, 0, 0); STAGE(SA(1, 1), Ab, lda, brow + HALF, t + 1);
;       WAIT_L(8); BAR; WAIT_L(0); MMA(0, 0, At, B0); BAR; SCHED;
;       LDB(B1, 0, 1); STAGE(SB(0, 0), Bt, ldb, bcol, t + 2);
;       BAR; WAIT_L(0); MMA(0, 1, At, B1); BAR;
;       LDA(At, 0, 1); STAGE(SA(0, 0), Ab, lda, brow, t + 2);
;       BAR; WAIT_L(0); MMA(1, 0, At, B0); BAR; SCHED;
;       STAGE(SB(0, 1), Bt, ldb, bcol + HALF, t + 2);
.LBB0_1624:
	ds_read_b128 v[174:177], v163
	ds_read_b128 v[178:181], v163 offset:1024
	ds_read_b128 v[182:185], v163 offset:2048
	ds_read_b128 v[186:189], v163 offset:3072
	v_add_u32_e32 v171, 0xc000, v149
	v_lshl_add_u64 v[238:239], v[134:135], 0, s[28:29]
	v_readfirstlane_b32 s50, v171
	v_add_u32_e32 v172, 0xe000, v149
	v_lshl_add_u64 v[164:165], v[238:239], 0, s[10:11]
	s_mov_b32 m0, s50
	v_lshl_add_u64 v[240:241], v[132:133], 0, s[28:29]
	v_readfirstlane_b32 s50, v172
	global_load_lds_dwordx4 v[164:165], off
	v_lshl_add_u64 v[164:165], v[240:241], 0, s[10:11]
	s_mov_b32 m0, s50
	s_nop 0
	global_load_lds_dwordx4 v[164:165], off
	ds_read_b128 v[166:169], v154
	ds_read_b128 v[190:193], v154 offset:1024
	ds_read_b128 v[194:197], v153
	ds_read_b128 v[198:201], v153 offset:1024
	ds_read_b128 v[202:205], v151
	ds_read_b128 v[206:209], v151 offset:1024
	ds_read_b128 v[210:213], v150
	ds_read_b128 v[214:217], v150 offset:1024
	s_waitcnt lgkmcnt(8)
	s_barrier
	s_waitcnt lgkmcnt(0)
	s_waitcnt lgkmcnt(0)
	v_mfma_f32_16x16x32_bf16 v[124:127], v[166:169], v[174:177], v[124:127]
	v_mfma_f32_16x16x32_bf16 v[120:123], v[166:169], v[182:185], v[120:123]
	v_mfma_f32_16x16x32_bf16 v[116:119], v[194:197], v[174:177], v[116:119]
	v_mfma_f32_16x16x32_bf16 v[112:115], v[194:197], v[182:185], v[112:115]
	v_mfma_f32_16x16x32_bf16 v[108:111], v[202:205], v[174:177], v[108:111]
	v_mfma_f32_16x16x32_bf16 v[104:107], v[202:205], v[182:185], v[104:107]
	v_mfma_f32_16x16x32_bf16 v[100:103], v[210:213], v[174:177], v[100:103]
	v_mfma_f32_16x16x32_bf16 v[96:99], v[210:213], v[182:185], v[96:99]
	v_mfma_f32_16x16x32_bf16 v[124:127], v[190:193], v[178:181], v[124:127]
	v_mfma_f32_16x16x32_bf16 v[120:123], v[190:193], v[186:189], v[120:123]
	v_mfma_f32_16x16x32_bf16 v[116:119], v[198:201], v[178:181], v[116:119]
	v_mfma_f32_16x16x32_bf16 v[112:115], v[198:201], v[186:189], v[112:115]
	v_mfma_f32_16x16x32_bf16 v[108:111], v[206:209], v[178:181], v[108:111]
	v_mfma_f32_16x16x32_bf16 v[104:107], v[206:209], v[186:189], v[104:107]
	v_mfma_f32_16x16x32_bf16 v[100:103], v[214:217], v[178:181], v[100:103]
	v_mfma_f32_16x16x32_bf16 v[96:99], v[214:217], v[186:189], v[96:99]
	s_barrier
	v_add_u32_e32 v164, s40, v155
	v_lshl_add_u64 v[242:243], v[142:143], 0, s[28:29]
	v_readfirstlane_b32 s50, v164
	v_add_u32_e32 v165, 0x2000, v164
	v_lshl_add_u64 v[234:235], v[242:243], 0, s[12:13]
	s_mov_b32 m0, s50
	v_lshl_add_u64 v[244:245], v[140:141], 0, s[28:29]
	v_readfirstlane_b32 s50, v165
	global_load_lds_dwordx4 v[234:235], off
	v_lshl_add_u64 v[234:235], v[244:245], 0, s[12:13]
	s_mov_b32 m0, s50
	s_nop 0
	global_load_lds_dwordx4 v[234:235], off
	ds_read_b128 v[218:221], v162
	ds_read_b128 v[222:225], v162 offset:1024
	ds_read_b128 v[226:229], v162 offset:2048
	ds_read_b128 v[230:233], v162 offset:3072
	s_barrier
	s_waitcnt lgkmcnt(0)
	s_waitcnt lgkmcnt(0)
	v_mfma_f32_16x16x32_bf16 v[92:95], v[166:169], v[218:221], v[92:95]
	v_mfma_f32_16x16x32_bf16 v[88:91], v[166:169], v[226:229], v[88:91]
	v_mfma_f32_16x16x32_bf16 v[84:87], v[194:197], v[218:221], v[84:87]
	v_mfma_f32_16x16x32_bf16 v[80:83], v[194:197], v[226:229], v[80:83]
	v_mfma_f32_16x16x32_bf16 v[76:79], v[202:205], v[218:221], v[76:79]
	v_mfma_f32_16x16x32_bf16 v[72:75], v[202:205], v[226:229], v[72:75]
	v_mfma_f32_16x16x32_bf16 v[68:71], v[210:213], v[218:221], v[68:71]
	v_mfma_f32_16x16x32_bf16 v[64:67], v[210:213], v[226:229], v[64:67]
	v_mfma_f32_16x16x32_bf16 v[92:95], v[190:193], v[222:225], v[92:95]
	v_mfma_f32_16x16x32_bf16 v[88:91], v[190:193], v[230:233], v[88:91]
	v_mfma_f32_16x16x32_bf16 v[84:87], v[198:201], v[222:225], v[84:87]
	v_mfma_f32_16x16x32_bf16 v[80:83], v[198:201], v[230:233], v[80:83]
	v_mfma_f32_16x16x32_bf16 v[76:79], v[206:209], v[222:225], v[76:79]
	v_mfma_f32_16x16x32_bf16 v[72:75], v[206:209], v[230:233], v[72:75]
	v_mfma_f32_16x16x32_bf16 v[68:71], v[214:217], v[222:225], v[68:71]
	v_mfma_f32_16x16x32_bf16 v[64:67], v[214:217], v[230:233], v[64:67]
	v_readfirstlane_b32 s50, v149
	v_lshl_add_u64 v[166:167], v[238:239], 0, s[14:15]
	s_mov_b32 m0, s50
	s_barrier
	global_load_lds_dwordx4 v[166:167], off
	v_add_u32_e32 v166, 0x2000, v149
	v_lshl_add_u64 v[168:169], v[240:241], 0, s[14:15]
	v_readfirstlane_b32 s50, v166
	s_mov_b32 m0, s50
	s_nop 0
	global_load_lds_dwordx4 v[168:169], off
	ds_read_b128 v[190:193], v154 offset:16384
	ds_read_b128 v[194:197], v154 offset:17408
	ds_read_b128 v[198:201], v153 offset:16384
	ds_read_b128 v[202:205], v153 offset:17408
	ds_read_b128 v[206:209], v151 offset:16384
	ds_read_b128 v[210:213], v151 offset:17408
	ds_read_b128 v[214:217], v150 offset:16384
	ds_read_b128 v[234:237], v150 offset:17408
	s_barrier
	s_waitcnt lgkmcnt(0)
	s_waitcnt lgkmcnt(0)
	v_mfma_f32_16x16x32_bf16 v[60:63], v[190:193], v[174:177], v[60:63]
	v_mfma_f32_16x16x32_bf16 v[56:59], v[190:193], v[182:185], v[56:59]
	v_mfma_f32_16x16x32_bf16 v[52:55], v[198:201], v[174:177], v[52:55]
	v_mfma_f32_16x16x32_bf16 v[48:51], v[198:201], v[182:185], v[48:51]
	v_mfma_f32_16x16x32_bf16 v[44:47], v[206:209], v[174:177], v[44:47]
	v_mfma_f32_16x16x32_bf16 v[40:43], v[206:209], v[182:185], v[40:43]
	v_mfma_f32_16x16x32_bf16 v[36:39], v[214:217], v[174:177], v[36:39]
	v_mfma_f32_16x16x32_bf16 v[32:35], v[214:217], v[182:185], v[32:35]
	v_mfma_f32_16x16x32_bf16 v[60:63], v[194:197], v[178:181], v[60:63]
	v_mfma_f32_16x16x32_bf16 v[56:59], v[194:197], v[186:189], v[56:59]
	v_mfma_f32_16x16x32_bf16 v[52:55], v[202:205], v[178:181], v[52:55]
	v_mfma_f32_16x16x32_bf16 v[48:51], v[202:205], v[186:189], v[48:51]
	v_mfma_f32_16x16x32_bf16 v[44:47], v[210:213], v[178:181], v[44:47]
	v_mfma_f32_16x16x32_bf16 v[40:43], v[210:213], v[186:189], v[40:43]
	v_mfma_f32_16x16x32_bf16 v[36:39], v[234:237], v[178:181], v[36:39]
	v_mfma_f32_16x16x32_bf16 v[32:35], v[234:237], v[186:189], v[32:35]
	s_barrier
; #define STAGE(P, BASE, LD, br, kt) do { const char* _g = (const char*)((BASE) + (size_t)(br) * (LD) + (size_t)(kt) * 64); \
;     for (int _i = 0; _i < 2; ++_i) { int _b = tidx * 16 + _i * 8192; int _r, _c; stage_rc(_b, _r, _c); \
;       __builtin_amdgcn_global_load_lds((const unsigned*)(_g + (unsigned)((_r * (LD) + _c) * 2)), (unsigned*)((char*)(P) + _b), 16, 0, 0); } } while (0)
; #define LDA(dst, b, h) for (int m = 0; m < 4; ++m) for (int k = 0; k < 2; ++k) \
;     dst[m][k] = *reinterpret_cast<const bf16x8*>((char*)SA(b, h) + lds_byte(wr * 64 + m * 16 + fr, k * 32 + fq * 8))
; #define LDB(dst, b, h) for (int n = 0; n < 2; ++n) for (int k = 0; k < 2; ++k) \
;     dst[n][k] = *reinterpret_cast<const bf16x8*>((char*)SB(b, h) + lds_byte(wc * 32 + n * 16 + fr, k * 32 + fq * 8))
; #define MMA(ai, bj, At_, Bt_) do { __builtin_amdgcn_s_setprio(1); \
;     for (int k = 0; k < 2; ++k) for (int m = 0; m < 4; ++m) for (int n = 0; n < 2; ++n) \
;       acc[ai][bj][m][n] = __builtin_amdgcn_mfma_f32_16x16x32_bf16(At_[m][k], Bt_[n][k], acc[ai][bj][m][n], 0, 0, 0); \
;     __builtin_amdgcn_s_setprio(0); } while (0)
; #define WAIT_V(n) asm volatile("s_waitcnt vmcnt(" #n ")" ::: "memory")
; #define WAIT_L(n) asm volatile("s_waitcnt lgkmcnt(" #n ")" ::: "memory")
; #define BAR __builtin_amdgcn_s_barrier()
; #define SCHED __builtin_amdgcn_sched_barrier(0)
; template <int EPI, int lda, int ldb, int N, int K>
; __device__ __forceinline__ void gemm_phase(const u16* __restrict__ A, const u16* __restrict__ Bt, const GemmEpi ep, int wv) {
;     ...
;       STAGE(SB(0, 1), Bt, ldb, bcol + HALF, t + 2);
;       WAIT_V(6); BAR; MMA(1, 1, At, B1); BAR;
;       LDB(B0, 1, 0); SCHED; LDA(At, 1, 0); STAGE(SA(0, 1), Ab, lda, brow + HALF, t + 2);
;       WAIT_L(8); BAR; WAIT_L(0); MMA(0, 0, At, B0); BAR; SCHED;
;       LDB(B1, 1, 1); STAGE(SB(1, 0), Bt, ldb, bcol, t + 3);
;       BAR; WAIT_L(0); MMA(0, 1, At, B1); BAR;
;       LDA(At, 1, 1); STAGE(SA(1, 0), Ab, lda, brow, t + 3);
	v_add_u32_e32 v167, s41, v155
	v_lshl_add_u64 v[246:247], v[138:139], 0, s[28:29]
	v_readfirstlane_b32 s50, v167
	v_lshl_add_u64 v[168:169], v[246:247], 0, s[16:17]
	s_mov_b32 m0, s50
	v_lshl_add_u64 v[248:249], v[136:137], 0, s[28:29]
	global_load_lds_dwordx4 v[168:169], off
	v_add_u32_e32 v168, 0x2000, v167
	v_lshl_add_u64 v[174:175], v[248:249], 0, s[16:17]
	v_readfirstlane_b32 s50, v168
	s_mov_b32 m0, s50
	s_nop 0
	global_load_lds_dwordx4 v[174:175], off
	s_waitcnt vmcnt(6)
	s_barrier
	v_mfma_f32_16x16x32_bf16 v[28:31], v[190:193], v[218:221], v[28:31]
	v_mfma_f32_16x16x32_bf16 v[24:27], v[190:193], v[226:229], v[24:27]
	v_mfma_f32_16x16x32_bf16 v[20:23], v[198:201], v[218:221], v[20:23]
	v_mfma_f32_16x16x32_bf16 v[16:19], v[198:201], v[226:229], v[16:19]
	v_mfma_f32_16x16x32_bf16 v[12:15], v[206:209], v[218:221], v[12:15]
	v_mfma_f32_16x16x32_bf16 v[8:11], v[206:209], v[226:229], v[8:11]
	v_mfma_f32_16x16x32_bf16 v[4:7], v[214:217], v[218:221], v[4:7]
	v_mfma_f32_16x16x32_bf16 v[0:3], v[214:217], v[226:229], v[0:3]
	v_mfma_f32_16x16x32_bf16 v[28:31], v[194:197], v[222:225], v[28:31]
	v_mfma_f32_16x16x32_bf16 v[24:27], v[194:197], v[230:233], v[24:27]
	v_mfma_f32_16x16x32_bf16 v[20:23], v[202:205], v[222:225], v[20:23]
	v_mfma_f32_16x16x32_bf16 v[16:19], v[202:205], v[230:233], v[16:19]
	v_mfma_f32_16x16x32_bf16 v[12:15], v[210:213], v[222:225], v[12:15]
	v_mfma_f32_16x16x32_bf16 v[8:11], v[210:213], v[230:233], v[8:11]
	v_mfma_f32_16x16x32_bf16 v[4:7], v[234:237], v[222:225], v[4:7]
	v_mfma_f32_16x16x32_bf16 v[0:3], v[234:237], v[230:233], v[0:3]
	s_barrier
	ds_read_b128 v[174:177], v158
	ds_read_b128 v[178:181], v158 offset:1024
	ds_read_b128 v[182:185], v158 offset:2048
	ds_read_b128 v[186:189], v158 offset:3072
	v_add_u32_e32 v169, 0x4000, v149
	v_add_u32_e32 v170, 0x6000, v149
	v_readfirstlane_b32 s50, v169
	v_lshl_add_u64 v[222:223], v[238:239], 0, s[18:19]
	s_mov_b32 m0, s50
	v_readfirstlane_b32 s50, v170
	global_load_lds_dwordx4 v[222:223], off
	v_lshl_add_u64 v[222:223], v[240:241], 0, s[18:19]
	s_mov_b32 m0, s50
	s_nop 0
	global_load_lds_dwordx4 v[222:223], off
	ds_read_b128 v[190:193], v154 offset:32768
	ds_read_b128 v[194:197], v154 offset:33792
	ds_read_b128 v[198:201], v153 offset:32768
	ds_read_b128 v[202:205], v153 offset:33792
	ds_read_b128 v[206:209], v151 offset:32768
	ds_read_b128 v[210:213], v151 offset:33792
	ds_read_b128 v[214:217], v150 offset:32768
	ds_read_b128 v[218:221], v150 offset:33792
	s_waitcnt lgkmcnt(8)
	s_barrier
	s_waitcnt lgkmcnt(0)
	s_waitcnt lgkmcnt(0)
	v_mfma_f32_16x16x32_bf16 v[124:127], v[190:193], v[174:177], v[124:127]
	v_mfma_f32_16x16x32_bf16 v[120:123], v[190:193], v[182:185], v[120:123]
	v_mfma_f32_16x16x32_bf16 v[116:119], v[198:201], v[174:177], v[116:119]
	v_mfma_f32_16x16x32_bf16 v[112:115], v[198:201], v[182:185], v[112:115]
	v_mfma_f32_16x16x32_bf16 v[108:111], v[206:209], v[174:177], v[108:111]
	v_mfma_f32_16x16x32_bf16 v[104:107], v[206:209], v[182:185], v[104:107]
	v_mfma_f32_16x16x32_bf16 v[100:103], v[214:217], v[174:177], v[100:103]
	v_mfma_f32_16x16x32_bf16 v[96:99], v[214:217], v[182:185], v[96:99]
	v_mfma_f32_16x16x32_bf16 v[124:127], v[194:197], v[178:181], v[124:127]
	v_mfma_f32_16x16x32_bf16 v[120:123], v[194:197], v[186:189], v[120:123]
	v_mfma_f32_16x16x32_bf16 v[116:119], v[202:205], v[178:181], v[116:119]
	v_mfma_f32_16x16x32_bf16 v[112:115], v[202:205], v[186:189], v[112:115]
	v_mfma_f32_16x16x32_bf16 v[108:111], v[210:213], v[178:181], v[108:111]
	v_mfma_f32_16x16x32_bf16 v[104:107], v[210:213], v[186:189], v[104:107]
	v_mfma_f32_16x16x32_bf16 v[100:103], v[218:221], v[178:181], v[100:103]
	v_mfma_f32_16x16x32_bf16 v[96:99], v[218:221], v[186:189], v[96:99]
	s_barrier
	v_readfirstlane_b32 s50, v157
	v_add_u32_e32 v173, 0x2000, v157
	v_lshl_add_u64 v[242:243], v[242:243], 0, s[20:21]
	s_mov_b32 m0, s50
	v_readfirstlane_b32 s50, v173
	global_load_lds_dwordx4 v[242:243], off
	v_lshl_add_u64 v[242:243], v[244:245], 0, s[20:21]
	s_mov_b32 m0, s50
	s_nop 0
	global_load_lds_dwordx4 v[242:243], off
	ds_read_b128 v[222:225], v156
	ds_read_b128 v[226:229], v156 offset:1024
	ds_read_b128 v[230:233], v156 offset:2048
	ds_read_b128 v[234:237], v156 offset:3072
	s_barrier
	s_waitcnt lgkmcnt(0)
	s_waitcnt lgkmcnt(0)
	v_mfma_f32_16x16x32_bf16 v[92:95], v[190:193], v[222:225], v[92:95]
	v_mfma_f32_16x16x32_bf16 v[88:91], v[190:193], v[230:233], v[88:91]
	v_mfma_f32_16x16x32_bf16 v[84:87], v[198:201], v[222:225], v[84:87]
	v_mfma_f32_16x16x32_bf16 v[80:83], v[198:201], v[230:233], v[80:83]
	v_mfma_f32_16x16x32_bf16 v[76:79], v[206:209], v[222:225], v[76:79]
	v_mfma_f32_16x16x32_bf16 v[72:75], v[206:209], v[230:233], v[72:75]
	v_mfma_f32_16x16x32_bf16 v[68:71], v[214:217], v[222:225], v[68:71]
	v_mfma_f32_16x16x32_bf16 v[64:67], v[214:217], v[230:233], v[64:67]
	v_mfma_f32_16x16x32_bf16 v[92:95], v[194:197], v[226:229], v[92:95]
	v_mfma_f32_16x16x32_bf16 v[88:91], v[194:197], v[234:237], v[88:91]
	v_mfma_f32_16x16x32_bf16 v[84:87], v[202:205], v[226:229], v[84:87]
	v_mfma_f32_16x16x32_bf16 v[80:83], v[202:205], v[234:237], v[80:83]
	v_mfma_f32_16x16x32_bf16 v[76:79], v[210:213], v[226:229], v[76:79]
	v_mfma_f32_16x16x32_bf16 v[72:75], v[210:213], v[234:237], v[72:75]
	v_mfma_f32_16x16x32_bf16 v[68:71], v[218:221], v[226:229], v[68:71]
	v_mfma_f32_16x16x32_bf16 v[64:67], v[218:221], v[234:237], v[64:67]
	v_readfirstlane_b32 s50, v159
	v_lshl_add_u64 v[238:239], v[238:239], 0, s[22:23]
	s_mov_b32 m0, s50
	v_readfirstlane_b32 s50, v160
	s_barrier
; #define STAGE(P, BASE, LD, br, kt) do { const char* _g = (const char*)((BASE) + (size_t)(br) * (LD) + (size_t)(kt) * 64); \
;     for (int _i = 0; _i < 2; ++_i) { int _b = tidx * 16 + _i * 8192; int _r, _c; stage_rc(_b, _r, _c); \
;       __builtin_amdgcn_global_load_lds((const unsigned*)(_g + (unsigned)((_r * (LD) + _c) * 2)), (unsigned*)((char*)(P) + _b), 16, 0, 0); } } while (0)
; #define LDA(dst, b, h) for (int m = 0; m < 4; ++m) for (int k = 0; k < 2; ++k) \
;     dst[m][k] = *reinterpret_cast<const bf16x8*>((char*)SA(b, h) + lds_byte(wr * 64 + m * 16 + fr, k * 32 + fq * 8))
; #define LDB(dst, b, h) for (int n = 0; n < 2; ++n) for (int k = 0; k < 2; ++k) \
;     dst[n][k] = *reinterpret_cast<const bf16x8*>((char*)SB(b, h) + lds_byte(wc * 32 + n * 16 + fr, k * 32 + fq * 8))
; #define MMA(ai, bj, At_, Bt_) do { __builtin_amdgcn_s_setprio(1); \
;     for (int k = 0; k < 2; ++k) for (int m = 0; m < 4; ++m) for (int n = 0; n < 2; ++n) \
;       acc[ai][bj][m][n] = __builtin_amdgcn_mfma_f32_16x16x32_bf16(At_[m][k], Bt_[n][k], acc[ai][bj][m][n], 0, 0, 0); \
;     __builtin_amdgcn_s_setprio(0); } while (0)
; #define WAIT_V(n) asm volatile("s_waitcnt vmcnt(" #n ")" ::: "memory")
; #define WAIT_L(n) asm volatile("s_waitcnt lgkmcnt(" #n ")" ::: "memory")
; #define BAR __builtin_amdgcn_s_barrier()
; #define SCHED __builtin_amdgcn_sched_barrier(0)
; template <int EPI, int lda, int ldb, int N, int K>
; __device__ __forceinline__ void gemm_phase(const u16* __restrict__ A, const u16* __restrict__ Bt, const GemmEpi ep, int wv) {
;     ...
;       LDA(At, 1, 1); STAGE(SA(1, 0), Ab, lda, brow, t + 3);
;       BAR; WAIT_L(0); MMA(1, 0, At, B0); BAR; SCHED;
;       STAGE(SB(1, 1), Bt, ldb, bcol + HALF, t + 3);
;       WAIT_V(6); BAR; MMA(1, 1, At, B1); BAR;
;     }
;     { LDB(B0, 0, 0); LDA(At, 0, 0); STAGE(SA(1, 1), Ab, lda, brow + HALF, nt - 1);
;       BAR; WAIT_L(0); MMA(0, 0, At, B0); BAR;
	global_load_lds_dwordx4 v[238:239], off
	v_lshl_add_u64 v[238:239], v[240:241], 0, s[22:23]
	s_mov_b32 m0, s50
	s_nop 0
	global_load_lds_dwordx4 v[238:239], off
	ds_read_b128 v[190:193], v154 offset:49152
	ds_read_b128 v[194:197], v154 offset:50176
	ds_read_b128 v[198:201], v153 offset:49152
	ds_read_b128 v[202:205], v153 offset:50176
	ds_read_b128 v[206:209], v151 offset:49152
	ds_read_b128 v[210:213], v151 offset:50176
	ds_read_b128 v[214:217], v150 offset:49152
	ds_read_b128 v[218:221], v150 offset:50176
	s_barrier
	s_waitcnt lgkmcnt(0)
	s_waitcnt lgkmcnt(0)
	v_mfma_f32_16x16x32_bf16 v[60:63], v[190:193], v[174:177], v[60:63]
	v_mfma_f32_16x16x32_bf16 v[56:59], v[190:193], v[182:185], v[56:59]
	v_mfma_f32_16x16x32_bf16 v[52:55], v[198:201], v[174:177], v[52:55]
	v_mfma_f32_16x16x32_bf16 v[48:51], v[198:201], v[182:185], v[48:51]
	v_mfma_f32_16x16x32_bf16 v[44:47], v[206:209], v[174:177], v[44:47]
	v_mfma_f32_16x16x32_bf16 v[40:43], v[206:209], v[182:185], v[40:43]
	v_mfma_f32_16x16x32_bf16 v[36:39], v[214:217], v[174:177], v[36:39]
	v_mfma_f32_16x16x32_bf16 v[32:35], v[214:217], v[182:185], v[32:35]
	v_mfma_f32_16x16x32_bf16 v[60:63], v[194:197], v[178:181], v[60:63]
	v_mfma_f32_16x16x32_bf16 v[56:59], v[194:197], v[186:189], v[56:59]
	v_mfma_f32_16x16x32_bf16 v[52:55], v[202:205], v[178:181], v[52:55]
	v_mfma_f32_16x16x32_bf16 v[48:51], v[202:205], v[186:189], v[48:51]
	v_mfma_f32_16x16x32_bf16 v[44:47], v[210:213], v[178:181], v[44:47]
	v_mfma_f32_16x16x32_bf16 v[40:43], v[210:213], v[186:189], v[40:43]
	v_mfma_f32_16x16x32_bf16 v[36:39], v[218:221], v[178:181], v[36:39]
	v_mfma_f32_16x16x32_bf16 v[32:35], v[218:221], v[186:189], v[32:35]
	s_barrier
	v_readfirstlane_b32 s50, v161
	v_add_u32_e32 v173, 0x2000, v161
	v_lshl_add_u64 v[174:175], v[246:247], 0, s[24:25]
	s_mov_b32 m0, s50
	v_readfirstlane_b32 s50, v173
	global_load_lds_dwordx4 v[174:175], off
	v_lshl_add_u64 v[174:175], v[248:249], 0, s[24:25]
	s_mov_b32 m0, s50
	s_nop 0
	global_load_lds_dwordx4 v[174:175], off
	s_waitcnt vmcnt(6)
	s_barrier
	v_mfma_f32_16x16x32_bf16 v[28:31], v[190:193], v[222:225], v[28:31]
	v_mfma_f32_16x16x32_bf16 v[24:27], v[190:193], v[230:233], v[24:27]
	v_mfma_f32_16x16x32_bf16 v[20:23], v[198:201], v[222:225], v[20:23]
	v_mfma_f32_16x16x32_bf16 v[16:19], v[198:201], v[230:233], v[16:19]
	v_mfma_f32_16x16x32_bf16 v[12:15], v[206:209], v[222:225], v[12:15]
	v_mfma_f32_16x16x32_bf16 v[8:11], v[206:209], v[230:233], v[8:11]
	v_mfma_f32_16x16x32_bf16 v[4:7], v[214:217], v[222:225], v[4:7]
	v_mfma_f32_16x16x32_bf16 v[0:3], v[214:217], v[230:233], v[0:3]
	v_mfma_f32_16x16x32_bf16 v[28:31], v[194:197], v[226:229], v[28:31]
	v_mfma_f32_16x16x32_bf16 v[24:27], v[194:197], v[234:237], v[24:27]
	v_mfma_f32_16x16x32_bf16 v[20:23], v[202:205], v[226:229], v[20:23]
	v_mfma_f32_16x16x32_bf16 v[16:19], v[202:205], v[234:237], v[16:19]
	v_mfma_f32_16x16x32_bf16 v[12:15], v[210:213], v[226:229], v[12:15]
	v_mfma_f32_16x16x32_bf16 v[8:11], v[210:213], v[234:237], v[8:11]
	v_mfma_f32_16x16x32_bf16 v[4:7], v[218:221], v[226:229], v[4:7]
	v_mfma_f32_16x16x32_bf16 v[0:3], v[218:221], v[234:237], v[0:3]
	s_add_i32 s49, s49, 2
	s_add_u32 s28, s28, 0x100
	s_addc_u32 s29, s29, 0
	s_cmpk_gt_u32 s49, 0x51
	s_barrier
	s_cbranch_scc0 .LBB0_1624
	s_add_i32 s28, s48, 0x80
	s_mul_hi_i32 s29, s28, 0x2b00
	s_mulk_i32 s28, 0x2b00
	s_add_u32 s28, s34, s28
	s_addc_u32 s29, s35, s29
	s_add_u32 s28, s28, 0x2a80
	s_addc_u32 s29, s29, 0
	v_readfirstlane_b32 s49, v171
	v_lshl_add_u64 v[160:161], s[28:29], 0, v[128:129]
	s_mov_b32 m0, s49
	ds_read_b128 v[132:135], v163
	ds_read_b128 v[136:139], v163 offset:1024
	ds_read_b128 v[140:143], v163 offset:2048
	ds_read_b128 v[174:177], v163 offset:3072
	ds_read_b128 v[178:181], v154
	ds_read_b128 v[182:185], v154 offset:1024
	ds_read_b128 v[186:189], v153
	ds_read_b128 v[190:193], v153 offset:1024
	ds_read_b128 v[194:197], v151
	ds_read_b128 v[198:201], v151 offset:1024
	ds_read_b128 v[202:205], v150
	ds_read_b128 v[206:209], v150 offset:1024
	global_load_lds_dwordx4 v[160:161], off
	v_lshl_add_u64 v[160:161], s[28:29], 0, v[130:131]
	v_readfirstlane_b32 s28, v172
	s_mov_b32 m0, s28
	s_nop 0
	global_load_lds_dwordx4 v[160:161], off
	s_barrier
	s_waitcnt lgkmcnt(0)
	s_waitcnt lgkmcnt(0)
	v_mfma_f32_16x16x32_bf16 v[124:127], v[178:181], v[132:135], v[124:127]
	v_mfma_f32_16x16x32_bf16 v[120:123], v[178:181], v[140:143], v[120:123]
	v_mfma_f32_16x16x32_bf16 v[116:119], v[186:189], v[132:135], v[116:119]
	v_mfma_f32_16x16x32_bf16 v[112:115], v[186:189], v[140:143], v[112:115]
	v_mfma_f32_16x16x32_bf16 v[108:111], v[194:197], v[132:135], v[108:111]
	v_mfma_f32_16x16x32_bf16 v[104:107], v[194:197], v[140:143], v[104:107]
	v_mfma_f32_16x16x32_bf16 v[100:103], v[202:205], v[132:135], v[100:103]
	v_mfma_f32_16x16x32_bf16 v[96:99], v[202:205], v[140:143], v[96:99]
	v_mfma_f32_16x16x32_bf16 v[124:127], v[182:185], v[136:139], v[124:127]
	v_mfma_f32_16x16x32_bf16 v[120:123], v[182:185], v[174:177], v[120:123]
	v_mfma_f32_16x16x32_bf16 v[116:119], v[190:193], v[136:139], v[116:119]
	v_mfma_f32_16x16x32_bf16 v[112:115], v[190:193], v[174:177], v[112:115]
	v_mfma_f32_16x16x32_bf16 v[108:111], v[198:201], v[136:139], v[108:111]
	v_mfma_f32_16x16x32_bf16 v[104:107], v[198:201], v[174:177], v[104:107]
	v_mfma_f32_16x16x32_bf16 v[100:103], v[206:209], v[136:139], v[100:103]
	v_mfma_f32_16x16x32_bf16 v[96:99], v[206:209], v[174:177], v[96:99]
	s_barrier
	ds_read_b128 v[210:213], v162
	ds_read_b128 v[214:217], v162 offset:1024
	ds_read_b128 v[218:221], v162 offset:2048
	ds_read_b128 v[160:163], v162 offset:3072
	s_barrier
; #define LDA(dst, b, h) for (int m = 0; m < 4; ++m) for (int k = 0; k < 2; ++k) \
;     dst[m][k] = *reinterpret_cast<const bf16x8*>((char*)SA(b, h) + lds_byte(wr * 64 + m * 16 + fr, k * 32 + fq * 8))
; #define LDB(dst, b, h) for (int n = 0; n < 2; ++n) for (int k = 0; k < 2; ++k) \
;     dst[n][k] = *reinterpret_cast<const bf16x8*>((char*)SB(b, h) + lds_byte(wc * 32 + n * 16 + fr, k * 32 + fq * 8))
; #define MMA(ai, bj, At_, Bt_) do { __builtin_amdgcn_s_setprio(1); \
;     for (int k = 0; k < 2; ++k) for (int m = 0; m < 4; ++m) for (int n = 0; n < 2; ++n) \
;       acc[ai][bj][m][n] = __builtin_amdgcn_mfma_f32_16x16x32_bf16(At_[m][k], Bt_[n][k], acc[ai][bj][m][n], 0, 0, 0); \
;     __builtin_amdgcn_s_setprio(0); } while (0)
; #define WAIT_V(n) asm volatile("s_waitcnt vmcnt(" #n ")" ::: "memory")
; #define WAIT_L(n) asm volatile("s_waitcnt lgkmcnt(" #n ")" ::: "memory")
; #define BAR __builtin_amdgcn_s_barrier()
; template <int EPI, int lda, int ldb, int N, int K>
; __device__ __forceinline__ void gemm_phase(const u16* __restrict__ A, const u16* __restrict__ Bt, const GemmEpi ep, int wv) {
;     ...
;       BAR; WAIT_L(0); MMA(0, 0, At, B0); BAR;
;       LDB(B1, 0, 1); BAR; WAIT_L(0); MMA(0, 1, At, B1); BAR;
;       LDA(At, 0, 1); WAIT_V(4); BAR; WAIT_L(0); MMA(1, 0, At, B0); MMA(1, 1, At, B1); BAR; }
;     { LDB(B0, 1, 0); LDA(At, 1, 0); WAIT_V(2); BAR; WAIT_L(0); MMA(0, 0, At, B0); BAR;
	s_waitcnt lgkmcnt(0)
	s_waitcnt lgkmcnt(0)
	v_mfma_f32_16x16x32_bf16 v[92:95], v[178:181], v[210:213], v[92:95]
	v_mfma_f32_16x16x32_bf16 v[88:91], v[178:181], v[218:221], v[88:91]
	v_mfma_f32_16x16x32_bf16 v[72:75], v[194:197], v[218:221], v[72:75]
	v_mfma_f32_16x16x32_bf16 v[68:71], v[202:205], v[210:213], v[68:71]
	v_mfma_f32_16x16x32_bf16 v[84:87], v[186:189], v[210:213], v[84:87]
	v_mfma_f32_16x16x32_bf16 v[80:83], v[186:189], v[218:221], v[80:83]
	v_mfma_f32_16x16x32_bf16 v[76:79], v[194:197], v[210:213], v[76:79]
	v_mfma_f32_16x16x32_bf16 v[64:67], v[202:205], v[218:221], v[64:67]
	v_mfma_f32_16x16x32_bf16 v[92:95], v[182:185], v[214:217], v[92:95]
	v_mfma_f32_16x16x32_bf16 v[88:91], v[182:185], v[160:163], v[88:91]
	v_mfma_f32_16x16x32_bf16 v[72:75], v[198:201], v[160:163], v[72:75]
	v_mfma_f32_16x16x32_bf16 v[68:71], v[206:209], v[214:217], v[68:71]
	v_mfma_f32_16x16x32_bf16 v[178:181], v[190:193], v[214:217], v[84:87]
	v_mfma_f32_16x16x32_bf16 v[182:185], v[190:193], v[160:163], v[80:83]
	v_mfma_f32_16x16x32_bf16 v[186:189], v[198:201], v[214:217], v[76:79]
	v_mfma_f32_16x16x32_bf16 v[190:193], v[206:209], v[160:163], v[64:67]
	s_barrier
	s_nop 0
	ds_read_b128 v[64:67], v154 offset:16384
	ds_read_b128 v[76:79], v154 offset:17408
	ds_read_b128 v[80:83], v153 offset:16384
	ds_read_b128 v[84:87], v153 offset:17408
	ds_read_b128 v[194:197], v151 offset:16384
	ds_read_b128 v[198:201], v151 offset:17408
	ds_read_b128 v[202:205], v150 offset:16384
	ds_read_b128 v[206:209], v150 offset:17408
	s_waitcnt vmcnt(4)
	s_barrier
	s_waitcnt lgkmcnt(0)
	s_waitcnt lgkmcnt(0)
	v_mfma_f32_16x16x32_bf16 v[60:63], v[64:67], v[132:135], v[60:63]
	v_mfma_f32_16x16x32_bf16 v[56:59], v[64:67], v[140:143], v[56:59]
	v_mfma_f32_16x16x32_bf16 v[52:55], v[80:83], v[132:135], v[52:55]
	v_mfma_f32_16x16x32_bf16 v[48:51], v[80:83], v[140:143], v[48:51]
	v_mfma_f32_16x16x32_bf16 v[44:47], v[194:197], v[132:135], v[44:47]
	v_mfma_f32_16x16x32_bf16 v[40:43], v[194:197], v[140:143], v[40:43]
	v_mfma_f32_16x16x32_bf16 v[36:39], v[202:205], v[132:135], v[36:39]
	v_mfma_f32_16x16x32_bf16 v[32:35], v[202:205], v[140:143], v[32:35]
	v_mfma_f32_16x16x32_bf16 v[60:63], v[76:79], v[136:139], v[60:63]
	v_mfma_f32_16x16x32_bf16 v[56:59], v[76:79], v[174:177], v[56:59]
	v_mfma_f32_16x16x32_bf16 v[52:55], v[84:87], v[136:139], v[52:55]
	v_mfma_f32_16x16x32_bf16 v[48:51], v[84:87], v[174:177], v[48:51]
	v_mfma_f32_16x16x32_bf16 v[44:47], v[198:201], v[136:139], v[44:47]
	v_mfma_f32_16x16x32_bf16 v[40:43], v[198:201], v[174:177], v[40:43]
	v_mfma_f32_16x16x32_bf16 v[36:39], v[206:209], v[136:139], v[36:39]
	v_mfma_f32_16x16x32_bf16 v[32:35], v[206:209], v[174:177], v[32:35]
	v_mfma_f32_16x16x32_bf16 v[28:31], v[64:67], v[210:213], v[28:31]
	v_mfma_f32_16x16x32_bf16 v[24:27], v[64:67], v[218:221], v[24:27]
	v_mfma_f32_16x16x32_bf16 v[12:15], v[194:197], v[210:213], v[12:15]
	v_mfma_f32_16x16x32_bf16 v[8:11], v[194:197], v[218:221], v[8:11]
	v_mfma_f32_16x16x32_bf16 v[20:23], v[80:83], v[210:213], v[20:23]
	v_mfma_f32_16x16x32_bf16 v[16:19], v[80:83], v[218:221], v[16:19]
	v_mfma_f32_16x16x32_bf16 v[4:7], v[202:205], v[210:213], v[4:7]
	v_mfma_f32_16x16x32_bf16 v[0:3], v[202:205], v[218:221], v[0:3]
	v_mfma_f32_16x16x32_bf16 v[28:31], v[76:79], v[214:217], v[28:31]
	v_mfma_f32_16x16x32_bf16 v[24:27], v[76:79], v[160:163], v[24:27]
	v_mfma_f32_16x16x32_bf16 v[12:15], v[198:201], v[214:217], v[12:15]
	v_mfma_f32_16x16x32_bf16 v[8:11], v[198:201], v[160:163], v[8:11]
	v_mfma_f32_16x16x32_bf16 v[132:135], v[84:87], v[214:217], v[20:23]
	v_mfma_f32_16x16x32_bf16 v[136:139], v[84:87], v[160:163], v[16:19]
	v_mfma_f32_16x16x32_bf16 v[140:143], v[206:209], v[214:217], v[4:7]
	v_mfma_f32_16x16x32_bf16 v[160:163], v[206:209], v[160:163], v[0:3]
	s_barrier
	s_nop 0
	ds_read_b128 v[0:3], v158
	ds_read_b128 v[4:7], v158 offset:1024
	ds_read_b128 v[16:19], v158 offset:2048
	ds_read_b128 v[172:175], v158 offset:3072
	ds_read_b128 v[20:23], v154 offset:32768
	ds_read_b128 v[194:197], v154 offset:33792
	ds_read_b128 v[198:201], v153 offset:32768
	ds_read_b128 v[202:205], v153 offset:33792
	ds_read_b128 v[206:209], v151 offset:32768
	ds_read_b128 v[210:213], v151 offset:33792
	ds_read_b128 v[214:217], v150 offset:32768
	ds_read_b128 v[218:221], v150 offset:33792
	s_waitcnt vmcnt(2)
	s_barrier
; #define LDA(dst, b, h) for (int m = 0; m < 4; ++m) for (int k = 0; k < 2; ++k) \
;     dst[m][k] = *reinterpret_cast<const bf16x8*>((char*)SA(b, h) + lds_byte(wr * 64 + m * 16 + fr, k * 32 + fq * 8))
; #define LDB(dst, b, h) for (int n = 0; n < 2; ++n) for (int k = 0; k < 2; ++k) \
;     dst[n][k] = *reinterpret_cast<const bf16x8*>((char*)SB(b, h) + lds_byte(wc * 32 + n * 16 + fr, k * 32 + fq * 8))
; #define MMA(ai, bj, At_, Bt_) do { __builtin_amdgcn_s_setprio(1); \
;     for (int k = 0; k < 2; ++k) for (int m = 0; m < 4; ++m) for (int n = 0; n < 2; ++n) \
;       acc[ai][bj][m][n] = __builtin_amdgcn_mfma_f32_16x16x32_bf16(At_[m][k], Bt_[n][k], acc[ai][bj][m][n], 0, 0, 0); \
;     __builtin_amdgcn_s_setprio(0); } while (0)
; #define WAIT_V(n) asm volatile("s_waitcnt vmcnt(" #n ")" ::: "memory")
; #define WAIT_L(n) asm volatile("s_waitcnt lgkmcnt(" #n ")" ::: "memory")
; #define BAR __builtin_amdgcn_s_barrier()
; template <int EPI, int lda, int ldb, int N, int K>
; __device__ __forceinline__ void gemm_phase(const u16* __restrict__ A, const u16* __restrict__ Bt, const GemmEpi ep, int wv) {
;     ...
;     { LDB(B0, 1, 0); LDA(At, 1, 0); WAIT_V(2); BAR; WAIT_L(0); MMA(0, 0, At, B0); BAR;
;       LDB(B1, 1, 1); WAIT_V(0); BAR; WAIT_L(0); MMA(0, 1, At, B1); BAR;
;       LDA(At, 1, 1); BAR; WAIT_L(0); MMA(1, 0, At, B0); MMA(1, 1, At, B1); BAR; }
;     if (wr == 0) BAR;
	s_waitcnt lgkmcnt(0)
	s_waitcnt lgkmcnt(0)
	v_mfma_f32_16x16x32_bf16 v[64:67], v[20:23], v[0:3], v[124:127]
	v_mfma_f32_16x16x32_bf16 v[76:79], v[20:23], v[16:19], v[120:123]
	v_mfma_f32_16x16x32_bf16 v[80:83], v[198:201], v[0:3], v[116:119]
	v_mfma_f32_16x16x32_bf16 v[84:87], v[198:201], v[16:19], v[112:115]
	v_mfma_f32_16x16x32_bf16 v[108:111], v[206:209], v[0:3], v[108:111]
	v_mfma_f32_16x16x32_bf16 v[104:107], v[206:209], v[16:19], v[104:107]
	v_mfma_f32_16x16x32_bf16 v[120:123], v[214:217], v[0:3], v[100:103]
	v_mfma_f32_16x16x32_bf16 v[124:127], v[214:217], v[16:19], v[96:99]
	v_mfma_f32_16x16x32_bf16 v[116:119], v[194:197], v[4:7], v[64:67]
	v_mfma_f32_16x16x32_bf16 v[112:115], v[194:197], v[172:175], v[76:79]
	v_mfma_f32_16x16x32_bf16 v[100:103], v[202:205], v[4:7], v[80:83]
	v_mfma_f32_16x16x32_bf16 v[96:99], v[202:205], v[172:175], v[84:87]
	v_mfma_f32_16x16x32_bf16 v[84:87], v[210:213], v[4:7], v[108:111]
	v_mfma_f32_16x16x32_bf16 v[80:83], v[210:213], v[172:175], v[104:107]
	v_mfma_f32_16x16x32_bf16 v[76:79], v[218:221], v[4:7], v[120:123]
	v_mfma_f32_16x16x32_bf16 v[64:67], v[218:221], v[172:175], v[124:127]
	s_barrier
	ds_read_b128 v[222:225], v156
	ds_read_b128 v[226:229], v156 offset:1024
	ds_read_b128 v[230:233], v156 offset:2048
	ds_read_b128 v[156:159], v156 offset:3072
	s_waitcnt vmcnt(0)
	s_barrier
	s_waitcnt lgkmcnt(0)
	s_waitcnt lgkmcnt(0)
	v_mfma_f32_16x16x32_bf16 v[92:95], v[20:23], v[222:225], v[92:95]
	v_mfma_f32_16x16x32_bf16 v[20:23], v[20:23], v[230:233], v[88:91]
	v_mfma_f32_16x16x32_bf16 v[88:91], v[198:201], v[222:225], v[178:181]
	v_mfma_f32_16x16x32_bf16 v[104:107], v[198:201], v[230:233], v[182:185]
	v_mfma_f32_16x16x32_bf16 v[176:179], v[206:209], v[222:225], v[186:189]
	v_mfma_f32_16x16x32_bf16 v[72:75], v[206:209], v[230:233], v[72:75]
	v_mfma_f32_16x16x32_bf16 v[68:71], v[214:217], v[222:225], v[68:71]
	v_mfma_f32_16x16x32_bf16 v[180:183], v[214:217], v[230:233], v[190:193]
	v_mfma_f32_16x16x32_bf16 v[124:127], v[194:197], v[226:229], v[92:95]
	v_mfma_f32_16x16x32_bf16 v[120:123], v[194:197], v[156:159], v[20:23]
	v_mfma_f32_16x16x32_bf16 v[108:111], v[202:205], v[226:229], v[88:91]
	v_mfma_f32_16x16x32_bf16 v[104:107], v[202:205], v[156:159], v[104:107]
	v_mfma_f32_16x16x32_bf16 v[92:95], v[210:213], v[226:229], v[176:179]
	v_mfma_f32_16x16x32_bf16 v[88:91], v[210:213], v[156:159], v[72:75]
	v_mfma_f32_16x16x32_bf16 v[72:75], v[218:221], v[226:229], v[68:71]
	v_mfma_f32_16x16x32_bf16 v[68:71], v[218:221], v[156:159], v[180:183]
	s_barrier
	ds_read_b128 v[176:179], v154 offset:49152
	ds_read_b128 v[180:183], v154 offset:50176
	ds_read_b128 v[184:187], v153 offset:49152
	ds_read_b128 v[188:191], v153 offset:50176
	ds_read_b128 v[192:195], v151 offset:49152
	ds_read_b128 v[196:199], v151 offset:50176
	ds_read_b128 v[200:203], v150 offset:49152
	ds_read_b128 v[204:207], v150 offset:50176
	s_barrier
	s_waitcnt lgkmcnt(0)
	s_waitcnt lgkmcnt(0)
	v_mfma_f32_16x16x32_bf16 v[20:23], v[176:179], v[0:3], v[60:63]
	v_mfma_f32_16x16x32_bf16 v[56:59], v[176:179], v[16:19], v[56:59]
	v_mfma_f32_16x16x32_bf16 v[60:63], v[184:187], v[0:3], v[52:55]
	v_mfma_f32_16x16x32_bf16 v[208:211], v[184:187], v[16:19], v[48:51]
	v_mfma_f32_16x16x32_bf16 v[44:47], v[192:195], v[0:3], v[44:47]
	v_mfma_f32_16x16x32_bf16 v[40:43], v[192:195], v[16:19], v[40:43]
	v_mfma_f32_16x16x32_bf16 v[0:3], v[200:203], v[0:3], v[36:39]
	v_mfma_f32_16x16x32_bf16 v[212:215], v[200:203], v[16:19], v[32:35]
	v_mfma_f32_16x16x32_bf16 v[52:55], v[180:183], v[4:7], v[20:23]
	v_mfma_f32_16x16x32_bf16 v[48:51], v[180:183], v[172:175], v[56:59]
	v_mfma_f32_16x16x32_bf16 v[36:39], v[188:191], v[4:7], v[60:63]
	v_mfma_f32_16x16x32_bf16 v[32:35], v[188:191], v[172:175], v[208:211]
	v_mfma_f32_16x16x32_bf16 v[20:23], v[196:199], v[4:7], v[44:47]
	v_mfma_f32_16x16x32_bf16 v[16:19], v[196:199], v[172:175], v[40:43]
	v_mfma_f32_16x16x32_bf16 v[4:7], v[204:207], v[4:7], v[0:3]
	v_mfma_f32_16x16x32_bf16 v[0:3], v[204:207], v[172:175], v[212:215]
	v_mfma_f32_16x16x32_bf16 v[28:31], v[176:179], v[222:225], v[28:31]
	v_mfma_f32_16x16x32_bf16 v[24:27], v[176:179], v[230:233], v[24:27]
	v_mfma_f32_16x16x32_bf16 v[40:43], v[184:187], v[222:225], v[132:135]
	v_mfma_f32_16x16x32_bf16 v[132:135], v[184:187], v[230:233], v[136:139]
	v_mfma_f32_16x16x32_bf16 v[12:15], v[192:195], v[222:225], v[12:15]
	v_mfma_f32_16x16x32_bf16 v[8:11], v[192:195], v[230:233], v[8:11]
	v_mfma_f32_16x16x32_bf16 v[136:139], v[200:203], v[222:225], v[140:143]
	v_mfma_f32_16x16x32_bf16 v[140:143], v[200:203], v[230:233], v[160:163]
	v_mfma_f32_16x16x32_bf16 v[60:63], v[180:183], v[226:229], v[28:31]
	v_mfma_f32_16x16x32_bf16 v[56:59], v[180:183], v[156:159], v[24:27]
	v_mfma_f32_16x16x32_bf16 v[44:47], v[188:191], v[226:229], v[40:43]
	v_mfma_f32_16x16x32_bf16 v[40:43], v[188:191], v[156:159], v[132:135]
	v_mfma_f32_16x16x32_bf16 v[28:31], v[196:199], v[226:229], v[12:15]
	v_mfma_f32_16x16x32_bf16 v[24:27], v[196:199], v[156:159], v[8:11]
	v_mfma_f32_16x16x32_bf16 v[12:15], v[204:207], v[226:229], v[136:139]
	v_mfma_f32_16x16x32_bf16 v[8:11], v[204:207], v[156:159], v[140:143]
	v_cmp_gt_u32_e32 vcc, s46, v147
	s_barrier
	s_and_saveexec_b64 s[28:29], vcc
	s_cbranch_execz .LBB0_1627
	s_barrier
